# GEMM K-loops: back edge rotated (7.11) - counter/exit test and next-iteration address selects moved in front of the loop-back barrier, exit path gets its own barrier copy (9 loops), on top of v030
# baseline (speedup 1.0000x reference)
; #define PG8_STAGE(bufoff, gbase, voff) do { _Pragma("unroll") for (int _i = 0; _i < 2; ++_i) \
;         __builtin_amdgcn_global_load_lds((const unsigned*)((const char*)(gbase) + (voff)[_i]), (LAS unsigned*)(lds + (bufoff) + ldsw + _i * 8192), 16, 0, 0); } while (0)
; #define PG8_LDA(dst, b, h) do { _Pragma("unroll") for (int m = 0; m < 4; ++m) _Pragma("unroll") for (int k = 0; k < 2; ++k) dst[m][k] = *(const LAS bf16x8*)(lds + PG8_SA(b, h) + aoff + m * 2048 + k * 1024); } while (0)
; #define PG8_LDB(dst, b, h) do { _Pragma("unroll") for (int n = 0; n < 2; ++n) _Pragma("unroll") for (int k = 0; k < 2; ++k) dst[n][k] = *(const LAS bf16x8*)(lds + PG8_SB(b, h) + boff + n * 2048 + k * 1024); } while (0)
; #define PG8_MMA(ai, bj, At, Bt) do { __builtin_amdgcn_s_setprio(1); _Pragma("unroll") for (int m = 0; m < 4; ++m) _Pragma("unroll") for (int n = 0; n < 2; ++n) _Pragma("unroll") for (int k = 0; k < 2; ++k) \
;         acc[ai][bj][m][n] = __builtin_amdgcn_mfma_f32_16x16x32_bf16(Bt[n][k], At[m][k], acc[ai][bj][m][n], 0, 0, 0); __builtin_amdgcn_s_setprio(0); } while (0)
; #define PG8_WAIT_V(n) asm volatile("s_waitcnt vmcnt(" #n ")" ::: "memory")
; #define PG8_BAR __builtin_amdgcn_s_barrier()
; template <class Epi, bool ALIGN_EPI>
; DI void gemm_phase(LAS unsigned char* lds, const Sched& S, const Epi& E, int tid) {
;     ...
;         const bool has_next = S.next(ui + 1, nxt);
;         const char* nA = has_next ? nxt.a : cA; const char* nB = has_next ? nxt.b : cB;
;         const int nt = cur.nt;
;         for (int t = 0; t < nt; t += 2) {
;             const bool last = (t == nt - 2);
;             const char* a1 = cA + (size_t)(t + 1) * kstep;
;             const char* a2 = last ? nA : cA + (size_t)(t + 2) * kstep; const char* b2 = last ? nB : cB + (size_t)(t + 2) * kstep;
;             const char* a3 = a2 + kstep; const char* b3 = b2 + kstep;
;             PG8_LDB(B0, 0, 0); PG8_LDB(B1, 0, 1); PG8_SCHED; PG8_LDA(At, 0, 0); PG8_STAGE(PG8_SA(1, 1), a1 + hstepA, voffA);
;             PG8_WAIT_V(8); PG8_WAIT_L(0); PG8_BAR; PG8_MMA(0, 0, At, B0); PG8_MMA(0, 1, At, B1); PG8_BAR; PG8_SCHED;
;             PG8_LDA(At, 0, 1); PG8_STAGE(PG8_SB(0, 0), b2, voffB); PG8_STAGE(PG8_SB(0, 1), b2 + hstepB, voffB); PG8_STAGE(PG8_SA(0, 0), a2, voffA);
;             PG8_WAIT_V(8); PG8_WAIT_L(0); PG8_BAR; PG8_MMA(1, 0, At, B0); PG8_MMA(1, 1, At, B1); PG8_BAR; PG8_SCHED;
.LBB0_324:
	s_add_u32 s22, s22, 0x40080
	s_addc_u32 s23, s23, 0
	s_add_u32 s45, s24, 0x100
	s_addc_u32 s46, s25, 0
	s_mov_b32 s47, -2
	s_add_u32 s24, s22, 0xfffc0080
	s_addc_u32 s25, s23, -1
	s_add_i32 s48, 0, 0x10000
	s_cmp_eq_u32 s47, 12
	s_cselect_b32 s27, s19, s25
	s_cselect_b32 s26, s18, s24
	v_add_u32_e32 v161, s48, v144
	s_cselect_b32 s25, s21, s46
	s_cselect_b32 s24, s20, s45
	s_add_i32 s50, 0, 0x14000
	ds_read_b128 v[148:151], v161
	ds_read_b128 v[152:155], v161 offset:1024
	ds_read_b128 v[156:159], v161 offset:2048
	ds_read_b128 v[162:165], v161 offset:3072
	v_add_u32_e32 v161, s50, v144
	ds_read_b128 v[166:169], v161
	ds_read_b128 v[170:173], v161 offset:1024
	ds_read_b128 v[174:177], v161 offset:2048
	ds_read_b128 v[178:181], v161 offset:3072
	v_lshl_add_u64 v[194:195], s[22:23], 0, v[140:141]
	s_add_i32 m0, s17, 0xc000
	ds_read_b128 v[182:185], v147
	ds_read_b128 v[186:189], v147 offset:1024
	ds_read_b128 v[190:193], v147 offset:2048
	ds_read_b128 v[202:205], v147 offset:3072
	ds_read_b128 v[206:209], v147 offset:4096
	ds_read_b128 v[210:213], v147 offset:5120
	ds_read_b128 v[214:217], v147 offset:6144
	ds_read_b128 v[218:221], v147 offset:7168
	global_load_lds_dwordx4 v[194:195], off
	v_lshl_add_u64 v[194:195], s[22:23], 0, v[142:143]
	s_add_i32 m0, s17, 0xe000
	s_nop 0
	global_load_lds_dwordx4 v[194:195], off
	s_waitcnt vmcnt(8)
	s_waitcnt lgkmcnt(0)
	s_barrier
	s_setprio 1
	s_waitcnt lgkmcnt(0)
	v_mfma_f32_16x16x32_bf16 v[128:131], v[148:151], v[182:185], 0
	v_mfma_f32_16x16x32_bf16 v[124:127], v[156:159], v[182:185], 0
	v_mfma_f32_16x16x32_bf16 v[112:115], v[148:151], v[190:193], 0
	v_mfma_f32_16x16x32_bf16 v[108:111], v[156:159], v[190:193], 0
	v_mfma_f32_16x16x32_bf16 v[96:99], v[148:151], v[206:209], 0
	v_mfma_f32_16x16x32_bf16 v[92:95], v[156:159], v[206:209], 0
	v_mfma_f32_16x16x32_bf16 v[80:83], v[148:151], v[214:217], 0
	v_mfma_f32_16x16x32_bf16 v[76:79], v[156:159], v[214:217], 0
	v_mfma_f32_16x16x32_bf16 v[128:131], v[152:155], v[186:189], v[128:131]
	v_mfma_f32_16x16x32_bf16 v[124:127], v[162:165], v[186:189], v[124:127]
	v_mfma_f32_16x16x32_bf16 v[112:115], v[152:155], v[202:205], v[112:115]
	v_mfma_f32_16x16x32_bf16 v[108:111], v[162:165], v[202:205], v[108:111]
	v_mfma_f32_16x16x32_bf16 v[96:99], v[152:155], v[210:213], v[96:99]
	v_mfma_f32_16x16x32_bf16 v[92:95], v[162:165], v[210:213], v[92:95]
	v_mfma_f32_16x16x32_bf16 v[80:83], v[152:155], v[218:221], v[80:83]
	v_mfma_f32_16x16x32_bf16 v[76:79], v[162:165], v[218:221], v[76:79]
	s_setprio 0
	s_setprio 1
	v_mfma_f32_16x16x32_bf16 v[120:123], v[166:169], v[182:185], 0
	v_mfma_f32_16x16x32_bf16 v[116:119], v[174:177], v[182:185], 0
	v_mfma_f32_16x16x32_bf16 v[104:107], v[166:169], v[190:193], 0
	v_mfma_f32_16x16x32_bf16 v[100:103], v[174:177], v[190:193], 0
	v_mfma_f32_16x16x32_bf16 v[88:91], v[166:169], v[206:209], 0
	v_mfma_f32_16x16x32_bf16 v[84:87], v[174:177], v[206:209], 0
	v_mfma_f32_16x16x32_bf16 v[72:75], v[166:169], v[214:217], 0
	v_mfma_f32_16x16x32_bf16 v[68:71], v[174:177], v[214:217], 0
	v_mfma_f32_16x16x32_bf16 v[120:123], v[170:173], v[186:189], v[120:123]
	v_mfma_f32_16x16x32_bf16 v[116:119], v[178:181], v[186:189], v[116:119]
	v_mfma_f32_16x16x32_bf16 v[104:107], v[170:173], v[202:205], v[104:107]
	v_mfma_f32_16x16x32_bf16 v[100:103], v[178:181], v[202:205], v[100:103]
	v_mfma_f32_16x16x32_bf16 v[88:91], v[170:173], v[210:213], v[88:91]
	v_mfma_f32_16x16x32_bf16 v[84:87], v[178:181], v[210:213], v[84:87]
	v_mfma_f32_16x16x32_bf16 v[72:75], v[170:173], v[218:221], v[72:75]
	v_mfma_f32_16x16x32_bf16 v[68:71], v[178:181], v[218:221], v[68:71]
	s_setprio 0
	s_barrier
	s_add_i32 s48, s48, s28
	v_lshl_add_u64 v[194:195], s[24:25], 0, v[136:137]
	s_mov_b32 m0, s48
	ds_read_b128 v[182:185], v147 offset:16384
	ds_read_b128 v[186:189], v147 offset:17408
	ds_read_b128 v[190:193], v147 offset:18432
	ds_read_b128 v[202:205], v147 offset:19456
	ds_read_b128 v[206:209], v147 offset:20480
	ds_read_b128 v[210:213], v147 offset:21504
	ds_read_b128 v[214:217], v147 offset:22528
	ds_read_b128 v[218:221], v147 offset:23552
	global_load_lds_dwordx4 v[194:195], off
	s_add_i32 m0, s48, 0x2000
	s_add_u32 s48, s24, 0x40000
	v_lshl_add_u64 v[222:223], s[24:25], 0, v[132:133]
	s_addc_u32 s49, s25, 0
	s_add_i32 s50, s50, s28
	global_load_lds_dwordx4 v[222:223], off
	v_lshl_add_u64 v[224:225], s[48:49], 0, v[136:137]
	s_mov_b32 m0, s50
	v_lshl_add_u64 v[226:227], s[26:27], 0, v[134:135]
	global_load_lds_dwordx4 v[224:225], off
	v_lshl_add_u64 v[224:225], s[48:49], 0, v[132:133]
	s_add_i32 m0, s50, 0x2000
	s_nop 0
	global_load_lds_dwordx4 v[224:225], off
	v_lshl_add_u64 v[224:225], s[26:27], 0, v[138:139]
	s_mov_b32 m0, s17
	s_nop 0
	global_load_lds_dwordx4 v[224:225], off
	s_mov_b32 m0, s36
	s_nop 0
	global_load_lds_dwordx4 v[226:227], off
	s_waitcnt vmcnt(8)
	s_waitcnt lgkmcnt(0)
	s_barrier
; #define PG8_STAGE(bufoff, gbase, voff) do { _Pragma("unroll") for (int _i = 0; _i < 2; ++_i) \
;         __builtin_amdgcn_global_load_lds((const unsigned*)((const char*)(gbase) + (voff)[_i]), (LAS unsigned*)(lds + (bufoff) + ldsw + _i * 8192), 16, 0, 0); } while (0)
; #define PG8_LDA(dst, b, h) do { _Pragma("unroll") for (int m = 0; m < 4; ++m) _Pragma("unroll") for (int k = 0; k < 2; ++k) dst[m][k] = *(const LAS bf16x8*)(lds + PG8_SA(b, h) + aoff + m * 2048 + k * 1024); } while (0)
; #define PG8_LDB(dst, b, h) do { _Pragma("unroll") for (int n = 0; n < 2; ++n) _Pragma("unroll") for (int k = 0; k < 2; ++k) dst[n][k] = *(const LAS bf16x8*)(lds + PG8_SB(b, h) + boff + n * 2048 + k * 1024); } while (0)
; #define PG8_MMA(ai, bj, At, Bt) do { __builtin_amdgcn_s_setprio(1); _Pragma("unroll") for (int m = 0; m < 4; ++m) _Pragma("unroll") for (int n = 0; n < 2; ++n) _Pragma("unroll") for (int k = 0; k < 2; ++k) \
;         acc[ai][bj][m][n] = __builtin_amdgcn_mfma_f32_16x16x32_bf16(Bt[n][k], At[m][k], acc[ai][bj][m][n], 0, 0, 0); __builtin_amdgcn_s_setprio(0); } while (0)
; #define PG8_WAIT_V(n) asm volatile("s_waitcnt vmcnt(" #n ")" ::: "memory")
; #define PG8_WAIT_L(n) asm volatile("s_waitcnt lgkmcnt(" #n ")" ::: "memory")
; #define PG8_BAR __builtin_amdgcn_s_barrier()
; #define PG8_SCHED __builtin_amdgcn_sched_barrier(0)
; template <class Epi, bool ALIGN_EPI>
; DI void gemm_phase(LAS unsigned char* lds, const Sched& S, const Epi& E, int tid) {
;     ...
;             PG8_WAIT_V(8); PG8_WAIT_L(0); PG8_BAR; PG8_MMA(0, 0, At, B0); PG8_MMA(0, 1, At, B1); PG8_BAR; PG8_SCHED;
;             PG8_LDA(At, 0, 1); PG8_STAGE(PG8_SB(0, 0), b2, voffB); PG8_STAGE(PG8_SB(0, 1), b2 + hstepB, voffB); PG8_STAGE(PG8_SA(0, 0), a2, voffA);
;             PG8_WAIT_V(8); PG8_WAIT_L(0); PG8_BAR; PG8_MMA(1, 0, At, B0); PG8_MMA(1, 1, At, B1); PG8_BAR; PG8_SCHED;
;             PG8_LDB(B0, 1, 0); PG8_LDB(B1, 1, 1); PG8_SCHED; PG8_LDA(At, 1, 0); PG8_STAGE(PG8_SA(0, 1), a2 + hstepA, voffA);
;             PG8_WAIT_V(8); PG8_WAIT_L(0); PG8_BAR; PG8_MMA(0, 0, At, B0); PG8_MMA(0, 1, At, B1); PG8_BAR; PG8_SCHED;
	s_setprio 1
	s_waitcnt lgkmcnt(0)
	v_mfma_f32_16x16x32_bf16 v[64:67], v[148:151], v[182:185], 0
	v_mfma_f32_16x16x32_bf16 v[60:63], v[156:159], v[182:185], 0
	v_mfma_f32_16x16x32_bf16 v[48:51], v[148:151], v[190:193], 0
	v_mfma_f32_16x16x32_bf16 v[44:47], v[156:159], v[190:193], 0
	v_mfma_f32_16x16x32_bf16 v[32:35], v[148:151], v[206:209], 0
	v_mfma_f32_16x16x32_bf16 v[28:31], v[156:159], v[206:209], 0
	v_mfma_f32_16x16x32_bf16 v[16:19], v[148:151], v[214:217], 0
	v_mfma_f32_16x16x32_bf16 v[12:15], v[156:159], v[214:217], 0
	v_mfma_f32_16x16x32_bf16 v[64:67], v[152:155], v[186:189], v[64:67]
	v_mfma_f32_16x16x32_bf16 v[60:63], v[162:165], v[186:189], v[60:63]
	v_mfma_f32_16x16x32_bf16 v[48:51], v[152:155], v[202:205], v[48:51]
	v_mfma_f32_16x16x32_bf16 v[44:47], v[162:165], v[202:205], v[44:47]
	v_mfma_f32_16x16x32_bf16 v[32:35], v[152:155], v[210:213], v[32:35]
	v_mfma_f32_16x16x32_bf16 v[28:31], v[162:165], v[210:213], v[28:31]
	v_mfma_f32_16x16x32_bf16 v[16:19], v[152:155], v[218:221], v[16:19]
	v_mfma_f32_16x16x32_bf16 v[12:15], v[162:165], v[218:221], v[12:15]
	s_setprio 0
	s_setprio 1
	v_mfma_f32_16x16x32_bf16 v[56:59], v[166:169], v[182:185], 0
	v_mfma_f32_16x16x32_bf16 v[52:55], v[174:177], v[182:185], 0
	v_mfma_f32_16x16x32_bf16 v[40:43], v[166:169], v[190:193], 0
	v_mfma_f32_16x16x32_bf16 v[36:39], v[174:177], v[190:193], 0
	v_mfma_f32_16x16x32_bf16 v[24:27], v[166:169], v[206:209], 0
	v_mfma_f32_16x16x32_bf16 v[20:23], v[174:177], v[206:209], 0
	v_mfma_f32_16x16x32_bf16 v[8:11], v[166:169], v[214:217], 0
	v_mfma_f32_16x16x32_bf16 v[4:7], v[174:177], v[214:217], 0
	v_mfma_f32_16x16x32_bf16 v[56:59], v[170:173], v[186:189], v[56:59]
	v_mfma_f32_16x16x32_bf16 v[52:55], v[178:181], v[186:189], v[52:55]
	v_mfma_f32_16x16x32_bf16 v[40:43], v[170:173], v[202:205], v[40:43]
	v_mfma_f32_16x16x32_bf16 v[36:39], v[178:181], v[202:205], v[36:39]
	v_mfma_f32_16x16x32_bf16 v[24:27], v[170:173], v[210:213], v[24:27]
	v_mfma_f32_16x16x32_bf16 v[20:23], v[178:181], v[210:213], v[20:23]
	v_mfma_f32_16x16x32_bf16 v[8:11], v[170:173], v[218:221], v[8:11]
	v_mfma_f32_16x16x32_bf16 v[4:7], v[178:181], v[218:221], v[4:7]
	s_setprio 0
	s_barrier
	s_add_i32 s48, 0, 0x18000
	v_add_u32_e32 v161, s48, v144
	s_add_i32 s49, 0, 0x1c000
	ds_read_b128 v[148:151], v161
	ds_read_b128 v[152:155], v161 offset:1024
	ds_read_b128 v[156:159], v161 offset:2048
	ds_read_b128 v[162:165], v161 offset:3072
	v_add_u32_e32 v161, s49, v144
	ds_read_b128 v[166:169], v161
	ds_read_b128 v[170:173], v161 offset:1024
	ds_read_b128 v[174:177], v161 offset:2048
	ds_read_b128 v[178:181], v161 offset:3072
	s_add_u32 s26, s26, 0x40000
	s_addc_u32 s27, s27, 0
	s_mov_b32 m0, s37
	v_lshl_add_u64 v[228:229], s[26:27], 0, v[138:139]
	ds_read_b128 v[182:185], v147 offset:32768
	ds_read_b128 v[186:189], v147 offset:33792
	ds_read_b128 v[190:193], v147 offset:34816
	ds_read_b128 v[202:205], v147 offset:35840
	ds_read_b128 v[206:209], v147 offset:36864
	ds_read_b128 v[210:213], v147 offset:37888
	ds_read_b128 v[214:217], v147 offset:38912
	ds_read_b128 v[218:221], v147 offset:39936
	global_load_lds_dwordx4 v[228:229], off
	v_lshl_add_u64 v[228:229], s[26:27], 0, v[134:135]
	s_mov_b32 m0, s38
	s_nop 0
	global_load_lds_dwordx4 v[228:229], off
	s_waitcnt vmcnt(8)
	s_waitcnt lgkmcnt(0)
	s_barrier
	s_setprio 1
	s_waitcnt lgkmcnt(0)
	v_mfma_f32_16x16x32_bf16 v[128:131], v[148:151], v[182:185], v[128:131]
	v_mfma_f32_16x16x32_bf16 v[124:127], v[156:159], v[182:185], v[124:127]
	v_mfma_f32_16x16x32_bf16 v[112:115], v[148:151], v[190:193], v[112:115]
	v_mfma_f32_16x16x32_bf16 v[108:111], v[156:159], v[190:193], v[108:111]
	v_mfma_f32_16x16x32_bf16 v[96:99], v[148:151], v[206:209], v[96:99]
	v_mfma_f32_16x16x32_bf16 v[92:95], v[156:159], v[206:209], v[92:95]
	v_mfma_f32_16x16x32_bf16 v[80:83], v[148:151], v[214:217], v[80:83]
	v_mfma_f32_16x16x32_bf16 v[76:79], v[156:159], v[214:217], v[76:79]
	v_mfma_f32_16x16x32_bf16 v[128:131], v[152:155], v[186:189], v[128:131]
	v_mfma_f32_16x16x32_bf16 v[124:127], v[162:165], v[186:189], v[124:127]
	v_mfma_f32_16x16x32_bf16 v[112:115], v[152:155], v[202:205], v[112:115]
	v_mfma_f32_16x16x32_bf16 v[108:111], v[162:165], v[202:205], v[108:111]
	v_mfma_f32_16x16x32_bf16 v[96:99], v[152:155], v[210:213], v[96:99]
	v_mfma_f32_16x16x32_bf16 v[92:95], v[162:165], v[210:213], v[92:95]
	v_mfma_f32_16x16x32_bf16 v[80:83], v[152:155], v[218:221], v[80:83]
	v_mfma_f32_16x16x32_bf16 v[76:79], v[162:165], v[218:221], v[76:79]
	s_setprio 0
	s_setprio 1
	v_mfma_f32_16x16x32_bf16 v[120:123], v[166:169], v[182:185], v[120:123]
	v_mfma_f32_16x16x32_bf16 v[116:119], v[174:177], v[182:185], v[116:119]
	v_mfma_f32_16x16x32_bf16 v[104:107], v[166:169], v[190:193], v[104:107]
	v_mfma_f32_16x16x32_bf16 v[100:103], v[174:177], v[190:193], v[100:103]
	v_mfma_f32_16x16x32_bf16 v[88:91], v[166:169], v[206:209], v[88:91]
	v_mfma_f32_16x16x32_bf16 v[84:87], v[174:177], v[206:209], v[84:87]
	v_mfma_f32_16x16x32_bf16 v[72:75], v[166:169], v[214:217], v[72:75]
	v_mfma_f32_16x16x32_bf16 v[68:71], v[174:177], v[214:217], v[68:71]
	v_mfma_f32_16x16x32_bf16 v[120:123], v[170:173], v[186:189], v[120:123]
	v_mfma_f32_16x16x32_bf16 v[116:119], v[178:181], v[186:189], v[116:119]
	v_mfma_f32_16x16x32_bf16 v[104:107], v[170:173], v[202:205], v[104:107]
	v_mfma_f32_16x16x32_bf16 v[100:103], v[178:181], v[202:205], v[100:103]
	v_mfma_f32_16x16x32_bf16 v[88:91], v[170:173], v[210:213], v[88:91]
	v_mfma_f32_16x16x32_bf16 v[84:87], v[178:181], v[210:213], v[84:87]
	v_mfma_f32_16x16x32_bf16 v[72:75], v[170:173], v[218:221], v[72:75]
	v_mfma_f32_16x16x32_bf16 v[68:71], v[178:181], v[218:221], v[68:71]
	s_setprio 0
	s_barrier
; #define PG8_STAGE(bufoff, gbase, voff) do { _Pragma("unroll") for (int _i = 0; _i < 2; ++_i) \
;         __builtin_amdgcn_global_load_lds((const unsigned*)((const char*)(gbase) + (voff)[_i]), (LAS unsigned*)(lds + (bufoff) + ldsw + _i * 8192), 16, 0, 0); } while (0)
; #define PG8_LDA(dst, b, h) do { _Pragma("unroll") for (int m = 0; m < 4; ++m) _Pragma("unroll") for (int k = 0; k < 2; ++k) dst[m][k] = *(const LAS bf16x8*)(lds + PG8_SA(b, h) + aoff + m * 2048 + k * 1024); } while (0)
; #define PG8_LDB(dst, b, h) do { _Pragma("unroll") for (int n = 0; n < 2; ++n) _Pragma("unroll") for (int k = 0; k < 2; ++k) dst[n][k] = *(const LAS bf16x8*)(lds + PG8_SB(b, h) + boff + n * 2048 + k * 1024); } while (0)
; #define PG8_MMA(ai, bj, At, Bt) do { __builtin_amdgcn_s_setprio(1); _Pragma("unroll") for (int m = 0; m < 4; ++m) _Pragma("unroll") for (int n = 0; n < 2; ++n) _Pragma("unroll") for (int k = 0; k < 2; ++k) \
;         acc[ai][bj][m][n] = __builtin_amdgcn_mfma_f32_16x16x32_bf16(Bt[n][k], At[m][k], acc[ai][bj][m][n], 0, 0, 0); __builtin_amdgcn_s_setprio(0); } while (0)
; #define PG8_WAIT_V(n) asm volatile("s_waitcnt vmcnt(" #n ")" ::: "memory")
; #define PG8_WAIT_L(n) asm volatile("s_waitcnt lgkmcnt(" #n ")" ::: "memory")
; #define PG8_BAR __builtin_amdgcn_s_barrier()
; #define PG8_SCHED __builtin_amdgcn_sched_barrier(0)
; template <class Epi, bool ALIGN_EPI>
; DI void gemm_phase(LAS unsigned char* lds, const Sched& S, const Epi& E, int tid) {
;     ...
;             PG8_WAIT_V(8); PG8_WAIT_L(0); PG8_BAR; PG8_MMA(1, 0, At, B0); PG8_MMA(1, 1, At, B1); PG8_BAR; PG8_SCHED;
;             PG8_LDB(B0, 1, 0); PG8_LDB(B1, 1, 1); PG8_SCHED; PG8_LDA(At, 1, 0); PG8_STAGE(PG8_SA(0, 1), a2 + hstepA, voffA);
;             PG8_WAIT_V(8); PG8_WAIT_L(0); PG8_BAR; PG8_MMA(0, 0, At, B0); PG8_MMA(0, 1, At, B1); PG8_BAR; PG8_SCHED;
;             PG8_LDA(At, 1, 1); PG8_STAGE(PG8_SB(1, 0), b3, voffB); PG8_STAGE(PG8_SB(1, 1), b3 + hstepB, voffB); PG8_STAGE(PG8_SA(1, 0), a3, voffA);
;             PG8_WAIT_V(8); PG8_WAIT_L(0); PG8_BAR; PG8_MMA(1, 0, At, B0); PG8_MMA(1, 1, At, B1); PG8_BAR; PG8_SCHED;
	s_add_i32 s26, s48, s28
	v_lshl_add_u64 v[194:195], v[194:195], 0, s[84:85]
	s_mov_b32 m0, s26
	ds_read_b128 v[182:185], v147 offset:49152
	ds_read_b128 v[186:189], v147 offset:50176
	ds_read_b128 v[190:193], v147 offset:51200
	ds_read_b128 v[202:205], v147 offset:52224
	ds_read_b128 v[206:209], v147 offset:53248
	ds_read_b128 v[210:213], v147 offset:54272
	ds_read_b128 v[214:217], v147 offset:55296
	ds_read_b128 v[218:221], v147 offset:56320
	global_load_lds_dwordx4 v[194:195], off
	s_add_i32 m0, s26, 0x2000
	s_add_u32 s24, s24, 0x40080
	v_lshl_add_u64 v[194:195], v[222:223], 0, s[84:85]
	s_addc_u32 s25, s25, 0
	s_add_i32 s26, s49, s28
	global_load_lds_dwordx4 v[194:195], off
	v_lshl_add_u64 v[194:195], s[24:25], 0, v[136:137]
	s_mov_b32 m0, s26
	s_nop 0
	global_load_lds_dwordx4 v[194:195], off
	v_lshl_add_u64 v[194:195], s[24:25], 0, v[132:133]
	s_add_i32 m0, s26, 0x2000
	s_nop 0
	global_load_lds_dwordx4 v[194:195], off
	v_lshl_add_u64 v[194:195], v[224:225], 0, s[84:85]
	s_mov_b32 m0, s39
	s_nop 0
	global_load_lds_dwordx4 v[194:195], off
	v_lshl_add_u64 v[194:195], v[226:227], 0, s[84:85]
	s_mov_b32 m0, s40
	s_nop 0
	global_load_lds_dwordx4 v[194:195], off
	s_waitcnt vmcnt(8)
	s_waitcnt lgkmcnt(0)
	s_barrier
	s_setprio 1
	s_waitcnt lgkmcnt(0)
	v_mfma_f32_16x16x32_bf16 v[64:67], v[148:151], v[182:185], v[64:67]
	v_mfma_f32_16x16x32_bf16 v[60:63], v[156:159], v[182:185], v[60:63]
	v_mfma_f32_16x16x32_bf16 v[48:51], v[148:151], v[190:193], v[48:51]
	v_mfma_f32_16x16x32_bf16 v[44:47], v[156:159], v[190:193], v[44:47]
	v_mfma_f32_16x16x32_bf16 v[32:35], v[148:151], v[206:209], v[32:35]
	v_mfma_f32_16x16x32_bf16 v[28:31], v[156:159], v[206:209], v[28:31]
	v_mfma_f32_16x16x32_bf16 v[16:19], v[148:151], v[214:217], v[16:19]
	v_mfma_f32_16x16x32_bf16 v[12:15], v[156:159], v[214:217], v[12:15]
	v_mfma_f32_16x16x32_bf16 v[64:67], v[152:155], v[186:189], v[64:67]
	v_mfma_f32_16x16x32_bf16 v[60:63], v[162:165], v[186:189], v[60:63]
	v_mfma_f32_16x16x32_bf16 v[48:51], v[152:155], v[202:205], v[48:51]
	v_mfma_f32_16x16x32_bf16 v[44:47], v[162:165], v[202:205], v[44:47]
	v_mfma_f32_16x16x32_bf16 v[32:35], v[152:155], v[210:213], v[32:35]
	v_mfma_f32_16x16x32_bf16 v[28:31], v[162:165], v[210:213], v[28:31]
	v_mfma_f32_16x16x32_bf16 v[16:19], v[152:155], v[218:221], v[16:19]
	v_mfma_f32_16x16x32_bf16 v[12:15], v[162:165], v[218:221], v[12:15]
	s_setprio 0
	s_setprio 1
	v_mfma_f32_16x16x32_bf16 v[56:59], v[166:169], v[182:185], v[56:59]
	v_mfma_f32_16x16x32_bf16 v[52:55], v[174:177], v[182:185], v[52:55]
	v_mfma_f32_16x16x32_bf16 v[40:43], v[166:169], v[190:193], v[40:43]
	v_mfma_f32_16x16x32_bf16 v[36:39], v[174:177], v[190:193], v[36:39]
	v_mfma_f32_16x16x32_bf16 v[24:27], v[166:169], v[206:209], v[24:27]
	v_mfma_f32_16x16x32_bf16 v[20:23], v[174:177], v[206:209], v[20:23]
	v_mfma_f32_16x16x32_bf16 v[8:11], v[166:169], v[214:217], v[8:11]
	v_mfma_f32_16x16x32_bf16 v[4:7], v[174:177], v[214:217], v[4:7]
	v_mfma_f32_16x16x32_bf16 v[56:59], v[170:173], v[186:189], v[56:59]
	v_mfma_f32_16x16x32_bf16 v[52:55], v[178:181], v[186:189], v[52:55]
	v_mfma_f32_16x16x32_bf16 v[40:43], v[170:173], v[202:205], v[40:43]
	v_mfma_f32_16x16x32_bf16 v[36:39], v[178:181], v[202:205], v[36:39]
	v_mfma_f32_16x16x32_bf16 v[24:27], v[170:173], v[210:213], v[24:27]
	v_mfma_f32_16x16x32_bf16 v[20:23], v[178:181], v[210:213], v[20:23]
	v_mfma_f32_16x16x32_bf16 v[8:11], v[170:173], v[218:221], v[8:11]
	v_mfma_f32_16x16x32_bf16 v[4:7], v[178:181], v[218:221], v[4:7]
	s_setprio 0
	s_add_i32 s47, s47, 2
	s_add_u32 s22, s22, 0x100
	s_addc_u32 s23, s23, 0
	s_add_u32 s45, s45, 0x100
	s_addc_u32 s46, s46, 0
	s_cmp_gt_u32 s47, 13
	s_add_u32 s24, s22, 0xfffc0080
	s_addc_u32 s25, s23, -1
	s_add_i32 s48, 0, 0x10000
	s_cmp_eq_u32 s47, 12
	s_cselect_b32 s27, s19, s25
	s_cselect_b32 s26, s18, s24
	v_add_u32_e32 v161, s48, v144
	s_cselect_b32 s25, s21, s46
	s_cselect_b32 s24, s20, s45
	s_add_i32 s50, 0, 0x14000
	s_barrier
.LBB0_325:
	ds_read_b128 v[148:151], v161
	ds_read_b128 v[152:155], v161 offset:1024
	ds_read_b128 v[156:159], v161 offset:2048
	ds_read_b128 v[162:165], v161 offset:3072
	v_add_u32_e32 v161, s50, v144
	ds_read_b128 v[166:169], v161
	ds_read_b128 v[170:173], v161 offset:1024
	ds_read_b128 v[174:177], v161 offset:2048
	ds_read_b128 v[178:181], v161 offset:3072
	v_lshl_add_u64 v[194:195], s[22:23], 0, v[140:141]
	s_add_i32 m0, s17, 0xc000
	ds_read_b128 v[182:185], v147
	ds_read_b128 v[186:189], v147 offset:1024
	ds_read_b128 v[190:193], v147 offset:2048
	ds_read_b128 v[202:205], v147 offset:3072
	ds_read_b128 v[206:209], v147 offset:4096
	ds_read_b128 v[210:213], v147 offset:5120
	ds_read_b128 v[214:217], v147 offset:6144
	ds_read_b128 v[218:221], v147 offset:7168
	global_load_lds_dwordx4 v[194:195], off
	v_lshl_add_u64 v[194:195], s[22:23], 0, v[142:143]
	s_add_i32 m0, s17, 0xe000
	s_nop 0
	global_load_lds_dwordx4 v[194:195], off
	s_waitcnt vmcnt(8)
	s_waitcnt lgkmcnt(0)
	s_barrier
; #define PG8_STAGE(bufoff, gbase, voff) do { _Pragma("unroll") for (int _i = 0; _i < 2; ++_i) \
;         __builtin_amdgcn_global_load_lds((const unsigned*)((const char*)(gbase) + (voff)[_i]), (LAS unsigned*)(lds + (bufoff) + ldsw + _i * 8192), 16, 0, 0); } while (0)
; #define PG8_LDA(dst, b, h) do { _Pragma("unroll") for (int m = 0; m < 4; ++m) _Pragma("unroll") for (int k = 0; k < 2; ++k) dst[m][k] = *(const LAS bf16x8*)(lds + PG8_SA(b, h) + aoff + m * 2048 + k * 1024); } while (0)
; #define PG8_LDB(dst, b, h) do { _Pragma("unroll") for (int n = 0; n < 2; ++n) _Pragma("unroll") for (int k = 0; k < 2; ++k) dst[n][k] = *(const LAS bf16x8*)(lds + PG8_SB(b, h) + boff + n * 2048 + k * 1024); } while (0)
; #define PG8_MMA(ai, bj, At, Bt) do { __builtin_amdgcn_s_setprio(1); _Pragma("unroll") for (int m = 0; m < 4; ++m) _Pragma("unroll") for (int n = 0; n < 2; ++n) _Pragma("unroll") for (int k = 0; k < 2; ++k) \
;         acc[ai][bj][m][n] = __builtin_amdgcn_mfma_f32_16x16x32_bf16(Bt[n][k], At[m][k], acc[ai][bj][m][n], 0, 0, 0); __builtin_amdgcn_s_setprio(0); } while (0)
; #define PG8_WAIT_V(n) asm volatile("s_waitcnt vmcnt(" #n ")" ::: "memory")
; #define PG8_WAIT_L(n) asm volatile("s_waitcnt lgkmcnt(" #n ")" ::: "memory")
; #define PG8_BAR __builtin_amdgcn_s_barrier()
; #define PG8_SCHED __builtin_amdgcn_sched_barrier(0)
; template <class Epi, bool ALIGN_EPI>
; DI void gemm_phase(LAS unsigned char* lds, const Sched& S, const Epi& E, int tid) {
;     ...
;             PG8_LDB(B0, 0, 0); PG8_LDB(B1, 0, 1); PG8_SCHED; PG8_LDA(At, 0, 0); PG8_STAGE(PG8_SA(1, 1), a1 + hstepA, voffA);
;             PG8_WAIT_V(8); PG8_WAIT_L(0); PG8_BAR; PG8_MMA(0, 0, At, B0); PG8_MMA(0, 1, At, B1); PG8_BAR; PG8_SCHED;
;             PG8_LDA(At, 0, 1); PG8_STAGE(PG8_SB(0, 0), b2, voffB); PG8_STAGE(PG8_SB(0, 1), b2 + hstepB, voffB); PG8_STAGE(PG8_SA(0, 0), a2, voffA);
;             PG8_WAIT_V(8); PG8_WAIT_L(0); PG8_BAR; PG8_MMA(1, 0, At, B0); PG8_MMA(1, 1, At, B1); PG8_BAR; PG8_SCHED;
;             PG8_LDB(B0, 1, 0); PG8_LDB(B1, 1, 1); PG8_SCHED; PG8_LDA(At, 1, 0); PG8_STAGE(PG8_SA(0, 1), a2 + hstepA, voffA);
;             PG8_WAIT_V(8); PG8_WAIT_L(0); PG8_BAR; PG8_MMA(0, 0, At, B0); PG8_MMA(0, 1, At, B1); PG8_BAR; PG8_SCHED;
	s_setprio 1
	s_waitcnt lgkmcnt(0)
	v_mfma_f32_16x16x32_bf16 v[128:131], v[148:151], v[182:185], v[128:131]
	v_mfma_f32_16x16x32_bf16 v[124:127], v[156:159], v[182:185], v[124:127]
	v_mfma_f32_16x16x32_bf16 v[112:115], v[148:151], v[190:193], v[112:115]
	v_mfma_f32_16x16x32_bf16 v[108:111], v[156:159], v[190:193], v[108:111]
	v_mfma_f32_16x16x32_bf16 v[96:99], v[148:151], v[206:209], v[96:99]
	v_mfma_f32_16x16x32_bf16 v[92:95], v[156:159], v[206:209], v[92:95]
	v_mfma_f32_16x16x32_bf16 v[80:83], v[148:151], v[214:217], v[80:83]
	v_mfma_f32_16x16x32_bf16 v[76:79], v[156:159], v[214:217], v[76:79]
	v_mfma_f32_16x16x32_bf16 v[128:131], v[152:155], v[186:189], v[128:131]
	v_mfma_f32_16x16x32_bf16 v[124:127], v[162:165], v[186:189], v[124:127]
	v_mfma_f32_16x16x32_bf16 v[112:115], v[152:155], v[202:205], v[112:115]
	v_mfma_f32_16x16x32_bf16 v[108:111], v[162:165], v[202:205], v[108:111]
	v_mfma_f32_16x16x32_bf16 v[96:99], v[152:155], v[210:213], v[96:99]
	v_mfma_f32_16x16x32_bf16 v[92:95], v[162:165], v[210:213], v[92:95]
	v_mfma_f32_16x16x32_bf16 v[80:83], v[152:155], v[218:221], v[80:83]
	v_mfma_f32_16x16x32_bf16 v[76:79], v[162:165], v[218:221], v[76:79]
	s_setprio 0
	s_setprio 1
	v_mfma_f32_16x16x32_bf16 v[120:123], v[166:169], v[182:185], v[120:123]
	v_mfma_f32_16x16x32_bf16 v[116:119], v[174:177], v[182:185], v[116:119]
	v_mfma_f32_16x16x32_bf16 v[104:107], v[166:169], v[190:193], v[104:107]
	v_mfma_f32_16x16x32_bf16 v[100:103], v[174:177], v[190:193], v[100:103]
	v_mfma_f32_16x16x32_bf16 v[88:91], v[166:169], v[206:209], v[88:91]
	v_mfma_f32_16x16x32_bf16 v[84:87], v[174:177], v[206:209], v[84:87]
	v_mfma_f32_16x16x32_bf16 v[72:75], v[166:169], v[214:217], v[72:75]
	v_mfma_f32_16x16x32_bf16 v[68:71], v[174:177], v[214:217], v[68:71]
	v_mfma_f32_16x16x32_bf16 v[120:123], v[170:173], v[186:189], v[120:123]
	v_mfma_f32_16x16x32_bf16 v[116:119], v[178:181], v[186:189], v[116:119]
	v_mfma_f32_16x16x32_bf16 v[104:107], v[170:173], v[202:205], v[104:107]
	v_mfma_f32_16x16x32_bf16 v[100:103], v[178:181], v[202:205], v[100:103]
	v_mfma_f32_16x16x32_bf16 v[88:91], v[170:173], v[210:213], v[88:91]
	v_mfma_f32_16x16x32_bf16 v[84:87], v[178:181], v[210:213], v[84:87]
	v_mfma_f32_16x16x32_bf16 v[72:75], v[170:173], v[218:221], v[72:75]
	v_mfma_f32_16x16x32_bf16 v[68:71], v[178:181], v[218:221], v[68:71]
	s_setprio 0
	s_barrier
	s_add_i32 s48, s48, s28
	v_lshl_add_u64 v[194:195], s[24:25], 0, v[136:137]
	s_mov_b32 m0, s48
	ds_read_b128 v[182:185], v147 offset:16384
	ds_read_b128 v[186:189], v147 offset:17408
	ds_read_b128 v[190:193], v147 offset:18432
	ds_read_b128 v[202:205], v147 offset:19456
	ds_read_b128 v[206:209], v147 offset:20480
	ds_read_b128 v[210:213], v147 offset:21504
	ds_read_b128 v[214:217], v147 offset:22528
	ds_read_b128 v[218:221], v147 offset:23552
	global_load_lds_dwordx4 v[194:195], off
	s_add_i32 m0, s48, 0x2000
	s_add_u32 s48, s24, 0x40000
	v_lshl_add_u64 v[222:223], s[24:25], 0, v[132:133]
	s_addc_u32 s49, s25, 0
	s_add_i32 s50, s50, s28
	global_load_lds_dwordx4 v[222:223], off
	v_lshl_add_u64 v[224:225], s[48:49], 0, v[136:137]
	s_mov_b32 m0, s50
	v_lshl_add_u64 v[226:227], s[26:27], 0, v[134:135]
	global_load_lds_dwordx4 v[224:225], off
	v_lshl_add_u64 v[224:225], s[48:49], 0, v[132:133]
	s_add_i32 m0, s50, 0x2000
	s_nop 0
	global_load_lds_dwordx4 v[224:225], off
	v_lshl_add_u64 v[224:225], s[26:27], 0, v[138:139]
	s_mov_b32 m0, s17
	s_nop 0
	global_load_lds_dwordx4 v[224:225], off
	s_mov_b32 m0, s36
	s_nop 0
	global_load_lds_dwordx4 v[226:227], off
	s_waitcnt vmcnt(8)
	s_waitcnt lgkmcnt(0)
	s_barrier
	s_setprio 1
	s_waitcnt lgkmcnt(0)
	v_mfma_f32_16x16x32_bf16 v[64:67], v[148:151], v[182:185], v[64:67]
	v_mfma_f32_16x16x32_bf16 v[60:63], v[156:159], v[182:185], v[60:63]
	v_mfma_f32_16x16x32_bf16 v[48:51], v[148:151], v[190:193], v[48:51]
	v_mfma_f32_16x16x32_bf16 v[44:47], v[156:159], v[190:193], v[44:47]
	v_mfma_f32_16x16x32_bf16 v[32:35], v[148:151], v[206:209], v[32:35]
	v_mfma_f32_16x16x32_bf16 v[28:31], v[156:159], v[206:209], v[28:31]
	v_mfma_f32_16x16x32_bf16 v[16:19], v[148:151], v[214:217], v[16:19]
	v_mfma_f32_16x16x32_bf16 v[12:15], v[156:159], v[214:217], v[12:15]
	v_mfma_f32_16x16x32_bf16 v[64:67], v[152:155], v[186:189], v[64:67]
	v_mfma_f32_16x16x32_bf16 v[60:63], v[162:165], v[186:189], v[60:63]
	v_mfma_f32_16x16x32_bf16 v[48:51], v[152:155], v[202:205], v[48:51]
	v_mfma_f32_16x16x32_bf16 v[44:47], v[162:165], v[202:205], v[44:47]
	v_mfma_f32_16x16x32_bf16 v[32:35], v[152:155], v[210:213], v[32:35]
	v_mfma_f32_16x16x32_bf16 v[28:31], v[162:165], v[210:213], v[28:31]
	v_mfma_f32_16x16x32_bf16 v[16:19], v[152:155], v[218:221], v[16:19]
	v_mfma_f32_16x16x32_bf16 v[12:15], v[162:165], v[218:221], v[12:15]
	s_setprio 0
	s_setprio 1
	v_mfma_f32_16x16x32_bf16 v[56:59], v[166:169], v[182:185], v[56:59]
	v_mfma_f32_16x16x32_bf16 v[52:55], v[174:177], v[182:185], v[52:55]
	v_mfma_f32_16x16x32_bf16 v[40:43], v[166:169], v[190:193], v[40:43]
	v_mfma_f32_16x16x32_bf16 v[36:39], v[174:177], v[190:193], v[36:39]
	v_mfma_f32_16x16x32_bf16 v[24:27], v[166:169], v[206:209], v[24:27]
	v_mfma_f32_16x16x32_bf16 v[20:23], v[174:177], v[206:209], v[20:23]
	v_mfma_f32_16x16x32_bf16 v[8:11], v[166:169], v[214:217], v[8:11]
	v_mfma_f32_16x16x32_bf16 v[4:7], v[174:177], v[214:217], v[4:7]
	v_mfma_f32_16x16x32_bf16 v[56:59], v[170:173], v[186:189], v[56:59]
	v_mfma_f32_16x16x32_bf16 v[52:55], v[178:181], v[186:189], v[52:55]
	v_mfma_f32_16x16x32_bf16 v[40:43], v[170:173], v[202:205], v[40:43]
	v_mfma_f32_16x16x32_bf16 v[36:39], v[178:181], v[202:205], v[36:39]
	v_mfma_f32_16x16x32_bf16 v[24:27], v[170:173], v[210:213], v[24:27]
	v_mfma_f32_16x16x32_bf16 v[20:23], v[178:181], v[210:213], v[20:23]
	v_mfma_f32_16x16x32_bf16 v[8:11], v[170:173], v[218:221], v[8:11]
	v_mfma_f32_16x16x32_bf16 v[4:7], v[178:181], v[218:221], v[4:7]
	s_setprio 0
	s_barrier
; #define PG8_STAGE(bufoff, gbase, voff) do { _Pragma("unroll") for (int _i = 0; _i < 2; ++_i) \
;         __builtin_amdgcn_global_load_lds((const unsigned*)((const char*)(gbase) + (voff)[_i]), (LAS unsigned*)(lds + (bufoff) + ldsw + _i * 8192), 16, 0, 0); } while (0)
; #define PG8_LDA(dst, b, h) do { _Pragma("unroll") for (int m = 0; m < 4; ++m) _Pragma("unroll") for (int k = 0; k < 2; ++k) dst[m][k] = *(const LAS bf16x8*)(lds + PG8_SA(b, h) + aoff + m * 2048 + k * 1024); } while (0)
; #define PG8_LDB(dst, b, h) do { _Pragma("unroll") for (int n = 0; n < 2; ++n) _Pragma("unroll") for (int k = 0; k < 2; ++k) dst[n][k] = *(const LAS bf16x8*)(lds + PG8_SB(b, h) + boff + n * 2048 + k * 1024); } while (0)
; #define PG8_MMA(ai, bj, At, Bt) do { __builtin_amdgcn_s_setprio(1); _Pragma("unroll") for (int m = 0; m < 4; ++m) _Pragma("unroll") for (int n = 0; n < 2; ++n) _Pragma("unroll") for (int k = 0; k < 2; ++k) \
;         acc[ai][bj][m][n] = __builtin_amdgcn_mfma_f32_16x16x32_bf16(Bt[n][k], At[m][k], acc[ai][bj][m][n], 0, 0, 0); __builtin_amdgcn_s_setprio(0); } while (0)
; #define PG8_WAIT_V(n) asm volatile("s_waitcnt vmcnt(" #n ")" ::: "memory")
; #define PG8_WAIT_L(n) asm volatile("s_waitcnt lgkmcnt(" #n ")" ::: "memory")
; #define PG8_BAR __builtin_amdgcn_s_barrier()
; #define PG8_SCHED __builtin_amdgcn_sched_barrier(0)
; template <class Epi, bool ALIGN_EPI>
; DI void gemm_phase(LAS unsigned char* lds, const Sched& S, const Epi& E, int tid) {
;     ...
;             PG8_LDB(B0, 1, 0); PG8_LDB(B1, 1, 1); PG8_SCHED; PG8_LDA(At, 1, 0); PG8_STAGE(PG8_SA(0, 1), a2 + hstepA, voffA);
;             PG8_WAIT_V(8); PG8_WAIT_L(0); PG8_BAR; PG8_MMA(0, 0, At, B0); PG8_MMA(0, 1, At, B1); PG8_BAR; PG8_SCHED;
;             PG8_LDA(At, 1, 1); PG8_STAGE(PG8_SB(1, 0), b3, voffB); PG8_STAGE(PG8_SB(1, 1), b3 + hstepB, voffB); PG8_STAGE(PG8_SA(1, 0), a3, voffA);
;             PG8_WAIT_V(8); PG8_WAIT_L(0); PG8_BAR; PG8_MMA(1, 0, At, B0); PG8_MMA(1, 1, At, B1); PG8_BAR; PG8_SCHED;
	s_add_i32 s48, 0, 0x18000
	v_add_u32_e32 v161, s48, v144
	s_add_i32 s49, 0, 0x1c000
	ds_read_b128 v[148:151], v161
	ds_read_b128 v[152:155], v161 offset:1024
	ds_read_b128 v[156:159], v161 offset:2048
	ds_read_b128 v[162:165], v161 offset:3072
	v_add_u32_e32 v161, s49, v144
	ds_read_b128 v[166:169], v161
	ds_read_b128 v[170:173], v161 offset:1024
	ds_read_b128 v[174:177], v161 offset:2048
	ds_read_b128 v[178:181], v161 offset:3072
	s_add_u32 s26, s26, 0x40000
	s_addc_u32 s27, s27, 0
	s_mov_b32 m0, s37
	v_lshl_add_u64 v[228:229], s[26:27], 0, v[138:139]
	ds_read_b128 v[182:185], v147 offset:32768
	ds_read_b128 v[186:189], v147 offset:33792
	ds_read_b128 v[190:193], v147 offset:34816
	ds_read_b128 v[202:205], v147 offset:35840
	ds_read_b128 v[206:209], v147 offset:36864
	ds_read_b128 v[210:213], v147 offset:37888
	ds_read_b128 v[214:217], v147 offset:38912
	ds_read_b128 v[218:221], v147 offset:39936
	global_load_lds_dwordx4 v[228:229], off
	v_lshl_add_u64 v[228:229], s[26:27], 0, v[134:135]
	s_mov_b32 m0, s38
	s_nop 0
	global_load_lds_dwordx4 v[228:229], off
	s_waitcnt vmcnt(8)
	s_waitcnt lgkmcnt(0)
	s_barrier
	s_setprio 1
	s_waitcnt lgkmcnt(0)
	v_mfma_f32_16x16x32_bf16 v[128:131], v[148:151], v[182:185], v[128:131]
	v_mfma_f32_16x16x32_bf16 v[124:127], v[156:159], v[182:185], v[124:127]
	v_mfma_f32_16x16x32_bf16 v[112:115], v[148:151], v[190:193], v[112:115]
	v_mfma_f32_16x16x32_bf16 v[108:111], v[156:159], v[190:193], v[108:111]
	v_mfma_f32_16x16x32_bf16 v[96:99], v[148:151], v[206:209], v[96:99]
	v_mfma_f32_16x16x32_bf16 v[92:95], v[156:159], v[206:209], v[92:95]
	v_mfma_f32_16x16x32_bf16 v[80:83], v[148:151], v[214:217], v[80:83]
	v_mfma_f32_16x16x32_bf16 v[76:79], v[156:159], v[214:217], v[76:79]
	v_mfma_f32_16x16x32_bf16 v[128:131], v[152:155], v[186:189], v[128:131]
	v_mfma_f32_16x16x32_bf16 v[124:127], v[162:165], v[186:189], v[124:127]
	v_mfma_f32_16x16x32_bf16 v[112:115], v[152:155], v[202:205], v[112:115]
	v_mfma_f32_16x16x32_bf16 v[108:111], v[162:165], v[202:205], v[108:111]
	v_mfma_f32_16x16x32_bf16 v[96:99], v[152:155], v[210:213], v[96:99]
	v_mfma_f32_16x16x32_bf16 v[92:95], v[162:165], v[210:213], v[92:95]
	v_mfma_f32_16x16x32_bf16 v[80:83], v[152:155], v[218:221], v[80:83]
	v_mfma_f32_16x16x32_bf16 v[76:79], v[162:165], v[218:221], v[76:79]
	s_setprio 0
	s_setprio 1
	v_mfma_f32_16x16x32_bf16 v[120:123], v[166:169], v[182:185], v[120:123]
	v_mfma_f32_16x16x32_bf16 v[116:119], v[174:177], v[182:185], v[116:119]
	v_mfma_f32_16x16x32_bf16 v[104:107], v[166:169], v[190:193], v[104:107]
	v_mfma_f32_16x16x32_bf16 v[100:103], v[174:177], v[190:193], v[100:103]
	v_mfma_f32_16x16x32_bf16 v[88:91], v[166:169], v[206:209], v[88:91]
	v_mfma_f32_16x16x32_bf16 v[84:87], v[174:177], v[206:209], v[84:87]
	v_mfma_f32_16x16x32_bf16 v[72:75], v[166:169], v[214:217], v[72:75]
	v_mfma_f32_16x16x32_bf16 v[68:71], v[174:177], v[214:217], v[68:71]
	v_mfma_f32_16x16x32_bf16 v[120:123], v[170:173], v[186:189], v[120:123]
	v_mfma_f32_16x16x32_bf16 v[116:119], v[178:181], v[186:189], v[116:119]
	v_mfma_f32_16x16x32_bf16 v[104:107], v[170:173], v[202:205], v[104:107]
	v_mfma_f32_16x16x32_bf16 v[100:103], v[178:181], v[202:205], v[100:103]
	v_mfma_f32_16x16x32_bf16 v[88:91], v[170:173], v[210:213], v[88:91]
	v_mfma_f32_16x16x32_bf16 v[84:87], v[178:181], v[210:213], v[84:87]
	v_mfma_f32_16x16x32_bf16 v[72:75], v[170:173], v[218:221], v[72:75]
	v_mfma_f32_16x16x32_bf16 v[68:71], v[178:181], v[218:221], v[68:71]
	s_setprio 0
	s_barrier
; #define PG8_STAGE(bufoff, gbase, voff) do { _Pragma("unroll") for (int _i = 0; _i < 2; ++_i) \
;         __builtin_amdgcn_global_load_lds((const unsigned*)((const char*)(gbase) + (voff)[_i]), (LAS unsigned*)(lds + (bufoff) + ldsw + _i * 8192), 16, 0, 0); } while (0)
; #define PG8_LDA(dst, b, h) do { _Pragma("unroll") for (int m = 0; m < 4; ++m) _Pragma("unroll") for (int k = 0; k < 2; ++k) dst[m][k] = *(const LAS bf16x8*)(lds + PG8_SA(b, h) + aoff + m * 2048 + k * 1024); } while (0)
; #define PG8_MMA(ai, bj, At, Bt) do { __builtin_amdgcn_s_setprio(1); _Pragma("unroll") for (int m = 0; m < 4; ++m) _Pragma("unroll") for (int n = 0; n < 2; ++n) _Pragma("unroll") for (int k = 0; k < 2; ++k) \
;         acc[ai][bj][m][n] = __builtin_amdgcn_mfma_f32_16x16x32_bf16(Bt[n][k], At[m][k], acc[ai][bj][m][n], 0, 0, 0); __builtin_amdgcn_s_setprio(0); } while (0)
; #define PG8_WAIT_V(n) asm volatile("s_waitcnt vmcnt(" #n ")" ::: "memory")
; #define PG8_WAIT_L(n) asm volatile("s_waitcnt lgkmcnt(" #n ")" ::: "memory")
; #define PG8_BAR __builtin_amdgcn_s_barrier()
; #define PG8_SCHED __builtin_amdgcn_sched_barrier(0)
; template <class Epi, bool ALIGN_EPI>
; DI void gemm_phase(LAS unsigned char* lds, const Sched& S, const Epi& E, int tid) {
;     ...
;             PG8_WAIT_V(8); PG8_WAIT_L(0); PG8_BAR; PG8_MMA(0, 0, At, B0); PG8_MMA(0, 1, At, B1); PG8_BAR; PG8_SCHED;
;             PG8_LDA(At, 1, 1); PG8_STAGE(PG8_SB(1, 0), b3, voffB); PG8_STAGE(PG8_SB(1, 1), b3 + hstepB, voffB); PG8_STAGE(PG8_SA(1, 0), a3, voffA);
;             PG8_WAIT_V(8); PG8_WAIT_L(0); PG8_BAR; PG8_MMA(1, 0, At, B0); PG8_MMA(1, 1, At, B1); PG8_BAR; PG8_SCHED;
;         }
;         if constexpr (ALIGN_EPI) { if (wr == 0) PG8_BAR; }
	s_add_i32 s26, s48, s28
	v_lshl_add_u64 v[194:195], v[194:195], 0, s[84:85]
	s_mov_b32 m0, s26
	ds_read_b128 v[182:185], v147 offset:49152
	ds_read_b128 v[186:189], v147 offset:50176
	ds_read_b128 v[190:193], v147 offset:51200
	ds_read_b128 v[202:205], v147 offset:52224
	ds_read_b128 v[206:209], v147 offset:53248
	ds_read_b128 v[210:213], v147 offset:54272
	ds_read_b128 v[214:217], v147 offset:55296
	ds_read_b128 v[218:221], v147 offset:56320
	global_load_lds_dwordx4 v[194:195], off
	s_add_i32 m0, s26, 0x2000
	s_add_u32 s24, s24, 0x40080
	v_lshl_add_u64 v[194:195], v[222:223], 0, s[84:85]
	s_addc_u32 s25, s25, 0
	s_add_i32 s26, s49, s28
	global_load_lds_dwordx4 v[194:195], off
	v_lshl_add_u64 v[194:195], s[24:25], 0, v[136:137]
	s_mov_b32 m0, s26
	s_nop 0
	global_load_lds_dwordx4 v[194:195], off
	v_lshl_add_u64 v[194:195], s[24:25], 0, v[132:133]
	s_add_i32 m0, s26, 0x2000
	s_nop 0
	global_load_lds_dwordx4 v[194:195], off
	v_lshl_add_u64 v[194:195], v[224:225], 0, s[84:85]
	s_mov_b32 m0, s39
	s_nop 0
	global_load_lds_dwordx4 v[194:195], off
	v_lshl_add_u64 v[194:195], v[226:227], 0, s[84:85]
	s_mov_b32 m0, s40
	s_nop 0
	global_load_lds_dwordx4 v[194:195], off
	s_waitcnt vmcnt(8)
	s_waitcnt lgkmcnt(0)
	s_barrier
	s_setprio 1
	s_waitcnt lgkmcnt(0)
	v_mfma_f32_16x16x32_bf16 v[64:67], v[148:151], v[182:185], v[64:67]
	v_mfma_f32_16x16x32_bf16 v[60:63], v[156:159], v[182:185], v[60:63]
	v_mfma_f32_16x16x32_bf16 v[48:51], v[148:151], v[190:193], v[48:51]
	v_mfma_f32_16x16x32_bf16 v[44:47], v[156:159], v[190:193], v[44:47]
	v_mfma_f32_16x16x32_bf16 v[32:35], v[148:151], v[206:209], v[32:35]
	v_mfma_f32_16x16x32_bf16 v[28:31], v[156:159], v[206:209], v[28:31]
	v_mfma_f32_16x16x32_bf16 v[16:19], v[148:151], v[214:217], v[16:19]
	v_mfma_f32_16x16x32_bf16 v[12:15], v[156:159], v[214:217], v[12:15]
	v_mfma_f32_16x16x32_bf16 v[64:67], v[152:155], v[186:189], v[64:67]
	v_mfma_f32_16x16x32_bf16 v[60:63], v[162:165], v[186:189], v[60:63]
	v_mfma_f32_16x16x32_bf16 v[48:51], v[152:155], v[202:205], v[48:51]
	v_mfma_f32_16x16x32_bf16 v[44:47], v[162:165], v[202:205], v[44:47]
	v_mfma_f32_16x16x32_bf16 v[32:35], v[152:155], v[210:213], v[32:35]
	v_mfma_f32_16x16x32_bf16 v[28:31], v[162:165], v[210:213], v[28:31]
	v_mfma_f32_16x16x32_bf16 v[16:19], v[152:155], v[218:221], v[16:19]
	v_mfma_f32_16x16x32_bf16 v[12:15], v[162:165], v[218:221], v[12:15]
	s_setprio 0
	s_setprio 1
	v_mfma_f32_16x16x32_bf16 v[56:59], v[166:169], v[182:185], v[56:59]
	v_mfma_f32_16x16x32_bf16 v[52:55], v[174:177], v[182:185], v[52:55]
	v_mfma_f32_16x16x32_bf16 v[40:43], v[166:169], v[190:193], v[40:43]
	v_mfma_f32_16x16x32_bf16 v[36:39], v[174:177], v[190:193], v[36:39]
	v_mfma_f32_16x16x32_bf16 v[24:27], v[166:169], v[206:209], v[24:27]
	v_mfma_f32_16x16x32_bf16 v[20:23], v[174:177], v[206:209], v[20:23]
	v_mfma_f32_16x16x32_bf16 v[8:11], v[166:169], v[214:217], v[8:11]
	v_mfma_f32_16x16x32_bf16 v[4:7], v[174:177], v[214:217], v[4:7]
	v_mfma_f32_16x16x32_bf16 v[56:59], v[170:173], v[186:189], v[56:59]
	v_mfma_f32_16x16x32_bf16 v[52:55], v[178:181], v[186:189], v[52:55]
	v_mfma_f32_16x16x32_bf16 v[40:43], v[170:173], v[202:205], v[40:43]
	v_mfma_f32_16x16x32_bf16 v[36:39], v[178:181], v[202:205], v[36:39]
	v_mfma_f32_16x16x32_bf16 v[24:27], v[170:173], v[210:213], v[24:27]
	v_mfma_f32_16x16x32_bf16 v[20:23], v[178:181], v[210:213], v[20:23]
	v_mfma_f32_16x16x32_bf16 v[8:11], v[170:173], v[218:221], v[8:11]
	v_mfma_f32_16x16x32_bf16 v[4:7], v[178:181], v[218:221], v[4:7]
	s_setprio 0
	s_add_i32 s47, s47, 2
	s_add_u32 s22, s22, 0x100
	s_addc_u32 s23, s23, 0
	s_add_u32 s45, s45, 0x100
	s_addc_u32 s46, s46, 0
	s_cmp_gt_u32 s47, 13
	s_cbranch_scc1 .Lkx_8
	s_add_u32 s24, s22, 0xfffc0080
	s_addc_u32 s25, s23, -1
	s_add_i32 s48, 0, 0x10000
	s_cmp_eq_u32 s47, 12
	s_cselect_b32 s27, s19, s25
	s_cselect_b32 s26, s18, s24
	v_add_u32_e32 v161, s48, v144
	s_cselect_b32 s25, s21, s46
	s_cselect_b32 s24, s20, s45
	s_add_i32 s50, 0, 0x14000
	s_barrier
	s_branch .LBB0_325
.Lkx_8:
	s_barrier
	s_and_b64 vcc, exec, s[6:7]
	s_cbranch_vccz .LBB0_328
	s_barrier

; #define PG8_STAGE(bufoff, gbase, voff) do { _Pragma("unroll") for (int _i = 0; _i < 2; ++_i) \
;         __builtin_amdgcn_global_load_lds((const unsigned*)((const char*)(gbase) + (voff)[_i]), (LAS unsigned*)(lds + (bufoff) + ldsw + _i * 8192), 16, 0, 0); } while (0)
; #define PG8_LDA(dst, b, h) do { _Pragma("unroll") for (int m = 0; m < 4; ++m) _Pragma("unroll") for (int k = 0; k < 2; ++k) dst[m][k] = *(const LAS bf16x8*)(lds + PG8_SA(b, h) + aoff + m * 2048 + k * 1024); } while (0)
; #define PG8_LDB(dst, b, h) do { _Pragma("unroll") for (int n = 0; n < 2; ++n) _Pragma("unroll") for (int k = 0; k < 2; ++k) dst[n][k] = *(const LAS bf16x8*)(lds + PG8_SB(b, h) + boff + n * 2048 + k * 1024); } while (0)
; #define PG8_MMA(ai, bj, At, Bt) do { __builtin_amdgcn_s_setprio(1); _Pragma("unroll") for (int m = 0; m < 4; ++m) _Pragma("unroll") for (int n = 0; n < 2; ++n) _Pragma("unroll") for (int k = 0; k < 2; ++k) \
;         acc[ai][bj][m][n] = __builtin_amdgcn_mfma_f32_16x16x32_bf16(Bt[n][k], At[m][k], acc[ai][bj][m][n], 0, 0, 0); __builtin_amdgcn_s_setprio(0); } while (0)
; #define PG8_WAIT_V(n) asm volatile("s_waitcnt vmcnt(" #n ")" ::: "memory")
; #define PG8_BAR __builtin_amdgcn_s_barrier()
; template <class Epi, bool ALIGN_EPI>
; DI void gemm_phase(LAS unsigned char* lds, const Sched& S, const Epi& E, int tid) {
;     ...
;         const bool has_next = S.next(ui + 1, nxt);
;         const char* nA = has_next ? nxt.a : cA; const char* nB = has_next ? nxt.b : cB;
;         const int nt = cur.nt;
;         for (int t = 0; t < nt; t += 2) {
;             const bool last = (t == nt - 2);
;             const char* a1 = cA + (size_t)(t + 1) * kstep;
;             const char* a2 = last ? nA : cA + (size_t)(t + 2) * kstep; const char* b2 = last ? nB : cB + (size_t)(t + 2) * kstep;
;             const char* a3 = a2 + kstep; const char* b3 = b2 + kstep;
;             PG8_LDB(B0, 0, 0); PG8_LDB(B1, 0, 1); PG8_SCHED; PG8_LDA(At, 0, 0); PG8_STAGE(PG8_SA(1, 1), a1 + hstepA, voffA);
;             PG8_WAIT_V(8); PG8_WAIT_L(0); PG8_BAR; PG8_MMA(0, 0, At, B0); PG8_MMA(0, 1, At, B1); PG8_BAR; PG8_SCHED;
;             PG8_LDA(At, 0, 1); PG8_STAGE(PG8_SB(0, 0), b2, voffB); PG8_STAGE(PG8_SB(0, 1), b2 + hstepB, voffB); PG8_STAGE(PG8_SA(0, 0), a2, voffA);
;             PG8_WAIT_V(8); PG8_WAIT_L(0); PG8_BAR; PG8_MMA(1, 0, At, B0); PG8_MMA(1, 1, At, B1); PG8_BAR; PG8_SCHED;
.LBB0_411:
	s_and_b64 s[24:25], s[16:17], exec
	s_cselect_b32 s56, s13, s21
	s_cselect_b32 s57, s12, s20
	s_cselect_b32 s58, s15, s23
	s_cselect_b32 s59, s14, s22
	s_add_i32 s60, s55, -2
	s_add_u32 s61, s22, 0x100
	s_mov_b32 s81, s63
	s_addc_u32 s62, s23, 0
	s_mov_b32 s24, 0
	s_waitcnt lgkmcnt(0)
	s_waitcnt lgkmcnt(0)
	s_add_i32 s63, s24, 2
	s_add_u32 s22, s20, 0x100
	s_addc_u32 s23, s21, 0
	s_add_i32 s64, 0, 0x10000
	s_cmp_eq_u32 s60, s24
	s_cselect_b32 s27, s56, s23
	s_cselect_b32 s26, s57, s22
	s_cselect_b32 s25, s58, s62
	s_cselect_b32 s24, s59, s61
	s_add_i32 s65, 0, 0x14000
	v_add_u32_e32 v144, s64, v161
	v_add_u32_e32 v174, s65, v161
	ds_read_b128 v[132:135], v144
	ds_read_b128 v[136:139], v144 offset:1024
	ds_read_b128 v[140:143], v144 offset:2048
	ds_read_b128 v[144:147], v144 offset:3072
	ds_read_b128 v[148:151], v174
	ds_read_b128 v[152:155], v174 offset:1024
	ds_read_b128 v[156:159], v174 offset:2048
	ds_read_b128 v[174:177], v174 offset:3072
	v_lshl_add_u64 v[190:191], s[20:21], 0, v[170:171]
	s_add_i32 m0, s39, 0xc000
	ds_read_b128 v[178:181], v193
	ds_read_b128 v[182:185], v193 offset:1024
	ds_read_b128 v[186:189], v193 offset:2048
	ds_read_b128 v[202:205], v193 offset:3072
	ds_read_b128 v[206:209], v193 offset:4096
	ds_read_b128 v[210:213], v193 offset:5120
	ds_read_b128 v[214:217], v193 offset:6144
	ds_read_b128 v[218:221], v193 offset:7168
	global_load_lds_dwordx4 v[190:191], off
	v_lshl_add_u64 v[190:191], s[20:21], 0, v[172:173]
	s_add_i32 m0, s39, 0xe000
	s_nop 0
	global_load_lds_dwordx4 v[190:191], off
	s_waitcnt vmcnt(8)
	s_waitcnt lgkmcnt(0)
	s_barrier
	s_setprio 1
	s_waitcnt lgkmcnt(0)
	v_mfma_f32_16x16x32_bf16 v[128:131], v[132:135], v[178:181], 0
	v_mfma_f32_16x16x32_bf16 v[124:127], v[140:143], v[178:181], 0
	v_mfma_f32_16x16x32_bf16 v[112:115], v[132:135], v[186:189], 0
	v_mfma_f32_16x16x32_bf16 v[108:111], v[140:143], v[186:189], 0
	v_mfma_f32_16x16x32_bf16 v[96:99], v[132:135], v[206:209], 0
	v_mfma_f32_16x16x32_bf16 v[92:95], v[140:143], v[206:209], 0
	v_mfma_f32_16x16x32_bf16 v[80:83], v[132:135], v[214:217], 0
	v_mfma_f32_16x16x32_bf16 v[76:79], v[140:143], v[214:217], 0
	v_mfma_f32_16x16x32_bf16 v[128:131], v[136:139], v[182:185], v[128:131]
	v_mfma_f32_16x16x32_bf16 v[124:127], v[144:147], v[182:185], v[124:127]
	v_mfma_f32_16x16x32_bf16 v[112:115], v[136:139], v[202:205], v[112:115]
	v_mfma_f32_16x16x32_bf16 v[108:111], v[144:147], v[202:205], v[108:111]
	v_mfma_f32_16x16x32_bf16 v[96:99], v[136:139], v[210:213], v[96:99]
	v_mfma_f32_16x16x32_bf16 v[92:95], v[144:147], v[210:213], v[92:95]
	v_mfma_f32_16x16x32_bf16 v[80:83], v[136:139], v[218:221], v[80:83]
	v_mfma_f32_16x16x32_bf16 v[76:79], v[144:147], v[218:221], v[76:79]
	s_setprio 0
	s_setprio 1
	v_mfma_f32_16x16x32_bf16 v[120:123], v[148:151], v[178:181], 0
	v_mfma_f32_16x16x32_bf16 v[116:119], v[156:159], v[178:181], 0
	v_mfma_f32_16x16x32_bf16 v[104:107], v[148:151], v[186:189], 0
	v_mfma_f32_16x16x32_bf16 v[100:103], v[156:159], v[186:189], 0
	v_mfma_f32_16x16x32_bf16 v[88:91], v[148:151], v[206:209], 0
	v_mfma_f32_16x16x32_bf16 v[84:87], v[156:159], v[206:209], 0
	v_mfma_f32_16x16x32_bf16 v[72:75], v[148:151], v[214:217], 0
	v_mfma_f32_16x16x32_bf16 v[68:71], v[156:159], v[214:217], 0
	v_mfma_f32_16x16x32_bf16 v[120:123], v[152:155], v[182:185], v[120:123]
	v_mfma_f32_16x16x32_bf16 v[116:119], v[174:177], v[182:185], v[116:119]
	v_mfma_f32_16x16x32_bf16 v[104:107], v[152:155], v[202:205], v[104:107]
	v_mfma_f32_16x16x32_bf16 v[100:103], v[174:177], v[202:205], v[100:103]
	v_mfma_f32_16x16x32_bf16 v[88:91], v[152:155], v[210:213], v[88:91]
	v_mfma_f32_16x16x32_bf16 v[84:87], v[174:177], v[210:213], v[84:87]
	v_mfma_f32_16x16x32_bf16 v[72:75], v[152:155], v[218:221], v[72:75]
	v_mfma_f32_16x16x32_bf16 v[68:71], v[174:177], v[218:221], v[68:71]
	s_setprio 0
	s_barrier
	s_add_i32 s20, s64, s38
	v_lshl_add_u64 v[190:191], s[24:25], 0, v[164:165]
	s_mov_b32 m0, s20
	ds_read_b128 v[178:181], v193 offset:16384
	ds_read_b128 v[182:185], v193 offset:17408
	ds_read_b128 v[186:189], v193 offset:18432
	ds_read_b128 v[202:205], v193 offset:19456
	ds_read_b128 v[206:209], v193 offset:20480
	ds_read_b128 v[210:213], v193 offset:21504
	ds_read_b128 v[214:217], v193 offset:22528
	ds_read_b128 v[218:221], v193 offset:23552
	global_load_lds_dwordx4 v[190:191], off
	s_add_i32 m0, s20, 0x2000
	s_add_u32 s20, s24, 0x104000
	v_lshl_add_u64 v[194:195], s[24:25], 0, v[168:169]
	s_addc_u32 s21, s25, 0
	s_add_i32 s64, s65, s38
	global_load_lds_dwordx4 v[194:195], off
	v_lshl_add_u64 v[222:223], s[20:21], 0, v[164:165]
	s_mov_b32 m0, s64
	v_lshl_add_u64 v[224:225], s[26:27], 0, v[166:167]
	global_load_lds_dwordx4 v[222:223], off
	v_lshl_add_u64 v[222:223], s[20:21], 0, v[168:169]
	s_add_i32 m0, s64, 0x2000
	s_nop 0
	global_load_lds_dwordx4 v[222:223], off
	v_lshl_add_u64 v[222:223], s[26:27], 0, v[162:163]
	s_mov_b32 m0, s39
	s_nop 0
	global_load_lds_dwordx4 v[222:223], off
	s_mov_b32 m0, s40
	s_nop 0
	global_load_lds_dwordx4 v[224:225], off
	s_waitcnt vmcnt(8)
	s_waitcnt lgkmcnt(0)
	s_barrier
; #define PG8_STAGE(bufoff, gbase, voff) do { _Pragma("unroll") for (int _i = 0; _i < 2; ++_i) \
;         __builtin_amdgcn_global_load_lds((const unsigned*)((const char*)(gbase) + (voff)[_i]), (LAS unsigned*)(lds + (bufoff) + ldsw + _i * 8192), 16, 0, 0); } while (0)
; #define PG8_LDA(dst, b, h) do { _Pragma("unroll") for (int m = 0; m < 4; ++m) _Pragma("unroll") for (int k = 0; k < 2; ++k) dst[m][k] = *(const LAS bf16x8*)(lds + PG8_SA(b, h) + aoff + m * 2048 + k * 1024); } while (0)
; #define PG8_LDB(dst, b, h) do { _Pragma("unroll") for (int n = 0; n < 2; ++n) _Pragma("unroll") for (int k = 0; k < 2; ++k) dst[n][k] = *(const LAS bf16x8*)(lds + PG8_SB(b, h) + boff + n * 2048 + k * 1024); } while (0)
; #define PG8_MMA(ai, bj, At, Bt) do { __builtin_amdgcn_s_setprio(1); _Pragma("unroll") for (int m = 0; m < 4; ++m) _Pragma("unroll") for (int n = 0; n < 2; ++n) _Pragma("unroll") for (int k = 0; k < 2; ++k) \
;         acc[ai][bj][m][n] = __builtin_amdgcn_mfma_f32_16x16x32_bf16(Bt[n][k], At[m][k], acc[ai][bj][m][n], 0, 0, 0); __builtin_amdgcn_s_setprio(0); } while (0)
; #define PG8_WAIT_V(n) asm volatile("s_waitcnt vmcnt(" #n ")" ::: "memory")
; #define PG8_WAIT_L(n) asm volatile("s_waitcnt lgkmcnt(" #n ")" ::: "memory")
; #define PG8_BAR __builtin_amdgcn_s_barrier()
; #define PG8_SCHED __builtin_amdgcn_sched_barrier(0)
; template <class Epi, bool ALIGN_EPI>
; DI void gemm_phase(LAS unsigned char* lds, const Sched& S, const Epi& E, int tid) {
;     ...
;             PG8_WAIT_V(8); PG8_WAIT_L(0); PG8_BAR; PG8_MMA(0, 0, At, B0); PG8_MMA(0, 1, At, B1); PG8_BAR; PG8_SCHED;
;             PG8_LDA(At, 0, 1); PG8_STAGE(PG8_SB(0, 0), b2, voffB); PG8_STAGE(PG8_SB(0, 1), b2 + hstepB, voffB); PG8_STAGE(PG8_SA(0, 0), a2, voffA);
;             PG8_WAIT_V(8); PG8_WAIT_L(0); PG8_BAR; PG8_MMA(1, 0, At, B0); PG8_MMA(1, 1, At, B1); PG8_BAR; PG8_SCHED;
;             PG8_LDB(B0, 1, 0); PG8_LDB(B1, 1, 1); PG8_SCHED; PG8_LDA(At, 1, 0); PG8_STAGE(PG8_SA(0, 1), a2 + hstepA, voffA);
;             PG8_WAIT_V(8); PG8_WAIT_L(0); PG8_BAR; PG8_MMA(0, 0, At, B0); PG8_MMA(0, 1, At, B1); PG8_BAR; PG8_SCHED;
	s_setprio 1
	s_waitcnt lgkmcnt(0)
	v_mfma_f32_16x16x32_bf16 v[64:67], v[132:135], v[178:181], 0
	v_mfma_f32_16x16x32_bf16 v[60:63], v[140:143], v[178:181], 0
	v_mfma_f32_16x16x32_bf16 v[48:51], v[132:135], v[186:189], 0
	v_mfma_f32_16x16x32_bf16 v[44:47], v[140:143], v[186:189], 0
	v_mfma_f32_16x16x32_bf16 v[32:35], v[132:135], v[206:209], 0
	v_mfma_f32_16x16x32_bf16 v[28:31], v[140:143], v[206:209], 0
	v_mfma_f32_16x16x32_bf16 v[16:19], v[132:135], v[214:217], 0
	v_mfma_f32_16x16x32_bf16 v[12:15], v[140:143], v[214:217], 0
	v_mfma_f32_16x16x32_bf16 v[64:67], v[136:139], v[182:185], v[64:67]
	v_mfma_f32_16x16x32_bf16 v[60:63], v[144:147], v[182:185], v[60:63]
	v_mfma_f32_16x16x32_bf16 v[48:51], v[136:139], v[202:205], v[48:51]
	v_mfma_f32_16x16x32_bf16 v[44:47], v[144:147], v[202:205], v[44:47]
	v_mfma_f32_16x16x32_bf16 v[32:35], v[136:139], v[210:213], v[32:35]
	v_mfma_f32_16x16x32_bf16 v[28:31], v[144:147], v[210:213], v[28:31]
	v_mfma_f32_16x16x32_bf16 v[16:19], v[136:139], v[218:221], v[16:19]
	v_mfma_f32_16x16x32_bf16 v[12:15], v[144:147], v[218:221], v[12:15]
	s_setprio 0
	s_setprio 1
	v_mfma_f32_16x16x32_bf16 v[56:59], v[148:151], v[178:181], 0
	v_mfma_f32_16x16x32_bf16 v[52:55], v[156:159], v[178:181], 0
	v_mfma_f32_16x16x32_bf16 v[40:43], v[148:151], v[186:189], 0
	v_mfma_f32_16x16x32_bf16 v[36:39], v[156:159], v[186:189], 0
	v_mfma_f32_16x16x32_bf16 v[24:27], v[148:151], v[206:209], 0
	v_mfma_f32_16x16x32_bf16 v[20:23], v[156:159], v[206:209], 0
	v_mfma_f32_16x16x32_bf16 v[8:11], v[148:151], v[214:217], 0
	v_mfma_f32_16x16x32_bf16 v[4:7], v[156:159], v[214:217], 0
	v_mfma_f32_16x16x32_bf16 v[56:59], v[152:155], v[182:185], v[56:59]
	v_mfma_f32_16x16x32_bf16 v[52:55], v[174:177], v[182:185], v[52:55]
	v_mfma_f32_16x16x32_bf16 v[40:43], v[152:155], v[202:205], v[40:43]
	v_mfma_f32_16x16x32_bf16 v[36:39], v[174:177], v[202:205], v[36:39]
	v_mfma_f32_16x16x32_bf16 v[24:27], v[152:155], v[210:213], v[24:27]
	v_mfma_f32_16x16x32_bf16 v[20:23], v[174:177], v[210:213], v[20:23]
	v_mfma_f32_16x16x32_bf16 v[8:11], v[152:155], v[218:221], v[8:11]
	v_mfma_f32_16x16x32_bf16 v[4:7], v[174:177], v[218:221], v[4:7]
	s_setprio 0
	s_barrier
	s_add_i32 s64, 0, 0x18000
	s_add_i32 s65, 0, 0x1c000
	v_add_u32_e32 v144, s64, v161
	v_add_u32_e32 v174, s65, v161
	ds_read_b128 v[132:135], v144
	ds_read_b128 v[136:139], v144 offset:1024
	ds_read_b128 v[140:143], v144 offset:2048
	ds_read_b128 v[144:147], v144 offset:3072
	ds_read_b128 v[148:151], v174
	ds_read_b128 v[152:155], v174 offset:1024
	ds_read_b128 v[156:159], v174 offset:2048
	ds_read_b128 v[174:177], v174 offset:3072
	s_add_u32 s20, s26, 0x104000
	s_addc_u32 s21, s27, 0
	s_mov_b32 m0, s41
	v_lshl_add_u64 v[226:227], s[20:21], 0, v[162:163]
	ds_read_b128 v[178:181], v193 offset:32768
	ds_read_b128 v[182:185], v193 offset:33792
	ds_read_b128 v[186:189], v193 offset:34816
	ds_read_b128 v[202:205], v193 offset:35840
	ds_read_b128 v[206:209], v193 offset:36864
	ds_read_b128 v[210:213], v193 offset:37888
	ds_read_b128 v[214:217], v193 offset:38912
	ds_read_b128 v[218:221], v193 offset:39936
	global_load_lds_dwordx4 v[226:227], off
	v_lshl_add_u64 v[226:227], s[20:21], 0, v[166:167]
	s_mov_b32 m0, s42
	s_nop 0
	global_load_lds_dwordx4 v[226:227], off
	s_waitcnt vmcnt(8)
	s_waitcnt lgkmcnt(0)
	s_barrier
	s_setprio 1
	s_waitcnt lgkmcnt(0)
	v_mfma_f32_16x16x32_bf16 v[128:131], v[132:135], v[178:181], v[128:131]
	v_mfma_f32_16x16x32_bf16 v[124:127], v[140:143], v[178:181], v[124:127]
	v_mfma_f32_16x16x32_bf16 v[112:115], v[132:135], v[186:189], v[112:115]
	v_mfma_f32_16x16x32_bf16 v[108:111], v[140:143], v[186:189], v[108:111]
	v_mfma_f32_16x16x32_bf16 v[96:99], v[132:135], v[206:209], v[96:99]
	v_mfma_f32_16x16x32_bf16 v[92:95], v[140:143], v[206:209], v[92:95]
	v_mfma_f32_16x16x32_bf16 v[80:83], v[132:135], v[214:217], v[80:83]
	v_mfma_f32_16x16x32_bf16 v[76:79], v[140:143], v[214:217], v[76:79]
	v_mfma_f32_16x16x32_bf16 v[128:131], v[136:139], v[182:185], v[128:131]
	v_mfma_f32_16x16x32_bf16 v[124:127], v[144:147], v[182:185], v[124:127]
	v_mfma_f32_16x16x32_bf16 v[112:115], v[136:139], v[202:205], v[112:115]
	v_mfma_f32_16x16x32_bf16 v[108:111], v[144:147], v[202:205], v[108:111]
	v_mfma_f32_16x16x32_bf16 v[96:99], v[136:139], v[210:213], v[96:99]
	v_mfma_f32_16x16x32_bf16 v[92:95], v[144:147], v[210:213], v[92:95]
	v_mfma_f32_16x16x32_bf16 v[80:83], v[136:139], v[218:221], v[80:83]
	v_mfma_f32_16x16x32_bf16 v[76:79], v[144:147], v[218:221], v[76:79]
	s_setprio 0
	s_setprio 1
	v_mfma_f32_16x16x32_bf16 v[120:123], v[148:151], v[178:181], v[120:123]
	v_mfma_f32_16x16x32_bf16 v[116:119], v[156:159], v[178:181], v[116:119]
	v_mfma_f32_16x16x32_bf16 v[104:107], v[148:151], v[186:189], v[104:107]
	v_mfma_f32_16x16x32_bf16 v[100:103], v[156:159], v[186:189], v[100:103]
	v_mfma_f32_16x16x32_bf16 v[88:91], v[148:151], v[206:209], v[88:91]
	v_mfma_f32_16x16x32_bf16 v[84:87], v[156:159], v[206:209], v[84:87]
	v_mfma_f32_16x16x32_bf16 v[72:75], v[148:151], v[214:217], v[72:75]
	v_mfma_f32_16x16x32_bf16 v[68:71], v[156:159], v[214:217], v[68:71]
	v_mfma_f32_16x16x32_bf16 v[120:123], v[152:155], v[182:185], v[120:123]
	v_mfma_f32_16x16x32_bf16 v[116:119], v[174:177], v[182:185], v[116:119]
	v_mfma_f32_16x16x32_bf16 v[104:107], v[152:155], v[202:205], v[104:107]
	v_mfma_f32_16x16x32_bf16 v[100:103], v[174:177], v[202:205], v[100:103]
	v_mfma_f32_16x16x32_bf16 v[88:91], v[152:155], v[210:213], v[88:91]
	v_mfma_f32_16x16x32_bf16 v[84:87], v[174:177], v[210:213], v[84:87]
	v_mfma_f32_16x16x32_bf16 v[72:75], v[152:155], v[218:221], v[72:75]
	v_mfma_f32_16x16x32_bf16 v[68:71], v[174:177], v[218:221], v[68:71]
	s_setprio 0
	s_barrier
; #define PG8_STAGE(bufoff, gbase, voff) do { _Pragma("unroll") for (int _i = 0; _i < 2; ++_i) \
;         __builtin_amdgcn_global_load_lds((const unsigned*)((const char*)(gbase) + (voff)[_i]), (LAS unsigned*)(lds + (bufoff) + ldsw + _i * 8192), 16, 0, 0); } while (0)
; #define PG8_LDA(dst, b, h) do { _Pragma("unroll") for (int m = 0; m < 4; ++m) _Pragma("unroll") for (int k = 0; k < 2; ++k) dst[m][k] = *(const LAS bf16x8*)(lds + PG8_SA(b, h) + aoff + m * 2048 + k * 1024); } while (0)
; #define PG8_LDB(dst, b, h) do { _Pragma("unroll") for (int n = 0; n < 2; ++n) _Pragma("unroll") for (int k = 0; k < 2; ++k) dst[n][k] = *(const LAS bf16x8*)(lds + PG8_SB(b, h) + boff + n * 2048 + k * 1024); } while (0)
; #define PG8_MMA(ai, bj, At, Bt) do { __builtin_amdgcn_s_setprio(1); _Pragma("unroll") for (int m = 0; m < 4; ++m) _Pragma("unroll") for (int n = 0; n < 2; ++n) _Pragma("unroll") for (int k = 0; k < 2; ++k) \
;         acc[ai][bj][m][n] = __builtin_amdgcn_mfma_f32_16x16x32_bf16(Bt[n][k], At[m][k], acc[ai][bj][m][n], 0, 0, 0); __builtin_amdgcn_s_setprio(0); } while (0)
; #define PG8_WAIT_V(n) asm volatile("s_waitcnt vmcnt(" #n ")" ::: "memory")
; #define PG8_WAIT_L(n) asm volatile("s_waitcnt lgkmcnt(" #n ")" ::: "memory")
; #define PG8_BAR __builtin_amdgcn_s_barrier()
; #define PG8_SCHED __builtin_amdgcn_sched_barrier(0)
; template <class Epi, bool ALIGN_EPI>
; DI void gemm_phase(LAS unsigned char* lds, const Sched& S, const Epi& E, int tid) {
;     ...
;             PG8_WAIT_V(8); PG8_WAIT_L(0); PG8_BAR; PG8_MMA(1, 0, At, B0); PG8_MMA(1, 1, At, B1); PG8_BAR; PG8_SCHED;
;             PG8_LDB(B0, 1, 0); PG8_LDB(B1, 1, 1); PG8_SCHED; PG8_LDA(At, 1, 0); PG8_STAGE(PG8_SA(0, 1), a2 + hstepA, voffA);
;             PG8_WAIT_V(8); PG8_WAIT_L(0); PG8_BAR; PG8_MMA(0, 0, At, B0); PG8_MMA(0, 1, At, B1); PG8_BAR; PG8_SCHED;
;             PG8_LDA(At, 1, 1); PG8_STAGE(PG8_SB(1, 0), b3, voffB); PG8_STAGE(PG8_SB(1, 1), b3 + hstepB, voffB); PG8_STAGE(PG8_SA(1, 0), a3, voffA);
;             PG8_WAIT_V(8); PG8_WAIT_L(0); PG8_BAR; PG8_MMA(1, 0, At, B0); PG8_MMA(1, 1, At, B1); PG8_BAR; PG8_SCHED;
	s_add_i32 s20, s64, s38
	v_lshl_add_u64 v[190:191], v[190:191], 0, s[84:85]
	s_mov_b32 m0, s20
	ds_read_b128 v[178:181], v193 offset:49152
	ds_read_b128 v[182:185], v193 offset:50176
	ds_read_b128 v[186:189], v193 offset:51200
	ds_read_b128 v[202:205], v193 offset:52224
	ds_read_b128 v[206:209], v193 offset:53248
	ds_read_b128 v[210:213], v193 offset:54272
	ds_read_b128 v[214:217], v193 offset:55296
	ds_read_b128 v[218:221], v193 offset:56320
	global_load_lds_dwordx4 v[190:191], off
	s_add_i32 m0, s20, 0x2000
	s_add_u32 s20, s24, 0x104080
	v_lshl_add_u64 v[190:191], v[194:195], 0, s[84:85]
	s_addc_u32 s21, s25, 0
	s_add_i32 s24, s65, s38
	global_load_lds_dwordx4 v[190:191], off
	v_lshl_add_u64 v[190:191], s[20:21], 0, v[164:165]
	s_mov_b32 m0, s24
	s_nop 0
	global_load_lds_dwordx4 v[190:191], off
	v_lshl_add_u64 v[190:191], s[20:21], 0, v[168:169]
	s_add_i32 m0, s24, 0x2000
	s_nop 0
	global_load_lds_dwordx4 v[190:191], off
	v_lshl_add_u64 v[190:191], v[222:223], 0, s[84:85]
	s_mov_b32 m0, s44
	s_nop 0
	global_load_lds_dwordx4 v[190:191], off
	v_lshl_add_u64 v[190:191], v[224:225], 0, s[84:85]
	s_mov_b32 m0, s45
	s_nop 0
	global_load_lds_dwordx4 v[190:191], off
	s_waitcnt vmcnt(8)
	s_waitcnt lgkmcnt(0)
	s_barrier
	s_setprio 1
	s_waitcnt lgkmcnt(0)
	v_mfma_f32_16x16x32_bf16 v[64:67], v[132:135], v[178:181], v[64:67]
	v_mfma_f32_16x16x32_bf16 v[60:63], v[140:143], v[178:181], v[60:63]
	v_mfma_f32_16x16x32_bf16 v[48:51], v[132:135], v[186:189], v[48:51]
	v_mfma_f32_16x16x32_bf16 v[44:47], v[140:143], v[186:189], v[44:47]
	v_mfma_f32_16x16x32_bf16 v[32:35], v[132:135], v[206:209], v[32:35]
	v_mfma_f32_16x16x32_bf16 v[28:31], v[140:143], v[206:209], v[28:31]
	v_mfma_f32_16x16x32_bf16 v[16:19], v[132:135], v[214:217], v[16:19]
	v_mfma_f32_16x16x32_bf16 v[12:15], v[140:143], v[214:217], v[12:15]
	v_mfma_f32_16x16x32_bf16 v[64:67], v[136:139], v[182:185], v[64:67]
	v_mfma_f32_16x16x32_bf16 v[60:63], v[144:147], v[182:185], v[60:63]
	v_mfma_f32_16x16x32_bf16 v[48:51], v[136:139], v[202:205], v[48:51]
	v_mfma_f32_16x16x32_bf16 v[44:47], v[144:147], v[202:205], v[44:47]
	v_mfma_f32_16x16x32_bf16 v[32:35], v[136:139], v[210:213], v[32:35]
	v_mfma_f32_16x16x32_bf16 v[28:31], v[144:147], v[210:213], v[28:31]
	v_mfma_f32_16x16x32_bf16 v[16:19], v[136:139], v[218:221], v[16:19]
	v_mfma_f32_16x16x32_bf16 v[12:15], v[144:147], v[218:221], v[12:15]
	s_setprio 0
	s_setprio 1
	v_mfma_f32_16x16x32_bf16 v[56:59], v[148:151], v[178:181], v[56:59]
	v_mfma_f32_16x16x32_bf16 v[52:55], v[156:159], v[178:181], v[52:55]
	v_mfma_f32_16x16x32_bf16 v[40:43], v[148:151], v[186:189], v[40:43]
	v_mfma_f32_16x16x32_bf16 v[36:39], v[156:159], v[186:189], v[36:39]
	v_mfma_f32_16x16x32_bf16 v[24:27], v[148:151], v[206:209], v[24:27]
	v_mfma_f32_16x16x32_bf16 v[20:23], v[156:159], v[206:209], v[20:23]
	v_mfma_f32_16x16x32_bf16 v[8:11], v[148:151], v[214:217], v[8:11]
	v_mfma_f32_16x16x32_bf16 v[4:7], v[156:159], v[214:217], v[4:7]
	v_mfma_f32_16x16x32_bf16 v[56:59], v[152:155], v[182:185], v[56:59]
	v_mfma_f32_16x16x32_bf16 v[52:55], v[174:177], v[182:185], v[52:55]
	v_mfma_f32_16x16x32_bf16 v[40:43], v[152:155], v[202:205], v[40:43]
	v_mfma_f32_16x16x32_bf16 v[36:39], v[174:177], v[202:205], v[36:39]
	v_mfma_f32_16x16x32_bf16 v[24:27], v[152:155], v[210:213], v[24:27]
	v_mfma_f32_16x16x32_bf16 v[20:23], v[174:177], v[210:213], v[20:23]
	v_mfma_f32_16x16x32_bf16 v[8:11], v[152:155], v[218:221], v[8:11]
	v_mfma_f32_16x16x32_bf16 v[4:7], v[174:177], v[218:221], v[4:7]
	s_setprio 0
	s_add_u32 s61, s61, 0x100
	s_addc_u32 s62, s62, 0
	s_cmp_ge_i32 s63, s55
	s_mov_b64 s[20:21], s[22:23]
	s_mov_b32 s24, s63
	s_add_i32 s63, s24, 2
	s_add_u32 s22, s20, 0x100
	s_addc_u32 s23, s21, 0
	s_add_i32 s64, 0, 0x10000
	s_cmp_eq_u32 s60, s24
	s_cselect_b32 s27, s56, s23
	s_cselect_b32 s26, s57, s22
	s_cselect_b32 s25, s58, s62
	s_cselect_b32 s24, s59, s61
	s_add_i32 s65, 0, 0x14000
	v_add_u32_e32 v144, s64, v161
	v_add_u32_e32 v174, s65, v161
	s_barrier
.LBB0_412:
	ds_read_b128 v[132:135], v144
	ds_read_b128 v[136:139], v144 offset:1024
	ds_read_b128 v[140:143], v144 offset:2048
	ds_read_b128 v[144:147], v144 offset:3072
	ds_read_b128 v[148:151], v174
	ds_read_b128 v[152:155], v174 offset:1024
	ds_read_b128 v[156:159], v174 offset:2048
	ds_read_b128 v[174:177], v174 offset:3072
	v_lshl_add_u64 v[190:191], s[20:21], 0, v[170:171]
	s_add_i32 m0, s39, 0xc000
	ds_read_b128 v[178:181], v193
	ds_read_b128 v[182:185], v193 offset:1024
	ds_read_b128 v[186:189], v193 offset:2048
	ds_read_b128 v[202:205], v193 offset:3072
	ds_read_b128 v[206:209], v193 offset:4096
	ds_read_b128 v[210:213], v193 offset:5120
	ds_read_b128 v[214:217], v193 offset:6144
	ds_read_b128 v[218:221], v193 offset:7168
	global_load_lds_dwordx4 v[190:191], off
	v_lshl_add_u64 v[190:191], s[20:21], 0, v[172:173]
	s_add_i32 m0, s39, 0xe000
	s_nop 0
	global_load_lds_dwordx4 v[190:191], off
	s_waitcnt vmcnt(8)
	s_waitcnt lgkmcnt(0)
	s_barrier
; #define PG8_STAGE(bufoff, gbase, voff) do { _Pragma("unroll") for (int _i = 0; _i < 2; ++_i) \
;         __builtin_amdgcn_global_load_lds((const unsigned*)((const char*)(gbase) + (voff)[_i]), (LAS unsigned*)(lds + (bufoff) + ldsw + _i * 8192), 16, 0, 0); } while (0)
; #define PG8_LDA(dst, b, h) do { _Pragma("unroll") for (int m = 0; m < 4; ++m) _Pragma("unroll") for (int k = 0; k < 2; ++k) dst[m][k] = *(const LAS bf16x8*)(lds + PG8_SA(b, h) + aoff + m * 2048 + k * 1024); } while (0)
; #define PG8_LDB(dst, b, h) do { _Pragma("unroll") for (int n = 0; n < 2; ++n) _Pragma("unroll") for (int k = 0; k < 2; ++k) dst[n][k] = *(const LAS bf16x8*)(lds + PG8_SB(b, h) + boff + n * 2048 + k * 1024); } while (0)
; #define PG8_MMA(ai, bj, At, Bt) do { __builtin_amdgcn_s_setprio(1); _Pragma("unroll") for (int m = 0; m < 4; ++m) _Pragma("unroll") for (int n = 0; n < 2; ++n) _Pragma("unroll") for (int k = 0; k < 2; ++k) \
;         acc[ai][bj][m][n] = __builtin_amdgcn_mfma_f32_16x16x32_bf16(Bt[n][k], At[m][k], acc[ai][bj][m][n], 0, 0, 0); __builtin_amdgcn_s_setprio(0); } while (0)
; #define PG8_WAIT_V(n) asm volatile("s_waitcnt vmcnt(" #n ")" ::: "memory")
; #define PG8_WAIT_L(n) asm volatile("s_waitcnt lgkmcnt(" #n ")" ::: "memory")
; #define PG8_BAR __builtin_amdgcn_s_barrier()
; #define PG8_SCHED __builtin_amdgcn_sched_barrier(0)
; template <class Epi, bool ALIGN_EPI>
; DI void gemm_phase(LAS unsigned char* lds, const Sched& S, const Epi& E, int tid) {
;     ...
;             PG8_LDB(B0, 0, 0); PG8_LDB(B1, 0, 1); PG8_SCHED; PG8_LDA(At, 0, 0); PG8_STAGE(PG8_SA(1, 1), a1 + hstepA, voffA);
;             PG8_WAIT_V(8); PG8_WAIT_L(0); PG8_BAR; PG8_MMA(0, 0, At, B0); PG8_MMA(0, 1, At, B1); PG8_BAR; PG8_SCHED;
;             PG8_LDA(At, 0, 1); PG8_STAGE(PG8_SB(0, 0), b2, voffB); PG8_STAGE(PG8_SB(0, 1), b2 + hstepB, voffB); PG8_STAGE(PG8_SA(0, 0), a2, voffA);
;             PG8_WAIT_V(8); PG8_WAIT_L(0); PG8_BAR; PG8_MMA(1, 0, At, B0); PG8_MMA(1, 1, At, B1); PG8_BAR; PG8_SCHED;
;             PG8_LDB(B0, 1, 0); PG8_LDB(B1, 1, 1); PG8_SCHED; PG8_LDA(At, 1, 0); PG8_STAGE(PG8_SA(0, 1), a2 + hstepA, voffA);
;             PG8_WAIT_V(8); PG8_WAIT_L(0); PG8_BAR; PG8_MMA(0, 0, At, B0); PG8_MMA(0, 1, At, B1); PG8_BAR; PG8_SCHED;
	s_setprio 1
	s_waitcnt lgkmcnt(0)
	v_mfma_f32_16x16x32_bf16 v[128:131], v[132:135], v[178:181], v[128:131]
	v_mfma_f32_16x16x32_bf16 v[124:127], v[140:143], v[178:181], v[124:127]
	v_mfma_f32_16x16x32_bf16 v[112:115], v[132:135], v[186:189], v[112:115]
	v_mfma_f32_16x16x32_bf16 v[108:111], v[140:143], v[186:189], v[108:111]
	v_mfma_f32_16x16x32_bf16 v[96:99], v[132:135], v[206:209], v[96:99]
	v_mfma_f32_16x16x32_bf16 v[92:95], v[140:143], v[206:209], v[92:95]
	v_mfma_f32_16x16x32_bf16 v[80:83], v[132:135], v[214:217], v[80:83]
	v_mfma_f32_16x16x32_bf16 v[76:79], v[140:143], v[214:217], v[76:79]
	v_mfma_f32_16x16x32_bf16 v[128:131], v[136:139], v[182:185], v[128:131]
	v_mfma_f32_16x16x32_bf16 v[124:127], v[144:147], v[182:185], v[124:127]
	v_mfma_f32_16x16x32_bf16 v[112:115], v[136:139], v[202:205], v[112:115]
	v_mfma_f32_16x16x32_bf16 v[108:111], v[144:147], v[202:205], v[108:111]
	v_mfma_f32_16x16x32_bf16 v[96:99], v[136:139], v[210:213], v[96:99]
	v_mfma_f32_16x16x32_bf16 v[92:95], v[144:147], v[210:213], v[92:95]
	v_mfma_f32_16x16x32_bf16 v[80:83], v[136:139], v[218:221], v[80:83]
	v_mfma_f32_16x16x32_bf16 v[76:79], v[144:147], v[218:221], v[76:79]
	s_setprio 0
	s_setprio 1
	v_mfma_f32_16x16x32_bf16 v[120:123], v[148:151], v[178:181], v[120:123]
	v_mfma_f32_16x16x32_bf16 v[116:119], v[156:159], v[178:181], v[116:119]
	v_mfma_f32_16x16x32_bf16 v[104:107], v[148:151], v[186:189], v[104:107]
	v_mfma_f32_16x16x32_bf16 v[100:103], v[156:159], v[186:189], v[100:103]
	v_mfma_f32_16x16x32_bf16 v[88:91], v[148:151], v[206:209], v[88:91]
	v_mfma_f32_16x16x32_bf16 v[84:87], v[156:159], v[206:209], v[84:87]
	v_mfma_f32_16x16x32_bf16 v[72:75], v[148:151], v[214:217], v[72:75]
	v_mfma_f32_16x16x32_bf16 v[68:71], v[156:159], v[214:217], v[68:71]
	v_mfma_f32_16x16x32_bf16 v[120:123], v[152:155], v[182:185], v[120:123]
	v_mfma_f32_16x16x32_bf16 v[116:119], v[174:177], v[182:185], v[116:119]
	v_mfma_f32_16x16x32_bf16 v[104:107], v[152:155], v[202:205], v[104:107]
	v_mfma_f32_16x16x32_bf16 v[100:103], v[174:177], v[202:205], v[100:103]
	v_mfma_f32_16x16x32_bf16 v[88:91], v[152:155], v[210:213], v[88:91]
	v_mfma_f32_16x16x32_bf16 v[84:87], v[174:177], v[210:213], v[84:87]
	v_mfma_f32_16x16x32_bf16 v[72:75], v[152:155], v[218:221], v[72:75]
	v_mfma_f32_16x16x32_bf16 v[68:71], v[174:177], v[218:221], v[68:71]
	s_setprio 0
	s_barrier
	s_add_i32 s20, s64, s38
	v_lshl_add_u64 v[190:191], s[24:25], 0, v[164:165]
	s_mov_b32 m0, s20
	ds_read_b128 v[178:181], v193 offset:16384
	ds_read_b128 v[182:185], v193 offset:17408
	ds_read_b128 v[186:189], v193 offset:18432
	ds_read_b128 v[202:205], v193 offset:19456
	ds_read_b128 v[206:209], v193 offset:20480
	ds_read_b128 v[210:213], v193 offset:21504
	ds_read_b128 v[214:217], v193 offset:22528
	ds_read_b128 v[218:221], v193 offset:23552
	global_load_lds_dwordx4 v[190:191], off
	s_add_i32 m0, s20, 0x2000
	s_add_u32 s20, s24, 0x104000
	v_lshl_add_u64 v[194:195], s[24:25], 0, v[168:169]
	s_addc_u32 s21, s25, 0
	s_add_i32 s64, s65, s38
	global_load_lds_dwordx4 v[194:195], off
	v_lshl_add_u64 v[222:223], s[20:21], 0, v[164:165]
	s_mov_b32 m0, s64
	v_lshl_add_u64 v[224:225], s[26:27], 0, v[166:167]
	global_load_lds_dwordx4 v[222:223], off
	v_lshl_add_u64 v[222:223], s[20:21], 0, v[168:169]
	s_add_i32 m0, s64, 0x2000
	s_nop 0
	global_load_lds_dwordx4 v[222:223], off
	v_lshl_add_u64 v[222:223], s[26:27], 0, v[162:163]
	s_mov_b32 m0, s39
	s_nop 0
	global_load_lds_dwordx4 v[222:223], off
	s_mov_b32 m0, s40
	s_nop 0
	global_load_lds_dwordx4 v[224:225], off
	s_waitcnt vmcnt(8)
	s_waitcnt lgkmcnt(0)
	s_barrier
	s_setprio 1
	s_waitcnt lgkmcnt(0)
	v_mfma_f32_16x16x32_bf16 v[64:67], v[132:135], v[178:181], v[64:67]
	v_mfma_f32_16x16x32_bf16 v[60:63], v[140:143], v[178:181], v[60:63]
	v_mfma_f32_16x16x32_bf16 v[48:51], v[132:135], v[186:189], v[48:51]
	v_mfma_f32_16x16x32_bf16 v[44:47], v[140:143], v[186:189], v[44:47]
	v_mfma_f32_16x16x32_bf16 v[32:35], v[132:135], v[206:209], v[32:35]
	v_mfma_f32_16x16x32_bf16 v[28:31], v[140:143], v[206:209], v[28:31]
	v_mfma_f32_16x16x32_bf16 v[16:19], v[132:135], v[214:217], v[16:19]
	v_mfma_f32_16x16x32_bf16 v[12:15], v[140:143], v[214:217], v[12:15]
	v_mfma_f32_16x16x32_bf16 v[64:67], v[136:139], v[182:185], v[64:67]
	v_mfma_f32_16x16x32_bf16 v[60:63], v[144:147], v[182:185], v[60:63]
	v_mfma_f32_16x16x32_bf16 v[48:51], v[136:139], v[202:205], v[48:51]
	v_mfma_f32_16x16x32_bf16 v[44:47], v[144:147], v[202:205], v[44:47]
	v_mfma_f32_16x16x32_bf16 v[32:35], v[136:139], v[210:213], v[32:35]
	v_mfma_f32_16x16x32_bf16 v[28:31], v[144:147], v[210:213], v[28:31]
	v_mfma_f32_16x16x32_bf16 v[16:19], v[136:139], v[218:221], v[16:19]
	v_mfma_f32_16x16x32_bf16 v[12:15], v[144:147], v[218:221], v[12:15]
	s_setprio 0
	s_setprio 1
	v_mfma_f32_16x16x32_bf16 v[56:59], v[148:151], v[178:181], v[56:59]
	v_mfma_f32_16x16x32_bf16 v[52:55], v[156:159], v[178:181], v[52:55]
	v_mfma_f32_16x16x32_bf16 v[40:43], v[148:151], v[186:189], v[40:43]
	v_mfma_f32_16x16x32_bf16 v[36:39], v[156:159], v[186:189], v[36:39]
	v_mfma_f32_16x16x32_bf16 v[24:27], v[148:151], v[206:209], v[24:27]
	v_mfma_f32_16x16x32_bf16 v[20:23], v[156:159], v[206:209], v[20:23]
	v_mfma_f32_16x16x32_bf16 v[8:11], v[148:151], v[214:217], v[8:11]
	v_mfma_f32_16x16x32_bf16 v[4:7], v[156:159], v[214:217], v[4:7]
	v_mfma_f32_16x16x32_bf16 v[56:59], v[152:155], v[182:185], v[56:59]
	v_mfma_f32_16x16x32_bf16 v[52:55], v[174:177], v[182:185], v[52:55]
	v_mfma_f32_16x16x32_bf16 v[40:43], v[152:155], v[202:205], v[40:43]
	v_mfma_f32_16x16x32_bf16 v[36:39], v[174:177], v[202:205], v[36:39]
	v_mfma_f32_16x16x32_bf16 v[24:27], v[152:155], v[210:213], v[24:27]
	v_mfma_f32_16x16x32_bf16 v[20:23], v[174:177], v[210:213], v[20:23]
	v_mfma_f32_16x16x32_bf16 v[8:11], v[152:155], v[218:221], v[8:11]
	v_mfma_f32_16x16x32_bf16 v[4:7], v[174:177], v[218:221], v[4:7]
	s_setprio 0
	s_barrier
; #define PG8_STAGE(bufoff, gbase, voff) do { _Pragma("unroll") for (int _i = 0; _i < 2; ++_i) \
;         __builtin_amdgcn_global_load_lds((const unsigned*)((const char*)(gbase) + (voff)[_i]), (LAS unsigned*)(lds + (bufoff) + ldsw + _i * 8192), 16, 0, 0); } while (0)
; #define PG8_LDA(dst, b, h) do { _Pragma("unroll") for (int m = 0; m < 4; ++m) _Pragma("unroll") for (int k = 0; k < 2; ++k) dst[m][k] = *(const LAS bf16x8*)(lds + PG8_SA(b, h) + aoff + m * 2048 + k * 1024); } while (0)
; #define PG8_LDB(dst, b, h) do { _Pragma("unroll") for (int n = 0; n < 2; ++n) _Pragma("unroll") for (int k = 0; k < 2; ++k) dst[n][k] = *(const LAS bf16x8*)(lds + PG8_SB(b, h) + boff + n * 2048 + k * 1024); } while (0)
; #define PG8_MMA(ai, bj, At, Bt) do { __builtin_amdgcn_s_setprio(1); _Pragma("unroll") for (int m = 0; m < 4; ++m) _Pragma("unroll") for (int n = 0; n < 2; ++n) _Pragma("unroll") for (int k = 0; k < 2; ++k) \
;         acc[ai][bj][m][n] = __builtin_amdgcn_mfma_f32_16x16x32_bf16(Bt[n][k], At[m][k], acc[ai][bj][m][n], 0, 0, 0); __builtin_amdgcn_s_setprio(0); } while (0)
; #define PG8_WAIT_V(n) asm volatile("s_waitcnt vmcnt(" #n ")" ::: "memory")
; #define PG8_WAIT_L(n) asm volatile("s_waitcnt lgkmcnt(" #n ")" ::: "memory")
; #define PG8_BAR __builtin_amdgcn_s_barrier()
; #define PG8_SCHED __builtin_amdgcn_sched_barrier(0)
; template <class Epi, bool ALIGN_EPI>
; DI void gemm_phase(LAS unsigned char* lds, const Sched& S, const Epi& E, int tid) {
;     ...
;             PG8_LDB(B0, 1, 0); PG8_LDB(B1, 1, 1); PG8_SCHED; PG8_LDA(At, 1, 0); PG8_STAGE(PG8_SA(0, 1), a2 + hstepA, voffA);
;             PG8_WAIT_V(8); PG8_WAIT_L(0); PG8_BAR; PG8_MMA(0, 0, At, B0); PG8_MMA(0, 1, At, B1); PG8_BAR; PG8_SCHED;
;             PG8_LDA(At, 1, 1); PG8_STAGE(PG8_SB(1, 0), b3, voffB); PG8_STAGE(PG8_SB(1, 1), b3 + hstepB, voffB); PG8_STAGE(PG8_SA(1, 0), a3, voffA);
;             PG8_WAIT_V(8); PG8_WAIT_L(0); PG8_BAR; PG8_MMA(1, 0, At, B0); PG8_MMA(1, 1, At, B1); PG8_BAR; PG8_SCHED;
	s_add_i32 s64, 0, 0x18000
	s_add_i32 s65, 0, 0x1c000
	v_add_u32_e32 v144, s64, v161
	v_add_u32_e32 v174, s65, v161
	ds_read_b128 v[132:135], v144
	ds_read_b128 v[136:139], v144 offset:1024
	ds_read_b128 v[140:143], v144 offset:2048
	ds_read_b128 v[144:147], v144 offset:3072
	ds_read_b128 v[148:151], v174
	ds_read_b128 v[152:155], v174 offset:1024
	ds_read_b128 v[156:159], v174 offset:2048
	ds_read_b128 v[174:177], v174 offset:3072
	s_add_u32 s20, s26, 0x104000
	s_addc_u32 s21, s27, 0
	s_mov_b32 m0, s41
	v_lshl_add_u64 v[226:227], s[20:21], 0, v[162:163]
	ds_read_b128 v[178:181], v193 offset:32768
	ds_read_b128 v[182:185], v193 offset:33792
	ds_read_b128 v[186:189], v193 offset:34816
	ds_read_b128 v[202:205], v193 offset:35840
	ds_read_b128 v[206:209], v193 offset:36864
	ds_read_b128 v[210:213], v193 offset:37888
	ds_read_b128 v[214:217], v193 offset:38912
	ds_read_b128 v[218:221], v193 offset:39936
	global_load_lds_dwordx4 v[226:227], off
	v_lshl_add_u64 v[226:227], s[20:21], 0, v[166:167]
	s_mov_b32 m0, s42
	s_nop 0
	global_load_lds_dwordx4 v[226:227], off
	s_waitcnt vmcnt(8)
	s_waitcnt lgkmcnt(0)
	s_barrier
	s_setprio 1
	s_waitcnt lgkmcnt(0)
	v_mfma_f32_16x16x32_bf16 v[128:131], v[132:135], v[178:181], v[128:131]
	v_mfma_f32_16x16x32_bf16 v[124:127], v[140:143], v[178:181], v[124:127]
	v_mfma_f32_16x16x32_bf16 v[112:115], v[132:135], v[186:189], v[112:115]
	v_mfma_f32_16x16x32_bf16 v[108:111], v[140:143], v[186:189], v[108:111]
	v_mfma_f32_16x16x32_bf16 v[96:99], v[132:135], v[206:209], v[96:99]
	v_mfma_f32_16x16x32_bf16 v[92:95], v[140:143], v[206:209], v[92:95]
	v_mfma_f32_16x16x32_bf16 v[80:83], v[132:135], v[214:217], v[80:83]
	v_mfma_f32_16x16x32_bf16 v[76:79], v[140:143], v[214:217], v[76:79]
	v_mfma_f32_16x16x32_bf16 v[128:131], v[136:139], v[182:185], v[128:131]
	v_mfma_f32_16x16x32_bf16 v[124:127], v[144:147], v[182:185], v[124:127]
	v_mfma_f32_16x16x32_bf16 v[112:115], v[136:139], v[202:205], v[112:115]
	v_mfma_f32_16x16x32_bf16 v[108:111], v[144:147], v[202:205], v[108:111]
	v_mfma_f32_16x16x32_bf16 v[96:99], v[136:139], v[210:213], v[96:99]
	v_mfma_f32_16x16x32_bf16 v[92:95], v[144:147], v[210:213], v[92:95]
	v_mfma_f32_16x16x32_bf16 v[80:83], v[136:139], v[218:221], v[80:83]
	v_mfma_f32_16x16x32_bf16 v[76:79], v[144:147], v[218:221], v[76:79]
	s_setprio 0
	s_setprio 1
	v_mfma_f32_16x16x32_bf16 v[120:123], v[148:151], v[178:181], v[120:123]
	v_mfma_f32_16x16x32_bf16 v[116:119], v[156:159], v[178:181], v[116:119]
	v_mfma_f32_16x16x32_bf16 v[104:107], v[148:151], v[186:189], v[104:107]
	v_mfma_f32_16x16x32_bf16 v[100:103], v[156:159], v[186:189], v[100:103]
	v_mfma_f32_16x16x32_bf16 v[88:91], v[148:151], v[206:209], v[88:91]
	v_mfma_f32_16x16x32_bf16 v[84:87], v[156:159], v[206:209], v[84:87]
	v_mfma_f32_16x16x32_bf16 v[72:75], v[148:151], v[214:217], v[72:75]
	v_mfma_f32_16x16x32_bf16 v[68:71], v[156:159], v[214:217], v[68:71]
	v_mfma_f32_16x16x32_bf16 v[120:123], v[152:155], v[182:185], v[120:123]
	v_mfma_f32_16x16x32_bf16 v[116:119], v[174:177], v[182:185], v[116:119]
	v_mfma_f32_16x16x32_bf16 v[104:107], v[152:155], v[202:205], v[104:107]
	v_mfma_f32_16x16x32_bf16 v[100:103], v[174:177], v[202:205], v[100:103]
	v_mfma_f32_16x16x32_bf16 v[88:91], v[152:155], v[210:213], v[88:91]
	v_mfma_f32_16x16x32_bf16 v[84:87], v[174:177], v[210:213], v[84:87]
	v_mfma_f32_16x16x32_bf16 v[72:75], v[152:155], v[218:221], v[72:75]
	v_mfma_f32_16x16x32_bf16 v[68:71], v[174:177], v[218:221], v[68:71]
	s_setprio 0
	s_barrier
; #define PG8_STAGE(bufoff, gbase, voff) do { _Pragma("unroll") for (int _i = 0; _i < 2; ++_i) \
;         __builtin_amdgcn_global_load_lds((const unsigned*)((const char*)(gbase) + (voff)[_i]), (LAS unsigned*)(lds + (bufoff) + ldsw + _i * 8192), 16, 0, 0); } while (0)
; #define PG8_LDA(dst, b, h) do { _Pragma("unroll") for (int m = 0; m < 4; ++m) _Pragma("unroll") for (int k = 0; k < 2; ++k) dst[m][k] = *(const LAS bf16x8*)(lds + PG8_SA(b, h) + aoff + m * 2048 + k * 1024); } while (0)
; #define PG8_MMA(ai, bj, At, Bt) do { __builtin_amdgcn_s_setprio(1); _Pragma("unroll") for (int m = 0; m < 4; ++m) _Pragma("unroll") for (int n = 0; n < 2; ++n) _Pragma("unroll") for (int k = 0; k < 2; ++k) \
;         acc[ai][bj][m][n] = __builtin_amdgcn_mfma_f32_16x16x32_bf16(Bt[n][k], At[m][k], acc[ai][bj][m][n], 0, 0, 0); __builtin_amdgcn_s_setprio(0); } while (0)
; #define PG8_WAIT_V(n) asm volatile("s_waitcnt vmcnt(" #n ")" ::: "memory")
; #define PG8_WAIT_L(n) asm volatile("s_waitcnt lgkmcnt(" #n ")" ::: "memory")
; #define PG8_BAR __builtin_amdgcn_s_barrier()
; #define PG8_SCHED __builtin_amdgcn_sched_barrier(0)
; template <class Epi, bool ALIGN_EPI>
; DI void gemm_phase(LAS unsigned char* lds, const Sched& S, const Epi& E, int tid) {
;     ...
;             PG8_WAIT_V(8); PG8_WAIT_L(0); PG8_BAR; PG8_MMA(0, 0, At, B0); PG8_MMA(0, 1, At, B1); PG8_BAR; PG8_SCHED;
;             PG8_LDA(At, 1, 1); PG8_STAGE(PG8_SB(1, 0), b3, voffB); PG8_STAGE(PG8_SB(1, 1), b3 + hstepB, voffB); PG8_STAGE(PG8_SA(1, 0), a3, voffA);
;             PG8_WAIT_V(8); PG8_WAIT_L(0); PG8_BAR; PG8_MMA(1, 0, At, B0); PG8_MMA(1, 1, At, B1); PG8_BAR; PG8_SCHED;
;         }
;         if constexpr (ALIGN_EPI) { if (wr == 0) PG8_BAR; }
	s_add_i32 s20, s64, s38
	v_lshl_add_u64 v[190:191], v[190:191], 0, s[84:85]
	s_mov_b32 m0, s20
	ds_read_b128 v[178:181], v193 offset:49152
	ds_read_b128 v[182:185], v193 offset:50176
	ds_read_b128 v[186:189], v193 offset:51200
	ds_read_b128 v[202:205], v193 offset:52224
	ds_read_b128 v[206:209], v193 offset:53248
	ds_read_b128 v[210:213], v193 offset:54272
	ds_read_b128 v[214:217], v193 offset:55296
	ds_read_b128 v[218:221], v193 offset:56320
	global_load_lds_dwordx4 v[190:191], off
	s_add_i32 m0, s20, 0x2000
	s_add_u32 s20, s24, 0x104080
	v_lshl_add_u64 v[190:191], v[194:195], 0, s[84:85]
	s_addc_u32 s21, s25, 0
	s_add_i32 s24, s65, s38
	global_load_lds_dwordx4 v[190:191], off
	v_lshl_add_u64 v[190:191], s[20:21], 0, v[164:165]
	s_mov_b32 m0, s24
	s_nop 0
	global_load_lds_dwordx4 v[190:191], off
	v_lshl_add_u64 v[190:191], s[20:21], 0, v[168:169]
	s_add_i32 m0, s24, 0x2000
	s_nop 0
	global_load_lds_dwordx4 v[190:191], off
	v_lshl_add_u64 v[190:191], v[222:223], 0, s[84:85]
	s_mov_b32 m0, s44
	s_nop 0
	global_load_lds_dwordx4 v[190:191], off
	v_lshl_add_u64 v[190:191], v[224:225], 0, s[84:85]
	s_mov_b32 m0, s45
	s_nop 0
	global_load_lds_dwordx4 v[190:191], off
	s_waitcnt vmcnt(8)
	s_waitcnt lgkmcnt(0)
	s_barrier
	s_setprio 1
	s_waitcnt lgkmcnt(0)
	v_mfma_f32_16x16x32_bf16 v[64:67], v[132:135], v[178:181], v[64:67]
	v_mfma_f32_16x16x32_bf16 v[60:63], v[140:143], v[178:181], v[60:63]
	v_mfma_f32_16x16x32_bf16 v[48:51], v[132:135], v[186:189], v[48:51]
	v_mfma_f32_16x16x32_bf16 v[44:47], v[140:143], v[186:189], v[44:47]
	v_mfma_f32_16x16x32_bf16 v[32:35], v[132:135], v[206:209], v[32:35]
	v_mfma_f32_16x16x32_bf16 v[28:31], v[140:143], v[206:209], v[28:31]
	v_mfma_f32_16x16x32_bf16 v[16:19], v[132:135], v[214:217], v[16:19]
	v_mfma_f32_16x16x32_bf16 v[12:15], v[140:143], v[214:217], v[12:15]
	v_mfma_f32_16x16x32_bf16 v[64:67], v[136:139], v[182:185], v[64:67]
	v_mfma_f32_16x16x32_bf16 v[60:63], v[144:147], v[182:185], v[60:63]
	v_mfma_f32_16x16x32_bf16 v[48:51], v[136:139], v[202:205], v[48:51]
	v_mfma_f32_16x16x32_bf16 v[44:47], v[144:147], v[202:205], v[44:47]
	v_mfma_f32_16x16x32_bf16 v[32:35], v[136:139], v[210:213], v[32:35]
	v_mfma_f32_16x16x32_bf16 v[28:31], v[144:147], v[210:213], v[28:31]
	v_mfma_f32_16x16x32_bf16 v[16:19], v[136:139], v[218:221], v[16:19]
	v_mfma_f32_16x16x32_bf16 v[12:15], v[144:147], v[218:221], v[12:15]
	s_setprio 0
	s_setprio 1
	v_mfma_f32_16x16x32_bf16 v[56:59], v[148:151], v[178:181], v[56:59]
	v_mfma_f32_16x16x32_bf16 v[52:55], v[156:159], v[178:181], v[52:55]
	v_mfma_f32_16x16x32_bf16 v[40:43], v[148:151], v[186:189], v[40:43]
	v_mfma_f32_16x16x32_bf16 v[36:39], v[156:159], v[186:189], v[36:39]
	v_mfma_f32_16x16x32_bf16 v[24:27], v[148:151], v[206:209], v[24:27]
	v_mfma_f32_16x16x32_bf16 v[20:23], v[156:159], v[206:209], v[20:23]
	v_mfma_f32_16x16x32_bf16 v[8:11], v[148:151], v[214:217], v[8:11]
	v_mfma_f32_16x16x32_bf16 v[4:7], v[156:159], v[214:217], v[4:7]
	v_mfma_f32_16x16x32_bf16 v[56:59], v[152:155], v[182:185], v[56:59]
	v_mfma_f32_16x16x32_bf16 v[52:55], v[174:177], v[182:185], v[52:55]
	v_mfma_f32_16x16x32_bf16 v[40:43], v[152:155], v[202:205], v[40:43]
	v_mfma_f32_16x16x32_bf16 v[36:39], v[174:177], v[202:205], v[36:39]
	v_mfma_f32_16x16x32_bf16 v[24:27], v[152:155], v[210:213], v[24:27]
	v_mfma_f32_16x16x32_bf16 v[20:23], v[174:177], v[210:213], v[20:23]
	v_mfma_f32_16x16x32_bf16 v[8:11], v[152:155], v[218:221], v[8:11]
	v_mfma_f32_16x16x32_bf16 v[4:7], v[174:177], v[218:221], v[4:7]
	s_setprio 0
	s_add_u32 s61, s61, 0x100
	s_addc_u32 s62, s62, 0
	s_cmp_ge_i32 s63, s55
	s_mov_b64 s[20:21], s[22:23]
	s_mov_b32 s24, s63
	s_cbranch_scc1 .Lkx_7
	s_add_i32 s63, s24, 2
	s_add_u32 s22, s20, 0x100
	s_addc_u32 s23, s21, 0
	s_add_i32 s64, 0, 0x10000
	s_cmp_eq_u32 s60, s24
	s_cselect_b32 s27, s56, s23
	s_cselect_b32 s26, s57, s22
	s_cselect_b32 s25, s58, s62
	s_cselect_b32 s24, s59, s61
	s_add_i32 s65, 0, 0x14000
	v_add_u32_e32 v144, s64, v161
	v_add_u32_e32 v174, s65, v161
	s_barrier
	s_branch .LBB0_412

; #define PG8_STAGE(bufoff, gbase, voff) do { _Pragma("unroll") for (int _i = 0; _i < 2; ++_i) \
;         __builtin_amdgcn_global_load_lds((const unsigned*)((const char*)(gbase) + (voff)[_i]), (LAS unsigned*)(lds + (bufoff) + ldsw + _i * 8192), 16, 0, 0); } while (0)
; #define PG8_LDA(dst, b, h) do { _Pragma("unroll") for (int m = 0; m < 4; ++m) _Pragma("unroll") for (int k = 0; k < 2; ++k) dst[m][k] = *(const LAS bf16x8*)(lds + PG8_SA(b, h) + aoff + m * 2048 + k * 1024); } while (0)
; #define PG8_LDB(dst, b, h) do { _Pragma("unroll") for (int n = 0; n < 2; ++n) _Pragma("unroll") for (int k = 0; k < 2; ++k) dst[n][k] = *(const LAS bf16x8*)(lds + PG8_SB(b, h) + boff + n * 2048 + k * 1024); } while (0)
; #define PG8_MMA(ai, bj, At, Bt) do { __builtin_amdgcn_s_setprio(1); _Pragma("unroll") for (int m = 0; m < 4; ++m) _Pragma("unroll") for (int n = 0; n < 2; ++n) _Pragma("unroll") for (int k = 0; k < 2; ++k) \
;         acc[ai][bj][m][n] = __builtin_amdgcn_mfma_f32_16x16x32_bf16(Bt[n][k], At[m][k], acc[ai][bj][m][n], 0, 0, 0); __builtin_amdgcn_s_setprio(0); } while (0)
; #define PG8_WAIT_V(n) asm volatile("s_waitcnt vmcnt(" #n ")" ::: "memory")
; #define PG8_BAR __builtin_amdgcn_s_barrier()
; template <class Epi, bool ALIGN_EPI>
; DI void gemm_phase(LAS unsigned char* lds, const Sched& S, const Epi& E, int tid) {
;     ...
;         const bool has_next = S.next(ui + 1, nxt);
;         const char* nA = has_next ? nxt.a : cA; const char* nB = has_next ? nxt.b : cB;
;         const int nt = cur.nt;
;         for (int t = 0; t < nt; t += 2) {
;             const bool last = (t == nt - 2);
;             const char* a1 = cA + (size_t)(t + 1) * kstep;
;             const char* a2 = last ? nA : cA + (size_t)(t + 2) * kstep; const char* b2 = last ? nB : cB + (size_t)(t + 2) * kstep;
;             const char* a3 = a2 + kstep; const char* b3 = b2 + kstep;
;             PG8_LDB(B0, 0, 0); PG8_LDB(B1, 0, 1); PG8_SCHED; PG8_LDA(At, 0, 0); PG8_STAGE(PG8_SA(1, 1), a1 + hstepA, voffA);
;             PG8_WAIT_V(8); PG8_WAIT_L(0); PG8_BAR; PG8_MMA(0, 0, At, B0); PG8_MMA(0, 1, At, B1); PG8_BAR; PG8_SCHED;
;             PG8_LDA(At, 0, 1); PG8_STAGE(PG8_SB(0, 0), b2, voffB); PG8_STAGE(PG8_SB(0, 1), b2 + hstepB, voffB); PG8_STAGE(PG8_SA(0, 0), a2, voffA);
;             PG8_WAIT_V(8); PG8_WAIT_L(0); PG8_BAR; PG8_MMA(1, 0, At, B0); PG8_MMA(1, 1, At, B1); PG8_BAR; PG8_SCHED;
.LBB0_652:
	s_add_u32 s22, s22, 0x40080
	s_addc_u32 s23, s23, 0
	s_add_u32 s37, s24, 0x100
	s_addc_u32 s38, s25, 0
	s_mov_b32 s39, -2
	s_add_u32 s24, s22, 0xfffc0080
	s_addc_u32 s25, s23, -1
	s_add_i32 s40, 0, 0x10000
	s_cmp_eq_u32 s39, 12
	s_cselect_b32 s29, s3, s25
	s_cselect_b32 s28, s2, s24
	v_add_u32_e32 v154, s40, v141
	s_cselect_b32 s25, s21, s38
	s_cselect_b32 s24, s20, s37
	s_add_i32 s58, 0, 0x14000
	ds_read_b128 v[146:149], v154
	ds_read_b128 v[150:153], v154 offset:1024
	ds_read_b128 v[162:165], v154 offset:2048
	ds_read_b128 v[166:169], v154 offset:3072
	v_add_u32_e32 v154, s58, v141
	ds_read_b128 v[170:173], v154
	ds_read_b128 v[174:177], v154 offset:1024
	ds_read_b128 v[178:181], v154 offset:2048
	ds_read_b128 v[182:185], v154 offset:3072
	v_lshl_add_u64 v[154:155], s[22:23], 0, v[142:143]
	s_add_i32 m0, s50, 0xc000
	ds_read_b128 v[186:189], v157
	ds_read_b128 v[190:193], v157 offset:1024
	ds_read_b128 v[202:205], v157 offset:2048
	ds_read_b128 v[206:209], v157 offset:3072
	ds_read_b128 v[210:213], v157 offset:4096
	ds_read_b128 v[214:217], v157 offset:5120
	ds_read_b128 v[218:221], v157 offset:6144
	ds_read_b128 v[222:225], v157 offset:7168
	global_load_lds_dwordx4 v[154:155], off
	v_lshl_add_u64 v[154:155], s[22:23], 0, v[144:145]
	s_add_i32 m0, s50, 0xe000
	s_nop 0
	global_load_lds_dwordx4 v[154:155], off
	s_waitcnt vmcnt(8)
	s_waitcnt lgkmcnt(0)
	s_barrier
	s_setprio 1
	s_waitcnt lgkmcnt(0)
	v_mfma_f32_16x16x32_bf16 v[128:131], v[146:149], v[186:189], 0
	v_mfma_f32_16x16x32_bf16 v[124:127], v[162:165], v[186:189], 0
	v_mfma_f32_16x16x32_bf16 v[112:115], v[146:149], v[202:205], 0
	v_mfma_f32_16x16x32_bf16 v[108:111], v[162:165], v[202:205], 0
	v_mfma_f32_16x16x32_bf16 v[96:99], v[146:149], v[210:213], 0
	v_mfma_f32_16x16x32_bf16 v[92:95], v[162:165], v[210:213], 0
	v_mfma_f32_16x16x32_bf16 v[80:83], v[146:149], v[218:221], 0
	v_mfma_f32_16x16x32_bf16 v[76:79], v[162:165], v[218:221], 0
	v_mfma_f32_16x16x32_bf16 v[128:131], v[150:153], v[190:193], v[128:131]
	v_mfma_f32_16x16x32_bf16 v[124:127], v[166:169], v[190:193], v[124:127]
	v_mfma_f32_16x16x32_bf16 v[112:115], v[150:153], v[206:209], v[112:115]
	v_mfma_f32_16x16x32_bf16 v[108:111], v[166:169], v[206:209], v[108:111]
	v_mfma_f32_16x16x32_bf16 v[96:99], v[150:153], v[214:217], v[96:99]
	v_mfma_f32_16x16x32_bf16 v[92:95], v[166:169], v[214:217], v[92:95]
	v_mfma_f32_16x16x32_bf16 v[80:83], v[150:153], v[222:225], v[80:83]
	v_mfma_f32_16x16x32_bf16 v[76:79], v[166:169], v[222:225], v[76:79]
	s_setprio 0
	s_setprio 1
	v_mfma_f32_16x16x32_bf16 v[120:123], v[170:173], v[186:189], 0
	v_mfma_f32_16x16x32_bf16 v[116:119], v[178:181], v[186:189], 0
	v_mfma_f32_16x16x32_bf16 v[104:107], v[170:173], v[202:205], 0
	v_mfma_f32_16x16x32_bf16 v[100:103], v[178:181], v[202:205], 0
	v_mfma_f32_16x16x32_bf16 v[88:91], v[170:173], v[210:213], 0
	v_mfma_f32_16x16x32_bf16 v[84:87], v[178:181], v[210:213], 0
	v_mfma_f32_16x16x32_bf16 v[72:75], v[170:173], v[218:221], 0
	v_mfma_f32_16x16x32_bf16 v[68:71], v[178:181], v[218:221], 0
	v_mfma_f32_16x16x32_bf16 v[120:123], v[174:177], v[190:193], v[120:123]
	v_mfma_f32_16x16x32_bf16 v[116:119], v[182:185], v[190:193], v[116:119]
	v_mfma_f32_16x16x32_bf16 v[104:107], v[174:177], v[206:209], v[104:107]
	v_mfma_f32_16x16x32_bf16 v[100:103], v[182:185], v[206:209], v[100:103]
	v_mfma_f32_16x16x32_bf16 v[88:91], v[174:177], v[214:217], v[88:91]
	v_mfma_f32_16x16x32_bf16 v[84:87], v[182:185], v[214:217], v[84:87]
	v_mfma_f32_16x16x32_bf16 v[72:75], v[174:177], v[222:225], v[72:75]
	v_mfma_f32_16x16x32_bf16 v[68:71], v[182:185], v[222:225], v[68:71]
	s_setprio 0
	s_barrier
	s_add_i32 s40, s40, s49
	v_lshl_add_u64 v[154:155], s[24:25], 0, v[134:135]
	s_mov_b32 m0, s40
	ds_read_b128 v[186:189], v157 offset:16384
	ds_read_b128 v[190:193], v157 offset:17408
	ds_read_b128 v[202:205], v157 offset:18432
	ds_read_b128 v[206:209], v157 offset:19456
	ds_read_b128 v[210:213], v157 offset:20480
	ds_read_b128 v[214:217], v157 offset:21504
	ds_read_b128 v[218:221], v157 offset:22528
	ds_read_b128 v[222:225], v157 offset:23552
	global_load_lds_dwordx4 v[154:155], off
	s_add_i32 m0, s40, 0x2000
	s_add_u32 s40, s24, 0x40000
	v_lshl_add_u64 v[158:159], s[24:25], 0, v[138:139]
	s_addc_u32 s41, s25, 0
	s_add_i32 s58, s58, s49
	global_load_lds_dwordx4 v[158:159], off
	v_lshl_add_u64 v[194:195], s[40:41], 0, v[134:135]
	s_mov_b32 m0, s58
	v_lshl_add_u64 v[226:227], s[28:29], 0, v[136:137]
	global_load_lds_dwordx4 v[194:195], off
	v_lshl_add_u64 v[194:195], s[40:41], 0, v[138:139]
	s_add_i32 m0, s58, 0x2000
	s_nop 0
	global_load_lds_dwordx4 v[194:195], off
	v_lshl_add_u64 v[194:195], s[28:29], 0, v[132:133]
	s_mov_b32 m0, s50
	s_nop 0
	global_load_lds_dwordx4 v[194:195], off
	s_mov_b32 m0, s51
	s_nop 0
	global_load_lds_dwordx4 v[226:227], off
	s_waitcnt vmcnt(8)
	s_waitcnt lgkmcnt(0)
	s_barrier
; #define PG8_STAGE(bufoff, gbase, voff) do { _Pragma("unroll") for (int _i = 0; _i < 2; ++_i) \
;         __builtin_amdgcn_global_load_lds((const unsigned*)((const char*)(gbase) + (voff)[_i]), (LAS unsigned*)(lds + (bufoff) + ldsw + _i * 8192), 16, 0, 0); } while (0)
; #define PG8_LDA(dst, b, h) do { _Pragma("unroll") for (int m = 0; m < 4; ++m) _Pragma("unroll") for (int k = 0; k < 2; ++k) dst[m][k] = *(const LAS bf16x8*)(lds + PG8_SA(b, h) + aoff + m * 2048 + k * 1024); } while (0)
; #define PG8_LDB(dst, b, h) do { _Pragma("unroll") for (int n = 0; n < 2; ++n) _Pragma("unroll") for (int k = 0; k < 2; ++k) dst[n][k] = *(const LAS bf16x8*)(lds + PG8_SB(b, h) + boff + n * 2048 + k * 1024); } while (0)
; #define PG8_MMA(ai, bj, At, Bt) do { __builtin_amdgcn_s_setprio(1); _Pragma("unroll") for (int m = 0; m < 4; ++m) _Pragma("unroll") for (int n = 0; n < 2; ++n) _Pragma("unroll") for (int k = 0; k < 2; ++k) \
;         acc[ai][bj][m][n] = __builtin_amdgcn_mfma_f32_16x16x32_bf16(Bt[n][k], At[m][k], acc[ai][bj][m][n], 0, 0, 0); __builtin_amdgcn_s_setprio(0); } while (0)
; #define PG8_WAIT_V(n) asm volatile("s_waitcnt vmcnt(" #n ")" ::: "memory")
; #define PG8_WAIT_L(n) asm volatile("s_waitcnt lgkmcnt(" #n ")" ::: "memory")
; #define PG8_BAR __builtin_amdgcn_s_barrier()
; #define PG8_SCHED __builtin_amdgcn_sched_barrier(0)
; template <class Epi, bool ALIGN_EPI>
; DI void gemm_phase(LAS unsigned char* lds, const Sched& S, const Epi& E, int tid) {
;     ...
;             PG8_WAIT_V(8); PG8_WAIT_L(0); PG8_BAR; PG8_MMA(0, 0, At, B0); PG8_MMA(0, 1, At, B1); PG8_BAR; PG8_SCHED;
;             PG8_LDA(At, 0, 1); PG8_STAGE(PG8_SB(0, 0), b2, voffB); PG8_STAGE(PG8_SB(0, 1), b2 + hstepB, voffB); PG8_STAGE(PG8_SA(0, 0), a2, voffA);
;             PG8_WAIT_V(8); PG8_WAIT_L(0); PG8_BAR; PG8_MMA(1, 0, At, B0); PG8_MMA(1, 1, At, B1); PG8_BAR; PG8_SCHED;
;             PG8_LDB(B0, 1, 0); PG8_LDB(B1, 1, 1); PG8_SCHED; PG8_LDA(At, 1, 0); PG8_STAGE(PG8_SA(0, 1), a2 + hstepA, voffA);
;             PG8_WAIT_V(8); PG8_WAIT_L(0); PG8_BAR; PG8_MMA(0, 0, At, B0); PG8_MMA(0, 1, At, B1); PG8_BAR; PG8_SCHED;
	s_setprio 1
	s_waitcnt lgkmcnt(0)
	v_mfma_f32_16x16x32_bf16 v[64:67], v[146:149], v[186:189], 0
	v_mfma_f32_16x16x32_bf16 v[60:63], v[162:165], v[186:189], 0
	v_mfma_f32_16x16x32_bf16 v[48:51], v[146:149], v[202:205], 0
	v_mfma_f32_16x16x32_bf16 v[44:47], v[162:165], v[202:205], 0
	v_mfma_f32_16x16x32_bf16 v[32:35], v[146:149], v[210:213], 0
	v_mfma_f32_16x16x32_bf16 v[28:31], v[162:165], v[210:213], 0
	v_mfma_f32_16x16x32_bf16 v[16:19], v[146:149], v[218:221], 0
	v_mfma_f32_16x16x32_bf16 v[12:15], v[162:165], v[218:221], 0
	v_mfma_f32_16x16x32_bf16 v[64:67], v[150:153], v[190:193], v[64:67]
	v_mfma_f32_16x16x32_bf16 v[60:63], v[166:169], v[190:193], v[60:63]
	v_mfma_f32_16x16x32_bf16 v[48:51], v[150:153], v[206:209], v[48:51]
	v_mfma_f32_16x16x32_bf16 v[44:47], v[166:169], v[206:209], v[44:47]
	v_mfma_f32_16x16x32_bf16 v[32:35], v[150:153], v[214:217], v[32:35]
	v_mfma_f32_16x16x32_bf16 v[28:31], v[166:169], v[214:217], v[28:31]
	v_mfma_f32_16x16x32_bf16 v[16:19], v[150:153], v[222:225], v[16:19]
	v_mfma_f32_16x16x32_bf16 v[12:15], v[166:169], v[222:225], v[12:15]
	s_setprio 0
	s_setprio 1
	v_mfma_f32_16x16x32_bf16 v[56:59], v[170:173], v[186:189], 0
	v_mfma_f32_16x16x32_bf16 v[52:55], v[178:181], v[186:189], 0
	v_mfma_f32_16x16x32_bf16 v[40:43], v[170:173], v[202:205], 0
	v_mfma_f32_16x16x32_bf16 v[36:39], v[178:181], v[202:205], 0
	v_mfma_f32_16x16x32_bf16 v[24:27], v[170:173], v[210:213], 0
	v_mfma_f32_16x16x32_bf16 v[20:23], v[178:181], v[210:213], 0
	v_mfma_f32_16x16x32_bf16 v[8:11], v[170:173], v[218:221], 0
	v_mfma_f32_16x16x32_bf16 v[4:7], v[178:181], v[218:221], 0
	v_mfma_f32_16x16x32_bf16 v[56:59], v[174:177], v[190:193], v[56:59]
	v_mfma_f32_16x16x32_bf16 v[52:55], v[182:185], v[190:193], v[52:55]
	v_mfma_f32_16x16x32_bf16 v[40:43], v[174:177], v[206:209], v[40:43]
	v_mfma_f32_16x16x32_bf16 v[36:39], v[182:185], v[206:209], v[36:39]
	v_mfma_f32_16x16x32_bf16 v[24:27], v[174:177], v[214:217], v[24:27]
	v_mfma_f32_16x16x32_bf16 v[20:23], v[182:185], v[214:217], v[20:23]
	v_mfma_f32_16x16x32_bf16 v[8:11], v[174:177], v[222:225], v[8:11]
	v_mfma_f32_16x16x32_bf16 v[4:7], v[182:185], v[222:225], v[4:7]
	s_setprio 0
	s_barrier
	s_add_i32 s40, 0, 0x18000
	v_add_u32_e32 v161, s40, v141
	s_add_i32 s41, 0, 0x1c000
	ds_read_b128 v[146:149], v161
	ds_read_b128 v[150:153], v161 offset:1024
	ds_read_b128 v[162:165], v161 offset:2048
	ds_read_b128 v[166:169], v161 offset:3072
	v_add_u32_e32 v161, s41, v141
	ds_read_b128 v[170:173], v161
	ds_read_b128 v[174:177], v161 offset:1024
	ds_read_b128 v[178:181], v161 offset:2048
	ds_read_b128 v[182:185], v161 offset:3072
	s_add_u32 s28, s28, 0x40000
	s_addc_u32 s29, s29, 0
	s_mov_b32 m0, s52
	v_lshl_add_u64 v[228:229], s[28:29], 0, v[132:133]
	ds_read_b128 v[186:189], v157 offset:32768
	ds_read_b128 v[190:193], v157 offset:33792
	ds_read_b128 v[202:205], v157 offset:34816
	ds_read_b128 v[206:209], v157 offset:35840
	ds_read_b128 v[210:213], v157 offset:36864
	ds_read_b128 v[214:217], v157 offset:37888
	ds_read_b128 v[218:221], v157 offset:38912
	ds_read_b128 v[222:225], v157 offset:39936
	global_load_lds_dwordx4 v[228:229], off
	v_lshl_add_u64 v[228:229], s[28:29], 0, v[136:137]
	s_mov_b32 m0, s53
	s_nop 0
	global_load_lds_dwordx4 v[228:229], off
	s_waitcnt vmcnt(8)
	s_waitcnt lgkmcnt(0)
	s_barrier
	s_setprio 1
	s_waitcnt lgkmcnt(0)
	v_mfma_f32_16x16x32_bf16 v[128:131], v[146:149], v[186:189], v[128:131]
	v_mfma_f32_16x16x32_bf16 v[124:127], v[162:165], v[186:189], v[124:127]
	v_mfma_f32_16x16x32_bf16 v[112:115], v[146:149], v[202:205], v[112:115]
	v_mfma_f32_16x16x32_bf16 v[108:111], v[162:165], v[202:205], v[108:111]
	v_mfma_f32_16x16x32_bf16 v[96:99], v[146:149], v[210:213], v[96:99]
	v_mfma_f32_16x16x32_bf16 v[92:95], v[162:165], v[210:213], v[92:95]
	v_mfma_f32_16x16x32_bf16 v[80:83], v[146:149], v[218:221], v[80:83]
	v_mfma_f32_16x16x32_bf16 v[76:79], v[162:165], v[218:221], v[76:79]
	v_mfma_f32_16x16x32_bf16 v[128:131], v[150:153], v[190:193], v[128:131]
	v_mfma_f32_16x16x32_bf16 v[124:127], v[166:169], v[190:193], v[124:127]
	v_mfma_f32_16x16x32_bf16 v[112:115], v[150:153], v[206:209], v[112:115]
	v_mfma_f32_16x16x32_bf16 v[108:111], v[166:169], v[206:209], v[108:111]
	v_mfma_f32_16x16x32_bf16 v[96:99], v[150:153], v[214:217], v[96:99]
	v_mfma_f32_16x16x32_bf16 v[92:95], v[166:169], v[214:217], v[92:95]
	v_mfma_f32_16x16x32_bf16 v[80:83], v[150:153], v[222:225], v[80:83]
	v_mfma_f32_16x16x32_bf16 v[76:79], v[166:169], v[222:225], v[76:79]
	s_setprio 0
	s_setprio 1
	v_mfma_f32_16x16x32_bf16 v[120:123], v[170:173], v[186:189], v[120:123]
	v_mfma_f32_16x16x32_bf16 v[116:119], v[178:181], v[186:189], v[116:119]
	v_mfma_f32_16x16x32_bf16 v[104:107], v[170:173], v[202:205], v[104:107]
	v_mfma_f32_16x16x32_bf16 v[100:103], v[178:181], v[202:205], v[100:103]
	v_mfma_f32_16x16x32_bf16 v[88:91], v[170:173], v[210:213], v[88:91]
	v_mfma_f32_16x16x32_bf16 v[84:87], v[178:181], v[210:213], v[84:87]
	v_mfma_f32_16x16x32_bf16 v[72:75], v[170:173], v[218:221], v[72:75]
	v_mfma_f32_16x16x32_bf16 v[68:71], v[178:181], v[218:221], v[68:71]
	v_mfma_f32_16x16x32_bf16 v[120:123], v[174:177], v[190:193], v[120:123]
	v_mfma_f32_16x16x32_bf16 v[116:119], v[182:185], v[190:193], v[116:119]
	v_mfma_f32_16x16x32_bf16 v[104:107], v[174:177], v[206:209], v[104:107]
	v_mfma_f32_16x16x32_bf16 v[100:103], v[182:185], v[206:209], v[100:103]
	v_mfma_f32_16x16x32_bf16 v[88:91], v[174:177], v[214:217], v[88:91]
	v_mfma_f32_16x16x32_bf16 v[84:87], v[182:185], v[214:217], v[84:87]
	v_mfma_f32_16x16x32_bf16 v[72:75], v[174:177], v[222:225], v[72:75]
	v_mfma_f32_16x16x32_bf16 v[68:71], v[182:185], v[222:225], v[68:71]
	s_setprio 0
	s_barrier
; #define PG8_STAGE(bufoff, gbase, voff) do { _Pragma("unroll") for (int _i = 0; _i < 2; ++_i) \
;         __builtin_amdgcn_global_load_lds((const unsigned*)((const char*)(gbase) + (voff)[_i]), (LAS unsigned*)(lds + (bufoff) + ldsw + _i * 8192), 16, 0, 0); } while (0)
; #define PG8_LDA(dst, b, h) do { _Pragma("unroll") for (int m = 0; m < 4; ++m) _Pragma("unroll") for (int k = 0; k < 2; ++k) dst[m][k] = *(const LAS bf16x8*)(lds + PG8_SA(b, h) + aoff + m * 2048 + k * 1024); } while (0)
; #define PG8_LDB(dst, b, h) do { _Pragma("unroll") for (int n = 0; n < 2; ++n) _Pragma("unroll") for (int k = 0; k < 2; ++k) dst[n][k] = *(const LAS bf16x8*)(lds + PG8_SB(b, h) + boff + n * 2048 + k * 1024); } while (0)
; #define PG8_MMA(ai, bj, At, Bt) do { __builtin_amdgcn_s_setprio(1); _Pragma("unroll") for (int m = 0; m < 4; ++m) _Pragma("unroll") for (int n = 0; n < 2; ++n) _Pragma("unroll") for (int k = 0; k < 2; ++k) \
;         acc[ai][bj][m][n] = __builtin_amdgcn_mfma_f32_16x16x32_bf16(Bt[n][k], At[m][k], acc[ai][bj][m][n], 0, 0, 0); __builtin_amdgcn_s_setprio(0); } while (0)
; #define PG8_WAIT_V(n) asm volatile("s_waitcnt vmcnt(" #n ")" ::: "memory")
; #define PG8_WAIT_L(n) asm volatile("s_waitcnt lgkmcnt(" #n ")" ::: "memory")
; #define PG8_BAR __builtin_amdgcn_s_barrier()
; #define PG8_SCHED __builtin_amdgcn_sched_barrier(0)
; template <class Epi, bool ALIGN_EPI>
; DI void gemm_phase(LAS unsigned char* lds, const Sched& S, const Epi& E, int tid) {
;     ...
;             PG8_WAIT_V(8); PG8_WAIT_L(0); PG8_BAR; PG8_MMA(1, 0, At, B0); PG8_MMA(1, 1, At, B1); PG8_BAR; PG8_SCHED;
;             PG8_LDB(B0, 1, 0); PG8_LDB(B1, 1, 1); PG8_SCHED; PG8_LDA(At, 1, 0); PG8_STAGE(PG8_SA(0, 1), a2 + hstepA, voffA);
;             PG8_WAIT_V(8); PG8_WAIT_L(0); PG8_BAR; PG8_MMA(0, 0, At, B0); PG8_MMA(0, 1, At, B1); PG8_BAR; PG8_SCHED;
;             PG8_LDA(At, 1, 1); PG8_STAGE(PG8_SB(1, 0), b3, voffB); PG8_STAGE(PG8_SB(1, 1), b3 + hstepB, voffB); PG8_STAGE(PG8_SA(1, 0), a3, voffA);
;             PG8_WAIT_V(8); PG8_WAIT_L(0); PG8_BAR; PG8_MMA(1, 0, At, B0); PG8_MMA(1, 1, At, B1); PG8_BAR; PG8_SCHED;
	s_add_i32 s28, s40, s49
	v_lshl_add_u64 v[154:155], v[154:155], 0, s[84:85]
	s_mov_b32 m0, s28
	ds_read_b128 v[186:189], v157 offset:49152
	ds_read_b128 v[190:193], v157 offset:50176
	ds_read_b128 v[202:205], v157 offset:51200
	ds_read_b128 v[206:209], v157 offset:52224
	ds_read_b128 v[210:213], v157 offset:53248
	ds_read_b128 v[214:217], v157 offset:54272
	ds_read_b128 v[218:221], v157 offset:55296
	ds_read_b128 v[222:225], v157 offset:56320
	global_load_lds_dwordx4 v[154:155], off
	s_add_i32 m0, s28, 0x2000
	s_add_u32 s24, s24, 0x40080
	v_lshl_add_u64 v[154:155], v[158:159], 0, s[84:85]
	s_addc_u32 s25, s25, 0
	s_add_i32 s28, s41, s49
	global_load_lds_dwordx4 v[154:155], off
	v_lshl_add_u64 v[154:155], s[24:25], 0, v[134:135]
	s_mov_b32 m0, s28
	s_nop 0
	global_load_lds_dwordx4 v[154:155], off
	v_lshl_add_u64 v[154:155], s[24:25], 0, v[138:139]
	s_add_i32 m0, s28, 0x2000
	s_nop 0
	global_load_lds_dwordx4 v[154:155], off
	v_lshl_add_u64 v[154:155], v[194:195], 0, s[84:85]
	s_mov_b32 m0, s54
	s_nop 0
	global_load_lds_dwordx4 v[154:155], off
	v_lshl_add_u64 v[154:155], v[226:227], 0, s[84:85]
	s_mov_b32 m0, s55
	s_nop 0
	global_load_lds_dwordx4 v[154:155], off
	s_waitcnt vmcnt(8)
	s_waitcnt lgkmcnt(0)
	s_barrier
	s_setprio 1
	s_waitcnt lgkmcnt(0)
	v_mfma_f32_16x16x32_bf16 v[64:67], v[146:149], v[186:189], v[64:67]
	v_mfma_f32_16x16x32_bf16 v[60:63], v[162:165], v[186:189], v[60:63]
	v_mfma_f32_16x16x32_bf16 v[48:51], v[146:149], v[202:205], v[48:51]
	v_mfma_f32_16x16x32_bf16 v[44:47], v[162:165], v[202:205], v[44:47]
	v_mfma_f32_16x16x32_bf16 v[32:35], v[146:149], v[210:213], v[32:35]
	v_mfma_f32_16x16x32_bf16 v[28:31], v[162:165], v[210:213], v[28:31]
	v_mfma_f32_16x16x32_bf16 v[16:19], v[146:149], v[218:221], v[16:19]
	v_mfma_f32_16x16x32_bf16 v[12:15], v[162:165], v[218:221], v[12:15]
	v_mfma_f32_16x16x32_bf16 v[64:67], v[150:153], v[190:193], v[64:67]
	v_mfma_f32_16x16x32_bf16 v[60:63], v[166:169], v[190:193], v[60:63]
	v_mfma_f32_16x16x32_bf16 v[48:51], v[150:153], v[206:209], v[48:51]
	v_mfma_f32_16x16x32_bf16 v[44:47], v[166:169], v[206:209], v[44:47]
	v_mfma_f32_16x16x32_bf16 v[32:35], v[150:153], v[214:217], v[32:35]
	v_mfma_f32_16x16x32_bf16 v[28:31], v[166:169], v[214:217], v[28:31]
	v_mfma_f32_16x16x32_bf16 v[16:19], v[150:153], v[222:225], v[16:19]
	v_mfma_f32_16x16x32_bf16 v[12:15], v[166:169], v[222:225], v[12:15]
	s_setprio 0
	s_setprio 1
	v_mfma_f32_16x16x32_bf16 v[56:59], v[170:173], v[186:189], v[56:59]
	v_mfma_f32_16x16x32_bf16 v[52:55], v[178:181], v[186:189], v[52:55]
	v_mfma_f32_16x16x32_bf16 v[40:43], v[170:173], v[202:205], v[40:43]
	v_mfma_f32_16x16x32_bf16 v[36:39], v[178:181], v[202:205], v[36:39]
	v_mfma_f32_16x16x32_bf16 v[24:27], v[170:173], v[210:213], v[24:27]
	v_mfma_f32_16x16x32_bf16 v[20:23], v[178:181], v[210:213], v[20:23]
	v_mfma_f32_16x16x32_bf16 v[8:11], v[170:173], v[218:221], v[8:11]
	v_mfma_f32_16x16x32_bf16 v[4:7], v[178:181], v[218:221], v[4:7]
	v_mfma_f32_16x16x32_bf16 v[56:59], v[174:177], v[190:193], v[56:59]
	v_mfma_f32_16x16x32_bf16 v[52:55], v[182:185], v[190:193], v[52:55]
	v_mfma_f32_16x16x32_bf16 v[40:43], v[174:177], v[206:209], v[40:43]
	v_mfma_f32_16x16x32_bf16 v[36:39], v[182:185], v[206:209], v[36:39]
	v_mfma_f32_16x16x32_bf16 v[24:27], v[174:177], v[214:217], v[24:27]
	v_mfma_f32_16x16x32_bf16 v[20:23], v[182:185], v[214:217], v[20:23]
	v_mfma_f32_16x16x32_bf16 v[8:11], v[174:177], v[222:225], v[8:11]
	v_mfma_f32_16x16x32_bf16 v[4:7], v[182:185], v[222:225], v[4:7]
	s_setprio 0
	s_add_i32 s39, s39, 2
	s_add_u32 s22, s22, 0x100
	s_addc_u32 s23, s23, 0
	s_add_u32 s37, s37, 0x100
	s_addc_u32 s38, s38, 0
	s_cmp_gt_u32 s39, 13
	s_add_u32 s24, s22, 0xfffc0080
	s_addc_u32 s25, s23, -1
	s_add_i32 s40, 0, 0x10000
	s_cmp_eq_u32 s39, 12
	s_cselect_b32 s29, s3, s25
	s_cselect_b32 s28, s2, s24
	v_add_u32_e32 v154, s40, v141
	s_cselect_b32 s25, s21, s38
	s_cselect_b32 s24, s20, s37
	s_add_i32 s58, 0, 0x14000
	s_barrier
.LBB0_653:
	ds_read_b128 v[146:149], v154
	ds_read_b128 v[150:153], v154 offset:1024
	ds_read_b128 v[162:165], v154 offset:2048
	ds_read_b128 v[166:169], v154 offset:3072
	v_add_u32_e32 v154, s58, v141
	ds_read_b128 v[170:173], v154
	ds_read_b128 v[174:177], v154 offset:1024
	ds_read_b128 v[178:181], v154 offset:2048
	ds_read_b128 v[182:185], v154 offset:3072
	v_lshl_add_u64 v[154:155], s[22:23], 0, v[142:143]
	s_add_i32 m0, s50, 0xc000
	ds_read_b128 v[186:189], v157
	ds_read_b128 v[190:193], v157 offset:1024
	ds_read_b128 v[202:205], v157 offset:2048
	ds_read_b128 v[206:209], v157 offset:3072
	ds_read_b128 v[210:213], v157 offset:4096
	ds_read_b128 v[214:217], v157 offset:5120
	ds_read_b128 v[218:221], v157 offset:6144
	ds_read_b128 v[222:225], v157 offset:7168
	global_load_lds_dwordx4 v[154:155], off
	v_lshl_add_u64 v[154:155], s[22:23], 0, v[144:145]
	s_add_i32 m0, s50, 0xe000
	s_nop 0
	global_load_lds_dwordx4 v[154:155], off
	s_waitcnt vmcnt(8)
	s_waitcnt lgkmcnt(0)
	s_barrier
; #define PG8_STAGE(bufoff, gbase, voff) do { _Pragma("unroll") for (int _i = 0; _i < 2; ++_i) \
;         __builtin_amdgcn_global_load_lds((const unsigned*)((const char*)(gbase) + (voff)[_i]), (LAS unsigned*)(lds + (bufoff) + ldsw + _i * 8192), 16, 0, 0); } while (0)
; #define PG8_LDA(dst, b, h) do { _Pragma("unroll") for (int m = 0; m < 4; ++m) _Pragma("unroll") for (int k = 0; k < 2; ++k) dst[m][k] = *(const LAS bf16x8*)(lds + PG8_SA(b, h) + aoff + m * 2048 + k * 1024); } while (0)
; #define PG8_LDB(dst, b, h) do { _Pragma("unroll") for (int n = 0; n < 2; ++n) _Pragma("unroll") for (int k = 0; k < 2; ++k) dst[n][k] = *(const LAS bf16x8*)(lds + PG8_SB(b, h) + boff + n * 2048 + k * 1024); } while (0)
; #define PG8_MMA(ai, bj, At, Bt) do { __builtin_amdgcn_s_setprio(1); _Pragma("unroll") for (int m = 0; m < 4; ++m) _Pragma("unroll") for (int n = 0; n < 2; ++n) _Pragma("unroll") for (int k = 0; k < 2; ++k) \
;         acc[ai][bj][m][n] = __builtin_amdgcn_mfma_f32_16x16x32_bf16(Bt[n][k], At[m][k], acc[ai][bj][m][n], 0, 0, 0); __builtin_amdgcn_s_setprio(0); } while (0)
; #define PG8_WAIT_V(n) asm volatile("s_waitcnt vmcnt(" #n ")" ::: "memory")
; #define PG8_WAIT_L(n) asm volatile("s_waitcnt lgkmcnt(" #n ")" ::: "memory")
; #define PG8_BAR __builtin_amdgcn_s_barrier()
; #define PG8_SCHED __builtin_amdgcn_sched_barrier(0)
; template <class Epi, bool ALIGN_EPI>
; DI void gemm_phase(LAS unsigned char* lds, const Sched& S, const Epi& E, int tid) {
;     ...
;             PG8_LDB(B0, 0, 0); PG8_LDB(B1, 0, 1); PG8_SCHED; PG8_LDA(At, 0, 0); PG8_STAGE(PG8_SA(1, 1), a1 + hstepA, voffA);
;             PG8_WAIT_V(8); PG8_WAIT_L(0); PG8_BAR; PG8_MMA(0, 0, At, B0); PG8_MMA(0, 1, At, B1); PG8_BAR; PG8_SCHED;
;             PG8_LDA(At, 0, 1); PG8_STAGE(PG8_SB(0, 0), b2, voffB); PG8_STAGE(PG8_SB(0, 1), b2 + hstepB, voffB); PG8_STAGE(PG8_SA(0, 0), a2, voffA);
;             PG8_WAIT_V(8); PG8_WAIT_L(0); PG8_BAR; PG8_MMA(1, 0, At, B0); PG8_MMA(1, 1, At, B1); PG8_BAR; PG8_SCHED;
;             PG8_LDB(B0, 1, 0); PG8_LDB(B1, 1, 1); PG8_SCHED; PG8_LDA(At, 1, 0); PG8_STAGE(PG8_SA(0, 1), a2 + hstepA, voffA);
;             PG8_WAIT_V(8); PG8_WAIT_L(0); PG8_BAR; PG8_MMA(0, 0, At, B0); PG8_MMA(0, 1, At, B1); PG8_BAR; PG8_SCHED;
	s_setprio 1
	s_waitcnt lgkmcnt(0)
	v_mfma_f32_16x16x32_bf16 v[128:131], v[146:149], v[186:189], v[128:131]
	v_mfma_f32_16x16x32_bf16 v[124:127], v[162:165], v[186:189], v[124:127]
	v_mfma_f32_16x16x32_bf16 v[112:115], v[146:149], v[202:205], v[112:115]
	v_mfma_f32_16x16x32_bf16 v[108:111], v[162:165], v[202:205], v[108:111]
	v_mfma_f32_16x16x32_bf16 v[96:99], v[146:149], v[210:213], v[96:99]
	v_mfma_f32_16x16x32_bf16 v[92:95], v[162:165], v[210:213], v[92:95]
	v_mfma_f32_16x16x32_bf16 v[80:83], v[146:149], v[218:221], v[80:83]
	v_mfma_f32_16x16x32_bf16 v[76:79], v[162:165], v[218:221], v[76:79]
	v_mfma_f32_16x16x32_bf16 v[128:131], v[150:153], v[190:193], v[128:131]
	v_mfma_f32_16x16x32_bf16 v[124:127], v[166:169], v[190:193], v[124:127]
	v_mfma_f32_16x16x32_bf16 v[112:115], v[150:153], v[206:209], v[112:115]
	v_mfma_f32_16x16x32_bf16 v[108:111], v[166:169], v[206:209], v[108:111]
	v_mfma_f32_16x16x32_bf16 v[96:99], v[150:153], v[214:217], v[96:99]
	v_mfma_f32_16x16x32_bf16 v[92:95], v[166:169], v[214:217], v[92:95]
	v_mfma_f32_16x16x32_bf16 v[80:83], v[150:153], v[222:225], v[80:83]
	v_mfma_f32_16x16x32_bf16 v[76:79], v[166:169], v[222:225], v[76:79]
	s_setprio 0
	s_setprio 1
	v_mfma_f32_16x16x32_bf16 v[120:123], v[170:173], v[186:189], v[120:123]
	v_mfma_f32_16x16x32_bf16 v[116:119], v[178:181], v[186:189], v[116:119]
	v_mfma_f32_16x16x32_bf16 v[104:107], v[170:173], v[202:205], v[104:107]
	v_mfma_f32_16x16x32_bf16 v[100:103], v[178:181], v[202:205], v[100:103]
	v_mfma_f32_16x16x32_bf16 v[88:91], v[170:173], v[210:213], v[88:91]
	v_mfma_f32_16x16x32_bf16 v[84:87], v[178:181], v[210:213], v[84:87]
	v_mfma_f32_16x16x32_bf16 v[72:75], v[170:173], v[218:221], v[72:75]
	v_mfma_f32_16x16x32_bf16 v[68:71], v[178:181], v[218:221], v[68:71]
	v_mfma_f32_16x16x32_bf16 v[120:123], v[174:177], v[190:193], v[120:123]
	v_mfma_f32_16x16x32_bf16 v[116:119], v[182:185], v[190:193], v[116:119]
	v_mfma_f32_16x16x32_bf16 v[104:107], v[174:177], v[206:209], v[104:107]
	v_mfma_f32_16x16x32_bf16 v[100:103], v[182:185], v[206:209], v[100:103]
	v_mfma_f32_16x16x32_bf16 v[88:91], v[174:177], v[214:217], v[88:91]
	v_mfma_f32_16x16x32_bf16 v[84:87], v[182:185], v[214:217], v[84:87]
	v_mfma_f32_16x16x32_bf16 v[72:75], v[174:177], v[222:225], v[72:75]
	v_mfma_f32_16x16x32_bf16 v[68:71], v[182:185], v[222:225], v[68:71]
	s_setprio 0
	s_barrier
	s_add_i32 s40, s40, s49
	v_lshl_add_u64 v[154:155], s[24:25], 0, v[134:135]
	s_mov_b32 m0, s40
	ds_read_b128 v[186:189], v157 offset:16384
	ds_read_b128 v[190:193], v157 offset:17408
	ds_read_b128 v[202:205], v157 offset:18432
	ds_read_b128 v[206:209], v157 offset:19456
	ds_read_b128 v[210:213], v157 offset:20480
	ds_read_b128 v[214:217], v157 offset:21504
	ds_read_b128 v[218:221], v157 offset:22528
	ds_read_b128 v[222:225], v157 offset:23552
	global_load_lds_dwordx4 v[154:155], off
	s_add_i32 m0, s40, 0x2000
	s_add_u32 s40, s24, 0x40000
	v_lshl_add_u64 v[158:159], s[24:25], 0, v[138:139]
	s_addc_u32 s41, s25, 0
	s_add_i32 s58, s58, s49
	global_load_lds_dwordx4 v[158:159], off
	v_lshl_add_u64 v[194:195], s[40:41], 0, v[134:135]
	s_mov_b32 m0, s58
	v_lshl_add_u64 v[226:227], s[28:29], 0, v[136:137]
	global_load_lds_dwordx4 v[194:195], off
	v_lshl_add_u64 v[194:195], s[40:41], 0, v[138:139]
	s_add_i32 m0, s58, 0x2000
	s_nop 0
	global_load_lds_dwordx4 v[194:195], off
	v_lshl_add_u64 v[194:195], s[28:29], 0, v[132:133]
	s_mov_b32 m0, s50
	s_nop 0
	global_load_lds_dwordx4 v[194:195], off
	s_mov_b32 m0, s51
	s_nop 0
	global_load_lds_dwordx4 v[226:227], off
	s_waitcnt vmcnt(8)
	s_waitcnt lgkmcnt(0)
	s_barrier
	s_setprio 1
	s_waitcnt lgkmcnt(0)
	v_mfma_f32_16x16x32_bf16 v[64:67], v[146:149], v[186:189], v[64:67]
	v_mfma_f32_16x16x32_bf16 v[60:63], v[162:165], v[186:189], v[60:63]
	v_mfma_f32_16x16x32_bf16 v[48:51], v[146:149], v[202:205], v[48:51]
	v_mfma_f32_16x16x32_bf16 v[44:47], v[162:165], v[202:205], v[44:47]
	v_mfma_f32_16x16x32_bf16 v[32:35], v[146:149], v[210:213], v[32:35]
	v_mfma_f32_16x16x32_bf16 v[28:31], v[162:165], v[210:213], v[28:31]
	v_mfma_f32_16x16x32_bf16 v[16:19], v[146:149], v[218:221], v[16:19]
	v_mfma_f32_16x16x32_bf16 v[12:15], v[162:165], v[218:221], v[12:15]
	v_mfma_f32_16x16x32_bf16 v[64:67], v[150:153], v[190:193], v[64:67]
	v_mfma_f32_16x16x32_bf16 v[60:63], v[166:169], v[190:193], v[60:63]
	v_mfma_f32_16x16x32_bf16 v[48:51], v[150:153], v[206:209], v[48:51]
	v_mfma_f32_16x16x32_bf16 v[44:47], v[166:169], v[206:209], v[44:47]
	v_mfma_f32_16x16x32_bf16 v[32:35], v[150:153], v[214:217], v[32:35]
	v_mfma_f32_16x16x32_bf16 v[28:31], v[166:169], v[214:217], v[28:31]
	v_mfma_f32_16x16x32_bf16 v[16:19], v[150:153], v[222:225], v[16:19]
	v_mfma_f32_16x16x32_bf16 v[12:15], v[166:169], v[222:225], v[12:15]
	s_setprio 0
	s_setprio 1
	v_mfma_f32_16x16x32_bf16 v[56:59], v[170:173], v[186:189], v[56:59]
	v_mfma_f32_16x16x32_bf16 v[52:55], v[178:181], v[186:189], v[52:55]
	v_mfma_f32_16x16x32_bf16 v[40:43], v[170:173], v[202:205], v[40:43]
	v_mfma_f32_16x16x32_bf16 v[36:39], v[178:181], v[202:205], v[36:39]
	v_mfma_f32_16x16x32_bf16 v[24:27], v[170:173], v[210:213], v[24:27]
	v_mfma_f32_16x16x32_bf16 v[20:23], v[178:181], v[210:213], v[20:23]
	v_mfma_f32_16x16x32_bf16 v[8:11], v[170:173], v[218:221], v[8:11]
	v_mfma_f32_16x16x32_bf16 v[4:7], v[178:181], v[218:221], v[4:7]
	v_mfma_f32_16x16x32_bf16 v[56:59], v[174:177], v[190:193], v[56:59]
	v_mfma_f32_16x16x32_bf16 v[52:55], v[182:185], v[190:193], v[52:55]
	v_mfma_f32_16x16x32_bf16 v[40:43], v[174:177], v[206:209], v[40:43]
	v_mfma_f32_16x16x32_bf16 v[36:39], v[182:185], v[206:209], v[36:39]
	v_mfma_f32_16x16x32_bf16 v[24:27], v[174:177], v[214:217], v[24:27]
	v_mfma_f32_16x16x32_bf16 v[20:23], v[182:185], v[214:217], v[20:23]
	v_mfma_f32_16x16x32_bf16 v[8:11], v[174:177], v[222:225], v[8:11]
	v_mfma_f32_16x16x32_bf16 v[4:7], v[182:185], v[222:225], v[4:7]
	s_setprio 0
	s_barrier
; #define PG8_STAGE(bufoff, gbase, voff) do { _Pragma("unroll") for (int _i = 0; _i < 2; ++_i) \
;         __builtin_amdgcn_global_load_lds((const unsigned*)((const char*)(gbase) + (voff)[_i]), (LAS unsigned*)(lds + (bufoff) + ldsw + _i * 8192), 16, 0, 0); } while (0)
; #define PG8_LDA(dst, b, h) do { _Pragma("unroll") for (int m = 0; m < 4; ++m) _Pragma("unroll") for (int k = 0; k < 2; ++k) dst[m][k] = *(const LAS bf16x8*)(lds + PG8_SA(b, h) + aoff + m * 2048 + k * 1024); } while (0)
; #define PG8_LDB(dst, b, h) do { _Pragma("unroll") for (int n = 0; n < 2; ++n) _Pragma("unroll") for (int k = 0; k < 2; ++k) dst[n][k] = *(const LAS bf16x8*)(lds + PG8_SB(b, h) + boff + n * 2048 + k * 1024); } while (0)
; #define PG8_MMA(ai, bj, At, Bt) do { __builtin_amdgcn_s_setprio(1); _Pragma("unroll") for (int m = 0; m < 4; ++m) _Pragma("unroll") for (int n = 0; n < 2; ++n) _Pragma("unroll") for (int k = 0; k < 2; ++k) \
;         acc[ai][bj][m][n] = __builtin_amdgcn_mfma_f32_16x16x32_bf16(Bt[n][k], At[m][k], acc[ai][bj][m][n], 0, 0, 0); __builtin_amdgcn_s_setprio(0); } while (0)
; #define PG8_WAIT_V(n) asm volatile("s_waitcnt vmcnt(" #n ")" ::: "memory")
; #define PG8_WAIT_L(n) asm volatile("s_waitcnt lgkmcnt(" #n ")" ::: "memory")
; #define PG8_BAR __builtin_amdgcn_s_barrier()
; #define PG8_SCHED __builtin_amdgcn_sched_barrier(0)
; template <class Epi, bool ALIGN_EPI>
; DI void gemm_phase(LAS unsigned char* lds, const Sched& S, const Epi& E, int tid) {
;     ...
;             PG8_LDB(B0, 1, 0); PG8_LDB(B1, 1, 1); PG8_SCHED; PG8_LDA(At, 1, 0); PG8_STAGE(PG8_SA(0, 1), a2 + hstepA, voffA);
;             PG8_WAIT_V(8); PG8_WAIT_L(0); PG8_BAR; PG8_MMA(0, 0, At, B0); PG8_MMA(0, 1, At, B1); PG8_BAR; PG8_SCHED;
;             PG8_LDA(At, 1, 1); PG8_STAGE(PG8_SB(1, 0), b3, voffB); PG8_STAGE(PG8_SB(1, 1), b3 + hstepB, voffB); PG8_STAGE(PG8_SA(1, 0), a3, voffA);
;             PG8_WAIT_V(8); PG8_WAIT_L(0); PG8_BAR; PG8_MMA(1, 0, At, B0); PG8_MMA(1, 1, At, B1); PG8_BAR; PG8_SCHED;
	s_add_i32 s40, 0, 0x18000
	v_add_u32_e32 v161, s40, v141
	s_add_i32 s41, 0, 0x1c000
	ds_read_b128 v[146:149], v161
	ds_read_b128 v[150:153], v161 offset:1024
	ds_read_b128 v[162:165], v161 offset:2048
	ds_read_b128 v[166:169], v161 offset:3072
	v_add_u32_e32 v161, s41, v141
	ds_read_b128 v[170:173], v161
	ds_read_b128 v[174:177], v161 offset:1024
	ds_read_b128 v[178:181], v161 offset:2048
	ds_read_b128 v[182:185], v161 offset:3072
	s_add_u32 s28, s28, 0x40000
	s_addc_u32 s29, s29, 0
	s_mov_b32 m0, s52
	v_lshl_add_u64 v[228:229], s[28:29], 0, v[132:133]
	ds_read_b128 v[186:189], v157 offset:32768
	ds_read_b128 v[190:193], v157 offset:33792
	ds_read_b128 v[202:205], v157 offset:34816
	ds_read_b128 v[206:209], v157 offset:35840
	ds_read_b128 v[210:213], v157 offset:36864
	ds_read_b128 v[214:217], v157 offset:37888
	ds_read_b128 v[218:221], v157 offset:38912
	ds_read_b128 v[222:225], v157 offset:39936
	global_load_lds_dwordx4 v[228:229], off
	v_lshl_add_u64 v[228:229], s[28:29], 0, v[136:137]
	s_mov_b32 m0, s53
	s_nop 0
	global_load_lds_dwordx4 v[228:229], off
	s_waitcnt vmcnt(8)
	s_waitcnt lgkmcnt(0)
	s_barrier
	s_setprio 1
	s_waitcnt lgkmcnt(0)
	v_mfma_f32_16x16x32_bf16 v[128:131], v[146:149], v[186:189], v[128:131]
	v_mfma_f32_16x16x32_bf16 v[124:127], v[162:165], v[186:189], v[124:127]
	v_mfma_f32_16x16x32_bf16 v[112:115], v[146:149], v[202:205], v[112:115]
	v_mfma_f32_16x16x32_bf16 v[108:111], v[162:165], v[202:205], v[108:111]
	v_mfma_f32_16x16x32_bf16 v[96:99], v[146:149], v[210:213], v[96:99]
	v_mfma_f32_16x16x32_bf16 v[92:95], v[162:165], v[210:213], v[92:95]
	v_mfma_f32_16x16x32_bf16 v[80:83], v[146:149], v[218:221], v[80:83]
	v_mfma_f32_16x16x32_bf16 v[76:79], v[162:165], v[218:221], v[76:79]
	v_mfma_f32_16x16x32_bf16 v[128:131], v[150:153], v[190:193], v[128:131]
	v_mfma_f32_16x16x32_bf16 v[124:127], v[166:169], v[190:193], v[124:127]
	v_mfma_f32_16x16x32_bf16 v[112:115], v[150:153], v[206:209], v[112:115]
	v_mfma_f32_16x16x32_bf16 v[108:111], v[166:169], v[206:209], v[108:111]
	v_mfma_f32_16x16x32_bf16 v[96:99], v[150:153], v[214:217], v[96:99]
	v_mfma_f32_16x16x32_bf16 v[92:95], v[166:169], v[214:217], v[92:95]
	v_mfma_f32_16x16x32_bf16 v[80:83], v[150:153], v[222:225], v[80:83]
	v_mfma_f32_16x16x32_bf16 v[76:79], v[166:169], v[222:225], v[76:79]
	s_setprio 0
	s_setprio 1
	v_mfma_f32_16x16x32_bf16 v[120:123], v[170:173], v[186:189], v[120:123]
	v_mfma_f32_16x16x32_bf16 v[116:119], v[178:181], v[186:189], v[116:119]
	v_mfma_f32_16x16x32_bf16 v[104:107], v[170:173], v[202:205], v[104:107]
	v_mfma_f32_16x16x32_bf16 v[100:103], v[178:181], v[202:205], v[100:103]
	v_mfma_f32_16x16x32_bf16 v[88:91], v[170:173], v[210:213], v[88:91]
	v_mfma_f32_16x16x32_bf16 v[84:87], v[178:181], v[210:213], v[84:87]
	v_mfma_f32_16x16x32_bf16 v[72:75], v[170:173], v[218:221], v[72:75]
	v_mfma_f32_16x16x32_bf16 v[68:71], v[178:181], v[218:221], v[68:71]
	v_mfma_f32_16x16x32_bf16 v[120:123], v[174:177], v[190:193], v[120:123]
	v_mfma_f32_16x16x32_bf16 v[116:119], v[182:185], v[190:193], v[116:119]
	v_mfma_f32_16x16x32_bf16 v[104:107], v[174:177], v[206:209], v[104:107]
	v_mfma_f32_16x16x32_bf16 v[100:103], v[182:185], v[206:209], v[100:103]
	v_mfma_f32_16x16x32_bf16 v[88:91], v[174:177], v[214:217], v[88:91]
	v_mfma_f32_16x16x32_bf16 v[84:87], v[182:185], v[214:217], v[84:87]
	v_mfma_f32_16x16x32_bf16 v[72:75], v[174:177], v[222:225], v[72:75]
	v_mfma_f32_16x16x32_bf16 v[68:71], v[182:185], v[222:225], v[68:71]
	s_setprio 0
	s_barrier
; #define PG8_STAGE(bufoff, gbase, voff) do { _Pragma("unroll") for (int _i = 0; _i < 2; ++_i) \
;         __builtin_amdgcn_global_load_lds((const unsigned*)((const char*)(gbase) + (voff)[_i]), (LAS unsigned*)(lds + (bufoff) + ldsw + _i * 8192), 16, 0, 0); } while (0)
; #define PG8_LDA(dst, b, h) do { _Pragma("unroll") for (int m = 0; m < 4; ++m) _Pragma("unroll") for (int k = 0; k < 2; ++k) dst[m][k] = *(const LAS bf16x8*)(lds + PG8_SA(b, h) + aoff + m * 2048 + k * 1024); } while (0)
; #define PG8_MMA(ai, bj, At, Bt) do { __builtin_amdgcn_s_setprio(1); _Pragma("unroll") for (int m = 0; m < 4; ++m) _Pragma("unroll") for (int n = 0; n < 2; ++n) _Pragma("unroll") for (int k = 0; k < 2; ++k) \
;         acc[ai][bj][m][n] = __builtin_amdgcn_mfma_f32_16x16x32_bf16(Bt[n][k], At[m][k], acc[ai][bj][m][n], 0, 0, 0); __builtin_amdgcn_s_setprio(0); } while (0)
; #define PG8_WAIT_V(n) asm volatile("s_waitcnt vmcnt(" #n ")" ::: "memory")
; #define PG8_WAIT_L(n) asm volatile("s_waitcnt lgkmcnt(" #n ")" ::: "memory")
; #define PG8_BAR __builtin_amdgcn_s_barrier()
; #define PG8_SCHED __builtin_amdgcn_sched_barrier(0)
; template <class Epi, bool ALIGN_EPI>
; DI void gemm_phase(LAS unsigned char* lds, const Sched& S, const Epi& E, int tid) {
;     ...
;             PG8_WAIT_V(8); PG8_WAIT_L(0); PG8_BAR; PG8_MMA(0, 0, At, B0); PG8_MMA(0, 1, At, B1); PG8_BAR; PG8_SCHED;
;             PG8_LDA(At, 1, 1); PG8_STAGE(PG8_SB(1, 0), b3, voffB); PG8_STAGE(PG8_SB(1, 1), b3 + hstepB, voffB); PG8_STAGE(PG8_SA(1, 0), a3, voffA);
;             PG8_WAIT_V(8); PG8_WAIT_L(0); PG8_BAR; PG8_MMA(1, 0, At, B0); PG8_MMA(1, 1, At, B1); PG8_BAR; PG8_SCHED;
;         }
;         if constexpr (ALIGN_EPI) { if (wr == 0) PG8_BAR; }
	s_add_i32 s28, s40, s49
	v_lshl_add_u64 v[154:155], v[154:155], 0, s[84:85]
	s_mov_b32 m0, s28
	ds_read_b128 v[186:189], v157 offset:49152
	ds_read_b128 v[190:193], v157 offset:50176
	ds_read_b128 v[202:205], v157 offset:51200
	ds_read_b128 v[206:209], v157 offset:52224
	ds_read_b128 v[210:213], v157 offset:53248
	ds_read_b128 v[214:217], v157 offset:54272
	ds_read_b128 v[218:221], v157 offset:55296
	ds_read_b128 v[222:225], v157 offset:56320
	global_load_lds_dwordx4 v[154:155], off
	s_add_i32 m0, s28, 0x2000
	s_add_u32 s24, s24, 0x40080
	v_lshl_add_u64 v[154:155], v[158:159], 0, s[84:85]
	s_addc_u32 s25, s25, 0
	s_add_i32 s28, s41, s49
	global_load_lds_dwordx4 v[154:155], off
	v_lshl_add_u64 v[154:155], s[24:25], 0, v[134:135]
	s_mov_b32 m0, s28
	s_nop 0
	global_load_lds_dwordx4 v[154:155], off
	v_lshl_add_u64 v[154:155], s[24:25], 0, v[138:139]
	s_add_i32 m0, s28, 0x2000
	s_nop 0
	global_load_lds_dwordx4 v[154:155], off
	v_lshl_add_u64 v[154:155], v[194:195], 0, s[84:85]
	s_mov_b32 m0, s54
	s_nop 0
	global_load_lds_dwordx4 v[154:155], off
	v_lshl_add_u64 v[154:155], v[226:227], 0, s[84:85]
	s_mov_b32 m0, s55
	s_nop 0
	global_load_lds_dwordx4 v[154:155], off
	s_waitcnt vmcnt(8)
	s_waitcnt lgkmcnt(0)
	s_barrier
	s_setprio 1
	s_waitcnt lgkmcnt(0)
	v_mfma_f32_16x16x32_bf16 v[64:67], v[146:149], v[186:189], v[64:67]
	v_mfma_f32_16x16x32_bf16 v[60:63], v[162:165], v[186:189], v[60:63]
	v_mfma_f32_16x16x32_bf16 v[48:51], v[146:149], v[202:205], v[48:51]
	v_mfma_f32_16x16x32_bf16 v[44:47], v[162:165], v[202:205], v[44:47]
	v_mfma_f32_16x16x32_bf16 v[32:35], v[146:149], v[210:213], v[32:35]
	v_mfma_f32_16x16x32_bf16 v[28:31], v[162:165], v[210:213], v[28:31]
	v_mfma_f32_16x16x32_bf16 v[16:19], v[146:149], v[218:221], v[16:19]
	v_mfma_f32_16x16x32_bf16 v[12:15], v[162:165], v[218:221], v[12:15]
	v_mfma_f32_16x16x32_bf16 v[64:67], v[150:153], v[190:193], v[64:67]
	v_mfma_f32_16x16x32_bf16 v[60:63], v[166:169], v[190:193], v[60:63]
	v_mfma_f32_16x16x32_bf16 v[48:51], v[150:153], v[206:209], v[48:51]
	v_mfma_f32_16x16x32_bf16 v[44:47], v[166:169], v[206:209], v[44:47]
	v_mfma_f32_16x16x32_bf16 v[32:35], v[150:153], v[214:217], v[32:35]
	v_mfma_f32_16x16x32_bf16 v[28:31], v[166:169], v[214:217], v[28:31]
	v_mfma_f32_16x16x32_bf16 v[16:19], v[150:153], v[222:225], v[16:19]
	v_mfma_f32_16x16x32_bf16 v[12:15], v[166:169], v[222:225], v[12:15]
	s_setprio 0
	s_setprio 1
	v_mfma_f32_16x16x32_bf16 v[56:59], v[170:173], v[186:189], v[56:59]
	v_mfma_f32_16x16x32_bf16 v[52:55], v[178:181], v[186:189], v[52:55]
	v_mfma_f32_16x16x32_bf16 v[40:43], v[170:173], v[202:205], v[40:43]
	v_mfma_f32_16x16x32_bf16 v[36:39], v[178:181], v[202:205], v[36:39]
	v_mfma_f32_16x16x32_bf16 v[24:27], v[170:173], v[210:213], v[24:27]
	v_mfma_f32_16x16x32_bf16 v[20:23], v[178:181], v[210:213], v[20:23]
	v_mfma_f32_16x16x32_bf16 v[8:11], v[170:173], v[218:221], v[8:11]
	v_mfma_f32_16x16x32_bf16 v[4:7], v[178:181], v[218:221], v[4:7]
	v_mfma_f32_16x16x32_bf16 v[56:59], v[174:177], v[190:193], v[56:59]
	v_mfma_f32_16x16x32_bf16 v[52:55], v[182:185], v[190:193], v[52:55]
	v_mfma_f32_16x16x32_bf16 v[40:43], v[174:177], v[206:209], v[40:43]
	v_mfma_f32_16x16x32_bf16 v[36:39], v[182:185], v[206:209], v[36:39]
	v_mfma_f32_16x16x32_bf16 v[24:27], v[174:177], v[214:217], v[24:27]
	v_mfma_f32_16x16x32_bf16 v[20:23], v[182:185], v[214:217], v[20:23]
	v_mfma_f32_16x16x32_bf16 v[8:11], v[174:177], v[222:225], v[8:11]
	v_mfma_f32_16x16x32_bf16 v[4:7], v[182:185], v[222:225], v[4:7]
	s_setprio 0
	s_add_i32 s39, s39, 2
	s_add_u32 s22, s22, 0x100
	s_addc_u32 s23, s23, 0
	s_add_u32 s37, s37, 0x100
	s_addc_u32 s38, s38, 0
	s_cmp_gt_u32 s39, 13
	s_cbranch_scc1 .Lkx_6
	s_add_u32 s24, s22, 0xfffc0080
	s_addc_u32 s25, s23, -1
	s_add_i32 s40, 0, 0x10000
	s_cmp_eq_u32 s39, 12
	s_cselect_b32 s29, s3, s25
	s_cselect_b32 s28, s2, s24
	v_add_u32_e32 v154, s40, v141
	s_cselect_b32 s25, s21, s38
	s_cselect_b32 s24, s20, s37
	s_add_i32 s58, 0, 0x14000
	s_barrier
	s_branch .LBB0_653
.Lkx_6:
	s_barrier
	s_and_b64 vcc, exec, s[18:19]
	s_cbranch_vccz .LBB0_656
	s_barrier

; #define PG8_STAGE(bufoff, gbase, voff) do { _Pragma("unroll") for (int _i = 0; _i < 2; ++_i) \
;         __builtin_amdgcn_global_load_lds((const unsigned*)((const char*)(gbase) + (voff)[_i]), (LAS unsigned*)(lds + (bufoff) + ldsw + _i * 8192), 16, 0, 0); } while (0)
; #define PG8_LDA(dst, b, h) do { _Pragma("unroll") for (int m = 0; m < 4; ++m) _Pragma("unroll") for (int k = 0; k < 2; ++k) dst[m][k] = *(const LAS bf16x8*)(lds + PG8_SA(b, h) + aoff + m * 2048 + k * 1024); } while (0)
; #define PG8_LDB(dst, b, h) do { _Pragma("unroll") for (int n = 0; n < 2; ++n) _Pragma("unroll") for (int k = 0; k < 2; ++k) dst[n][k] = *(const LAS bf16x8*)(lds + PG8_SB(b, h) + boff + n * 2048 + k * 1024); } while (0)
; #define PG8_MMA(ai, bj, At, Bt) do { __builtin_amdgcn_s_setprio(1); _Pragma("unroll") for (int m = 0; m < 4; ++m) _Pragma("unroll") for (int n = 0; n < 2; ++n) _Pragma("unroll") for (int k = 0; k < 2; ++k) \
;         acc[ai][bj][m][n] = __builtin_amdgcn_mfma_f32_16x16x32_bf16(Bt[n][k], At[m][k], acc[ai][bj][m][n], 0, 0, 0); __builtin_amdgcn_s_setprio(0); } while (0)
; #define PG8_WAIT_V(n) asm volatile("s_waitcnt vmcnt(" #n ")" ::: "memory")
; #define PG8_BAR __builtin_amdgcn_s_barrier()
; template <class Epi, bool ALIGN_EPI>
; DI void gemm_phase(LAS unsigned char* lds, const Sched& S, const Epi& E, int tid) {
;     ...
;         const bool has_next = S.next(ui + 1, nxt);
;         const char* nA = has_next ? nxt.a : cA; const char* nB = has_next ? nxt.b : cB;
;         const int nt = cur.nt;
;         for (int t = 0; t < nt; t += 2) {
;             const bool last = (t == nt - 2);
;             const char* a1 = cA + (size_t)(t + 1) * kstep;
;             const char* a2 = last ? nA : cA + (size_t)(t + 2) * kstep; const char* b2 = last ? nB : cB + (size_t)(t + 2) * kstep;
;             const char* a3 = a2 + kstep; const char* b3 = b2 + kstep;
;             PG8_LDB(B0, 0, 0); PG8_LDB(B1, 0, 1); PG8_SCHED; PG8_LDA(At, 0, 0); PG8_STAGE(PG8_SA(1, 1), a1 + hstepA, voffA);
;             PG8_WAIT_V(8); PG8_WAIT_L(0); PG8_BAR; PG8_MMA(0, 0, At, B0); PG8_MMA(0, 1, At, B1); PG8_BAR; PG8_SCHED;
;             PG8_LDA(At, 0, 1); PG8_STAGE(PG8_SB(0, 0), b2, voffB); PG8_STAGE(PG8_SB(0, 1), b2 + hstepB, voffB); PG8_STAGE(PG8_SA(0, 0), a2, voffA);
;             PG8_WAIT_V(8); PG8_WAIT_L(0); PG8_BAR; PG8_MMA(1, 0, At, B0); PG8_MMA(1, 1, At, B1); PG8_BAR; PG8_SCHED;
.LBB0_1048:
	s_and_b64 s[22:23], s[44:45], exec
	s_cselect_b32 s1, s35, s3
	s_cselect_b32 s37, s34, s2
	s_cselect_b32 s38, s43, s21
	s_cselect_b32 s39, s42, s20
	s_add_u32 s2, s2, 0x40080
	s_addc_u32 s3, s3, 0
	s_add_u32 s40, s20, 0x100
	s_addc_u32 s41, s21, 0
	s_mov_b32 s46, -2
	s_add_u32 s20, s2, 0xfffc0080
	s_addc_u32 s21, s3, -1
	s_add_i32 s47, 0, 0x10000
	s_cmp_eq_u32 s46, 12
	s_cselect_b32 s23, s1, s21
	s_cselect_b32 s22, s37, s20
	v_add_u32_e32 v158, s47, v141
	s_cselect_b32 s21, s38, s41
	s_cselect_b32 s20, s39, s40
	s_add_i32 s68, 0, 0x14000
	ds_read_b128 v[146:149], v158
	ds_read_b128 v[150:153], v158 offset:1024
	ds_read_b128 v[154:157], v158 offset:2048
	ds_read_b128 v[162:165], v158 offset:3072
	v_add_u32_e32 v158, s68, v141
	ds_read_b128 v[166:169], v158
	ds_read_b128 v[174:177], v158 offset:1024
	ds_read_b128 v[178:181], v158 offset:2048
	ds_read_b128 v[182:185], v158 offset:3072
	v_lshl_add_u64 v[158:159], s[2:3], 0, v[142:143]
	s_add_i32 m0, s55, 0xc000
	ds_read_b128 v[186:189], v172
	ds_read_b128 v[190:193], v172 offset:1024
	ds_read_b128 v[202:205], v172 offset:2048
	ds_read_b128 v[206:209], v172 offset:3072
	ds_read_b128 v[210:213], v172 offset:4096
	ds_read_b128 v[214:217], v172 offset:5120
	ds_read_b128 v[218:221], v172 offset:6144
	ds_read_b128 v[222:225], v172 offset:7168
	global_load_lds_dwordx4 v[158:159], off
	v_lshl_add_u64 v[158:159], s[2:3], 0, v[144:145]
	s_add_i32 m0, s55, 0xe000
	s_nop 0
	global_load_lds_dwordx4 v[158:159], off
	s_waitcnt vmcnt(8)
	s_waitcnt lgkmcnt(0)
	s_barrier
	s_setprio 1
	s_waitcnt lgkmcnt(0)
	v_mfma_f32_16x16x32_bf16 v[128:131], v[146:149], v[186:189], 0
	v_mfma_f32_16x16x32_bf16 v[124:127], v[154:157], v[186:189], 0
	v_mfma_f32_16x16x32_bf16 v[112:115], v[146:149], v[202:205], 0
	v_mfma_f32_16x16x32_bf16 v[108:111], v[154:157], v[202:205], 0
	v_mfma_f32_16x16x32_bf16 v[96:99], v[146:149], v[210:213], 0
	v_mfma_f32_16x16x32_bf16 v[92:95], v[154:157], v[210:213], 0
	v_mfma_f32_16x16x32_bf16 v[80:83], v[146:149], v[218:221], 0
	v_mfma_f32_16x16x32_bf16 v[76:79], v[154:157], v[218:221], 0
	v_mfma_f32_16x16x32_bf16 v[128:131], v[150:153], v[190:193], v[128:131]
	v_mfma_f32_16x16x32_bf16 v[124:127], v[162:165], v[190:193], v[124:127]
	v_mfma_f32_16x16x32_bf16 v[112:115], v[150:153], v[206:209], v[112:115]
	v_mfma_f32_16x16x32_bf16 v[108:111], v[162:165], v[206:209], v[108:111]
	v_mfma_f32_16x16x32_bf16 v[96:99], v[150:153], v[214:217], v[96:99]
	v_mfma_f32_16x16x32_bf16 v[92:95], v[162:165], v[214:217], v[92:95]
	v_mfma_f32_16x16x32_bf16 v[80:83], v[150:153], v[222:225], v[80:83]
	v_mfma_f32_16x16x32_bf16 v[76:79], v[162:165], v[222:225], v[76:79]
	s_setprio 0
	s_setprio 1
	v_mfma_f32_16x16x32_bf16 v[120:123], v[166:169], v[186:189], 0
	v_mfma_f32_16x16x32_bf16 v[116:119], v[178:181], v[186:189], 0
	v_mfma_f32_16x16x32_bf16 v[104:107], v[166:169], v[202:205], 0
	v_mfma_f32_16x16x32_bf16 v[100:103], v[178:181], v[202:205], 0
	v_mfma_f32_16x16x32_bf16 v[88:91], v[166:169], v[210:213], 0
	v_mfma_f32_16x16x32_bf16 v[84:87], v[178:181], v[210:213], 0
	v_mfma_f32_16x16x32_bf16 v[72:75], v[166:169], v[218:221], 0
	v_mfma_f32_16x16x32_bf16 v[68:71], v[178:181], v[218:221], 0
	v_mfma_f32_16x16x32_bf16 v[120:123], v[174:177], v[190:193], v[120:123]
	v_mfma_f32_16x16x32_bf16 v[116:119], v[182:185], v[190:193], v[116:119]
	v_mfma_f32_16x16x32_bf16 v[104:107], v[174:177], v[206:209], v[104:107]
	v_mfma_f32_16x16x32_bf16 v[100:103], v[182:185], v[206:209], v[100:103]
	v_mfma_f32_16x16x32_bf16 v[88:91], v[174:177], v[214:217], v[88:91]
	v_mfma_f32_16x16x32_bf16 v[84:87], v[182:185], v[214:217], v[84:87]
	v_mfma_f32_16x16x32_bf16 v[72:75], v[174:177], v[222:225], v[72:75]
	v_mfma_f32_16x16x32_bf16 v[68:71], v[182:185], v[222:225], v[68:71]
	s_setprio 0
	s_barrier
	s_add_i32 s47, s47, s54
	v_lshl_add_u64 v[158:159], s[20:21], 0, v[134:135]
	s_mov_b32 m0, s47
	ds_read_b128 v[186:189], v172 offset:16384
	ds_read_b128 v[190:193], v172 offset:17408
	ds_read_b128 v[202:205], v172 offset:18432
	ds_read_b128 v[206:209], v172 offset:19456
	ds_read_b128 v[210:213], v172 offset:20480
	ds_read_b128 v[214:217], v172 offset:21504
	ds_read_b128 v[218:221], v172 offset:22528
	ds_read_b128 v[222:225], v172 offset:23552
	global_load_lds_dwordx4 v[158:159], off
	s_add_i32 m0, s47, 0x2000
	s_add_u32 s48, s20, 0x40000
	v_lshl_add_u64 v[170:171], s[20:21], 0, v[138:139]
	s_addc_u32 s49, s21, 0
	s_add_i32 s47, s68, s54
	global_load_lds_dwordx4 v[170:171], off
	v_lshl_add_u64 v[194:195], s[48:49], 0, v[134:135]
	s_mov_b32 m0, s47
	v_lshl_add_u64 v[226:227], s[22:23], 0, v[136:137]
	global_load_lds_dwordx4 v[194:195], off
	v_lshl_add_u64 v[194:195], s[48:49], 0, v[138:139]
	s_add_i32 m0, s47, 0x2000
	s_nop 0
	global_load_lds_dwordx4 v[194:195], off
	v_lshl_add_u64 v[194:195], s[22:23], 0, v[132:133]
	s_mov_b32 m0, s55
	s_nop 0
	global_load_lds_dwordx4 v[194:195], off
	s_mov_b32 m0, s56
	s_nop 0
	global_load_lds_dwordx4 v[226:227], off
	s_waitcnt vmcnt(8)
	s_waitcnt lgkmcnt(0)
	s_barrier
; #define PG8_STAGE(bufoff, gbase, voff) do { _Pragma("unroll") for (int _i = 0; _i < 2; ++_i) \
;         __builtin_amdgcn_global_load_lds((const unsigned*)((const char*)(gbase) + (voff)[_i]), (LAS unsigned*)(lds + (bufoff) + ldsw + _i * 8192), 16, 0, 0); } while (0)
; #define PG8_LDA(dst, b, h) do { _Pragma("unroll") for (int m = 0; m < 4; ++m) _Pragma("unroll") for (int k = 0; k < 2; ++k) dst[m][k] = *(const LAS bf16x8*)(lds + PG8_SA(b, h) + aoff + m * 2048 + k * 1024); } while (0)
; #define PG8_LDB(dst, b, h) do { _Pragma("unroll") for (int n = 0; n < 2; ++n) _Pragma("unroll") for (int k = 0; k < 2; ++k) dst[n][k] = *(const LAS bf16x8*)(lds + PG8_SB(b, h) + boff + n * 2048 + k * 1024); } while (0)
; #define PG8_MMA(ai, bj, At, Bt) do { __builtin_amdgcn_s_setprio(1); _Pragma("unroll") for (int m = 0; m < 4; ++m) _Pragma("unroll") for (int n = 0; n < 2; ++n) _Pragma("unroll") for (int k = 0; k < 2; ++k) \
;         acc[ai][bj][m][n] = __builtin_amdgcn_mfma_f32_16x16x32_bf16(Bt[n][k], At[m][k], acc[ai][bj][m][n], 0, 0, 0); __builtin_amdgcn_s_setprio(0); } while (0)
; #define PG8_WAIT_V(n) asm volatile("s_waitcnt vmcnt(" #n ")" ::: "memory")
; #define PG8_WAIT_L(n) asm volatile("s_waitcnt lgkmcnt(" #n ")" ::: "memory")
; #define PG8_BAR __builtin_amdgcn_s_barrier()
; #define PG8_SCHED __builtin_amdgcn_sched_barrier(0)
; template <class Epi, bool ALIGN_EPI>
; DI void gemm_phase(LAS unsigned char* lds, const Sched& S, const Epi& E, int tid) {
;     ...
;             PG8_WAIT_V(8); PG8_WAIT_L(0); PG8_BAR; PG8_MMA(0, 0, At, B0); PG8_MMA(0, 1, At, B1); PG8_BAR; PG8_SCHED;
;             PG8_LDA(At, 0, 1); PG8_STAGE(PG8_SB(0, 0), b2, voffB); PG8_STAGE(PG8_SB(0, 1), b2 + hstepB, voffB); PG8_STAGE(PG8_SA(0, 0), a2, voffA);
;             PG8_WAIT_V(8); PG8_WAIT_L(0); PG8_BAR; PG8_MMA(1, 0, At, B0); PG8_MMA(1, 1, At, B1); PG8_BAR; PG8_SCHED;
;             PG8_LDB(B0, 1, 0); PG8_LDB(B1, 1, 1); PG8_SCHED; PG8_LDA(At, 1, 0); PG8_STAGE(PG8_SA(0, 1), a2 + hstepA, voffA);
;             PG8_WAIT_V(8); PG8_WAIT_L(0); PG8_BAR; PG8_MMA(0, 0, At, B0); PG8_MMA(0, 1, At, B1); PG8_BAR; PG8_SCHED;
	s_setprio 1
	s_waitcnt lgkmcnt(0)
	v_mfma_f32_16x16x32_bf16 v[64:67], v[146:149], v[186:189], 0
	v_mfma_f32_16x16x32_bf16 v[60:63], v[154:157], v[186:189], 0
	v_mfma_f32_16x16x32_bf16 v[48:51], v[146:149], v[202:205], 0
	v_mfma_f32_16x16x32_bf16 v[44:47], v[154:157], v[202:205], 0
	v_mfma_f32_16x16x32_bf16 v[32:35], v[146:149], v[210:213], 0
	v_mfma_f32_16x16x32_bf16 v[28:31], v[154:157], v[210:213], 0
	v_mfma_f32_16x16x32_bf16 v[16:19], v[146:149], v[218:221], 0
	v_mfma_f32_16x16x32_bf16 v[12:15], v[154:157], v[218:221], 0
	v_mfma_f32_16x16x32_bf16 v[64:67], v[150:153], v[190:193], v[64:67]
	v_mfma_f32_16x16x32_bf16 v[60:63], v[162:165], v[190:193], v[60:63]
	v_mfma_f32_16x16x32_bf16 v[48:51], v[150:153], v[206:209], v[48:51]
	v_mfma_f32_16x16x32_bf16 v[44:47], v[162:165], v[206:209], v[44:47]
	v_mfma_f32_16x16x32_bf16 v[32:35], v[150:153], v[214:217], v[32:35]
	v_mfma_f32_16x16x32_bf16 v[28:31], v[162:165], v[214:217], v[28:31]
	v_mfma_f32_16x16x32_bf16 v[16:19], v[150:153], v[222:225], v[16:19]
	v_mfma_f32_16x16x32_bf16 v[12:15], v[162:165], v[222:225], v[12:15]
	s_setprio 0
	s_setprio 1
	v_mfma_f32_16x16x32_bf16 v[56:59], v[166:169], v[186:189], 0
	v_mfma_f32_16x16x32_bf16 v[52:55], v[178:181], v[186:189], 0
	v_mfma_f32_16x16x32_bf16 v[40:43], v[166:169], v[202:205], 0
	v_mfma_f32_16x16x32_bf16 v[36:39], v[178:181], v[202:205], 0
	v_mfma_f32_16x16x32_bf16 v[24:27], v[166:169], v[210:213], 0
	v_mfma_f32_16x16x32_bf16 v[20:23], v[178:181], v[210:213], 0
	v_mfma_f32_16x16x32_bf16 v[8:11], v[166:169], v[218:221], 0
	v_mfma_f32_16x16x32_bf16 v[4:7], v[178:181], v[218:221], 0
	v_mfma_f32_16x16x32_bf16 v[56:59], v[174:177], v[190:193], v[56:59]
	v_mfma_f32_16x16x32_bf16 v[52:55], v[182:185], v[190:193], v[52:55]
	v_mfma_f32_16x16x32_bf16 v[40:43], v[174:177], v[206:209], v[40:43]
	v_mfma_f32_16x16x32_bf16 v[36:39], v[182:185], v[206:209], v[36:39]
	v_mfma_f32_16x16x32_bf16 v[24:27], v[174:177], v[214:217], v[24:27]
	v_mfma_f32_16x16x32_bf16 v[20:23], v[182:185], v[214:217], v[20:23]
	v_mfma_f32_16x16x32_bf16 v[8:11], v[174:177], v[222:225], v[8:11]
	v_mfma_f32_16x16x32_bf16 v[4:7], v[182:185], v[222:225], v[4:7]
	s_setprio 0
	s_barrier
	s_add_i32 s47, 0, 0x18000
	s_add_i32 s48, 0, 0x1c000
	v_add_u32_e32 v162, s47, v141
	v_add_u32_e32 v173, s48, v141
	ds_read_b128 v[146:149], v162
	ds_read_b128 v[150:153], v162 offset:1024
	ds_read_b128 v[154:157], v162 offset:2048
	ds_read_b128 v[162:165], v162 offset:3072
	ds_read_b128 v[166:169], v173
	ds_read_b128 v[174:177], v173 offset:1024
	ds_read_b128 v[178:181], v173 offset:2048
	ds_read_b128 v[182:185], v173 offset:3072
	s_add_u32 s22, s22, 0x40000
	s_addc_u32 s23, s23, 0
	s_mov_b32 m0, s57
	v_lshl_add_u64 v[228:229], s[22:23], 0, v[132:133]
	ds_read_b128 v[186:189], v172 offset:32768
	ds_read_b128 v[190:193], v172 offset:33792
	ds_read_b128 v[202:205], v172 offset:34816
	ds_read_b128 v[206:209], v172 offset:35840
	ds_read_b128 v[210:213], v172 offset:36864
	ds_read_b128 v[214:217], v172 offset:37888
	ds_read_b128 v[218:221], v172 offset:38912
	ds_read_b128 v[222:225], v172 offset:39936
	global_load_lds_dwordx4 v[228:229], off
	v_lshl_add_u64 v[228:229], s[22:23], 0, v[136:137]
	s_mov_b32 m0, s58
	s_nop 0
	global_load_lds_dwordx4 v[228:229], off
	s_waitcnt vmcnt(8)
	s_waitcnt lgkmcnt(0)
	s_barrier
	s_setprio 1
	s_waitcnt lgkmcnt(0)
	v_mfma_f32_16x16x32_bf16 v[128:131], v[146:149], v[186:189], v[128:131]
	v_mfma_f32_16x16x32_bf16 v[124:127], v[154:157], v[186:189], v[124:127]
	v_mfma_f32_16x16x32_bf16 v[112:115], v[146:149], v[202:205], v[112:115]
	v_mfma_f32_16x16x32_bf16 v[108:111], v[154:157], v[202:205], v[108:111]
	v_mfma_f32_16x16x32_bf16 v[96:99], v[146:149], v[210:213], v[96:99]
	v_mfma_f32_16x16x32_bf16 v[92:95], v[154:157], v[210:213], v[92:95]
	v_mfma_f32_16x16x32_bf16 v[80:83], v[146:149], v[218:221], v[80:83]
	v_mfma_f32_16x16x32_bf16 v[76:79], v[154:157], v[218:221], v[76:79]
	v_mfma_f32_16x16x32_bf16 v[128:131], v[150:153], v[190:193], v[128:131]
	v_mfma_f32_16x16x32_bf16 v[124:127], v[162:165], v[190:193], v[124:127]
	v_mfma_f32_16x16x32_bf16 v[112:115], v[150:153], v[206:209], v[112:115]
	v_mfma_f32_16x16x32_bf16 v[108:111], v[162:165], v[206:209], v[108:111]
	v_mfma_f32_16x16x32_bf16 v[96:99], v[150:153], v[214:217], v[96:99]
	v_mfma_f32_16x16x32_bf16 v[92:95], v[162:165], v[214:217], v[92:95]
	v_mfma_f32_16x16x32_bf16 v[80:83], v[150:153], v[222:225], v[80:83]
	v_mfma_f32_16x16x32_bf16 v[76:79], v[162:165], v[222:225], v[76:79]
	s_setprio 0
	s_setprio 1
	v_mfma_f32_16x16x32_bf16 v[120:123], v[166:169], v[186:189], v[120:123]
	v_mfma_f32_16x16x32_bf16 v[116:119], v[178:181], v[186:189], v[116:119]
	v_mfma_f32_16x16x32_bf16 v[104:107], v[166:169], v[202:205], v[104:107]
	v_mfma_f32_16x16x32_bf16 v[100:103], v[178:181], v[202:205], v[100:103]
	v_mfma_f32_16x16x32_bf16 v[88:91], v[166:169], v[210:213], v[88:91]
	v_mfma_f32_16x16x32_bf16 v[84:87], v[178:181], v[210:213], v[84:87]
	v_mfma_f32_16x16x32_bf16 v[72:75], v[166:169], v[218:221], v[72:75]
	v_mfma_f32_16x16x32_bf16 v[68:71], v[178:181], v[218:221], v[68:71]
	v_mfma_f32_16x16x32_bf16 v[120:123], v[174:177], v[190:193], v[120:123]
	v_mfma_f32_16x16x32_bf16 v[116:119], v[182:185], v[190:193], v[116:119]
	v_mfma_f32_16x16x32_bf16 v[104:107], v[174:177], v[206:209], v[104:107]
	v_mfma_f32_16x16x32_bf16 v[100:103], v[182:185], v[206:209], v[100:103]
	v_mfma_f32_16x16x32_bf16 v[88:91], v[174:177], v[214:217], v[88:91]
	v_mfma_f32_16x16x32_bf16 v[84:87], v[182:185], v[214:217], v[84:87]
	v_mfma_f32_16x16x32_bf16 v[72:75], v[174:177], v[222:225], v[72:75]
	v_mfma_f32_16x16x32_bf16 v[68:71], v[182:185], v[222:225], v[68:71]
	s_setprio 0
	s_barrier
; #define PG8_STAGE(bufoff, gbase, voff) do { _Pragma("unroll") for (int _i = 0; _i < 2; ++_i) \
;         __builtin_amdgcn_global_load_lds((const unsigned*)((const char*)(gbase) + (voff)[_i]), (LAS unsigned*)(lds + (bufoff) + ldsw + _i * 8192), 16, 0, 0); } while (0)
; #define PG8_LDA(dst, b, h) do { _Pragma("unroll") for (int m = 0; m < 4; ++m) _Pragma("unroll") for (int k = 0; k < 2; ++k) dst[m][k] = *(const LAS bf16x8*)(lds + PG8_SA(b, h) + aoff + m * 2048 + k * 1024); } while (0)
; #define PG8_LDB(dst, b, h) do { _Pragma("unroll") for (int n = 0; n < 2; ++n) _Pragma("unroll") for (int k = 0; k < 2; ++k) dst[n][k] = *(const LAS bf16x8*)(lds + PG8_SB(b, h) + boff + n * 2048 + k * 1024); } while (0)
; #define PG8_MMA(ai, bj, At, Bt) do { __builtin_amdgcn_s_setprio(1); _Pragma("unroll") for (int m = 0; m < 4; ++m) _Pragma("unroll") for (int n = 0; n < 2; ++n) _Pragma("unroll") for (int k = 0; k < 2; ++k) \
;         acc[ai][bj][m][n] = __builtin_amdgcn_mfma_f32_16x16x32_bf16(Bt[n][k], At[m][k], acc[ai][bj][m][n], 0, 0, 0); __builtin_amdgcn_s_setprio(0); } while (0)
; #define PG8_WAIT_V(n) asm volatile("s_waitcnt vmcnt(" #n ")" ::: "memory")
; #define PG8_WAIT_L(n) asm volatile("s_waitcnt lgkmcnt(" #n ")" ::: "memory")
; #define PG8_BAR __builtin_amdgcn_s_barrier()
; #define PG8_SCHED __builtin_amdgcn_sched_barrier(0)
; template <class Epi, bool ALIGN_EPI>
; DI void gemm_phase(LAS unsigned char* lds, const Sched& S, const Epi& E, int tid) {
;     ...
;         for (int t = 0; t < nt; t += 2) {
;             const bool last = (t == nt - 2);
;             const char* a1 = cA + (size_t)(t + 1) * kstep;
;             const char* a2 = last ? nA : cA + (size_t)(t + 2) * kstep; const char* b2 = last ? nB : cB + (size_t)(t + 2) * kstep;
;             const char* a3 = a2 + kstep; const char* b3 = b2 + kstep;
;             PG8_LDB(B0, 0, 0); PG8_LDB(B1, 0, 1); PG8_SCHED; PG8_LDA(At, 0, 0); PG8_STAGE(PG8_SA(1, 1), a1 + hstepA, voffA);
;     ...
;             PG8_WAIT_V(8); PG8_WAIT_L(0); PG8_BAR; PG8_MMA(0, 0, At, B0); PG8_MMA(0, 1, At, B1); PG8_BAR; PG8_SCHED;
;             PG8_LDA(At, 1, 1); PG8_STAGE(PG8_SB(1, 0), b3, voffB); PG8_STAGE(PG8_SB(1, 1), b3 + hstepB, voffB); PG8_STAGE(PG8_SA(1, 0), a3, voffA);
;             PG8_WAIT_V(8); PG8_WAIT_L(0); PG8_BAR; PG8_MMA(1, 0, At, B0); PG8_MMA(1, 1, At, B1); PG8_BAR; PG8_SCHED;
	s_add_i32 s22, s47, s54
	v_lshl_add_u64 v[158:159], v[158:159], 0, s[84:85]
	s_mov_b32 m0, s22
	ds_read_b128 v[186:189], v172 offset:49152
	ds_read_b128 v[190:193], v172 offset:50176
	ds_read_b128 v[202:205], v172 offset:51200
	ds_read_b128 v[206:209], v172 offset:52224
	ds_read_b128 v[210:213], v172 offset:53248
	ds_read_b128 v[214:217], v172 offset:54272
	ds_read_b128 v[218:221], v172 offset:55296
	ds_read_b128 v[222:225], v172 offset:56320
	global_load_lds_dwordx4 v[158:159], off
	s_add_i32 m0, s22, 0x2000
	s_add_u32 s20, s20, 0x40080
	v_lshl_add_u64 v[158:159], v[170:171], 0, s[84:85]
	s_addc_u32 s21, s21, 0
	s_add_i32 s22, s48, s54
	global_load_lds_dwordx4 v[158:159], off
	v_lshl_add_u64 v[158:159], s[20:21], 0, v[134:135]
	s_mov_b32 m0, s22
	s_nop 0
	global_load_lds_dwordx4 v[158:159], off
	v_lshl_add_u64 v[158:159], s[20:21], 0, v[138:139]
	s_add_i32 m0, s22, 0x2000
	s_nop 0
	global_load_lds_dwordx4 v[158:159], off
	v_lshl_add_u64 v[158:159], v[194:195], 0, s[84:85]
	s_mov_b32 m0, s59
	s_nop 0
	global_load_lds_dwordx4 v[158:159], off
	v_lshl_add_u64 v[158:159], v[226:227], 0, s[84:85]
	s_mov_b32 m0, s60
	s_nop 0
	global_load_lds_dwordx4 v[158:159], off
	s_waitcnt vmcnt(8)
	s_waitcnt lgkmcnt(0)
	s_barrier
	s_setprio 1
	s_waitcnt lgkmcnt(0)
	v_mfma_f32_16x16x32_bf16 v[64:67], v[146:149], v[186:189], v[64:67]
	v_mfma_f32_16x16x32_bf16 v[60:63], v[154:157], v[186:189], v[60:63]
	v_mfma_f32_16x16x32_bf16 v[48:51], v[146:149], v[202:205], v[48:51]
	v_mfma_f32_16x16x32_bf16 v[44:47], v[154:157], v[202:205], v[44:47]
	v_mfma_f32_16x16x32_bf16 v[32:35], v[146:149], v[210:213], v[32:35]
	v_mfma_f32_16x16x32_bf16 v[28:31], v[154:157], v[210:213], v[28:31]
	v_mfma_f32_16x16x32_bf16 v[16:19], v[146:149], v[218:221], v[16:19]
	v_mfma_f32_16x16x32_bf16 v[12:15], v[154:157], v[218:221], v[12:15]
	v_mfma_f32_16x16x32_bf16 v[64:67], v[150:153], v[190:193], v[64:67]
	v_mfma_f32_16x16x32_bf16 v[60:63], v[162:165], v[190:193], v[60:63]
	v_mfma_f32_16x16x32_bf16 v[48:51], v[150:153], v[206:209], v[48:51]
	v_mfma_f32_16x16x32_bf16 v[44:47], v[162:165], v[206:209], v[44:47]
	v_mfma_f32_16x16x32_bf16 v[32:35], v[150:153], v[214:217], v[32:35]
	v_mfma_f32_16x16x32_bf16 v[28:31], v[162:165], v[214:217], v[28:31]
	v_mfma_f32_16x16x32_bf16 v[16:19], v[150:153], v[222:225], v[16:19]
	v_mfma_f32_16x16x32_bf16 v[12:15], v[162:165], v[222:225], v[12:15]
	s_setprio 0
	s_setprio 1
	v_mfma_f32_16x16x32_bf16 v[56:59], v[166:169], v[186:189], v[56:59]
	v_mfma_f32_16x16x32_bf16 v[52:55], v[178:181], v[186:189], v[52:55]
	v_mfma_f32_16x16x32_bf16 v[40:43], v[166:169], v[202:205], v[40:43]
	v_mfma_f32_16x16x32_bf16 v[36:39], v[178:181], v[202:205], v[36:39]
	v_mfma_f32_16x16x32_bf16 v[24:27], v[166:169], v[210:213], v[24:27]
	v_mfma_f32_16x16x32_bf16 v[20:23], v[178:181], v[210:213], v[20:23]
	v_mfma_f32_16x16x32_bf16 v[8:11], v[166:169], v[218:221], v[8:11]
	v_mfma_f32_16x16x32_bf16 v[4:7], v[178:181], v[218:221], v[4:7]
	v_mfma_f32_16x16x32_bf16 v[56:59], v[174:177], v[190:193], v[56:59]
	v_mfma_f32_16x16x32_bf16 v[52:55], v[182:185], v[190:193], v[52:55]
	v_mfma_f32_16x16x32_bf16 v[40:43], v[174:177], v[206:209], v[40:43]
	v_mfma_f32_16x16x32_bf16 v[36:39], v[182:185], v[206:209], v[36:39]
	v_mfma_f32_16x16x32_bf16 v[24:27], v[174:177], v[214:217], v[24:27]
	v_mfma_f32_16x16x32_bf16 v[20:23], v[182:185], v[214:217], v[20:23]
	v_mfma_f32_16x16x32_bf16 v[8:11], v[174:177], v[222:225], v[8:11]
	v_mfma_f32_16x16x32_bf16 v[4:7], v[182:185], v[222:225], v[4:7]
	s_setprio 0
	s_add_i32 s46, s46, 2
	s_add_u32 s2, s2, 0x100
	s_addc_u32 s3, s3, 0
	s_add_u32 s40, s40, 0x100
	s_addc_u32 s41, s41, 0
	s_cmp_gt_u32 s46, 13
	s_add_u32 s20, s2, 0xfffc0080
	s_addc_u32 s21, s3, -1
	s_add_i32 s47, 0, 0x10000
	s_cmp_eq_u32 s46, 12
	s_cselect_b32 s23, s1, s21
	s_cselect_b32 s22, s37, s20
	v_add_u32_e32 v158, s47, v141
	s_cselect_b32 s21, s38, s41
	s_cselect_b32 s20, s39, s40
	s_add_i32 s68, 0, 0x14000
	s_barrier
.LBB0_1049:
	ds_read_b128 v[146:149], v158
	ds_read_b128 v[150:153], v158 offset:1024
	ds_read_b128 v[154:157], v158 offset:2048
	ds_read_b128 v[162:165], v158 offset:3072
	v_add_u32_e32 v158, s68, v141
	ds_read_b128 v[166:169], v158
	ds_read_b128 v[174:177], v158 offset:1024
	ds_read_b128 v[178:181], v158 offset:2048
	ds_read_b128 v[182:185], v158 offset:3072
	v_lshl_add_u64 v[158:159], s[2:3], 0, v[142:143]
	s_add_i32 m0, s55, 0xc000
	ds_read_b128 v[186:189], v172
	ds_read_b128 v[190:193], v172 offset:1024
	ds_read_b128 v[202:205], v172 offset:2048
	ds_read_b128 v[206:209], v172 offset:3072
	ds_read_b128 v[210:213], v172 offset:4096
	ds_read_b128 v[214:217], v172 offset:5120
	ds_read_b128 v[218:221], v172 offset:6144
	ds_read_b128 v[222:225], v172 offset:7168
	global_load_lds_dwordx4 v[158:159], off
	v_lshl_add_u64 v[158:159], s[2:3], 0, v[144:145]
	s_add_i32 m0, s55, 0xe000
	s_nop 0
	global_load_lds_dwordx4 v[158:159], off
	s_waitcnt vmcnt(8)
	s_waitcnt lgkmcnt(0)
	s_barrier
; #define PG8_STAGE(bufoff, gbase, voff) do { _Pragma("unroll") for (int _i = 0; _i < 2; ++_i) \
;         __builtin_amdgcn_global_load_lds((const unsigned*)((const char*)(gbase) + (voff)[_i]), (LAS unsigned*)(lds + (bufoff) + ldsw + _i * 8192), 16, 0, 0); } while (0)
; #define PG8_LDA(dst, b, h) do { _Pragma("unroll") for (int m = 0; m < 4; ++m) _Pragma("unroll") for (int k = 0; k < 2; ++k) dst[m][k] = *(const LAS bf16x8*)(lds + PG8_SA(b, h) + aoff + m * 2048 + k * 1024); } while (0)
; #define PG8_LDB(dst, b, h) do { _Pragma("unroll") for (int n = 0; n < 2; ++n) _Pragma("unroll") for (int k = 0; k < 2; ++k) dst[n][k] = *(const LAS bf16x8*)(lds + PG8_SB(b, h) + boff + n * 2048 + k * 1024); } while (0)
; #define PG8_MMA(ai, bj, At, Bt) do { __builtin_amdgcn_s_setprio(1); _Pragma("unroll") for (int m = 0; m < 4; ++m) _Pragma("unroll") for (int n = 0; n < 2; ++n) _Pragma("unroll") for (int k = 0; k < 2; ++k) \
;         acc[ai][bj][m][n] = __builtin_amdgcn_mfma_f32_16x16x32_bf16(Bt[n][k], At[m][k], acc[ai][bj][m][n], 0, 0, 0); __builtin_amdgcn_s_setprio(0); } while (0)
; #define PG8_WAIT_V(n) asm volatile("s_waitcnt vmcnt(" #n ")" ::: "memory")
; #define PG8_WAIT_L(n) asm volatile("s_waitcnt lgkmcnt(" #n ")" ::: "memory")
; #define PG8_BAR __builtin_amdgcn_s_barrier()
; #define PG8_SCHED __builtin_amdgcn_sched_barrier(0)
; template <class Epi, bool ALIGN_EPI>
; DI void gemm_phase(LAS unsigned char* lds, const Sched& S, const Epi& E, int tid) {
;     ...
;             PG8_LDB(B0, 0, 0); PG8_LDB(B1, 0, 1); PG8_SCHED; PG8_LDA(At, 0, 0); PG8_STAGE(PG8_SA(1, 1), a1 + hstepA, voffA);
;             PG8_WAIT_V(8); PG8_WAIT_L(0); PG8_BAR; PG8_MMA(0, 0, At, B0); PG8_MMA(0, 1, At, B1); PG8_BAR; PG8_SCHED;
;             PG8_LDA(At, 0, 1); PG8_STAGE(PG8_SB(0, 0), b2, voffB); PG8_STAGE(PG8_SB(0, 1), b2 + hstepB, voffB); PG8_STAGE(PG8_SA(0, 0), a2, voffA);
;             PG8_WAIT_V(8); PG8_WAIT_L(0); PG8_BAR; PG8_MMA(1, 0, At, B0); PG8_MMA(1, 1, At, B1); PG8_BAR; PG8_SCHED;
;             PG8_LDB(B0, 1, 0); PG8_LDB(B1, 1, 1); PG8_SCHED; PG8_LDA(At, 1, 0); PG8_STAGE(PG8_SA(0, 1), a2 + hstepA, voffA);
;             PG8_WAIT_V(8); PG8_WAIT_L(0); PG8_BAR; PG8_MMA(0, 0, At, B0); PG8_MMA(0, 1, At, B1); PG8_BAR; PG8_SCHED;
;             PG8_LDA(At, 1, 1); PG8_STAGE(PG8_SB(1, 0), b3, voffB); PG8_STAGE(PG8_SB(1, 1), b3 + hstepB, voffB); PG8_STAGE(PG8_SA(1, 0), a3, voffA);
	s_setprio 1
	s_waitcnt lgkmcnt(0)
	v_mfma_f32_16x16x32_bf16 v[128:131], v[146:149], v[186:189], v[128:131]
	v_mfma_f32_16x16x32_bf16 v[124:127], v[154:157], v[186:189], v[124:127]
	v_mfma_f32_16x16x32_bf16 v[112:115], v[146:149], v[202:205], v[112:115]
	v_mfma_f32_16x16x32_bf16 v[108:111], v[154:157], v[202:205], v[108:111]
	v_mfma_f32_16x16x32_bf16 v[96:99], v[146:149], v[210:213], v[96:99]
	v_mfma_f32_16x16x32_bf16 v[92:95], v[154:157], v[210:213], v[92:95]
	v_mfma_f32_16x16x32_bf16 v[80:83], v[146:149], v[218:221], v[80:83]
	v_mfma_f32_16x16x32_bf16 v[76:79], v[154:157], v[218:221], v[76:79]
	v_mfma_f32_16x16x32_bf16 v[128:131], v[150:153], v[190:193], v[128:131]
	v_mfma_f32_16x16x32_bf16 v[124:127], v[162:165], v[190:193], v[124:127]
	v_mfma_f32_16x16x32_bf16 v[112:115], v[150:153], v[206:209], v[112:115]
	v_mfma_f32_16x16x32_bf16 v[108:111], v[162:165], v[206:209], v[108:111]
	v_mfma_f32_16x16x32_bf16 v[96:99], v[150:153], v[214:217], v[96:99]
	v_mfma_f32_16x16x32_bf16 v[92:95], v[162:165], v[214:217], v[92:95]
	v_mfma_f32_16x16x32_bf16 v[80:83], v[150:153], v[222:225], v[80:83]
	v_mfma_f32_16x16x32_bf16 v[76:79], v[162:165], v[222:225], v[76:79]
	s_setprio 0
	s_setprio 1
	v_mfma_f32_16x16x32_bf16 v[120:123], v[166:169], v[186:189], v[120:123]
	v_mfma_f32_16x16x32_bf16 v[116:119], v[178:181], v[186:189], v[116:119]
	v_mfma_f32_16x16x32_bf16 v[104:107], v[166:169], v[202:205], v[104:107]
	v_mfma_f32_16x16x32_bf16 v[100:103], v[178:181], v[202:205], v[100:103]
	v_mfma_f32_16x16x32_bf16 v[88:91], v[166:169], v[210:213], v[88:91]
	v_mfma_f32_16x16x32_bf16 v[84:87], v[178:181], v[210:213], v[84:87]
	v_mfma_f32_16x16x32_bf16 v[72:75], v[166:169], v[218:221], v[72:75]
	v_mfma_f32_16x16x32_bf16 v[68:71], v[178:181], v[218:221], v[68:71]
	v_mfma_f32_16x16x32_bf16 v[120:123], v[174:177], v[190:193], v[120:123]
	v_mfma_f32_16x16x32_bf16 v[116:119], v[182:185], v[190:193], v[116:119]
	v_mfma_f32_16x16x32_bf16 v[104:107], v[174:177], v[206:209], v[104:107]
	v_mfma_f32_16x16x32_bf16 v[100:103], v[182:185], v[206:209], v[100:103]
	v_mfma_f32_16x16x32_bf16 v[88:91], v[174:177], v[214:217], v[88:91]
	v_mfma_f32_16x16x32_bf16 v[84:87], v[182:185], v[214:217], v[84:87]
	v_mfma_f32_16x16x32_bf16 v[72:75], v[174:177], v[222:225], v[72:75]
	v_mfma_f32_16x16x32_bf16 v[68:71], v[182:185], v[222:225], v[68:71]
	s_setprio 0
	s_barrier
	s_add_i32 s47, s47, s54
	v_lshl_add_u64 v[158:159], s[20:21], 0, v[134:135]
	s_mov_b32 m0, s47
	ds_read_b128 v[186:189], v172 offset:16384
	ds_read_b128 v[190:193], v172 offset:17408
	ds_read_b128 v[202:205], v172 offset:18432
	ds_read_b128 v[206:209], v172 offset:19456
	ds_read_b128 v[210:213], v172 offset:20480
	ds_read_b128 v[214:217], v172 offset:21504
	ds_read_b128 v[218:221], v172 offset:22528
	ds_read_b128 v[222:225], v172 offset:23552
	global_load_lds_dwordx4 v[158:159], off
	s_add_i32 m0, s47, 0x2000
	s_add_u32 s48, s20, 0x40000
	v_lshl_add_u64 v[170:171], s[20:21], 0, v[138:139]
	s_addc_u32 s49, s21, 0
	s_add_i32 s47, s68, s54
	global_load_lds_dwordx4 v[170:171], off
	v_lshl_add_u64 v[194:195], s[48:49], 0, v[134:135]
	s_mov_b32 m0, s47
	v_lshl_add_u64 v[226:227], s[22:23], 0, v[136:137]
	global_load_lds_dwordx4 v[194:195], off
	v_lshl_add_u64 v[194:195], s[48:49], 0, v[138:139]
	s_add_i32 m0, s47, 0x2000
	s_nop 0
	global_load_lds_dwordx4 v[194:195], off
	v_lshl_add_u64 v[194:195], s[22:23], 0, v[132:133]
	s_mov_b32 m0, s55
	s_nop 0
	global_load_lds_dwordx4 v[194:195], off
	s_mov_b32 m0, s56
	s_nop 0
	global_load_lds_dwordx4 v[226:227], off
	s_waitcnt vmcnt(8)
	s_waitcnt lgkmcnt(0)
	s_barrier
	s_setprio 1
	s_waitcnt lgkmcnt(0)
	v_mfma_f32_16x16x32_bf16 v[64:67], v[146:149], v[186:189], v[64:67]
	v_mfma_f32_16x16x32_bf16 v[60:63], v[154:157], v[186:189], v[60:63]
	v_mfma_f32_16x16x32_bf16 v[48:51], v[146:149], v[202:205], v[48:51]
	v_mfma_f32_16x16x32_bf16 v[44:47], v[154:157], v[202:205], v[44:47]
	v_mfma_f32_16x16x32_bf16 v[32:35], v[146:149], v[210:213], v[32:35]
	v_mfma_f32_16x16x32_bf16 v[28:31], v[154:157], v[210:213], v[28:31]
	v_mfma_f32_16x16x32_bf16 v[16:19], v[146:149], v[218:221], v[16:19]
	v_mfma_f32_16x16x32_bf16 v[12:15], v[154:157], v[218:221], v[12:15]
	v_mfma_f32_16x16x32_bf16 v[64:67], v[150:153], v[190:193], v[64:67]
	v_mfma_f32_16x16x32_bf16 v[60:63], v[162:165], v[190:193], v[60:63]
	v_mfma_f32_16x16x32_bf16 v[48:51], v[150:153], v[206:209], v[48:51]
	v_mfma_f32_16x16x32_bf16 v[44:47], v[162:165], v[206:209], v[44:47]
	v_mfma_f32_16x16x32_bf16 v[32:35], v[150:153], v[214:217], v[32:35]
	v_mfma_f32_16x16x32_bf16 v[28:31], v[162:165], v[214:217], v[28:31]
	v_mfma_f32_16x16x32_bf16 v[16:19], v[150:153], v[222:225], v[16:19]
	v_mfma_f32_16x16x32_bf16 v[12:15], v[162:165], v[222:225], v[12:15]
	s_setprio 0
	s_setprio 1
	v_mfma_f32_16x16x32_bf16 v[56:59], v[166:169], v[186:189], v[56:59]
	v_mfma_f32_16x16x32_bf16 v[52:55], v[178:181], v[186:189], v[52:55]
	v_mfma_f32_16x16x32_bf16 v[40:43], v[166:169], v[202:205], v[40:43]
	v_mfma_f32_16x16x32_bf16 v[36:39], v[178:181], v[202:205], v[36:39]
	v_mfma_f32_16x16x32_bf16 v[24:27], v[166:169], v[210:213], v[24:27]
	v_mfma_f32_16x16x32_bf16 v[20:23], v[178:181], v[210:213], v[20:23]
	v_mfma_f32_16x16x32_bf16 v[8:11], v[166:169], v[218:221], v[8:11]
	v_mfma_f32_16x16x32_bf16 v[4:7], v[178:181], v[218:221], v[4:7]
	v_mfma_f32_16x16x32_bf16 v[56:59], v[174:177], v[190:193], v[56:59]
	v_mfma_f32_16x16x32_bf16 v[52:55], v[182:185], v[190:193], v[52:55]
	v_mfma_f32_16x16x32_bf16 v[40:43], v[174:177], v[206:209], v[40:43]
	v_mfma_f32_16x16x32_bf16 v[36:39], v[182:185], v[206:209], v[36:39]
	v_mfma_f32_16x16x32_bf16 v[24:27], v[174:177], v[214:217], v[24:27]
	v_mfma_f32_16x16x32_bf16 v[20:23], v[182:185], v[214:217], v[20:23]
	v_mfma_f32_16x16x32_bf16 v[8:11], v[174:177], v[222:225], v[8:11]
	v_mfma_f32_16x16x32_bf16 v[4:7], v[182:185], v[222:225], v[4:7]
	s_setprio 0
	s_barrier
; #define PG8_STAGE(bufoff, gbase, voff) do { _Pragma("unroll") for (int _i = 0; _i < 2; ++_i) \
;         __builtin_amdgcn_global_load_lds((const unsigned*)((const char*)(gbase) + (voff)[_i]), (LAS unsigned*)(lds + (bufoff) + ldsw + _i * 8192), 16, 0, 0); } while (0)
; #define PG8_LDA(dst, b, h) do { _Pragma("unroll") for (int m = 0; m < 4; ++m) _Pragma("unroll") for (int k = 0; k < 2; ++k) dst[m][k] = *(const LAS bf16x8*)(lds + PG8_SA(b, h) + aoff + m * 2048 + k * 1024); } while (0)
; #define PG8_LDB(dst, b, h) do { _Pragma("unroll") for (int n = 0; n < 2; ++n) _Pragma("unroll") for (int k = 0; k < 2; ++k) dst[n][k] = *(const LAS bf16x8*)(lds + PG8_SB(b, h) + boff + n * 2048 + k * 1024); } while (0)
; #define PG8_MMA(ai, bj, At, Bt) do { __builtin_amdgcn_s_setprio(1); _Pragma("unroll") for (int m = 0; m < 4; ++m) _Pragma("unroll") for (int n = 0; n < 2; ++n) _Pragma("unroll") for (int k = 0; k < 2; ++k) \
;         acc[ai][bj][m][n] = __builtin_amdgcn_mfma_f32_16x16x32_bf16(Bt[n][k], At[m][k], acc[ai][bj][m][n], 0, 0, 0); __builtin_amdgcn_s_setprio(0); } while (0)
; #define PG8_WAIT_V(n) asm volatile("s_waitcnt vmcnt(" #n ")" ::: "memory")
; #define PG8_WAIT_L(n) asm volatile("s_waitcnt lgkmcnt(" #n ")" ::: "memory")
; #define PG8_BAR __builtin_amdgcn_s_barrier()
; #define PG8_SCHED __builtin_amdgcn_sched_barrier(0)
; template <class Epi, bool ALIGN_EPI>
; DI void gemm_phase(LAS unsigned char* lds, const Sched& S, const Epi& E, int tid) {
;     ...
;             PG8_LDB(B0, 1, 0); PG8_LDB(B1, 1, 1); PG8_SCHED; PG8_LDA(At, 1, 0); PG8_STAGE(PG8_SA(0, 1), a2 + hstepA, voffA);
;             PG8_WAIT_V(8); PG8_WAIT_L(0); PG8_BAR; PG8_MMA(0, 0, At, B0); PG8_MMA(0, 1, At, B1); PG8_BAR; PG8_SCHED;
	s_add_i32 s47, 0, 0x18000
	s_add_i32 s48, 0, 0x1c000
	v_add_u32_e32 v162, s47, v141
	v_add_u32_e32 v173, s48, v141
	ds_read_b128 v[146:149], v162
	ds_read_b128 v[150:153], v162 offset:1024
	ds_read_b128 v[154:157], v162 offset:2048
	ds_read_b128 v[162:165], v162 offset:3072
	ds_read_b128 v[166:169], v173
	ds_read_b128 v[174:177], v173 offset:1024
	ds_read_b128 v[178:181], v173 offset:2048
	ds_read_b128 v[182:185], v173 offset:3072
	s_add_u32 s22, s22, 0x40000
	s_addc_u32 s23, s23, 0
	s_mov_b32 m0, s57
	v_lshl_add_u64 v[228:229], s[22:23], 0, v[132:133]
	ds_read_b128 v[186:189], v172 offset:32768
	ds_read_b128 v[190:193], v172 offset:33792
	ds_read_b128 v[202:205], v172 offset:34816
	ds_read_b128 v[206:209], v172 offset:35840
	ds_read_b128 v[210:213], v172 offset:36864
	ds_read_b128 v[214:217], v172 offset:37888
	ds_read_b128 v[218:221], v172 offset:38912
	ds_read_b128 v[222:225], v172 offset:39936
	global_load_lds_dwordx4 v[228:229], off
	v_lshl_add_u64 v[228:229], s[22:23], 0, v[136:137]
	s_mov_b32 m0, s58
	s_nop 0
	global_load_lds_dwordx4 v[228:229], off
	s_waitcnt vmcnt(8)
	s_waitcnt lgkmcnt(0)
	s_barrier
	s_setprio 1
	s_waitcnt lgkmcnt(0)
	v_mfma_f32_16x16x32_bf16 v[128:131], v[146:149], v[186:189], v[128:131]
	v_mfma_f32_16x16x32_bf16 v[124:127], v[154:157], v[186:189], v[124:127]
	v_mfma_f32_16x16x32_bf16 v[112:115], v[146:149], v[202:205], v[112:115]
	v_mfma_f32_16x16x32_bf16 v[108:111], v[154:157], v[202:205], v[108:111]
	v_mfma_f32_16x16x32_bf16 v[96:99], v[146:149], v[210:213], v[96:99]
	v_mfma_f32_16x16x32_bf16 v[92:95], v[154:157], v[210:213], v[92:95]
	v_mfma_f32_16x16x32_bf16 v[80:83], v[146:149], v[218:221], v[80:83]
	v_mfma_f32_16x16x32_bf16 v[76:79], v[154:157], v[218:221], v[76:79]
	v_mfma_f32_16x16x32_bf16 v[128:131], v[150:153], v[190:193], v[128:131]
	v_mfma_f32_16x16x32_bf16 v[124:127], v[162:165], v[190:193], v[124:127]
	v_mfma_f32_16x16x32_bf16 v[112:115], v[150:153], v[206:209], v[112:115]
	v_mfma_f32_16x16x32_bf16 v[108:111], v[162:165], v[206:209], v[108:111]
	v_mfma_f32_16x16x32_bf16 v[96:99], v[150:153], v[214:217], v[96:99]
	v_mfma_f32_16x16x32_bf16 v[92:95], v[162:165], v[214:217], v[92:95]
	v_mfma_f32_16x16x32_bf16 v[80:83], v[150:153], v[222:225], v[80:83]
	v_mfma_f32_16x16x32_bf16 v[76:79], v[162:165], v[222:225], v[76:79]
	s_setprio 0
	s_setprio 1
	v_mfma_f32_16x16x32_bf16 v[120:123], v[166:169], v[186:189], v[120:123]
	v_mfma_f32_16x16x32_bf16 v[116:119], v[178:181], v[186:189], v[116:119]
	v_mfma_f32_16x16x32_bf16 v[104:107], v[166:169], v[202:205], v[104:107]
	v_mfma_f32_16x16x32_bf16 v[100:103], v[178:181], v[202:205], v[100:103]
	v_mfma_f32_16x16x32_bf16 v[88:91], v[166:169], v[210:213], v[88:91]
	v_mfma_f32_16x16x32_bf16 v[84:87], v[178:181], v[210:213], v[84:87]
	v_mfma_f32_16x16x32_bf16 v[72:75], v[166:169], v[218:221], v[72:75]
	v_mfma_f32_16x16x32_bf16 v[68:71], v[178:181], v[218:221], v[68:71]
	v_mfma_f32_16x16x32_bf16 v[120:123], v[174:177], v[190:193], v[120:123]
	v_mfma_f32_16x16x32_bf16 v[116:119], v[182:185], v[190:193], v[116:119]
	v_mfma_f32_16x16x32_bf16 v[104:107], v[174:177], v[206:209], v[104:107]
	v_mfma_f32_16x16x32_bf16 v[100:103], v[182:185], v[206:209], v[100:103]
	v_mfma_f32_16x16x32_bf16 v[88:91], v[174:177], v[214:217], v[88:91]
	v_mfma_f32_16x16x32_bf16 v[84:87], v[182:185], v[214:217], v[84:87]
	v_mfma_f32_16x16x32_bf16 v[72:75], v[174:177], v[222:225], v[72:75]
	v_mfma_f32_16x16x32_bf16 v[68:71], v[182:185], v[222:225], v[68:71]
	s_setprio 0
	s_barrier
; #define PG8_STAGE(bufoff, gbase, voff) do { _Pragma("unroll") for (int _i = 0; _i < 2; ++_i) \
;         __builtin_amdgcn_global_load_lds((const unsigned*)((const char*)(gbase) + (voff)[_i]), (LAS unsigned*)(lds + (bufoff) + ldsw + _i * 8192), 16, 0, 0); } while (0)
; #define PG8_LDA(dst, b, h) do { _Pragma("unroll") for (int m = 0; m < 4; ++m) _Pragma("unroll") for (int k = 0; k < 2; ++k) dst[m][k] = *(const LAS bf16x8*)(lds + PG8_SA(b, h) + aoff + m * 2048 + k * 1024); } while (0)
; #define PG8_MMA(ai, bj, At, Bt) do { __builtin_amdgcn_s_setprio(1); _Pragma("unroll") for (int m = 0; m < 4; ++m) _Pragma("unroll") for (int n = 0; n < 2; ++n) _Pragma("unroll") for (int k = 0; k < 2; ++k) \
;         acc[ai][bj][m][n] = __builtin_amdgcn_mfma_f32_16x16x32_bf16(Bt[n][k], At[m][k], acc[ai][bj][m][n], 0, 0, 0); __builtin_amdgcn_s_setprio(0); } while (0)
; #define PG8_WAIT_V(n) asm volatile("s_waitcnt vmcnt(" #n ")" ::: "memory")
; #define PG8_WAIT_L(n) asm volatile("s_waitcnt lgkmcnt(" #n ")" ::: "memory")
; #define PG8_BAR __builtin_amdgcn_s_barrier()
; #define PG8_SCHED __builtin_amdgcn_sched_barrier(0)
; template <class Epi, bool ALIGN_EPI>
; DI void gemm_phase(LAS unsigned char* lds, const Sched& S, const Epi& E, int tid) {
;     ...
;             PG8_LDA(At, 1, 1); PG8_STAGE(PG8_SB(1, 0), b3, voffB); PG8_STAGE(PG8_SB(1, 1), b3 + hstepB, voffB); PG8_STAGE(PG8_SA(1, 0), a3, voffA);
;             PG8_WAIT_V(8); PG8_WAIT_L(0); PG8_BAR; PG8_MMA(1, 0, At, B0); PG8_MMA(1, 1, At, B1); PG8_BAR; PG8_SCHED;
;         }
;         if constexpr (ALIGN_EPI) { if (wr == 0) PG8_BAR; }
	s_add_i32 s22, s47, s54
	v_lshl_add_u64 v[158:159], v[158:159], 0, s[84:85]
	s_mov_b32 m0, s22
	ds_read_b128 v[186:189], v172 offset:49152
	ds_read_b128 v[190:193], v172 offset:50176
	ds_read_b128 v[202:205], v172 offset:51200
	ds_read_b128 v[206:209], v172 offset:52224
	ds_read_b128 v[210:213], v172 offset:53248
	ds_read_b128 v[214:217], v172 offset:54272
	ds_read_b128 v[218:221], v172 offset:55296
	ds_read_b128 v[222:225], v172 offset:56320
	global_load_lds_dwordx4 v[158:159], off
	s_add_i32 m0, s22, 0x2000
	s_add_u32 s20, s20, 0x40080
	v_lshl_add_u64 v[158:159], v[170:171], 0, s[84:85]
	s_addc_u32 s21, s21, 0
	s_add_i32 s22, s48, s54
	global_load_lds_dwordx4 v[158:159], off
	v_lshl_add_u64 v[158:159], s[20:21], 0, v[134:135]
	s_mov_b32 m0, s22
	s_nop 0
	global_load_lds_dwordx4 v[158:159], off
	v_lshl_add_u64 v[158:159], s[20:21], 0, v[138:139]
	s_add_i32 m0, s22, 0x2000
	s_nop 0
	global_load_lds_dwordx4 v[158:159], off
	v_lshl_add_u64 v[158:159], v[194:195], 0, s[84:85]
	s_mov_b32 m0, s59
	s_nop 0
	global_load_lds_dwordx4 v[158:159], off
	v_lshl_add_u64 v[158:159], v[226:227], 0, s[84:85]
	s_mov_b32 m0, s60
	s_nop 0
	global_load_lds_dwordx4 v[158:159], off
	s_waitcnt vmcnt(8)
	s_waitcnt lgkmcnt(0)
	s_barrier
	s_setprio 1
	s_waitcnt lgkmcnt(0)
	v_mfma_f32_16x16x32_bf16 v[64:67], v[146:149], v[186:189], v[64:67]
	v_mfma_f32_16x16x32_bf16 v[60:63], v[154:157], v[186:189], v[60:63]
	v_mfma_f32_16x16x32_bf16 v[48:51], v[146:149], v[202:205], v[48:51]
	v_mfma_f32_16x16x32_bf16 v[44:47], v[154:157], v[202:205], v[44:47]
	v_mfma_f32_16x16x32_bf16 v[32:35], v[146:149], v[210:213], v[32:35]
	v_mfma_f32_16x16x32_bf16 v[28:31], v[154:157], v[210:213], v[28:31]
	v_mfma_f32_16x16x32_bf16 v[16:19], v[146:149], v[218:221], v[16:19]
	v_mfma_f32_16x16x32_bf16 v[12:15], v[154:157], v[218:221], v[12:15]
	v_mfma_f32_16x16x32_bf16 v[64:67], v[150:153], v[190:193], v[64:67]
	v_mfma_f32_16x16x32_bf16 v[60:63], v[162:165], v[190:193], v[60:63]
	v_mfma_f32_16x16x32_bf16 v[48:51], v[150:153], v[206:209], v[48:51]
	v_mfma_f32_16x16x32_bf16 v[44:47], v[162:165], v[206:209], v[44:47]
	v_mfma_f32_16x16x32_bf16 v[32:35], v[150:153], v[214:217], v[32:35]
	v_mfma_f32_16x16x32_bf16 v[28:31], v[162:165], v[214:217], v[28:31]
	v_mfma_f32_16x16x32_bf16 v[16:19], v[150:153], v[222:225], v[16:19]
	v_mfma_f32_16x16x32_bf16 v[12:15], v[162:165], v[222:225], v[12:15]
	s_setprio 0
	s_setprio 1
	v_mfma_f32_16x16x32_bf16 v[56:59], v[166:169], v[186:189], v[56:59]
	v_mfma_f32_16x16x32_bf16 v[52:55], v[178:181], v[186:189], v[52:55]
	v_mfma_f32_16x16x32_bf16 v[40:43], v[166:169], v[202:205], v[40:43]
	v_mfma_f32_16x16x32_bf16 v[36:39], v[178:181], v[202:205], v[36:39]
	v_mfma_f32_16x16x32_bf16 v[24:27], v[166:169], v[210:213], v[24:27]
	v_mfma_f32_16x16x32_bf16 v[20:23], v[178:181], v[210:213], v[20:23]
	v_mfma_f32_16x16x32_bf16 v[8:11], v[166:169], v[218:221], v[8:11]
	v_mfma_f32_16x16x32_bf16 v[4:7], v[178:181], v[218:221], v[4:7]
	v_mfma_f32_16x16x32_bf16 v[56:59], v[174:177], v[190:193], v[56:59]
	v_mfma_f32_16x16x32_bf16 v[52:55], v[182:185], v[190:193], v[52:55]
	v_mfma_f32_16x16x32_bf16 v[40:43], v[174:177], v[206:209], v[40:43]
	v_mfma_f32_16x16x32_bf16 v[36:39], v[182:185], v[206:209], v[36:39]
	v_mfma_f32_16x16x32_bf16 v[24:27], v[174:177], v[214:217], v[24:27]
	v_mfma_f32_16x16x32_bf16 v[20:23], v[182:185], v[214:217], v[20:23]
	v_mfma_f32_16x16x32_bf16 v[8:11], v[174:177], v[222:225], v[8:11]
	v_mfma_f32_16x16x32_bf16 v[4:7], v[182:185], v[222:225], v[4:7]
	s_setprio 0
	s_add_i32 s46, s46, 2
	s_add_u32 s2, s2, 0x100
	s_addc_u32 s3, s3, 0
	s_add_u32 s40, s40, 0x100
	s_addc_u32 s41, s41, 0
	s_cmp_gt_u32 s46, 13
	s_cbranch_scc1 .Lkx_5
	s_add_u32 s20, s2, 0xfffc0080
	s_addc_u32 s21, s3, -1
	s_add_i32 s47, 0, 0x10000
	s_cmp_eq_u32 s46, 12
	s_cselect_b32 s23, s1, s21
	s_cselect_b32 s22, s37, s20
	v_add_u32_e32 v158, s47, v141
	s_cselect_b32 s21, s38, s41
	s_cselect_b32 s20, s39, s40
	s_add_i32 s68, 0, 0x14000
	s_barrier
	s_branch .LBB0_1049
.Lkx_5:
	s_barrier
	s_and_b64 vcc, exec, s[16:17]
	s_cbranch_vccz .LBB0_1052
	s_barrier

; #define PG8_STAGE(bufoff, gbase, voff) do { _Pragma("unroll") for (int _i = 0; _i < 2; ++_i) \
;         __builtin_amdgcn_global_load_lds((const unsigned*)((const char*)(gbase) + (voff)[_i]), (LAS unsigned*)(lds + (bufoff) + ldsw + _i * 8192), 16, 0, 0); } while (0)
; #define PG8_LDA(dst, b, h) do { _Pragma("unroll") for (int m = 0; m < 4; ++m) _Pragma("unroll") for (int k = 0; k < 2; ++k) dst[m][k] = *(const LAS bf16x8*)(lds + PG8_SA(b, h) + aoff + m * 2048 + k * 1024); } while (0)
; #define PG8_LDB(dst, b, h) do { _Pragma("unroll") for (int n = 0; n < 2; ++n) _Pragma("unroll") for (int k = 0; k < 2; ++k) dst[n][k] = *(const LAS bf16x8*)(lds + PG8_SB(b, h) + boff + n * 2048 + k * 1024); } while (0)
; #define PG8_MMA(ai, bj, At, Bt) do { __builtin_amdgcn_s_setprio(1); _Pragma("unroll") for (int m = 0; m < 4; ++m) _Pragma("unroll") for (int n = 0; n < 2; ++n) _Pragma("unroll") for (int k = 0; k < 2; ++k) \
;         acc[ai][bj][m][n] = __builtin_amdgcn_mfma_f32_16x16x32_bf16(Bt[n][k], At[m][k], acc[ai][bj][m][n], 0, 0, 0); __builtin_amdgcn_s_setprio(0); } while (0)
; #define PG8_WAIT_V(n) asm volatile("s_waitcnt vmcnt(" #n ")" ::: "memory")
; #define PG8_BAR __builtin_amdgcn_s_barrier()
; template <class Epi, bool ALIGN_EPI>
; DI void gemm_phase(LAS unsigned char* lds, const Sched& S, const Epi& E, int tid) {
;     ...
;         const bool has_next = S.next(ui + 1, nxt);
;         const char* nA = has_next ? nxt.a : cA; const char* nB = has_next ? nxt.b : cB;
;         const int nt = cur.nt;
;         for (int t = 0; t < nt; t += 2) {
;             const bool last = (t == nt - 2);
;             const char* a1 = cA + (size_t)(t + 1) * kstep;
;             const char* a2 = last ? nA : cA + (size_t)(t + 2) * kstep; const char* b2 = last ? nB : cB + (size_t)(t + 2) * kstep;
;             const char* a3 = a2 + kstep; const char* b3 = b2 + kstep;
;             PG8_LDB(B0, 0, 0); PG8_LDB(B1, 0, 1); PG8_SCHED; PG8_LDA(At, 0, 0); PG8_STAGE(PG8_SA(1, 1), a1 + hstepA, voffA);
;             PG8_WAIT_V(8); PG8_WAIT_L(0); PG8_BAR; PG8_MMA(0, 0, At, B0); PG8_MMA(0, 1, At, B1); PG8_BAR; PG8_SCHED;
;             PG8_LDA(At, 0, 1); PG8_STAGE(PG8_SB(0, 0), b2, voffB); PG8_STAGE(PG8_SB(0, 1), b2 + hstepB, voffB); PG8_STAGE(PG8_SA(0, 0), a2, voffA);
;             PG8_WAIT_V(8); PG8_WAIT_L(0); PG8_BAR; PG8_MMA(1, 0, At, B0); PG8_MMA(1, 1, At, B1); PG8_BAR; PG8_SCHED;
.LBB0_1764:
	s_and_b64 s[28:29], s[18:19], exec
	s_cselect_b32 s54, s15, s25
	s_cselect_b32 s55, s14, s24
	s_cselect_b32 s56, s17, s27
	s_cselect_b32 s57, s16, s26
	s_add_i32 s58, s23, -2
	s_add_u32 s24, s24, 0x40080
	s_addc_u32 s25, s25, 0
	s_add_u32 s59, s26, 0x100
	s_mov_b32 s81, s63
	s_addc_u32 s60, s27, 0
	s_mov_b32 s26, 0
	s_waitcnt lgkmcnt(0)
	s_add_i32 s61, s26, 2
	s_add_u32 s27, s24, 0xfffc0080
	s_addc_u32 s28, s25, -1
	s_add_i32 s62, 0, 0x10000
	s_cmp_eq_u32 s58, s26
	s_cselect_b32 s29, s54, s28
	s_cselect_b32 s28, s55, s27
	s_cselect_b32 s27, s56, s60
	s_cselect_b32 s26, s57, s59
	s_add_i32 s64, 0, 0x14000
	v_add_u32_e32 v144, s62, v161
	v_add_u32_e32 v174, s64, v161
	ds_read_b128 v[132:135], v144
	ds_read_b128 v[136:139], v144 offset:1024
	ds_read_b128 v[140:143], v144 offset:2048
	ds_read_b128 v[144:147], v144 offset:3072
	ds_read_b128 v[148:151], v174
	ds_read_b128 v[152:155], v174 offset:1024
	ds_read_b128 v[156:159], v174 offset:2048
	ds_read_b128 v[174:177], v174 offset:3072
	v_lshl_add_u64 v[190:191], s[24:25], 0, v[170:171]
	s_add_i32 m0, s41, 0xc000
	ds_read_b128 v[178:181], v193
	ds_read_b128 v[182:185], v193 offset:1024
	ds_read_b128 v[186:189], v193 offset:2048
	ds_read_b128 v[202:205], v193 offset:3072
	ds_read_b128 v[206:209], v193 offset:4096
	ds_read_b128 v[210:213], v193 offset:5120
	ds_read_b128 v[214:217], v193 offset:6144
	ds_read_b128 v[218:221], v193 offset:7168
	global_load_lds_dwordx4 v[190:191], off
	v_lshl_add_u64 v[190:191], s[24:25], 0, v[172:173]
	s_add_i32 m0, s41, 0xe000
	s_nop 0
	global_load_lds_dwordx4 v[190:191], off
	s_waitcnt vmcnt(8)
	s_waitcnt lgkmcnt(0)
	s_barrier
	s_setprio 1
	s_waitcnt lgkmcnt(0)
	v_mfma_f32_16x16x32_bf16 v[128:131], v[132:135], v[178:181], 0
	v_mfma_f32_16x16x32_bf16 v[124:127], v[140:143], v[178:181], 0
	v_mfma_f32_16x16x32_bf16 v[112:115], v[132:135], v[186:189], 0
	v_mfma_f32_16x16x32_bf16 v[108:111], v[140:143], v[186:189], 0
	v_mfma_f32_16x16x32_bf16 v[96:99], v[132:135], v[206:209], 0
	v_mfma_f32_16x16x32_bf16 v[92:95], v[140:143], v[206:209], 0
	v_mfma_f32_16x16x32_bf16 v[80:83], v[132:135], v[214:217], 0
	v_mfma_f32_16x16x32_bf16 v[76:79], v[140:143], v[214:217], 0
	v_mfma_f32_16x16x32_bf16 v[128:131], v[136:139], v[182:185], v[128:131]
	v_mfma_f32_16x16x32_bf16 v[124:127], v[144:147], v[182:185], v[124:127]
	v_mfma_f32_16x16x32_bf16 v[112:115], v[136:139], v[202:205], v[112:115]
	v_mfma_f32_16x16x32_bf16 v[108:111], v[144:147], v[202:205], v[108:111]
	v_mfma_f32_16x16x32_bf16 v[96:99], v[136:139], v[210:213], v[96:99]
	v_mfma_f32_16x16x32_bf16 v[92:95], v[144:147], v[210:213], v[92:95]
	v_mfma_f32_16x16x32_bf16 v[80:83], v[136:139], v[218:221], v[80:83]
	v_mfma_f32_16x16x32_bf16 v[76:79], v[144:147], v[218:221], v[76:79]
	s_setprio 0
	s_setprio 1
	v_mfma_f32_16x16x32_bf16 v[120:123], v[148:151], v[178:181], 0
	v_mfma_f32_16x16x32_bf16 v[116:119], v[156:159], v[178:181], 0
	v_mfma_f32_16x16x32_bf16 v[104:107], v[148:151], v[186:189], 0
	v_mfma_f32_16x16x32_bf16 v[100:103], v[156:159], v[186:189], 0
	v_mfma_f32_16x16x32_bf16 v[88:91], v[148:151], v[206:209], 0
	v_mfma_f32_16x16x32_bf16 v[84:87], v[156:159], v[206:209], 0
	v_mfma_f32_16x16x32_bf16 v[72:75], v[148:151], v[214:217], 0
	v_mfma_f32_16x16x32_bf16 v[68:71], v[156:159], v[214:217], 0
	v_mfma_f32_16x16x32_bf16 v[120:123], v[152:155], v[182:185], v[120:123]
	v_mfma_f32_16x16x32_bf16 v[116:119], v[174:177], v[182:185], v[116:119]
	v_mfma_f32_16x16x32_bf16 v[104:107], v[152:155], v[202:205], v[104:107]
	v_mfma_f32_16x16x32_bf16 v[100:103], v[174:177], v[202:205], v[100:103]
	v_mfma_f32_16x16x32_bf16 v[88:91], v[152:155], v[210:213], v[88:91]
	v_mfma_f32_16x16x32_bf16 v[84:87], v[174:177], v[210:213], v[84:87]
	v_mfma_f32_16x16x32_bf16 v[72:75], v[152:155], v[218:221], v[72:75]
	v_mfma_f32_16x16x32_bf16 v[68:71], v[174:177], v[218:221], v[68:71]
	s_setprio 0
	s_barrier
	s_add_i32 s62, s62, s40
	v_lshl_add_u64 v[190:191], s[26:27], 0, v[164:165]
	s_mov_b32 m0, s62
	ds_read_b128 v[178:181], v193 offset:16384
	ds_read_b128 v[182:185], v193 offset:17408
	ds_read_b128 v[186:189], v193 offset:18432
	ds_read_b128 v[202:205], v193 offset:19456
	ds_read_b128 v[206:209], v193 offset:20480
	ds_read_b128 v[210:213], v193 offset:21504
	ds_read_b128 v[214:217], v193 offset:22528
	ds_read_b128 v[218:221], v193 offset:23552
	global_load_lds_dwordx4 v[190:191], off
	s_add_i32 m0, s62, 0x2000
	s_add_u32 s62, s26, 0x40000
	v_lshl_add_u64 v[194:195], s[26:27], 0, v[168:169]
	s_addc_u32 s63, s27, 0
	s_add_i32 s64, s64, s40
	global_load_lds_dwordx4 v[194:195], off
	v_lshl_add_u64 v[222:223], s[62:63], 0, v[164:165]
	s_mov_b32 m0, s64
	v_lshl_add_u64 v[224:225], s[28:29], 0, v[166:167]
	global_load_lds_dwordx4 v[222:223], off
	v_lshl_add_u64 v[222:223], s[62:63], 0, v[168:169]
	s_add_i32 m0, s64, 0x2000
	s_nop 0
	global_load_lds_dwordx4 v[222:223], off
	v_lshl_add_u64 v[222:223], s[28:29], 0, v[162:163]
	s_mov_b32 m0, s41
	s_nop 0
	global_load_lds_dwordx4 v[222:223], off
	s_mov_b32 m0, s42
	s_nop 0
	global_load_lds_dwordx4 v[224:225], off
	s_waitcnt vmcnt(8)
	s_waitcnt lgkmcnt(0)
	s_barrier
; #define PG8_STAGE(bufoff, gbase, voff) do { _Pragma("unroll") for (int _i = 0; _i < 2; ++_i) \
;         __builtin_amdgcn_global_load_lds((const unsigned*)((const char*)(gbase) + (voff)[_i]), (LAS unsigned*)(lds + (bufoff) + ldsw + _i * 8192), 16, 0, 0); } while (0)
; #define PG8_LDA(dst, b, h) do { _Pragma("unroll") for (int m = 0; m < 4; ++m) _Pragma("unroll") for (int k = 0; k < 2; ++k) dst[m][k] = *(const LAS bf16x8*)(lds + PG8_SA(b, h) + aoff + m * 2048 + k * 1024); } while (0)
; #define PG8_LDB(dst, b, h) do { _Pragma("unroll") for (int n = 0; n < 2; ++n) _Pragma("unroll") for (int k = 0; k < 2; ++k) dst[n][k] = *(const LAS bf16x8*)(lds + PG8_SB(b, h) + boff + n * 2048 + k * 1024); } while (0)
; #define PG8_MMA(ai, bj, At, Bt) do { __builtin_amdgcn_s_setprio(1); _Pragma("unroll") for (int m = 0; m < 4; ++m) _Pragma("unroll") for (int n = 0; n < 2; ++n) _Pragma("unroll") for (int k = 0; k < 2; ++k) \
;         acc[ai][bj][m][n] = __builtin_amdgcn_mfma_f32_16x16x32_bf16(Bt[n][k], At[m][k], acc[ai][bj][m][n], 0, 0, 0); __builtin_amdgcn_s_setprio(0); } while (0)
; #define PG8_WAIT_V(n) asm volatile("s_waitcnt vmcnt(" #n ")" ::: "memory")
; #define PG8_WAIT_L(n) asm volatile("s_waitcnt lgkmcnt(" #n ")" ::: "memory")
; #define PG8_BAR __builtin_amdgcn_s_barrier()
; #define PG8_SCHED __builtin_amdgcn_sched_barrier(0)
; template <class Epi, bool ALIGN_EPI>
; DI void gemm_phase(LAS unsigned char* lds, const Sched& S, const Epi& E, int tid) {
;     ...
;             PG8_WAIT_V(8); PG8_WAIT_L(0); PG8_BAR; PG8_MMA(1, 0, At, B0); PG8_MMA(1, 1, At, B1); PG8_BAR; PG8_SCHED;
;             PG8_LDB(B0, 1, 0); PG8_LDB(B1, 1, 1); PG8_SCHED; PG8_LDA(At, 1, 0); PG8_STAGE(PG8_SA(0, 1), a2 + hstepA, voffA);
;             PG8_WAIT_V(8); PG8_WAIT_L(0); PG8_BAR; PG8_MMA(0, 0, At, B0); PG8_MMA(0, 1, At, B1); PG8_BAR; PG8_SCHED;
	s_setprio 1
	s_waitcnt lgkmcnt(0)
	v_mfma_f32_16x16x32_bf16 v[64:67], v[132:135], v[178:181], 0
	v_mfma_f32_16x16x32_bf16 v[60:63], v[140:143], v[178:181], 0
	v_mfma_f32_16x16x32_bf16 v[48:51], v[132:135], v[186:189], 0
	v_mfma_f32_16x16x32_bf16 v[44:47], v[140:143], v[186:189], 0
	v_mfma_f32_16x16x32_bf16 v[32:35], v[132:135], v[206:209], 0
	v_mfma_f32_16x16x32_bf16 v[28:31], v[140:143], v[206:209], 0
	v_mfma_f32_16x16x32_bf16 v[16:19], v[132:135], v[214:217], 0
	v_mfma_f32_16x16x32_bf16 v[12:15], v[140:143], v[214:217], 0
	v_mfma_f32_16x16x32_bf16 v[64:67], v[136:139], v[182:185], v[64:67]
	v_mfma_f32_16x16x32_bf16 v[60:63], v[144:147], v[182:185], v[60:63]
	v_mfma_f32_16x16x32_bf16 v[48:51], v[136:139], v[202:205], v[48:51]
	v_mfma_f32_16x16x32_bf16 v[44:47], v[144:147], v[202:205], v[44:47]
	v_mfma_f32_16x16x32_bf16 v[32:35], v[136:139], v[210:213], v[32:35]
	v_mfma_f32_16x16x32_bf16 v[28:31], v[144:147], v[210:213], v[28:31]
	v_mfma_f32_16x16x32_bf16 v[16:19], v[136:139], v[218:221], v[16:19]
	v_mfma_f32_16x16x32_bf16 v[12:15], v[144:147], v[218:221], v[12:15]
	s_setprio 0
	s_setprio 1
	v_mfma_f32_16x16x32_bf16 v[56:59], v[148:151], v[178:181], 0
	v_mfma_f32_16x16x32_bf16 v[52:55], v[156:159], v[178:181], 0
	v_mfma_f32_16x16x32_bf16 v[40:43], v[148:151], v[186:189], 0
	v_mfma_f32_16x16x32_bf16 v[36:39], v[156:159], v[186:189], 0
	v_mfma_f32_16x16x32_bf16 v[24:27], v[148:151], v[206:209], 0
	v_mfma_f32_16x16x32_bf16 v[20:23], v[156:159], v[206:209], 0
	v_mfma_f32_16x16x32_bf16 v[8:11], v[148:151], v[214:217], 0
	v_mfma_f32_16x16x32_bf16 v[4:7], v[156:159], v[214:217], 0
	v_mfma_f32_16x16x32_bf16 v[56:59], v[152:155], v[182:185], v[56:59]
	v_mfma_f32_16x16x32_bf16 v[52:55], v[174:177], v[182:185], v[52:55]
	v_mfma_f32_16x16x32_bf16 v[40:43], v[152:155], v[202:205], v[40:43]
	v_mfma_f32_16x16x32_bf16 v[36:39], v[174:177], v[202:205], v[36:39]
	v_mfma_f32_16x16x32_bf16 v[24:27], v[152:155], v[210:213], v[24:27]
	v_mfma_f32_16x16x32_bf16 v[20:23], v[174:177], v[210:213], v[20:23]
	v_mfma_f32_16x16x32_bf16 v[8:11], v[152:155], v[218:221], v[8:11]
	v_mfma_f32_16x16x32_bf16 v[4:7], v[174:177], v[218:221], v[4:7]
	s_setprio 0
	s_barrier
	s_add_i32 s62, 0, 0x18000
	s_add_i32 s63, 0, 0x1c000
	v_add_u32_e32 v144, s62, v161
	v_add_u32_e32 v174, s63, v161
	ds_read_b128 v[132:135], v144
	ds_read_b128 v[136:139], v144 offset:1024
	ds_read_b128 v[140:143], v144 offset:2048
	ds_read_b128 v[144:147], v144 offset:3072
	ds_read_b128 v[148:151], v174
	ds_read_b128 v[152:155], v174 offset:1024
	ds_read_b128 v[156:159], v174 offset:2048
	ds_read_b128 v[174:177], v174 offset:3072
	s_add_u32 s28, s28, 0x40000
	s_addc_u32 s29, s29, 0
	s_mov_b32 m0, s43
	v_lshl_add_u64 v[226:227], s[28:29], 0, v[162:163]
	ds_read_b128 v[178:181], v193 offset:32768
	ds_read_b128 v[182:185], v193 offset:33792
	ds_read_b128 v[186:189], v193 offset:34816
	ds_read_b128 v[202:205], v193 offset:35840
	ds_read_b128 v[206:209], v193 offset:36864
	ds_read_b128 v[210:213], v193 offset:37888
	ds_read_b128 v[214:217], v193 offset:38912
	ds_read_b128 v[218:221], v193 offset:39936
	global_load_lds_dwordx4 v[226:227], off
	v_lshl_add_u64 v[226:227], s[28:29], 0, v[166:167]
	s_mov_b32 m0, s44
	s_nop 0
	global_load_lds_dwordx4 v[226:227], off
	s_waitcnt vmcnt(8)
	s_waitcnt lgkmcnt(0)
	s_barrier
	s_setprio 1
	s_waitcnt lgkmcnt(0)
	v_mfma_f32_16x16x32_bf16 v[128:131], v[132:135], v[178:181], v[128:131]
	v_mfma_f32_16x16x32_bf16 v[124:127], v[140:143], v[178:181], v[124:127]
	v_mfma_f32_16x16x32_bf16 v[112:115], v[132:135], v[186:189], v[112:115]
	v_mfma_f32_16x16x32_bf16 v[108:111], v[140:143], v[186:189], v[108:111]
	v_mfma_f32_16x16x32_bf16 v[96:99], v[132:135], v[206:209], v[96:99]
	v_mfma_f32_16x16x32_bf16 v[92:95], v[140:143], v[206:209], v[92:95]
	v_mfma_f32_16x16x32_bf16 v[80:83], v[132:135], v[214:217], v[80:83]
	v_mfma_f32_16x16x32_bf16 v[76:79], v[140:143], v[214:217], v[76:79]
	v_mfma_f32_16x16x32_bf16 v[128:131], v[136:139], v[182:185], v[128:131]
	v_mfma_f32_16x16x32_bf16 v[124:127], v[144:147], v[182:185], v[124:127]
	v_mfma_f32_16x16x32_bf16 v[112:115], v[136:139], v[202:205], v[112:115]
	v_mfma_f32_16x16x32_bf16 v[108:111], v[144:147], v[202:205], v[108:111]
	v_mfma_f32_16x16x32_bf16 v[96:99], v[136:139], v[210:213], v[96:99]
	v_mfma_f32_16x16x32_bf16 v[92:95], v[144:147], v[210:213], v[92:95]
	v_mfma_f32_16x16x32_bf16 v[80:83], v[136:139], v[218:221], v[80:83]
	v_mfma_f32_16x16x32_bf16 v[76:79], v[144:147], v[218:221], v[76:79]
	s_setprio 0
	s_setprio 1
	v_mfma_f32_16x16x32_bf16 v[120:123], v[148:151], v[178:181], v[120:123]
	v_mfma_f32_16x16x32_bf16 v[116:119], v[156:159], v[178:181], v[116:119]
	v_mfma_f32_16x16x32_bf16 v[104:107], v[148:151], v[186:189], v[104:107]
	v_mfma_f32_16x16x32_bf16 v[100:103], v[156:159], v[186:189], v[100:103]
	v_mfma_f32_16x16x32_bf16 v[88:91], v[148:151], v[206:209], v[88:91]
	v_mfma_f32_16x16x32_bf16 v[84:87], v[156:159], v[206:209], v[84:87]
	v_mfma_f32_16x16x32_bf16 v[72:75], v[148:151], v[214:217], v[72:75]
	v_mfma_f32_16x16x32_bf16 v[68:71], v[156:159], v[214:217], v[68:71]
	v_mfma_f32_16x16x32_bf16 v[120:123], v[152:155], v[182:185], v[120:123]
	v_mfma_f32_16x16x32_bf16 v[116:119], v[174:177], v[182:185], v[116:119]
	v_mfma_f32_16x16x32_bf16 v[104:107], v[152:155], v[202:205], v[104:107]
	v_mfma_f32_16x16x32_bf16 v[100:103], v[174:177], v[202:205], v[100:103]
	v_mfma_f32_16x16x32_bf16 v[88:91], v[152:155], v[210:213], v[88:91]
	v_mfma_f32_16x16x32_bf16 v[84:87], v[174:177], v[210:213], v[84:87]
	v_mfma_f32_16x16x32_bf16 v[72:75], v[152:155], v[218:221], v[72:75]
	v_mfma_f32_16x16x32_bf16 v[68:71], v[174:177], v[218:221], v[68:71]
	s_setprio 0
	s_barrier
; #define PG8_STAGE(bufoff, gbase, voff) do { _Pragma("unroll") for (int _i = 0; _i < 2; ++_i) \
;         __builtin_amdgcn_global_load_lds((const unsigned*)((const char*)(gbase) + (voff)[_i]), (LAS unsigned*)(lds + (bufoff) + ldsw + _i * 8192), 16, 0, 0); } while (0)
; #define PG8_LDA(dst, b, h) do { _Pragma("unroll") for (int m = 0; m < 4; ++m) _Pragma("unroll") for (int k = 0; k < 2; ++k) dst[m][k] = *(const LAS bf16x8*)(lds + PG8_SA(b, h) + aoff + m * 2048 + k * 1024); } while (0)
; #define PG8_LDB(dst, b, h) do { _Pragma("unroll") for (int n = 0; n < 2; ++n) _Pragma("unroll") for (int k = 0; k < 2; ++k) dst[n][k] = *(const LAS bf16x8*)(lds + PG8_SB(b, h) + boff + n * 2048 + k * 1024); } while (0)
; #define PG8_MMA(ai, bj, At, Bt) do { __builtin_amdgcn_s_setprio(1); _Pragma("unroll") for (int m = 0; m < 4; ++m) _Pragma("unroll") for (int n = 0; n < 2; ++n) _Pragma("unroll") for (int k = 0; k < 2; ++k) \
;         acc[ai][bj][m][n] = __builtin_amdgcn_mfma_f32_16x16x32_bf16(Bt[n][k], At[m][k], acc[ai][bj][m][n], 0, 0, 0); __builtin_amdgcn_s_setprio(0); } while (0)
; #define PG8_WAIT_V(n) asm volatile("s_waitcnt vmcnt(" #n ")" ::: "memory")
; #define PG8_WAIT_L(n) asm volatile("s_waitcnt lgkmcnt(" #n ")" ::: "memory")
; #define PG8_BAR __builtin_amdgcn_s_barrier()
; #define PG8_SCHED __builtin_amdgcn_sched_barrier(0)
; template <class Epi, bool ALIGN_EPI>
; DI void gemm_phase(LAS unsigned char* lds, const Sched& S, const Epi& E, int tid) {
;     ...
;         for (int t = 0; t < nt; t += 2) {
;             const bool last = (t == nt - 2);
;             const char* a1 = cA + (size_t)(t + 1) * kstep;
;             const char* a2 = last ? nA : cA + (size_t)(t + 2) * kstep; const char* b2 = last ? nB : cB + (size_t)(t + 2) * kstep;
;             const char* a3 = a2 + kstep; const char* b3 = b2 + kstep;
;             PG8_LDB(B0, 0, 0); PG8_LDB(B1, 0, 1); PG8_SCHED; PG8_LDA(At, 0, 0); PG8_STAGE(PG8_SA(1, 1), a1 + hstepA, voffA);
;     ...
;             PG8_WAIT_V(8); PG8_WAIT_L(0); PG8_BAR; PG8_MMA(0, 0, At, B0); PG8_MMA(0, 1, At, B1); PG8_BAR; PG8_SCHED;
;             PG8_LDA(At, 1, 1); PG8_STAGE(PG8_SB(1, 0), b3, voffB); PG8_STAGE(PG8_SB(1, 1), b3 + hstepB, voffB); PG8_STAGE(PG8_SA(1, 0), a3, voffA);
;             PG8_WAIT_V(8); PG8_WAIT_L(0); PG8_BAR; PG8_MMA(1, 0, At, B0); PG8_MMA(1, 1, At, B1); PG8_BAR; PG8_SCHED;
	s_add_i32 s28, s62, s40
	v_lshl_add_u64 v[190:191], v[190:191], 0, s[84:85]
	s_mov_b32 m0, s28
	ds_read_b128 v[178:181], v193 offset:49152
	ds_read_b128 v[182:185], v193 offset:50176
	ds_read_b128 v[186:189], v193 offset:51200
	ds_read_b128 v[202:205], v193 offset:52224
	ds_read_b128 v[206:209], v193 offset:53248
	ds_read_b128 v[210:213], v193 offset:54272
	ds_read_b128 v[214:217], v193 offset:55296
	ds_read_b128 v[218:221], v193 offset:56320
	global_load_lds_dwordx4 v[190:191], off
	s_add_i32 m0, s28, 0x2000
	s_add_u32 s26, s26, 0x40080
	v_lshl_add_u64 v[190:191], v[194:195], 0, s[84:85]
	s_addc_u32 s27, s27, 0
	s_add_i32 s28, s63, s40
	global_load_lds_dwordx4 v[190:191], off
	v_lshl_add_u64 v[190:191], s[26:27], 0, v[164:165]
	s_mov_b32 m0, s28
	s_nop 0
	global_load_lds_dwordx4 v[190:191], off
	v_lshl_add_u64 v[190:191], s[26:27], 0, v[168:169]
	s_add_i32 m0, s28, 0x2000
	s_nop 0
	global_load_lds_dwordx4 v[190:191], off
	v_lshl_add_u64 v[190:191], v[222:223], 0, s[84:85]
	s_mov_b32 m0, s46
	s_nop 0
	global_load_lds_dwordx4 v[190:191], off
	v_lshl_add_u64 v[190:191], v[224:225], 0, s[84:85]
	s_mov_b32 m0, s47
	s_nop 0
	global_load_lds_dwordx4 v[190:191], off
	s_waitcnt vmcnt(8)
	s_waitcnt lgkmcnt(0)
	s_barrier
	s_setprio 1
	s_waitcnt lgkmcnt(0)
	v_mfma_f32_16x16x32_bf16 v[64:67], v[132:135], v[178:181], v[64:67]
	v_mfma_f32_16x16x32_bf16 v[60:63], v[140:143], v[178:181], v[60:63]
	v_mfma_f32_16x16x32_bf16 v[48:51], v[132:135], v[186:189], v[48:51]
	v_mfma_f32_16x16x32_bf16 v[44:47], v[140:143], v[186:189], v[44:47]
	v_mfma_f32_16x16x32_bf16 v[32:35], v[132:135], v[206:209], v[32:35]
	v_mfma_f32_16x16x32_bf16 v[28:31], v[140:143], v[206:209], v[28:31]
	v_mfma_f32_16x16x32_bf16 v[16:19], v[132:135], v[214:217], v[16:19]
	v_mfma_f32_16x16x32_bf16 v[12:15], v[140:143], v[214:217], v[12:15]
	v_mfma_f32_16x16x32_bf16 v[64:67], v[136:139], v[182:185], v[64:67]
	v_mfma_f32_16x16x32_bf16 v[60:63], v[144:147], v[182:185], v[60:63]
	v_mfma_f32_16x16x32_bf16 v[48:51], v[136:139], v[202:205], v[48:51]
	v_mfma_f32_16x16x32_bf16 v[44:47], v[144:147], v[202:205], v[44:47]
	v_mfma_f32_16x16x32_bf16 v[32:35], v[136:139], v[210:213], v[32:35]
	v_mfma_f32_16x16x32_bf16 v[28:31], v[144:147], v[210:213], v[28:31]
	v_mfma_f32_16x16x32_bf16 v[16:19], v[136:139], v[218:221], v[16:19]
	v_mfma_f32_16x16x32_bf16 v[12:15], v[144:147], v[218:221], v[12:15]
	s_setprio 0
	s_setprio 1
	v_mfma_f32_16x16x32_bf16 v[56:59], v[148:151], v[178:181], v[56:59]
	v_mfma_f32_16x16x32_bf16 v[52:55], v[156:159], v[178:181], v[52:55]
	v_mfma_f32_16x16x32_bf16 v[40:43], v[148:151], v[186:189], v[40:43]
	v_mfma_f32_16x16x32_bf16 v[36:39], v[156:159], v[186:189], v[36:39]
	v_mfma_f32_16x16x32_bf16 v[24:27], v[148:151], v[206:209], v[24:27]
	v_mfma_f32_16x16x32_bf16 v[20:23], v[156:159], v[206:209], v[20:23]
	v_mfma_f32_16x16x32_bf16 v[8:11], v[148:151], v[214:217], v[8:11]
	v_mfma_f32_16x16x32_bf16 v[4:7], v[156:159], v[214:217], v[4:7]
	v_mfma_f32_16x16x32_bf16 v[56:59], v[152:155], v[182:185], v[56:59]
	v_mfma_f32_16x16x32_bf16 v[52:55], v[174:177], v[182:185], v[52:55]
	v_mfma_f32_16x16x32_bf16 v[40:43], v[152:155], v[202:205], v[40:43]
	v_mfma_f32_16x16x32_bf16 v[36:39], v[174:177], v[202:205], v[36:39]
	v_mfma_f32_16x16x32_bf16 v[24:27], v[152:155], v[210:213], v[24:27]
	v_mfma_f32_16x16x32_bf16 v[20:23], v[174:177], v[210:213], v[20:23]
	v_mfma_f32_16x16x32_bf16 v[8:11], v[152:155], v[218:221], v[8:11]
	v_mfma_f32_16x16x32_bf16 v[4:7], v[174:177], v[218:221], v[4:7]
	s_setprio 0
	s_add_u32 s24, s24, 0x100
	s_addc_u32 s25, s25, 0
	s_add_u32 s59, s59, 0x100
	s_addc_u32 s60, s60, 0
	s_cmp_ge_i32 s61, s23
	s_mov_b32 s26, s61
	s_add_i32 s61, s26, 2
	s_add_u32 s27, s24, 0xfffc0080
	s_addc_u32 s28, s25, -1
	s_add_i32 s62, 0, 0x10000
	s_cmp_eq_u32 s58, s26
	s_cselect_b32 s29, s54, s28
	s_cselect_b32 s28, s55, s27
	s_cselect_b32 s27, s56, s60
	s_cselect_b32 s26, s57, s59
	s_add_i32 s64, 0, 0x14000
	v_add_u32_e32 v144, s62, v161
	v_add_u32_e32 v174, s64, v161
	s_barrier
.LBB0_1765:
	ds_read_b128 v[132:135], v144
	ds_read_b128 v[136:139], v144 offset:1024
	ds_read_b128 v[140:143], v144 offset:2048
	ds_read_b128 v[144:147], v144 offset:3072
	ds_read_b128 v[148:151], v174
	ds_read_b128 v[152:155], v174 offset:1024
	ds_read_b128 v[156:159], v174 offset:2048
	ds_read_b128 v[174:177], v174 offset:3072
	v_lshl_add_u64 v[190:191], s[24:25], 0, v[170:171]
	s_add_i32 m0, s41, 0xc000
	ds_read_b128 v[178:181], v193
	ds_read_b128 v[182:185], v193 offset:1024
	ds_read_b128 v[186:189], v193 offset:2048
	ds_read_b128 v[202:205], v193 offset:3072
	ds_read_b128 v[206:209], v193 offset:4096
	ds_read_b128 v[210:213], v193 offset:5120
	ds_read_b128 v[214:217], v193 offset:6144
	ds_read_b128 v[218:221], v193 offset:7168
	global_load_lds_dwordx4 v[190:191], off
	v_lshl_add_u64 v[190:191], s[24:25], 0, v[172:173]
	s_add_i32 m0, s41, 0xe000
	s_nop 0
	global_load_lds_dwordx4 v[190:191], off
	s_waitcnt vmcnt(8)
	s_waitcnt lgkmcnt(0)
	s_barrier
; #define PG8_STAGE(bufoff, gbase, voff) do { _Pragma("unroll") for (int _i = 0; _i < 2; ++_i) \
;         __builtin_amdgcn_global_load_lds((const unsigned*)((const char*)(gbase) + (voff)[_i]), (LAS unsigned*)(lds + (bufoff) + ldsw + _i * 8192), 16, 0, 0); } while (0)
; #define PG8_LDA(dst, b, h) do { _Pragma("unroll") for (int m = 0; m < 4; ++m) _Pragma("unroll") for (int k = 0; k < 2; ++k) dst[m][k] = *(const LAS bf16x8*)(lds + PG8_SA(b, h) + aoff + m * 2048 + k * 1024); } while (0)
; #define PG8_LDB(dst, b, h) do { _Pragma("unroll") for (int n = 0; n < 2; ++n) _Pragma("unroll") for (int k = 0; k < 2; ++k) dst[n][k] = *(const LAS bf16x8*)(lds + PG8_SB(b, h) + boff + n * 2048 + k * 1024); } while (0)
; #define PG8_MMA(ai, bj, At, Bt) do { __builtin_amdgcn_s_setprio(1); _Pragma("unroll") for (int m = 0; m < 4; ++m) _Pragma("unroll") for (int n = 0; n < 2; ++n) _Pragma("unroll") for (int k = 0; k < 2; ++k) \
;         acc[ai][bj][m][n] = __builtin_amdgcn_mfma_f32_16x16x32_bf16(Bt[n][k], At[m][k], acc[ai][bj][m][n], 0, 0, 0); __builtin_amdgcn_s_setprio(0); } while (0)
; #define PG8_WAIT_V(n) asm volatile("s_waitcnt vmcnt(" #n ")" ::: "memory")
; #define PG8_WAIT_L(n) asm volatile("s_waitcnt lgkmcnt(" #n ")" ::: "memory")
; #define PG8_BAR __builtin_amdgcn_s_barrier()
; #define PG8_SCHED __builtin_amdgcn_sched_barrier(0)
; template <class Epi, bool ALIGN_EPI>
; DI void gemm_phase(LAS unsigned char* lds, const Sched& S, const Epi& E, int tid) {
;     ...
;             PG8_LDB(B0, 0, 0); PG8_LDB(B1, 0, 1); PG8_SCHED; PG8_LDA(At, 0, 0); PG8_STAGE(PG8_SA(1, 1), a1 + hstepA, voffA);
;             PG8_WAIT_V(8); PG8_WAIT_L(0); PG8_BAR; PG8_MMA(0, 0, At, B0); PG8_MMA(0, 1, At, B1); PG8_BAR; PG8_SCHED;
;             PG8_LDA(At, 0, 1); PG8_STAGE(PG8_SB(0, 0), b2, voffB); PG8_STAGE(PG8_SB(0, 1), b2 + hstepB, voffB); PG8_STAGE(PG8_SA(0, 0), a2, voffA);
;             PG8_WAIT_V(8); PG8_WAIT_L(0); PG8_BAR; PG8_MMA(1, 0, At, B0); PG8_MMA(1, 1, At, B1); PG8_BAR; PG8_SCHED;
;             PG8_LDB(B0, 1, 0); PG8_LDB(B1, 1, 1); PG8_SCHED; PG8_LDA(At, 1, 0); PG8_STAGE(PG8_SA(0, 1), a2 + hstepA, voffA);
;             PG8_WAIT_V(8); PG8_WAIT_L(0); PG8_BAR; PG8_MMA(0, 0, At, B0); PG8_MMA(0, 1, At, B1); PG8_BAR; PG8_SCHED;
;             PG8_LDA(At, 1, 1); PG8_STAGE(PG8_SB(1, 0), b3, voffB); PG8_STAGE(PG8_SB(1, 1), b3 + hstepB, voffB); PG8_STAGE(PG8_SA(1, 0), a3, voffA);
	s_setprio 1
	s_waitcnt lgkmcnt(0)
	v_mfma_f32_16x16x32_bf16 v[128:131], v[132:135], v[178:181], v[128:131]
	v_mfma_f32_16x16x32_bf16 v[124:127], v[140:143], v[178:181], v[124:127]
	v_mfma_f32_16x16x32_bf16 v[112:115], v[132:135], v[186:189], v[112:115]
	v_mfma_f32_16x16x32_bf16 v[108:111], v[140:143], v[186:189], v[108:111]
	v_mfma_f32_16x16x32_bf16 v[96:99], v[132:135], v[206:209], v[96:99]
	v_mfma_f32_16x16x32_bf16 v[92:95], v[140:143], v[206:209], v[92:95]
	v_mfma_f32_16x16x32_bf16 v[80:83], v[132:135], v[214:217], v[80:83]
	v_mfma_f32_16x16x32_bf16 v[76:79], v[140:143], v[214:217], v[76:79]
	v_mfma_f32_16x16x32_bf16 v[128:131], v[136:139], v[182:185], v[128:131]
	v_mfma_f32_16x16x32_bf16 v[124:127], v[144:147], v[182:185], v[124:127]
	v_mfma_f32_16x16x32_bf16 v[112:115], v[136:139], v[202:205], v[112:115]
	v_mfma_f32_16x16x32_bf16 v[108:111], v[144:147], v[202:205], v[108:111]
	v_mfma_f32_16x16x32_bf16 v[96:99], v[136:139], v[210:213], v[96:99]
	v_mfma_f32_16x16x32_bf16 v[92:95], v[144:147], v[210:213], v[92:95]
	v_mfma_f32_16x16x32_bf16 v[80:83], v[136:139], v[218:221], v[80:83]
	v_mfma_f32_16x16x32_bf16 v[76:79], v[144:147], v[218:221], v[76:79]
	s_setprio 0
	s_setprio 1
	v_mfma_f32_16x16x32_bf16 v[120:123], v[148:151], v[178:181], v[120:123]
	v_mfma_f32_16x16x32_bf16 v[116:119], v[156:159], v[178:181], v[116:119]
	v_mfma_f32_16x16x32_bf16 v[104:107], v[148:151], v[186:189], v[104:107]
	v_mfma_f32_16x16x32_bf16 v[100:103], v[156:159], v[186:189], v[100:103]
	v_mfma_f32_16x16x32_bf16 v[88:91], v[148:151], v[206:209], v[88:91]
	v_mfma_f32_16x16x32_bf16 v[84:87], v[156:159], v[206:209], v[84:87]
	v_mfma_f32_16x16x32_bf16 v[72:75], v[148:151], v[214:217], v[72:75]
	v_mfma_f32_16x16x32_bf16 v[68:71], v[156:159], v[214:217], v[68:71]
	v_mfma_f32_16x16x32_bf16 v[120:123], v[152:155], v[182:185], v[120:123]
	v_mfma_f32_16x16x32_bf16 v[116:119], v[174:177], v[182:185], v[116:119]
	v_mfma_f32_16x16x32_bf16 v[104:107], v[152:155], v[202:205], v[104:107]
	v_mfma_f32_16x16x32_bf16 v[100:103], v[174:177], v[202:205], v[100:103]
	v_mfma_f32_16x16x32_bf16 v[88:91], v[152:155], v[210:213], v[88:91]
	v_mfma_f32_16x16x32_bf16 v[84:87], v[174:177], v[210:213], v[84:87]
	v_mfma_f32_16x16x32_bf16 v[72:75], v[152:155], v[218:221], v[72:75]
	v_mfma_f32_16x16x32_bf16 v[68:71], v[174:177], v[218:221], v[68:71]
	s_setprio 0
	s_barrier
	s_add_i32 s62, s62, s40
	v_lshl_add_u64 v[190:191], s[26:27], 0, v[164:165]
	s_mov_b32 m0, s62
	ds_read_b128 v[178:181], v193 offset:16384
	ds_read_b128 v[182:185], v193 offset:17408
	ds_read_b128 v[186:189], v193 offset:18432
	ds_read_b128 v[202:205], v193 offset:19456
	ds_read_b128 v[206:209], v193 offset:20480
	ds_read_b128 v[210:213], v193 offset:21504
	ds_read_b128 v[214:217], v193 offset:22528
	ds_read_b128 v[218:221], v193 offset:23552
	global_load_lds_dwordx4 v[190:191], off
	s_add_i32 m0, s62, 0x2000
	s_add_u32 s62, s26, 0x40000
	v_lshl_add_u64 v[194:195], s[26:27], 0, v[168:169]
	s_addc_u32 s63, s27, 0
	s_add_i32 s64, s64, s40
	global_load_lds_dwordx4 v[194:195], off
	v_lshl_add_u64 v[222:223], s[62:63], 0, v[164:165]
	s_mov_b32 m0, s64
	v_lshl_add_u64 v[224:225], s[28:29], 0, v[166:167]
	global_load_lds_dwordx4 v[222:223], off
	v_lshl_add_u64 v[222:223], s[62:63], 0, v[168:169]
	s_add_i32 m0, s64, 0x2000
	s_nop 0
	global_load_lds_dwordx4 v[222:223], off
	v_lshl_add_u64 v[222:223], s[28:29], 0, v[162:163]
	s_mov_b32 m0, s41
	s_nop 0
	global_load_lds_dwordx4 v[222:223], off
	s_mov_b32 m0, s42
	s_nop 0
	global_load_lds_dwordx4 v[224:225], off
	s_waitcnt vmcnt(8)
	s_waitcnt lgkmcnt(0)
	s_barrier
	s_setprio 1
	s_waitcnt lgkmcnt(0)
	v_mfma_f32_16x16x32_bf16 v[64:67], v[132:135], v[178:181], v[64:67]
	v_mfma_f32_16x16x32_bf16 v[60:63], v[140:143], v[178:181], v[60:63]
	v_mfma_f32_16x16x32_bf16 v[48:51], v[132:135], v[186:189], v[48:51]
	v_mfma_f32_16x16x32_bf16 v[44:47], v[140:143], v[186:189], v[44:47]
	v_mfma_f32_16x16x32_bf16 v[32:35], v[132:135], v[206:209], v[32:35]
	v_mfma_f32_16x16x32_bf16 v[28:31], v[140:143], v[206:209], v[28:31]
	v_mfma_f32_16x16x32_bf16 v[16:19], v[132:135], v[214:217], v[16:19]
	v_mfma_f32_16x16x32_bf16 v[12:15], v[140:143], v[214:217], v[12:15]
	v_mfma_f32_16x16x32_bf16 v[64:67], v[136:139], v[182:185], v[64:67]
	v_mfma_f32_16x16x32_bf16 v[60:63], v[144:147], v[182:185], v[60:63]
	v_mfma_f32_16x16x32_bf16 v[48:51], v[136:139], v[202:205], v[48:51]
	v_mfma_f32_16x16x32_bf16 v[44:47], v[144:147], v[202:205], v[44:47]
	v_mfma_f32_16x16x32_bf16 v[32:35], v[136:139], v[210:213], v[32:35]
	v_mfma_f32_16x16x32_bf16 v[28:31], v[144:147], v[210:213], v[28:31]
	v_mfma_f32_16x16x32_bf16 v[16:19], v[136:139], v[218:221], v[16:19]
	v_mfma_f32_16x16x32_bf16 v[12:15], v[144:147], v[218:221], v[12:15]
	s_setprio 0
	s_setprio 1
	v_mfma_f32_16x16x32_bf16 v[56:59], v[148:151], v[178:181], v[56:59]
	v_mfma_f32_16x16x32_bf16 v[52:55], v[156:159], v[178:181], v[52:55]
	v_mfma_f32_16x16x32_bf16 v[40:43], v[148:151], v[186:189], v[40:43]
	v_mfma_f32_16x16x32_bf16 v[36:39], v[156:159], v[186:189], v[36:39]
	v_mfma_f32_16x16x32_bf16 v[24:27], v[148:151], v[206:209], v[24:27]
	v_mfma_f32_16x16x32_bf16 v[20:23], v[156:159], v[206:209], v[20:23]
	v_mfma_f32_16x16x32_bf16 v[8:11], v[148:151], v[214:217], v[8:11]
	v_mfma_f32_16x16x32_bf16 v[4:7], v[156:159], v[214:217], v[4:7]
	v_mfma_f32_16x16x32_bf16 v[56:59], v[152:155], v[182:185], v[56:59]
	v_mfma_f32_16x16x32_bf16 v[52:55], v[174:177], v[182:185], v[52:55]
	v_mfma_f32_16x16x32_bf16 v[40:43], v[152:155], v[202:205], v[40:43]
	v_mfma_f32_16x16x32_bf16 v[36:39], v[174:177], v[202:205], v[36:39]
	v_mfma_f32_16x16x32_bf16 v[24:27], v[152:155], v[210:213], v[24:27]
	v_mfma_f32_16x16x32_bf16 v[20:23], v[174:177], v[210:213], v[20:23]
	v_mfma_f32_16x16x32_bf16 v[8:11], v[152:155], v[218:221], v[8:11]
	v_mfma_f32_16x16x32_bf16 v[4:7], v[174:177], v[218:221], v[4:7]
	s_setprio 0
	s_barrier
; #define PG8_STAGE(bufoff, gbase, voff) do { _Pragma("unroll") for (int _i = 0; _i < 2; ++_i) \
;         __builtin_amdgcn_global_load_lds((const unsigned*)((const char*)(gbase) + (voff)[_i]), (LAS unsigned*)(lds + (bufoff) + ldsw + _i * 8192), 16, 0, 0); } while (0)
; #define PG8_LDA(dst, b, h) do { _Pragma("unroll") for (int m = 0; m < 4; ++m) _Pragma("unroll") for (int k = 0; k < 2; ++k) dst[m][k] = *(const LAS bf16x8*)(lds + PG8_SA(b, h) + aoff + m * 2048 + k * 1024); } while (0)
; #define PG8_LDB(dst, b, h) do { _Pragma("unroll") for (int n = 0; n < 2; ++n) _Pragma("unroll") for (int k = 0; k < 2; ++k) dst[n][k] = *(const LAS bf16x8*)(lds + PG8_SB(b, h) + boff + n * 2048 + k * 1024); } while (0)
; #define PG8_MMA(ai, bj, At, Bt) do { __builtin_amdgcn_s_setprio(1); _Pragma("unroll") for (int m = 0; m < 4; ++m) _Pragma("unroll") for (int n = 0; n < 2; ++n) _Pragma("unroll") for (int k = 0; k < 2; ++k) \
;         acc[ai][bj][m][n] = __builtin_amdgcn_mfma_f32_16x16x32_bf16(Bt[n][k], At[m][k], acc[ai][bj][m][n], 0, 0, 0); __builtin_amdgcn_s_setprio(0); } while (0)
; #define PG8_WAIT_V(n) asm volatile("s_waitcnt vmcnt(" #n ")" ::: "memory")
; #define PG8_WAIT_L(n) asm volatile("s_waitcnt lgkmcnt(" #n ")" ::: "memory")
; #define PG8_BAR __builtin_amdgcn_s_barrier()
; #define PG8_SCHED __builtin_amdgcn_sched_barrier(0)
; template <class Epi, bool ALIGN_EPI>
; DI void gemm_phase(LAS unsigned char* lds, const Sched& S, const Epi& E, int tid) {
;     ...
;             PG8_LDB(B0, 1, 0); PG8_LDB(B1, 1, 1); PG8_SCHED; PG8_LDA(At, 1, 0); PG8_STAGE(PG8_SA(0, 1), a2 + hstepA, voffA);
;             PG8_WAIT_V(8); PG8_WAIT_L(0); PG8_BAR; PG8_MMA(0, 0, At, B0); PG8_MMA(0, 1, At, B1); PG8_BAR; PG8_SCHED;
	s_add_i32 s62, 0, 0x18000
	s_add_i32 s63, 0, 0x1c000
	v_add_u32_e32 v144, s62, v161
	v_add_u32_e32 v174, s63, v161
	ds_read_b128 v[132:135], v144
	ds_read_b128 v[136:139], v144 offset:1024
	ds_read_b128 v[140:143], v144 offset:2048
	ds_read_b128 v[144:147], v144 offset:3072
	ds_read_b128 v[148:151], v174
	ds_read_b128 v[152:155], v174 offset:1024
	ds_read_b128 v[156:159], v174 offset:2048
	ds_read_b128 v[174:177], v174 offset:3072
	s_add_u32 s28, s28, 0x40000
	s_addc_u32 s29, s29, 0
	s_mov_b32 m0, s43
	v_lshl_add_u64 v[226:227], s[28:29], 0, v[162:163]
	ds_read_b128 v[178:181], v193 offset:32768
	ds_read_b128 v[182:185], v193 offset:33792
	ds_read_b128 v[186:189], v193 offset:34816
	ds_read_b128 v[202:205], v193 offset:35840
	ds_read_b128 v[206:209], v193 offset:36864
	ds_read_b128 v[210:213], v193 offset:37888
	ds_read_b128 v[214:217], v193 offset:38912
	ds_read_b128 v[218:221], v193 offset:39936
	global_load_lds_dwordx4 v[226:227], off
	v_lshl_add_u64 v[226:227], s[28:29], 0, v[166:167]
	s_mov_b32 m0, s44
	s_nop 0
	global_load_lds_dwordx4 v[226:227], off
	s_waitcnt vmcnt(8)
	s_waitcnt lgkmcnt(0)
	s_barrier
	s_setprio 1
	s_waitcnt lgkmcnt(0)
	v_mfma_f32_16x16x32_bf16 v[128:131], v[132:135], v[178:181], v[128:131]
	v_mfma_f32_16x16x32_bf16 v[124:127], v[140:143], v[178:181], v[124:127]
	v_mfma_f32_16x16x32_bf16 v[112:115], v[132:135], v[186:189], v[112:115]
	v_mfma_f32_16x16x32_bf16 v[108:111], v[140:143], v[186:189], v[108:111]
	v_mfma_f32_16x16x32_bf16 v[96:99], v[132:135], v[206:209], v[96:99]
	v_mfma_f32_16x16x32_bf16 v[92:95], v[140:143], v[206:209], v[92:95]
	v_mfma_f32_16x16x32_bf16 v[80:83], v[132:135], v[214:217], v[80:83]
	v_mfma_f32_16x16x32_bf16 v[76:79], v[140:143], v[214:217], v[76:79]
	v_mfma_f32_16x16x32_bf16 v[128:131], v[136:139], v[182:185], v[128:131]
	v_mfma_f32_16x16x32_bf16 v[124:127], v[144:147], v[182:185], v[124:127]
	v_mfma_f32_16x16x32_bf16 v[112:115], v[136:139], v[202:205], v[112:115]
	v_mfma_f32_16x16x32_bf16 v[108:111], v[144:147], v[202:205], v[108:111]
	v_mfma_f32_16x16x32_bf16 v[96:99], v[136:139], v[210:213], v[96:99]
	v_mfma_f32_16x16x32_bf16 v[92:95], v[144:147], v[210:213], v[92:95]
	v_mfma_f32_16x16x32_bf16 v[80:83], v[136:139], v[218:221], v[80:83]
	v_mfma_f32_16x16x32_bf16 v[76:79], v[144:147], v[218:221], v[76:79]
	s_setprio 0
	s_setprio 1
	v_mfma_f32_16x16x32_bf16 v[120:123], v[148:151], v[178:181], v[120:123]
	v_mfma_f32_16x16x32_bf16 v[116:119], v[156:159], v[178:181], v[116:119]
	v_mfma_f32_16x16x32_bf16 v[104:107], v[148:151], v[186:189], v[104:107]
	v_mfma_f32_16x16x32_bf16 v[100:103], v[156:159], v[186:189], v[100:103]
	v_mfma_f32_16x16x32_bf16 v[88:91], v[148:151], v[206:209], v[88:91]
	v_mfma_f32_16x16x32_bf16 v[84:87], v[156:159], v[206:209], v[84:87]
	v_mfma_f32_16x16x32_bf16 v[72:75], v[148:151], v[214:217], v[72:75]
	v_mfma_f32_16x16x32_bf16 v[68:71], v[156:159], v[214:217], v[68:71]
	v_mfma_f32_16x16x32_bf16 v[120:123], v[152:155], v[182:185], v[120:123]
	v_mfma_f32_16x16x32_bf16 v[116:119], v[174:177], v[182:185], v[116:119]
	v_mfma_f32_16x16x32_bf16 v[104:107], v[152:155], v[202:205], v[104:107]
	v_mfma_f32_16x16x32_bf16 v[100:103], v[174:177], v[202:205], v[100:103]
	v_mfma_f32_16x16x32_bf16 v[88:91], v[152:155], v[210:213], v[88:91]
	v_mfma_f32_16x16x32_bf16 v[84:87], v[174:177], v[210:213], v[84:87]
	v_mfma_f32_16x16x32_bf16 v[72:75], v[152:155], v[218:221], v[72:75]
	v_mfma_f32_16x16x32_bf16 v[68:71], v[174:177], v[218:221], v[68:71]
	s_setprio 0
	s_barrier
; #define PG8_STAGE(bufoff, gbase, voff) do { _Pragma("unroll") for (int _i = 0; _i < 2; ++_i) \
;         __builtin_amdgcn_global_load_lds((const unsigned*)((const char*)(gbase) + (voff)[_i]), (LAS unsigned*)(lds + (bufoff) + ldsw + _i * 8192), 16, 0, 0); } while (0)
; #define PG8_LDA(dst, b, h) do { _Pragma("unroll") for (int m = 0; m < 4; ++m) _Pragma("unroll") for (int k = 0; k < 2; ++k) dst[m][k] = *(const LAS bf16x8*)(lds + PG8_SA(b, h) + aoff + m * 2048 + k * 1024); } while (0)
; #define PG8_MMA(ai, bj, At, Bt) do { __builtin_amdgcn_s_setprio(1); _Pragma("unroll") for (int m = 0; m < 4; ++m) _Pragma("unroll") for (int n = 0; n < 2; ++n) _Pragma("unroll") for (int k = 0; k < 2; ++k) \
;         acc[ai][bj][m][n] = __builtin_amdgcn_mfma_f32_16x16x32_bf16(Bt[n][k], At[m][k], acc[ai][bj][m][n], 0, 0, 0); __builtin_amdgcn_s_setprio(0); } while (0)
; #define PG8_WAIT_V(n) asm volatile("s_waitcnt vmcnt(" #n ")" ::: "memory")
; #define PG8_WAIT_L(n) asm volatile("s_waitcnt lgkmcnt(" #n ")" ::: "memory")
; #define PG8_BAR __builtin_amdgcn_s_barrier()
; #define PG8_SCHED __builtin_amdgcn_sched_barrier(0)
; template <class Epi, bool ALIGN_EPI>
; DI void gemm_phase(LAS unsigned char* lds, const Sched& S, const Epi& E, int tid) {
;     ...
;             PG8_LDA(At, 1, 1); PG8_STAGE(PG8_SB(1, 0), b3, voffB); PG8_STAGE(PG8_SB(1, 1), b3 + hstepB, voffB); PG8_STAGE(PG8_SA(1, 0), a3, voffA);
;             PG8_WAIT_V(8); PG8_WAIT_L(0); PG8_BAR; PG8_MMA(1, 0, At, B0); PG8_MMA(1, 1, At, B1); PG8_BAR; PG8_SCHED;
;         }
;         if constexpr (ALIGN_EPI) { if (wr == 0) PG8_BAR; }
	s_add_i32 s28, s62, s40
	v_lshl_add_u64 v[190:191], v[190:191], 0, s[84:85]
	s_mov_b32 m0, s28
	ds_read_b128 v[178:181], v193 offset:49152
	ds_read_b128 v[182:185], v193 offset:50176
	ds_read_b128 v[186:189], v193 offset:51200
	ds_read_b128 v[202:205], v193 offset:52224
	ds_read_b128 v[206:209], v193 offset:53248
	ds_read_b128 v[210:213], v193 offset:54272
	ds_read_b128 v[214:217], v193 offset:55296
	ds_read_b128 v[218:221], v193 offset:56320
	global_load_lds_dwordx4 v[190:191], off
	s_add_i32 m0, s28, 0x2000
	s_add_u32 s26, s26, 0x40080
	v_lshl_add_u64 v[190:191], v[194:195], 0, s[84:85]
	s_addc_u32 s27, s27, 0
	s_add_i32 s28, s63, s40
	global_load_lds_dwordx4 v[190:191], off
	v_lshl_add_u64 v[190:191], s[26:27], 0, v[164:165]
	s_mov_b32 m0, s28
	s_nop 0
	global_load_lds_dwordx4 v[190:191], off
	v_lshl_add_u64 v[190:191], s[26:27], 0, v[168:169]
	s_add_i32 m0, s28, 0x2000
	s_nop 0
	global_load_lds_dwordx4 v[190:191], off
	v_lshl_add_u64 v[190:191], v[222:223], 0, s[84:85]
	s_mov_b32 m0, s46
	s_nop 0
	global_load_lds_dwordx4 v[190:191], off
	v_lshl_add_u64 v[190:191], v[224:225], 0, s[84:85]
	s_mov_b32 m0, s47
	s_nop 0
	global_load_lds_dwordx4 v[190:191], off
	s_waitcnt vmcnt(8)
	s_waitcnt lgkmcnt(0)
	s_barrier
	s_setprio 1
	s_waitcnt lgkmcnt(0)
	v_mfma_f32_16x16x32_bf16 v[64:67], v[132:135], v[178:181], v[64:67]
	v_mfma_f32_16x16x32_bf16 v[60:63], v[140:143], v[178:181], v[60:63]
	v_mfma_f32_16x16x32_bf16 v[48:51], v[132:135], v[186:189], v[48:51]
	v_mfma_f32_16x16x32_bf16 v[44:47], v[140:143], v[186:189], v[44:47]
	v_mfma_f32_16x16x32_bf16 v[32:35], v[132:135], v[206:209], v[32:35]
	v_mfma_f32_16x16x32_bf16 v[28:31], v[140:143], v[206:209], v[28:31]
	v_mfma_f32_16x16x32_bf16 v[16:19], v[132:135], v[214:217], v[16:19]
	v_mfma_f32_16x16x32_bf16 v[12:15], v[140:143], v[214:217], v[12:15]
	v_mfma_f32_16x16x32_bf16 v[64:67], v[136:139], v[182:185], v[64:67]
	v_mfma_f32_16x16x32_bf16 v[60:63], v[144:147], v[182:185], v[60:63]
	v_mfma_f32_16x16x32_bf16 v[48:51], v[136:139], v[202:205], v[48:51]
	v_mfma_f32_16x16x32_bf16 v[44:47], v[144:147], v[202:205], v[44:47]
	v_mfma_f32_16x16x32_bf16 v[32:35], v[136:139], v[210:213], v[32:35]
	v_mfma_f32_16x16x32_bf16 v[28:31], v[144:147], v[210:213], v[28:31]
	v_mfma_f32_16x16x32_bf16 v[16:19], v[136:139], v[218:221], v[16:19]
	v_mfma_f32_16x16x32_bf16 v[12:15], v[144:147], v[218:221], v[12:15]
	s_setprio 0
	s_setprio 1
	v_mfma_f32_16x16x32_bf16 v[56:59], v[148:151], v[178:181], v[56:59]
	v_mfma_f32_16x16x32_bf16 v[52:55], v[156:159], v[178:181], v[52:55]
	v_mfma_f32_16x16x32_bf16 v[40:43], v[148:151], v[186:189], v[40:43]
	v_mfma_f32_16x16x32_bf16 v[36:39], v[156:159], v[186:189], v[36:39]
	v_mfma_f32_16x16x32_bf16 v[24:27], v[148:151], v[206:209], v[24:27]
	v_mfma_f32_16x16x32_bf16 v[20:23], v[156:159], v[206:209], v[20:23]
	v_mfma_f32_16x16x32_bf16 v[8:11], v[148:151], v[214:217], v[8:11]
	v_mfma_f32_16x16x32_bf16 v[4:7], v[156:159], v[214:217], v[4:7]
	v_mfma_f32_16x16x32_bf16 v[56:59], v[152:155], v[182:185], v[56:59]
	v_mfma_f32_16x16x32_bf16 v[52:55], v[174:177], v[182:185], v[52:55]
	v_mfma_f32_16x16x32_bf16 v[40:43], v[152:155], v[202:205], v[40:43]
	v_mfma_f32_16x16x32_bf16 v[36:39], v[174:177], v[202:205], v[36:39]
	v_mfma_f32_16x16x32_bf16 v[24:27], v[152:155], v[210:213], v[24:27]
	v_mfma_f32_16x16x32_bf16 v[20:23], v[174:177], v[210:213], v[20:23]
	v_mfma_f32_16x16x32_bf16 v[8:11], v[152:155], v[218:221], v[8:11]
	v_mfma_f32_16x16x32_bf16 v[4:7], v[174:177], v[218:221], v[4:7]
	s_setprio 0
	s_add_u32 s24, s24, 0x100
	s_addc_u32 s25, s25, 0
	s_add_u32 s59, s59, 0x100
	s_addc_u32 s60, s60, 0
	s_cmp_ge_i32 s61, s23
	s_mov_b32 s26, s61
	s_cbranch_scc1 .Lkx_4
	s_add_i32 s61, s26, 2
	s_add_u32 s27, s24, 0xfffc0080
	s_addc_u32 s28, s25, -1
	s_add_i32 s62, 0, 0x10000
	s_cmp_eq_u32 s58, s26
	s_cselect_b32 s29, s54, s28
	s_cselect_b32 s28, s55, s27
	s_cselect_b32 s27, s56, s60
	s_cselect_b32 s26, s57, s59
	s_add_i32 s64, 0, 0x14000
	v_add_u32_e32 v144, s62, v161
	v_add_u32_e32 v174, s64, v161
	s_barrier
	s_branch .LBB0_1765

; #define PG8_STAGE(bufoff, gbase, voff) do { _Pragma("unroll") for (int _i = 0; _i < 2; ++_i) \
;         __builtin_amdgcn_global_load_lds((const unsigned*)((const char*)(gbase) + (voff)[_i]), (LAS unsigned*)(lds + (bufoff) + ldsw + _i * 8192), 16, 0, 0); } while (0)
; #define PG8_LDA(dst, b, h) do { _Pragma("unroll") for (int m = 0; m < 4; ++m) _Pragma("unroll") for (int k = 0; k < 2; ++k) dst[m][k] = *(const LAS bf16x8*)(lds + PG8_SA(b, h) + aoff + m * 2048 + k * 1024); } while (0)
; #define PG8_LDB(dst, b, h) do { _Pragma("unroll") for (int n = 0; n < 2; ++n) _Pragma("unroll") for (int k = 0; k < 2; ++k) dst[n][k] = *(const LAS bf16x8*)(lds + PG8_SB(b, h) + boff + n * 2048 + k * 1024); } while (0)
; #define PG8_MMA(ai, bj, At, Bt) do { __builtin_amdgcn_s_setprio(1); _Pragma("unroll") for (int m = 0; m < 4; ++m) _Pragma("unroll") for (int n = 0; n < 2; ++n) _Pragma("unroll") for (int k = 0; k < 2; ++k) \
;         acc[ai][bj][m][n] = __builtin_amdgcn_mfma_f32_16x16x32_bf16(Bt[n][k], At[m][k], acc[ai][bj][m][n], 0, 0, 0); __builtin_amdgcn_s_setprio(0); } while (0)
; #define PG8_WAIT_V(n) asm volatile("s_waitcnt vmcnt(" #n ")" ::: "memory")
; #define PG8_BAR __builtin_amdgcn_s_barrier()
; template <class Epi, bool ALIGN_EPI>
; DI void gemm_phase(LAS unsigned char* lds, const Sched& S, const Epi& E, int tid) {
;     ...
;         const bool has_next = S.next(ui + 1, nxt);
;         const char* nA = has_next ? nxt.a : cA; const char* nB = has_next ? nxt.b : cB;
;         const int nt = cur.nt;
;         for (int t = 0; t < nt; t += 2) {
;             const bool last = (t == nt - 2);
;             const char* a1 = cA + (size_t)(t + 1) * kstep;
;             const char* a2 = last ? nA : cA + (size_t)(t + 2) * kstep; const char* b2 = last ? nB : cB + (size_t)(t + 2) * kstep;
;             const char* a3 = a2 + kstep; const char* b3 = b2 + kstep;
;             PG8_LDB(B0, 0, 0); PG8_LDB(B1, 0, 1); PG8_SCHED; PG8_LDA(At, 0, 0); PG8_STAGE(PG8_SA(1, 1), a1 + hstepA, voffA);
;             PG8_WAIT_V(8); PG8_WAIT_L(0); PG8_BAR; PG8_MMA(0, 0, At, B0); PG8_MMA(0, 1, At, B1); PG8_BAR; PG8_SCHED;
;             PG8_LDA(At, 0, 1); PG8_STAGE(PG8_SB(0, 0), b2, voffB); PG8_STAGE(PG8_SB(0, 1), b2 + hstepB, voffB); PG8_STAGE(PG8_SA(0, 0), a2, voffA);
;             PG8_WAIT_V(8); PG8_WAIT_L(0); PG8_BAR; PG8_MMA(1, 0, At, B0); PG8_MMA(1, 1, At, B1); PG8_BAR; PG8_SCHED;
.LBB0_1960:
	s_add_u32 s22, s22, 0x40080
	s_addc_u32 s23, s23, 0
	s_add_u32 s45, s24, 0x100
	s_addc_u32 s46, s25, 0
	s_mov_b32 s47, -2
	s_add_u32 s24, s22, 0xfffc0080
	s_addc_u32 s25, s23, -1
	s_add_i32 s48, 0, 0x10000
	s_cmp_eq_u32 s47, 12
	s_cselect_b32 s27, s19, s25
	s_cselect_b32 s26, s18, s24
	v_add_u32_e32 v161, s48, v144
	s_cselect_b32 s25, s21, s46
	s_cselect_b32 s24, s20, s45
	s_add_i32 s50, 0, 0x14000
	ds_read_b128 v[148:151], v161
	ds_read_b128 v[152:155], v161 offset:1024
	ds_read_b128 v[156:159], v161 offset:2048
	ds_read_b128 v[162:165], v161 offset:3072
	v_add_u32_e32 v161, s50, v144
	ds_read_b128 v[166:169], v161
	ds_read_b128 v[170:173], v161 offset:1024
	ds_read_b128 v[174:177], v161 offset:2048
	ds_read_b128 v[178:181], v161 offset:3072
	v_lshl_add_u64 v[194:195], s[22:23], 0, v[140:141]
	s_add_i32 m0, s17, 0xc000
	ds_read_b128 v[182:185], v147
	ds_read_b128 v[186:189], v147 offset:1024
	ds_read_b128 v[190:193], v147 offset:2048
	ds_read_b128 v[202:205], v147 offset:3072
	ds_read_b128 v[206:209], v147 offset:4096
	ds_read_b128 v[210:213], v147 offset:5120
	ds_read_b128 v[214:217], v147 offset:6144
	ds_read_b128 v[218:221], v147 offset:7168
	global_load_lds_dwordx4 v[194:195], off
	v_lshl_add_u64 v[194:195], s[22:23], 0, v[142:143]
	s_add_i32 m0, s17, 0xe000
	s_nop 0
	global_load_lds_dwordx4 v[194:195], off
	s_waitcnt vmcnt(8)
	s_waitcnt lgkmcnt(0)
	s_barrier
	s_setprio 1
	s_waitcnt lgkmcnt(0)
	v_mfma_f32_16x16x32_bf16 v[128:131], v[148:151], v[182:185], 0
	v_mfma_f32_16x16x32_bf16 v[124:127], v[156:159], v[182:185], 0
	v_mfma_f32_16x16x32_bf16 v[120:123], v[148:151], v[190:193], 0
	v_mfma_f32_16x16x32_bf16 v[112:115], v[156:159], v[190:193], 0
	v_mfma_f32_16x16x32_bf16 v[100:103], v[148:151], v[206:209], 0
	v_mfma_f32_16x16x32_bf16 v[92:95], v[156:159], v[206:209], 0
	v_mfma_f32_16x16x32_bf16 v[88:91], v[148:151], v[214:217], 0
	v_mfma_f32_16x16x32_bf16 v[80:83], v[156:159], v[214:217], 0
	v_mfma_f32_16x16x32_bf16 v[128:131], v[152:155], v[186:189], v[128:131]
	v_mfma_f32_16x16x32_bf16 v[124:127], v[162:165], v[186:189], v[124:127]
	v_mfma_f32_16x16x32_bf16 v[120:123], v[152:155], v[202:205], v[120:123]
	v_mfma_f32_16x16x32_bf16 v[112:115], v[162:165], v[202:205], v[112:115]
	v_mfma_f32_16x16x32_bf16 v[100:103], v[152:155], v[210:213], v[100:103]
	v_mfma_f32_16x16x32_bf16 v[92:95], v[162:165], v[210:213], v[92:95]
	v_mfma_f32_16x16x32_bf16 v[88:91], v[152:155], v[218:221], v[88:91]
	v_mfma_f32_16x16x32_bf16 v[80:83], v[162:165], v[218:221], v[80:83]
	s_setprio 0
	s_setprio 1
	v_mfma_f32_16x16x32_bf16 v[116:119], v[166:169], v[182:185], 0
	v_mfma_f32_16x16x32_bf16 v[108:111], v[174:177], v[182:185], 0
	v_mfma_f32_16x16x32_bf16 v[104:107], v[166:169], v[190:193], 0
	v_mfma_f32_16x16x32_bf16 v[96:99], v[174:177], v[190:193], 0
	v_mfma_f32_16x16x32_bf16 v[84:87], v[166:169], v[206:209], 0
	v_mfma_f32_16x16x32_bf16 v[76:79], v[174:177], v[206:209], 0
	v_mfma_f32_16x16x32_bf16 v[72:75], v[166:169], v[214:217], 0
	v_mfma_f32_16x16x32_bf16 v[68:71], v[174:177], v[214:217], 0
	v_mfma_f32_16x16x32_bf16 v[116:119], v[170:173], v[186:189], v[116:119]
	v_mfma_f32_16x16x32_bf16 v[108:111], v[178:181], v[186:189], v[108:111]
	v_mfma_f32_16x16x32_bf16 v[104:107], v[170:173], v[202:205], v[104:107]
	v_mfma_f32_16x16x32_bf16 v[96:99], v[178:181], v[202:205], v[96:99]
	v_mfma_f32_16x16x32_bf16 v[84:87], v[170:173], v[210:213], v[84:87]
	v_mfma_f32_16x16x32_bf16 v[76:79], v[178:181], v[210:213], v[76:79]
	v_mfma_f32_16x16x32_bf16 v[72:75], v[170:173], v[218:221], v[72:75]
	v_mfma_f32_16x16x32_bf16 v[68:71], v[178:181], v[218:221], v[68:71]
	s_setprio 0
	s_barrier
	s_add_i32 s48, s48, s28
	v_lshl_add_u64 v[194:195], s[24:25], 0, v[136:137]
	s_mov_b32 m0, s48
	ds_read_b128 v[182:185], v147 offset:16384
	ds_read_b128 v[186:189], v147 offset:17408
	ds_read_b128 v[190:193], v147 offset:18432
	ds_read_b128 v[202:205], v147 offset:19456
	ds_read_b128 v[206:209], v147 offset:20480
	ds_read_b128 v[210:213], v147 offset:21504
	ds_read_b128 v[214:217], v147 offset:22528
	ds_read_b128 v[218:221], v147 offset:23552
	global_load_lds_dwordx4 v[194:195], off
	s_add_i32 m0, s48, 0x2000
	s_add_u32 s48, s24, 0x40000
	v_lshl_add_u64 v[222:223], s[24:25], 0, v[132:133]
	s_addc_u32 s49, s25, 0
	s_add_i32 s50, s50, s28
	global_load_lds_dwordx4 v[222:223], off
	v_lshl_add_u64 v[224:225], s[48:49], 0, v[136:137]
	s_mov_b32 m0, s50
	v_lshl_add_u64 v[226:227], s[26:27], 0, v[134:135]
	global_load_lds_dwordx4 v[224:225], off
	v_lshl_add_u64 v[224:225], s[48:49], 0, v[132:133]
	s_add_i32 m0, s50, 0x2000
	s_nop 0
	global_load_lds_dwordx4 v[224:225], off
	v_lshl_add_u64 v[224:225], s[26:27], 0, v[138:139]
	s_mov_b32 m0, s17
	s_nop 0
	global_load_lds_dwordx4 v[224:225], off
	s_mov_b32 m0, s36
	s_nop 0
	global_load_lds_dwordx4 v[226:227], off
	s_waitcnt vmcnt(8)
	s_waitcnt lgkmcnt(0)
	s_barrier
; #define PG8_STAGE(bufoff, gbase, voff) do { _Pragma("unroll") for (int _i = 0; _i < 2; ++_i) \
;         __builtin_amdgcn_global_load_lds((const unsigned*)((const char*)(gbase) + (voff)[_i]), (LAS unsigned*)(lds + (bufoff) + ldsw + _i * 8192), 16, 0, 0); } while (0)
; #define PG8_LDA(dst, b, h) do { _Pragma("unroll") for (int m = 0; m < 4; ++m) _Pragma("unroll") for (int k = 0; k < 2; ++k) dst[m][k] = *(const LAS bf16x8*)(lds + PG8_SA(b, h) + aoff + m * 2048 + k * 1024); } while (0)
; #define PG8_LDB(dst, b, h) do { _Pragma("unroll") for (int n = 0; n < 2; ++n) _Pragma("unroll") for (int k = 0; k < 2; ++k) dst[n][k] = *(const LAS bf16x8*)(lds + PG8_SB(b, h) + boff + n * 2048 + k * 1024); } while (0)
; #define PG8_MMA(ai, bj, At, Bt) do { __builtin_amdgcn_s_setprio(1); _Pragma("unroll") for (int m = 0; m < 4; ++m) _Pragma("unroll") for (int n = 0; n < 2; ++n) _Pragma("unroll") for (int k = 0; k < 2; ++k) \
;         acc[ai][bj][m][n] = __builtin_amdgcn_mfma_f32_16x16x32_bf16(Bt[n][k], At[m][k], acc[ai][bj][m][n], 0, 0, 0); __builtin_amdgcn_s_setprio(0); } while (0)
; #define PG8_WAIT_V(n) asm volatile("s_waitcnt vmcnt(" #n ")" ::: "memory")
; #define PG8_WAIT_L(n) asm volatile("s_waitcnt lgkmcnt(" #n ")" ::: "memory")
; #define PG8_BAR __builtin_amdgcn_s_barrier()
; #define PG8_SCHED __builtin_amdgcn_sched_barrier(0)
; template <class Epi, bool ALIGN_EPI>
; DI void gemm_phase(LAS unsigned char* lds, const Sched& S, const Epi& E, int tid) {
;     ...
;             PG8_WAIT_V(8); PG8_WAIT_L(0); PG8_BAR; PG8_MMA(1, 0, At, B0); PG8_MMA(1, 1, At, B1); PG8_BAR; PG8_SCHED;
;             PG8_LDB(B0, 1, 0); PG8_LDB(B1, 1, 1); PG8_SCHED; PG8_LDA(At, 1, 0); PG8_STAGE(PG8_SA(0, 1), a2 + hstepA, voffA);
;             PG8_WAIT_V(8); PG8_WAIT_L(0); PG8_BAR; PG8_MMA(0, 0, At, B0); PG8_MMA(0, 1, At, B1); PG8_BAR; PG8_SCHED;
	s_setprio 1
	s_waitcnt lgkmcnt(0)
	v_mfma_f32_16x16x32_bf16 v[64:67], v[148:151], v[182:185], 0
	v_mfma_f32_16x16x32_bf16 v[60:63], v[156:159], v[182:185], 0
	v_mfma_f32_16x16x32_bf16 v[56:59], v[148:151], v[190:193], 0
	v_mfma_f32_16x16x32_bf16 v[48:51], v[156:159], v[190:193], 0
	v_mfma_f32_16x16x32_bf16 v[40:43], v[148:151], v[206:209], 0
	v_mfma_f32_16x16x32_bf16 v[32:35], v[156:159], v[206:209], 0
	v_mfma_f32_16x16x32_bf16 v[24:27], v[148:151], v[214:217], 0
	v_mfma_f32_16x16x32_bf16 v[16:19], v[156:159], v[214:217], 0
	v_mfma_f32_16x16x32_bf16 v[64:67], v[152:155], v[186:189], v[64:67]
	v_mfma_f32_16x16x32_bf16 v[60:63], v[162:165], v[186:189], v[60:63]
	v_mfma_f32_16x16x32_bf16 v[56:59], v[152:155], v[202:205], v[56:59]
	v_mfma_f32_16x16x32_bf16 v[48:51], v[162:165], v[202:205], v[48:51]
	v_mfma_f32_16x16x32_bf16 v[40:43], v[152:155], v[210:213], v[40:43]
	v_mfma_f32_16x16x32_bf16 v[32:35], v[162:165], v[210:213], v[32:35]
	v_mfma_f32_16x16x32_bf16 v[24:27], v[152:155], v[218:221], v[24:27]
	v_mfma_f32_16x16x32_bf16 v[16:19], v[162:165], v[218:221], v[16:19]
	s_setprio 0
	s_setprio 1
	v_mfma_f32_16x16x32_bf16 v[52:55], v[166:169], v[182:185], 0
	v_mfma_f32_16x16x32_bf16 v[44:47], v[174:177], v[182:185], 0
	v_mfma_f32_16x16x32_bf16 v[36:39], v[166:169], v[190:193], 0
	v_mfma_f32_16x16x32_bf16 v[28:31], v[174:177], v[190:193], 0
	v_mfma_f32_16x16x32_bf16 v[20:23], v[166:169], v[206:209], 0
	v_mfma_f32_16x16x32_bf16 v[12:15], v[174:177], v[206:209], 0
	v_mfma_f32_16x16x32_bf16 v[8:11], v[166:169], v[214:217], 0
	v_mfma_f32_16x16x32_bf16 v[4:7], v[174:177], v[214:217], 0
	v_mfma_f32_16x16x32_bf16 v[52:55], v[170:173], v[186:189], v[52:55]
	v_mfma_f32_16x16x32_bf16 v[44:47], v[178:181], v[186:189], v[44:47]
	v_mfma_f32_16x16x32_bf16 v[36:39], v[170:173], v[202:205], v[36:39]
	v_mfma_f32_16x16x32_bf16 v[28:31], v[178:181], v[202:205], v[28:31]
	v_mfma_f32_16x16x32_bf16 v[20:23], v[170:173], v[210:213], v[20:23]
	v_mfma_f32_16x16x32_bf16 v[12:15], v[178:181], v[210:213], v[12:15]
	v_mfma_f32_16x16x32_bf16 v[8:11], v[170:173], v[218:221], v[8:11]
	v_mfma_f32_16x16x32_bf16 v[4:7], v[178:181], v[218:221], v[4:7]
	s_setprio 0
	s_barrier
	s_add_i32 s48, 0, 0x18000
	v_add_u32_e32 v161, s48, v144
	s_add_i32 s49, 0, 0x1c000
	ds_read_b128 v[148:151], v161
	ds_read_b128 v[152:155], v161 offset:1024
	ds_read_b128 v[156:159], v161 offset:2048
	ds_read_b128 v[162:165], v161 offset:3072
	v_add_u32_e32 v161, s49, v144
	ds_read_b128 v[166:169], v161
	ds_read_b128 v[170:173], v161 offset:1024
	ds_read_b128 v[174:177], v161 offset:2048
	ds_read_b128 v[178:181], v161 offset:3072
	s_add_u32 s26, s26, 0x40000
	s_addc_u32 s27, s27, 0
	s_mov_b32 m0, s37
	v_lshl_add_u64 v[228:229], s[26:27], 0, v[138:139]
	ds_read_b128 v[182:185], v147 offset:32768
	ds_read_b128 v[186:189], v147 offset:33792
	ds_read_b128 v[190:193], v147 offset:34816
	ds_read_b128 v[202:205], v147 offset:35840
	ds_read_b128 v[206:209], v147 offset:36864
	ds_read_b128 v[210:213], v147 offset:37888
	ds_read_b128 v[214:217], v147 offset:38912
	ds_read_b128 v[218:221], v147 offset:39936
	global_load_lds_dwordx4 v[228:229], off
	v_lshl_add_u64 v[228:229], s[26:27], 0, v[134:135]
	s_mov_b32 m0, s38
	s_nop 0
	global_load_lds_dwordx4 v[228:229], off
	s_waitcnt vmcnt(8)
	s_waitcnt lgkmcnt(0)
	s_barrier
	s_setprio 1
	s_waitcnt lgkmcnt(0)
	v_mfma_f32_16x16x32_bf16 v[128:131], v[148:151], v[182:185], v[128:131]
	v_mfma_f32_16x16x32_bf16 v[124:127], v[156:159], v[182:185], v[124:127]
	v_mfma_f32_16x16x32_bf16 v[120:123], v[148:151], v[190:193], v[120:123]
	v_mfma_f32_16x16x32_bf16 v[112:115], v[156:159], v[190:193], v[112:115]
	v_mfma_f32_16x16x32_bf16 v[100:103], v[148:151], v[206:209], v[100:103]
	v_mfma_f32_16x16x32_bf16 v[92:95], v[156:159], v[206:209], v[92:95]
	v_mfma_f32_16x16x32_bf16 v[88:91], v[148:151], v[214:217], v[88:91]
	v_mfma_f32_16x16x32_bf16 v[80:83], v[156:159], v[214:217], v[80:83]
	v_mfma_f32_16x16x32_bf16 v[128:131], v[152:155], v[186:189], v[128:131]
	v_mfma_f32_16x16x32_bf16 v[124:127], v[162:165], v[186:189], v[124:127]
	v_mfma_f32_16x16x32_bf16 v[120:123], v[152:155], v[202:205], v[120:123]
	v_mfma_f32_16x16x32_bf16 v[112:115], v[162:165], v[202:205], v[112:115]
	v_mfma_f32_16x16x32_bf16 v[100:103], v[152:155], v[210:213], v[100:103]
	v_mfma_f32_16x16x32_bf16 v[92:95], v[162:165], v[210:213], v[92:95]
	v_mfma_f32_16x16x32_bf16 v[88:91], v[152:155], v[218:221], v[88:91]
	v_mfma_f32_16x16x32_bf16 v[80:83], v[162:165], v[218:221], v[80:83]
	s_setprio 0
	s_setprio 1
	v_mfma_f32_16x16x32_bf16 v[116:119], v[166:169], v[182:185], v[116:119]
	v_mfma_f32_16x16x32_bf16 v[108:111], v[174:177], v[182:185], v[108:111]
	v_mfma_f32_16x16x32_bf16 v[104:107], v[166:169], v[190:193], v[104:107]
	v_mfma_f32_16x16x32_bf16 v[96:99], v[174:177], v[190:193], v[96:99]
	v_mfma_f32_16x16x32_bf16 v[84:87], v[166:169], v[206:209], v[84:87]
	v_mfma_f32_16x16x32_bf16 v[76:79], v[174:177], v[206:209], v[76:79]
	v_mfma_f32_16x16x32_bf16 v[72:75], v[166:169], v[214:217], v[72:75]
	v_mfma_f32_16x16x32_bf16 v[68:71], v[174:177], v[214:217], v[68:71]
	v_mfma_f32_16x16x32_bf16 v[116:119], v[170:173], v[186:189], v[116:119]
	v_mfma_f32_16x16x32_bf16 v[108:111], v[178:181], v[186:189], v[108:111]
	v_mfma_f32_16x16x32_bf16 v[104:107], v[170:173], v[202:205], v[104:107]
	v_mfma_f32_16x16x32_bf16 v[96:99], v[178:181], v[202:205], v[96:99]
	v_mfma_f32_16x16x32_bf16 v[84:87], v[170:173], v[210:213], v[84:87]
	v_mfma_f32_16x16x32_bf16 v[76:79], v[178:181], v[210:213], v[76:79]
	v_mfma_f32_16x16x32_bf16 v[72:75], v[170:173], v[218:221], v[72:75]
	v_mfma_f32_16x16x32_bf16 v[68:71], v[178:181], v[218:221], v[68:71]
	s_setprio 0
	s_barrier
; #define PG8_STAGE(bufoff, gbase, voff) do { _Pragma("unroll") for (int _i = 0; _i < 2; ++_i) \
;         __builtin_amdgcn_global_load_lds((const unsigned*)((const char*)(gbase) + (voff)[_i]), (LAS unsigned*)(lds + (bufoff) + ldsw + _i * 8192), 16, 0, 0); } while (0)
; #define PG8_LDA(dst, b, h) do { _Pragma("unroll") for (int m = 0; m < 4; ++m) _Pragma("unroll") for (int k = 0; k < 2; ++k) dst[m][k] = *(const LAS bf16x8*)(lds + PG8_SA(b, h) + aoff + m * 2048 + k * 1024); } while (0)
; #define PG8_LDB(dst, b, h) do { _Pragma("unroll") for (int n = 0; n < 2; ++n) _Pragma("unroll") for (int k = 0; k < 2; ++k) dst[n][k] = *(const LAS bf16x8*)(lds + PG8_SB(b, h) + boff + n * 2048 + k * 1024); } while (0)
; #define PG8_MMA(ai, bj, At, Bt) do { __builtin_amdgcn_s_setprio(1); _Pragma("unroll") for (int m = 0; m < 4; ++m) _Pragma("unroll") for (int n = 0; n < 2; ++n) _Pragma("unroll") for (int k = 0; k < 2; ++k) \
;         acc[ai][bj][m][n] = __builtin_amdgcn_mfma_f32_16x16x32_bf16(Bt[n][k], At[m][k], acc[ai][bj][m][n], 0, 0, 0); __builtin_amdgcn_s_setprio(0); } while (0)
; #define PG8_WAIT_V(n) asm volatile("s_waitcnt vmcnt(" #n ")" ::: "memory")
; #define PG8_WAIT_L(n) asm volatile("s_waitcnt lgkmcnt(" #n ")" ::: "memory")
; #define PG8_BAR __builtin_amdgcn_s_barrier()
; #define PG8_SCHED __builtin_amdgcn_sched_barrier(0)
; template <class Epi, bool ALIGN_EPI>
; DI void gemm_phase(LAS unsigned char* lds, const Sched& S, const Epi& E, int tid) {
;     ...
;         for (int t = 0; t < nt; t += 2) {
;             const bool last = (t == nt - 2);
;             const char* a1 = cA + (size_t)(t + 1) * kstep;
;             const char* a2 = last ? nA : cA + (size_t)(t + 2) * kstep; const char* b2 = last ? nB : cB + (size_t)(t + 2) * kstep;
;             const char* a3 = a2 + kstep; const char* b3 = b2 + kstep;
;             PG8_LDB(B0, 0, 0); PG8_LDB(B1, 0, 1); PG8_SCHED; PG8_LDA(At, 0, 0); PG8_STAGE(PG8_SA(1, 1), a1 + hstepA, voffA);
;     ...
;             PG8_WAIT_V(8); PG8_WAIT_L(0); PG8_BAR; PG8_MMA(0, 0, At, B0); PG8_MMA(0, 1, At, B1); PG8_BAR; PG8_SCHED;
;             PG8_LDA(At, 1, 1); PG8_STAGE(PG8_SB(1, 0), b3, voffB); PG8_STAGE(PG8_SB(1, 1), b3 + hstepB, voffB); PG8_STAGE(PG8_SA(1, 0), a3, voffA);
;             PG8_WAIT_V(8); PG8_WAIT_L(0); PG8_BAR; PG8_MMA(1, 0, At, B0); PG8_MMA(1, 1, At, B1); PG8_BAR; PG8_SCHED;
	s_add_i32 s26, s48, s28
	v_lshl_add_u64 v[194:195], v[194:195], 0, s[84:85]
	s_mov_b32 m0, s26
	ds_read_b128 v[182:185], v147 offset:49152
	ds_read_b128 v[186:189], v147 offset:50176
	ds_read_b128 v[190:193], v147 offset:51200
	ds_read_b128 v[202:205], v147 offset:52224
	ds_read_b128 v[206:209], v147 offset:53248
	ds_read_b128 v[210:213], v147 offset:54272
	ds_read_b128 v[214:217], v147 offset:55296
	ds_read_b128 v[218:221], v147 offset:56320
	global_load_lds_dwordx4 v[194:195], off
	s_add_i32 m0, s26, 0x2000
	s_add_u32 s24, s24, 0x40080
	v_lshl_add_u64 v[194:195], v[222:223], 0, s[84:85]
	s_addc_u32 s25, s25, 0
	s_add_i32 s26, s49, s28
	global_load_lds_dwordx4 v[194:195], off
	v_lshl_add_u64 v[194:195], s[24:25], 0, v[136:137]
	s_mov_b32 m0, s26
	s_nop 0
	global_load_lds_dwordx4 v[194:195], off
	v_lshl_add_u64 v[194:195], s[24:25], 0, v[132:133]
	s_add_i32 m0, s26, 0x2000
	s_nop 0
	global_load_lds_dwordx4 v[194:195], off
	v_lshl_add_u64 v[194:195], v[224:225], 0, s[84:85]
	s_mov_b32 m0, s39
	s_nop 0
	global_load_lds_dwordx4 v[194:195], off
	v_lshl_add_u64 v[194:195], v[226:227], 0, s[84:85]
	s_mov_b32 m0, s40
	s_nop 0
	global_load_lds_dwordx4 v[194:195], off
	s_waitcnt vmcnt(8)
	s_waitcnt lgkmcnt(0)
	s_barrier
	s_setprio 1
	s_waitcnt lgkmcnt(0)
	v_mfma_f32_16x16x32_bf16 v[64:67], v[148:151], v[182:185], v[64:67]
	v_mfma_f32_16x16x32_bf16 v[60:63], v[156:159], v[182:185], v[60:63]
	v_mfma_f32_16x16x32_bf16 v[56:59], v[148:151], v[190:193], v[56:59]
	v_mfma_f32_16x16x32_bf16 v[48:51], v[156:159], v[190:193], v[48:51]
	v_mfma_f32_16x16x32_bf16 v[40:43], v[148:151], v[206:209], v[40:43]
	v_mfma_f32_16x16x32_bf16 v[32:35], v[156:159], v[206:209], v[32:35]
	v_mfma_f32_16x16x32_bf16 v[24:27], v[148:151], v[214:217], v[24:27]
	v_mfma_f32_16x16x32_bf16 v[16:19], v[156:159], v[214:217], v[16:19]
	v_mfma_f32_16x16x32_bf16 v[64:67], v[152:155], v[186:189], v[64:67]
	v_mfma_f32_16x16x32_bf16 v[60:63], v[162:165], v[186:189], v[60:63]
	v_mfma_f32_16x16x32_bf16 v[56:59], v[152:155], v[202:205], v[56:59]
	v_mfma_f32_16x16x32_bf16 v[48:51], v[162:165], v[202:205], v[48:51]
	v_mfma_f32_16x16x32_bf16 v[40:43], v[152:155], v[210:213], v[40:43]
	v_mfma_f32_16x16x32_bf16 v[32:35], v[162:165], v[210:213], v[32:35]
	v_mfma_f32_16x16x32_bf16 v[24:27], v[152:155], v[218:221], v[24:27]
	v_mfma_f32_16x16x32_bf16 v[16:19], v[162:165], v[218:221], v[16:19]
	s_setprio 0
	s_setprio 1
	v_mfma_f32_16x16x32_bf16 v[52:55], v[166:169], v[182:185], v[52:55]
	v_mfma_f32_16x16x32_bf16 v[44:47], v[174:177], v[182:185], v[44:47]
	v_mfma_f32_16x16x32_bf16 v[36:39], v[166:169], v[190:193], v[36:39]
	v_mfma_f32_16x16x32_bf16 v[28:31], v[174:177], v[190:193], v[28:31]
	v_mfma_f32_16x16x32_bf16 v[20:23], v[166:169], v[206:209], v[20:23]
	v_mfma_f32_16x16x32_bf16 v[12:15], v[174:177], v[206:209], v[12:15]
	v_mfma_f32_16x16x32_bf16 v[8:11], v[166:169], v[214:217], v[8:11]
	v_mfma_f32_16x16x32_bf16 v[4:7], v[174:177], v[214:217], v[4:7]
	v_mfma_f32_16x16x32_bf16 v[52:55], v[170:173], v[186:189], v[52:55]
	v_mfma_f32_16x16x32_bf16 v[44:47], v[178:181], v[186:189], v[44:47]
	v_mfma_f32_16x16x32_bf16 v[36:39], v[170:173], v[202:205], v[36:39]
	v_mfma_f32_16x16x32_bf16 v[28:31], v[178:181], v[202:205], v[28:31]
	v_mfma_f32_16x16x32_bf16 v[20:23], v[170:173], v[210:213], v[20:23]
	v_mfma_f32_16x16x32_bf16 v[12:15], v[178:181], v[210:213], v[12:15]
	v_mfma_f32_16x16x32_bf16 v[8:11], v[170:173], v[218:221], v[8:11]
	v_mfma_f32_16x16x32_bf16 v[4:7], v[178:181], v[218:221], v[4:7]
	s_setprio 0
	s_add_i32 s47, s47, 2
	s_add_u32 s22, s22, 0x100
	s_addc_u32 s23, s23, 0
	s_add_u32 s45, s45, 0x100
	s_addc_u32 s46, s46, 0
	s_cmp_gt_u32 s47, 13
	s_add_u32 s24, s22, 0xfffc0080
	s_addc_u32 s25, s23, -1
	s_add_i32 s48, 0, 0x10000
	s_cmp_eq_u32 s47, 12
	s_cselect_b32 s27, s19, s25
	s_cselect_b32 s26, s18, s24
	v_add_u32_e32 v161, s48, v144
	s_cselect_b32 s25, s21, s46
	s_cselect_b32 s24, s20, s45
	s_add_i32 s50, 0, 0x14000
	s_barrier
.LBB0_1961:
	ds_read_b128 v[148:151], v161
	ds_read_b128 v[152:155], v161 offset:1024
	ds_read_b128 v[156:159], v161 offset:2048
	ds_read_b128 v[162:165], v161 offset:3072
	v_add_u32_e32 v161, s50, v144
	ds_read_b128 v[166:169], v161
	ds_read_b128 v[170:173], v161 offset:1024
	ds_read_b128 v[174:177], v161 offset:2048
	ds_read_b128 v[178:181], v161 offset:3072
	v_lshl_add_u64 v[194:195], s[22:23], 0, v[140:141]
	s_add_i32 m0, s17, 0xc000
	ds_read_b128 v[182:185], v147
	ds_read_b128 v[186:189], v147 offset:1024
	ds_read_b128 v[190:193], v147 offset:2048
	ds_read_b128 v[202:205], v147 offset:3072
	ds_read_b128 v[206:209], v147 offset:4096
	ds_read_b128 v[210:213], v147 offset:5120
	ds_read_b128 v[214:217], v147 offset:6144
	ds_read_b128 v[218:221], v147 offset:7168
	global_load_lds_dwordx4 v[194:195], off
	v_lshl_add_u64 v[194:195], s[22:23], 0, v[142:143]
	s_add_i32 m0, s17, 0xe000
	s_nop 0
	global_load_lds_dwordx4 v[194:195], off
	s_waitcnt vmcnt(8)
	s_waitcnt lgkmcnt(0)
	s_barrier
; #define PG8_STAGE(bufoff, gbase, voff) do { _Pragma("unroll") for (int _i = 0; _i < 2; ++_i) \
;         __builtin_amdgcn_global_load_lds((const unsigned*)((const char*)(gbase) + (voff)[_i]), (LAS unsigned*)(lds + (bufoff) + ldsw + _i * 8192), 16, 0, 0); } while (0)
; #define PG8_LDA(dst, b, h) do { _Pragma("unroll") for (int m = 0; m < 4; ++m) _Pragma("unroll") for (int k = 0; k < 2; ++k) dst[m][k] = *(const LAS bf16x8*)(lds + PG8_SA(b, h) + aoff + m * 2048 + k * 1024); } while (0)
; #define PG8_LDB(dst, b, h) do { _Pragma("unroll") for (int n = 0; n < 2; ++n) _Pragma("unroll") for (int k = 0; k < 2; ++k) dst[n][k] = *(const LAS bf16x8*)(lds + PG8_SB(b, h) + boff + n * 2048 + k * 1024); } while (0)
; #define PG8_MMA(ai, bj, At, Bt) do { __builtin_amdgcn_s_setprio(1); _Pragma("unroll") for (int m = 0; m < 4; ++m) _Pragma("unroll") for (int n = 0; n < 2; ++n) _Pragma("unroll") for (int k = 0; k < 2; ++k) \
;         acc[ai][bj][m][n] = __builtin_amdgcn_mfma_f32_16x16x32_bf16(Bt[n][k], At[m][k], acc[ai][bj][m][n], 0, 0, 0); __builtin_amdgcn_s_setprio(0); } while (0)
; #define PG8_WAIT_V(n) asm volatile("s_waitcnt vmcnt(" #n ")" ::: "memory")
; #define PG8_WAIT_L(n) asm volatile("s_waitcnt lgkmcnt(" #n ")" ::: "memory")
; #define PG8_BAR __builtin_amdgcn_s_barrier()
; #define PG8_SCHED __builtin_amdgcn_sched_barrier(0)
; template <class Epi, bool ALIGN_EPI>
; DI void gemm_phase(LAS unsigned char* lds, const Sched& S, const Epi& E, int tid) {
;     ...
;             PG8_LDB(B0, 0, 0); PG8_LDB(B1, 0, 1); PG8_SCHED; PG8_LDA(At, 0, 0); PG8_STAGE(PG8_SA(1, 1), a1 + hstepA, voffA);
;             PG8_WAIT_V(8); PG8_WAIT_L(0); PG8_BAR; PG8_MMA(0, 0, At, B0); PG8_MMA(0, 1, At, B1); PG8_BAR; PG8_SCHED;
;             PG8_LDA(At, 0, 1); PG8_STAGE(PG8_SB(0, 0), b2, voffB); PG8_STAGE(PG8_SB(0, 1), b2 + hstepB, voffB); PG8_STAGE(PG8_SA(0, 0), a2, voffA);
;             PG8_WAIT_V(8); PG8_WAIT_L(0); PG8_BAR; PG8_MMA(1, 0, At, B0); PG8_MMA(1, 1, At, B1); PG8_BAR; PG8_SCHED;
;             PG8_LDB(B0, 1, 0); PG8_LDB(B1, 1, 1); PG8_SCHED; PG8_LDA(At, 1, 0); PG8_STAGE(PG8_SA(0, 1), a2 + hstepA, voffA);
;             PG8_WAIT_V(8); PG8_WAIT_L(0); PG8_BAR; PG8_MMA(0, 0, At, B0); PG8_MMA(0, 1, At, B1); PG8_BAR; PG8_SCHED;
;             PG8_LDA(At, 1, 1); PG8_STAGE(PG8_SB(1, 0), b3, voffB); PG8_STAGE(PG8_SB(1, 1), b3 + hstepB, voffB); PG8_STAGE(PG8_SA(1, 0), a3, voffA);
	s_setprio 1
	s_waitcnt lgkmcnt(0)
	v_mfma_f32_16x16x32_bf16 v[128:131], v[148:151], v[182:185], v[128:131]
	v_mfma_f32_16x16x32_bf16 v[124:127], v[156:159], v[182:185], v[124:127]
	v_mfma_f32_16x16x32_bf16 v[120:123], v[148:151], v[190:193], v[120:123]
	v_mfma_f32_16x16x32_bf16 v[112:115], v[156:159], v[190:193], v[112:115]
	v_mfma_f32_16x16x32_bf16 v[100:103], v[148:151], v[206:209], v[100:103]
	v_mfma_f32_16x16x32_bf16 v[92:95], v[156:159], v[206:209], v[92:95]
	v_mfma_f32_16x16x32_bf16 v[88:91], v[148:151], v[214:217], v[88:91]
	v_mfma_f32_16x16x32_bf16 v[80:83], v[156:159], v[214:217], v[80:83]
	v_mfma_f32_16x16x32_bf16 v[128:131], v[152:155], v[186:189], v[128:131]
	v_mfma_f32_16x16x32_bf16 v[124:127], v[162:165], v[186:189], v[124:127]
	v_mfma_f32_16x16x32_bf16 v[120:123], v[152:155], v[202:205], v[120:123]
	v_mfma_f32_16x16x32_bf16 v[112:115], v[162:165], v[202:205], v[112:115]
	v_mfma_f32_16x16x32_bf16 v[100:103], v[152:155], v[210:213], v[100:103]
	v_mfma_f32_16x16x32_bf16 v[92:95], v[162:165], v[210:213], v[92:95]
	v_mfma_f32_16x16x32_bf16 v[88:91], v[152:155], v[218:221], v[88:91]
	v_mfma_f32_16x16x32_bf16 v[80:83], v[162:165], v[218:221], v[80:83]
	s_setprio 0
	s_setprio 1
	v_mfma_f32_16x16x32_bf16 v[116:119], v[166:169], v[182:185], v[116:119]
	v_mfma_f32_16x16x32_bf16 v[108:111], v[174:177], v[182:185], v[108:111]
	v_mfma_f32_16x16x32_bf16 v[104:107], v[166:169], v[190:193], v[104:107]
	v_mfma_f32_16x16x32_bf16 v[96:99], v[174:177], v[190:193], v[96:99]
	v_mfma_f32_16x16x32_bf16 v[84:87], v[166:169], v[206:209], v[84:87]
	v_mfma_f32_16x16x32_bf16 v[76:79], v[174:177], v[206:209], v[76:79]
	v_mfma_f32_16x16x32_bf16 v[72:75], v[166:169], v[214:217], v[72:75]
	v_mfma_f32_16x16x32_bf16 v[68:71], v[174:177], v[214:217], v[68:71]
	v_mfma_f32_16x16x32_bf16 v[116:119], v[170:173], v[186:189], v[116:119]
	v_mfma_f32_16x16x32_bf16 v[108:111], v[178:181], v[186:189], v[108:111]
	v_mfma_f32_16x16x32_bf16 v[104:107], v[170:173], v[202:205], v[104:107]
	v_mfma_f32_16x16x32_bf16 v[96:99], v[178:181], v[202:205], v[96:99]
	v_mfma_f32_16x16x32_bf16 v[84:87], v[170:173], v[210:213], v[84:87]
	v_mfma_f32_16x16x32_bf16 v[76:79], v[178:181], v[210:213], v[76:79]
	v_mfma_f32_16x16x32_bf16 v[72:75], v[170:173], v[218:221], v[72:75]
	v_mfma_f32_16x16x32_bf16 v[68:71], v[178:181], v[218:221], v[68:71]
	s_setprio 0
	s_barrier
	s_add_i32 s48, s48, s28
	v_lshl_add_u64 v[194:195], s[24:25], 0, v[136:137]
	s_mov_b32 m0, s48
	ds_read_b128 v[182:185], v147 offset:16384
	ds_read_b128 v[186:189], v147 offset:17408
	ds_read_b128 v[190:193], v147 offset:18432
	ds_read_b128 v[202:205], v147 offset:19456
	ds_read_b128 v[206:209], v147 offset:20480
	ds_read_b128 v[210:213], v147 offset:21504
	ds_read_b128 v[214:217], v147 offset:22528
	ds_read_b128 v[218:221], v147 offset:23552
	global_load_lds_dwordx4 v[194:195], off
	s_add_i32 m0, s48, 0x2000
	s_add_u32 s48, s24, 0x40000
	v_lshl_add_u64 v[222:223], s[24:25], 0, v[132:133]
	s_addc_u32 s49, s25, 0
	s_add_i32 s50, s50, s28
	global_load_lds_dwordx4 v[222:223], off
	v_lshl_add_u64 v[224:225], s[48:49], 0, v[136:137]
	s_mov_b32 m0, s50
	v_lshl_add_u64 v[226:227], s[26:27], 0, v[134:135]
	global_load_lds_dwordx4 v[224:225], off
	v_lshl_add_u64 v[224:225], s[48:49], 0, v[132:133]
	s_add_i32 m0, s50, 0x2000
	s_nop 0
	global_load_lds_dwordx4 v[224:225], off
	v_lshl_add_u64 v[224:225], s[26:27], 0, v[138:139]
	s_mov_b32 m0, s17
	s_nop 0
	global_load_lds_dwordx4 v[224:225], off
	s_mov_b32 m0, s36
	s_nop 0
	global_load_lds_dwordx4 v[226:227], off
	s_waitcnt vmcnt(8)
	s_waitcnt lgkmcnt(0)
	s_barrier
	s_setprio 1
	s_waitcnt lgkmcnt(0)
	v_mfma_f32_16x16x32_bf16 v[64:67], v[148:151], v[182:185], v[64:67]
	v_mfma_f32_16x16x32_bf16 v[60:63], v[156:159], v[182:185], v[60:63]
	v_mfma_f32_16x16x32_bf16 v[56:59], v[148:151], v[190:193], v[56:59]
	v_mfma_f32_16x16x32_bf16 v[48:51], v[156:159], v[190:193], v[48:51]
	v_mfma_f32_16x16x32_bf16 v[40:43], v[148:151], v[206:209], v[40:43]
	v_mfma_f32_16x16x32_bf16 v[32:35], v[156:159], v[206:209], v[32:35]
	v_mfma_f32_16x16x32_bf16 v[24:27], v[148:151], v[214:217], v[24:27]
	v_mfma_f32_16x16x32_bf16 v[16:19], v[156:159], v[214:217], v[16:19]
	v_mfma_f32_16x16x32_bf16 v[64:67], v[152:155], v[186:189], v[64:67]
	v_mfma_f32_16x16x32_bf16 v[60:63], v[162:165], v[186:189], v[60:63]
	v_mfma_f32_16x16x32_bf16 v[56:59], v[152:155], v[202:205], v[56:59]
	v_mfma_f32_16x16x32_bf16 v[48:51], v[162:165], v[202:205], v[48:51]
	v_mfma_f32_16x16x32_bf16 v[40:43], v[152:155], v[210:213], v[40:43]
	v_mfma_f32_16x16x32_bf16 v[32:35], v[162:165], v[210:213], v[32:35]
	v_mfma_f32_16x16x32_bf16 v[24:27], v[152:155], v[218:221], v[24:27]
	v_mfma_f32_16x16x32_bf16 v[16:19], v[162:165], v[218:221], v[16:19]
	s_setprio 0
	s_setprio 1
	v_mfma_f32_16x16x32_bf16 v[52:55], v[166:169], v[182:185], v[52:55]
	v_mfma_f32_16x16x32_bf16 v[44:47], v[174:177], v[182:185], v[44:47]
	v_mfma_f32_16x16x32_bf16 v[36:39], v[166:169], v[190:193], v[36:39]
	v_mfma_f32_16x16x32_bf16 v[28:31], v[174:177], v[190:193], v[28:31]
	v_mfma_f32_16x16x32_bf16 v[20:23], v[166:169], v[206:209], v[20:23]
	v_mfma_f32_16x16x32_bf16 v[12:15], v[174:177], v[206:209], v[12:15]
	v_mfma_f32_16x16x32_bf16 v[8:11], v[166:169], v[214:217], v[8:11]
	v_mfma_f32_16x16x32_bf16 v[4:7], v[174:177], v[214:217], v[4:7]
	v_mfma_f32_16x16x32_bf16 v[52:55], v[170:173], v[186:189], v[52:55]
	v_mfma_f32_16x16x32_bf16 v[44:47], v[178:181], v[186:189], v[44:47]
	v_mfma_f32_16x16x32_bf16 v[36:39], v[170:173], v[202:205], v[36:39]
	v_mfma_f32_16x16x32_bf16 v[28:31], v[178:181], v[202:205], v[28:31]
	v_mfma_f32_16x16x32_bf16 v[20:23], v[170:173], v[210:213], v[20:23]
	v_mfma_f32_16x16x32_bf16 v[12:15], v[178:181], v[210:213], v[12:15]
	v_mfma_f32_16x16x32_bf16 v[8:11], v[170:173], v[218:221], v[8:11]
	v_mfma_f32_16x16x32_bf16 v[4:7], v[178:181], v[218:221], v[4:7]
	s_setprio 0
	s_barrier
; #define PG8_STAGE(bufoff, gbase, voff) do { _Pragma("unroll") for (int _i = 0; _i < 2; ++_i) \
;         __builtin_amdgcn_global_load_lds((const unsigned*)((const char*)(gbase) + (voff)[_i]), (LAS unsigned*)(lds + (bufoff) + ldsw + _i * 8192), 16, 0, 0); } while (0)
; #define PG8_LDA(dst, b, h) do { _Pragma("unroll") for (int m = 0; m < 4; ++m) _Pragma("unroll") for (int k = 0; k < 2; ++k) dst[m][k] = *(const LAS bf16x8*)(lds + PG8_SA(b, h) + aoff + m * 2048 + k * 1024); } while (0)
; #define PG8_LDB(dst, b, h) do { _Pragma("unroll") for (int n = 0; n < 2; ++n) _Pragma("unroll") for (int k = 0; k < 2; ++k) dst[n][k] = *(const LAS bf16x8*)(lds + PG8_SB(b, h) + boff + n * 2048 + k * 1024); } while (0)
; #define PG8_MMA(ai, bj, At, Bt) do { __builtin_amdgcn_s_setprio(1); _Pragma("unroll") for (int m = 0; m < 4; ++m) _Pragma("unroll") for (int n = 0; n < 2; ++n) _Pragma("unroll") for (int k = 0; k < 2; ++k) \
;         acc[ai][bj][m][n] = __builtin_amdgcn_mfma_f32_16x16x32_bf16(Bt[n][k], At[m][k], acc[ai][bj][m][n], 0, 0, 0); __builtin_amdgcn_s_setprio(0); } while (0)
; #define PG8_WAIT_V(n) asm volatile("s_waitcnt vmcnt(" #n ")" ::: "memory")
; #define PG8_WAIT_L(n) asm volatile("s_waitcnt lgkmcnt(" #n ")" ::: "memory")
; #define PG8_BAR __builtin_amdgcn_s_barrier()
; #define PG8_SCHED __builtin_amdgcn_sched_barrier(0)
; template <class Epi, bool ALIGN_EPI>
; DI void gemm_phase(LAS unsigned char* lds, const Sched& S, const Epi& E, int tid) {
;     ...
;             PG8_LDB(B0, 1, 0); PG8_LDB(B1, 1, 1); PG8_SCHED; PG8_LDA(At, 1, 0); PG8_STAGE(PG8_SA(0, 1), a2 + hstepA, voffA);
;             PG8_WAIT_V(8); PG8_WAIT_L(0); PG8_BAR; PG8_MMA(0, 0, At, B0); PG8_MMA(0, 1, At, B1); PG8_BAR; PG8_SCHED;
	s_add_i32 s48, 0, 0x18000
	v_add_u32_e32 v161, s48, v144
	s_add_i32 s49, 0, 0x1c000
	ds_read_b128 v[148:151], v161
	ds_read_b128 v[152:155], v161 offset:1024
	ds_read_b128 v[156:159], v161 offset:2048
	ds_read_b128 v[162:165], v161 offset:3072
	v_add_u32_e32 v161, s49, v144
	ds_read_b128 v[166:169], v161
	ds_read_b128 v[170:173], v161 offset:1024
	ds_read_b128 v[174:177], v161 offset:2048
	ds_read_b128 v[178:181], v161 offset:3072
	s_add_u32 s26, s26, 0x40000
	s_addc_u32 s27, s27, 0
	s_mov_b32 m0, s37
	v_lshl_add_u64 v[228:229], s[26:27], 0, v[138:139]
	ds_read_b128 v[182:185], v147 offset:32768
	ds_read_b128 v[186:189], v147 offset:33792
	ds_read_b128 v[190:193], v147 offset:34816
	ds_read_b128 v[202:205], v147 offset:35840
	ds_read_b128 v[206:209], v147 offset:36864
	ds_read_b128 v[210:213], v147 offset:37888
	ds_read_b128 v[214:217], v147 offset:38912
	ds_read_b128 v[218:221], v147 offset:39936
	global_load_lds_dwordx4 v[228:229], off
	v_lshl_add_u64 v[228:229], s[26:27], 0, v[134:135]
	s_mov_b32 m0, s38
	s_nop 0
	global_load_lds_dwordx4 v[228:229], off
	s_waitcnt vmcnt(8)
	s_waitcnt lgkmcnt(0)
	s_barrier
	s_setprio 1
	s_waitcnt lgkmcnt(0)
	v_mfma_f32_16x16x32_bf16 v[128:131], v[148:151], v[182:185], v[128:131]
	v_mfma_f32_16x16x32_bf16 v[124:127], v[156:159], v[182:185], v[124:127]
	v_mfma_f32_16x16x32_bf16 v[120:123], v[148:151], v[190:193], v[120:123]
	v_mfma_f32_16x16x32_bf16 v[112:115], v[156:159], v[190:193], v[112:115]
	v_mfma_f32_16x16x32_bf16 v[100:103], v[148:151], v[206:209], v[100:103]
	v_mfma_f32_16x16x32_bf16 v[92:95], v[156:159], v[206:209], v[92:95]
	v_mfma_f32_16x16x32_bf16 v[88:91], v[148:151], v[214:217], v[88:91]
	v_mfma_f32_16x16x32_bf16 v[80:83], v[156:159], v[214:217], v[80:83]
	v_mfma_f32_16x16x32_bf16 v[128:131], v[152:155], v[186:189], v[128:131]
	v_mfma_f32_16x16x32_bf16 v[124:127], v[162:165], v[186:189], v[124:127]
	v_mfma_f32_16x16x32_bf16 v[120:123], v[152:155], v[202:205], v[120:123]
	v_mfma_f32_16x16x32_bf16 v[112:115], v[162:165], v[202:205], v[112:115]
	v_mfma_f32_16x16x32_bf16 v[100:103], v[152:155], v[210:213], v[100:103]
	v_mfma_f32_16x16x32_bf16 v[92:95], v[162:165], v[210:213], v[92:95]
	v_mfma_f32_16x16x32_bf16 v[88:91], v[152:155], v[218:221], v[88:91]
	v_mfma_f32_16x16x32_bf16 v[80:83], v[162:165], v[218:221], v[80:83]
	s_setprio 0
	s_setprio 1
	v_mfma_f32_16x16x32_bf16 v[116:119], v[166:169], v[182:185], v[116:119]
	v_mfma_f32_16x16x32_bf16 v[108:111], v[174:177], v[182:185], v[108:111]
	v_mfma_f32_16x16x32_bf16 v[104:107], v[166:169], v[190:193], v[104:107]
	v_mfma_f32_16x16x32_bf16 v[96:99], v[174:177], v[190:193], v[96:99]
	v_mfma_f32_16x16x32_bf16 v[84:87], v[166:169], v[206:209], v[84:87]
	v_mfma_f32_16x16x32_bf16 v[76:79], v[174:177], v[206:209], v[76:79]
	v_mfma_f32_16x16x32_bf16 v[72:75], v[166:169], v[214:217], v[72:75]
	v_mfma_f32_16x16x32_bf16 v[68:71], v[174:177], v[214:217], v[68:71]
	v_mfma_f32_16x16x32_bf16 v[116:119], v[170:173], v[186:189], v[116:119]
	v_mfma_f32_16x16x32_bf16 v[108:111], v[178:181], v[186:189], v[108:111]
	v_mfma_f32_16x16x32_bf16 v[104:107], v[170:173], v[202:205], v[104:107]
	v_mfma_f32_16x16x32_bf16 v[96:99], v[178:181], v[202:205], v[96:99]
	v_mfma_f32_16x16x32_bf16 v[84:87], v[170:173], v[210:213], v[84:87]
	v_mfma_f32_16x16x32_bf16 v[76:79], v[178:181], v[210:213], v[76:79]
	v_mfma_f32_16x16x32_bf16 v[72:75], v[170:173], v[218:221], v[72:75]
	v_mfma_f32_16x16x32_bf16 v[68:71], v[178:181], v[218:221], v[68:71]
	s_setprio 0
	s_barrier
; #define PG8_STAGE(bufoff, gbase, voff) do { _Pragma("unroll") for (int _i = 0; _i < 2; ++_i) \
;         __builtin_amdgcn_global_load_lds((const unsigned*)((const char*)(gbase) + (voff)[_i]), (LAS unsigned*)(lds + (bufoff) + ldsw + _i * 8192), 16, 0, 0); } while (0)
; #define PG8_LDA(dst, b, h) do { _Pragma("unroll") for (int m = 0; m < 4; ++m) _Pragma("unroll") for (int k = 0; k < 2; ++k) dst[m][k] = *(const LAS bf16x8*)(lds + PG8_SA(b, h) + aoff + m * 2048 + k * 1024); } while (0)
; #define PG8_MMA(ai, bj, At, Bt) do { __builtin_amdgcn_s_setprio(1); _Pragma("unroll") for (int m = 0; m < 4; ++m) _Pragma("unroll") for (int n = 0; n < 2; ++n) _Pragma("unroll") for (int k = 0; k < 2; ++k) \
;         acc[ai][bj][m][n] = __builtin_amdgcn_mfma_f32_16x16x32_bf16(Bt[n][k], At[m][k], acc[ai][bj][m][n], 0, 0, 0); __builtin_amdgcn_s_setprio(0); } while (0)
; #define PG8_WAIT_V(n) asm volatile("s_waitcnt vmcnt(" #n ")" ::: "memory")
; #define PG8_WAIT_L(n) asm volatile("s_waitcnt lgkmcnt(" #n ")" ::: "memory")
; #define PG8_BAR __builtin_amdgcn_s_barrier()
; #define PG8_SCHED __builtin_amdgcn_sched_barrier(0)
; template <class Epi, bool ALIGN_EPI>
; DI void gemm_phase(LAS unsigned char* lds, const Sched& S, const Epi& E, int tid) {
;     ...
;             PG8_LDA(At, 1, 1); PG8_STAGE(PG8_SB(1, 0), b3, voffB); PG8_STAGE(PG8_SB(1, 1), b3 + hstepB, voffB); PG8_STAGE(PG8_SA(1, 0), a3, voffA);
;             PG8_WAIT_V(8); PG8_WAIT_L(0); PG8_BAR; PG8_MMA(1, 0, At, B0); PG8_MMA(1, 1, At, B1); PG8_BAR; PG8_SCHED;
;         }
;         if constexpr (ALIGN_EPI) { if (wr == 0) PG8_BAR; }
	s_add_i32 s26, s48, s28
	v_lshl_add_u64 v[194:195], v[194:195], 0, s[84:85]
	s_mov_b32 m0, s26
	ds_read_b128 v[182:185], v147 offset:49152
	ds_read_b128 v[186:189], v147 offset:50176
	ds_read_b128 v[190:193], v147 offset:51200
	ds_read_b128 v[202:205], v147 offset:52224
	ds_read_b128 v[206:209], v147 offset:53248
	ds_read_b128 v[210:213], v147 offset:54272
	ds_read_b128 v[214:217], v147 offset:55296
	ds_read_b128 v[218:221], v147 offset:56320
	global_load_lds_dwordx4 v[194:195], off
	s_add_i32 m0, s26, 0x2000
	s_add_u32 s24, s24, 0x40080
	v_lshl_add_u64 v[194:195], v[222:223], 0, s[84:85]
	s_addc_u32 s25, s25, 0
	s_add_i32 s26, s49, s28
	global_load_lds_dwordx4 v[194:195], off
	v_lshl_add_u64 v[194:195], s[24:25], 0, v[136:137]
	s_mov_b32 m0, s26
	s_nop 0
	global_load_lds_dwordx4 v[194:195], off
	v_lshl_add_u64 v[194:195], s[24:25], 0, v[132:133]
	s_add_i32 m0, s26, 0x2000
	s_nop 0
	global_load_lds_dwordx4 v[194:195], off
	v_lshl_add_u64 v[194:195], v[224:225], 0, s[84:85]
	s_mov_b32 m0, s39
	s_nop 0
	global_load_lds_dwordx4 v[194:195], off
	v_lshl_add_u64 v[194:195], v[226:227], 0, s[84:85]
	s_mov_b32 m0, s40
	s_nop 0
	global_load_lds_dwordx4 v[194:195], off
	s_waitcnt vmcnt(8)
	s_waitcnt lgkmcnt(0)
	s_barrier
	s_setprio 1
	s_waitcnt lgkmcnt(0)
	v_mfma_f32_16x16x32_bf16 v[64:67], v[148:151], v[182:185], v[64:67]
	v_mfma_f32_16x16x32_bf16 v[60:63], v[156:159], v[182:185], v[60:63]
	v_mfma_f32_16x16x32_bf16 v[56:59], v[148:151], v[190:193], v[56:59]
	v_mfma_f32_16x16x32_bf16 v[48:51], v[156:159], v[190:193], v[48:51]
	v_mfma_f32_16x16x32_bf16 v[40:43], v[148:151], v[206:209], v[40:43]
	v_mfma_f32_16x16x32_bf16 v[32:35], v[156:159], v[206:209], v[32:35]
	v_mfma_f32_16x16x32_bf16 v[24:27], v[148:151], v[214:217], v[24:27]
	v_mfma_f32_16x16x32_bf16 v[16:19], v[156:159], v[214:217], v[16:19]
	v_mfma_f32_16x16x32_bf16 v[64:67], v[152:155], v[186:189], v[64:67]
	v_mfma_f32_16x16x32_bf16 v[60:63], v[162:165], v[186:189], v[60:63]
	v_mfma_f32_16x16x32_bf16 v[56:59], v[152:155], v[202:205], v[56:59]
	v_mfma_f32_16x16x32_bf16 v[48:51], v[162:165], v[202:205], v[48:51]
	v_mfma_f32_16x16x32_bf16 v[40:43], v[152:155], v[210:213], v[40:43]
	v_mfma_f32_16x16x32_bf16 v[32:35], v[162:165], v[210:213], v[32:35]
	v_mfma_f32_16x16x32_bf16 v[24:27], v[152:155], v[218:221], v[24:27]
	v_mfma_f32_16x16x32_bf16 v[16:19], v[162:165], v[218:221], v[16:19]
	s_setprio 0
	s_setprio 1
	v_mfma_f32_16x16x32_bf16 v[52:55], v[166:169], v[182:185], v[52:55]
	v_mfma_f32_16x16x32_bf16 v[44:47], v[174:177], v[182:185], v[44:47]
	v_mfma_f32_16x16x32_bf16 v[36:39], v[166:169], v[190:193], v[36:39]
	v_mfma_f32_16x16x32_bf16 v[28:31], v[174:177], v[190:193], v[28:31]
	v_mfma_f32_16x16x32_bf16 v[20:23], v[166:169], v[206:209], v[20:23]
	v_mfma_f32_16x16x32_bf16 v[12:15], v[174:177], v[206:209], v[12:15]
	v_mfma_f32_16x16x32_bf16 v[8:11], v[166:169], v[214:217], v[8:11]
	v_mfma_f32_16x16x32_bf16 v[4:7], v[174:177], v[214:217], v[4:7]
	v_mfma_f32_16x16x32_bf16 v[52:55], v[170:173], v[186:189], v[52:55]
	v_mfma_f32_16x16x32_bf16 v[44:47], v[178:181], v[186:189], v[44:47]
	v_mfma_f32_16x16x32_bf16 v[36:39], v[170:173], v[202:205], v[36:39]
	v_mfma_f32_16x16x32_bf16 v[28:31], v[178:181], v[202:205], v[28:31]
	v_mfma_f32_16x16x32_bf16 v[20:23], v[170:173], v[210:213], v[20:23]
	v_mfma_f32_16x16x32_bf16 v[12:15], v[178:181], v[210:213], v[12:15]
	v_mfma_f32_16x16x32_bf16 v[8:11], v[170:173], v[218:221], v[8:11]
	v_mfma_f32_16x16x32_bf16 v[4:7], v[178:181], v[218:221], v[4:7]
	s_setprio 0
	s_add_i32 s47, s47, 2
	s_add_u32 s22, s22, 0x100
	s_addc_u32 s23, s23, 0
	s_add_u32 s45, s45, 0x100
	s_addc_u32 s46, s46, 0
	s_cmp_gt_u32 s47, 13
	s_cbranch_scc1 .Lkx_3
	s_add_u32 s24, s22, 0xfffc0080
	s_addc_u32 s25, s23, -1
	s_add_i32 s48, 0, 0x10000
	s_cmp_eq_u32 s47, 12
	s_cselect_b32 s27, s19, s25
	s_cselect_b32 s26, s18, s24
	v_add_u32_e32 v161, s48, v144
	s_cselect_b32 s25, s21, s46
	s_cselect_b32 s24, s20, s45
	s_add_i32 s50, 0, 0x14000
	s_barrier
	s_branch .LBB0_1961

; #define PG8_STAGE(bufoff, gbase, voff) do { _Pragma("unroll") for (int _i = 0; _i < 2; ++_i) \
;         __builtin_amdgcn_global_load_lds((const unsigned*)((const char*)(gbase) + (voff)[_i]), (LAS unsigned*)(lds + (bufoff) + ldsw + _i * 8192), 16, 0, 0); } while (0)
; #define PG8_LDA(dst, b, h) do { _Pragma("unroll") for (int m = 0; m < 4; ++m) _Pragma("unroll") for (int k = 0; k < 2; ++k) dst[m][k] = *(const LAS bf16x8*)(lds + PG8_SA(b, h) + aoff + m * 2048 + k * 1024); } while (0)
; #define PG8_LDB(dst, b, h) do { _Pragma("unroll") for (int n = 0; n < 2; ++n) _Pragma("unroll") for (int k = 0; k < 2; ++k) dst[n][k] = *(const LAS bf16x8*)(lds + PG8_SB(b, h) + boff + n * 2048 + k * 1024); } while (0)
; #define PG8_MMA(ai, bj, At, Bt) do { __builtin_amdgcn_s_setprio(1); _Pragma("unroll") for (int m = 0; m < 4; ++m) _Pragma("unroll") for (int n = 0; n < 2; ++n) _Pragma("unroll") for (int k = 0; k < 2; ++k) \
;         acc[ai][bj][m][n] = __builtin_amdgcn_mfma_f32_16x16x32_bf16(Bt[n][k], At[m][k], acc[ai][bj][m][n], 0, 0, 0); __builtin_amdgcn_s_setprio(0); } while (0)
; #define PG8_WAIT_V(n) asm volatile("s_waitcnt vmcnt(" #n ")" ::: "memory")
; #define PG8_BAR __builtin_amdgcn_s_barrier()
; template <class Epi, bool ALIGN_EPI>
; DI void gemm_phase(LAS unsigned char* lds, const Sched& S, const Epi& E, int tid) {
;     ...
;         const bool has_next = S.next(ui + 1, nxt);
;         const char* nA = has_next ? nxt.a : cA; const char* nB = has_next ? nxt.b : cB;
;         const int nt = cur.nt;
;         for (int t = 0; t < nt; t += 2) {
;             const bool last = (t == nt - 2);
;             const char* a1 = cA + (size_t)(t + 1) * kstep;
;             const char* a2 = last ? nA : cA + (size_t)(t + 2) * kstep; const char* b2 = last ? nB : cB + (size_t)(t + 2) * kstep;
;             const char* a3 = a2 + kstep; const char* b3 = b2 + kstep;
;             PG8_LDB(B0, 0, 0); PG8_LDB(B1, 0, 1); PG8_SCHED; PG8_LDA(At, 0, 0); PG8_STAGE(PG8_SA(1, 1), a1 + hstepA, voffA);
;             PG8_WAIT_V(8); PG8_WAIT_L(0); PG8_BAR; PG8_MMA(0, 0, At, B0); PG8_MMA(0, 1, At, B1); PG8_BAR; PG8_SCHED;
;             PG8_LDA(At, 0, 1); PG8_STAGE(PG8_SB(0, 0), b2, voffB); PG8_STAGE(PG8_SB(0, 1), b2 + hstepB, voffB); PG8_STAGE(PG8_SA(0, 0), a2, voffA);
;             PG8_WAIT_V(8); PG8_WAIT_L(0); PG8_BAR; PG8_MMA(1, 0, At, B0); PG8_MMA(1, 1, At, B1); PG8_BAR; PG8_SCHED;
.LBB0_2124:
	s_and_b64 s[28:29], s[18:19], exec
	s_cselect_b32 s54, s15, s25
	s_cselect_b32 s55, s14, s24
	s_cselect_b32 s56, s17, s27
	s_cselect_b32 s57, s16, s26
	s_add_i32 s58, s23, -2
	s_add_u32 s24, s24, 0x20080
	s_addc_u32 s25, s25, 0
	s_add_u32 s59, s26, 0x100
	s_mov_b32 s81, s63
	s_addc_u32 s60, s27, 0
	s_mov_b32 s26, 0
	s_waitcnt lgkmcnt(0)
	s_add_i32 s61, s26, 2
	s_add_u32 s27, s24, 0xfffe0080
	s_addc_u32 s28, s25, -1
	s_add_i32 s62, 0, 0x10000
	s_cmp_eq_u32 s58, s26
	s_cselect_b32 s29, s54, s28
	s_cselect_b32 s28, s55, s27
	s_cselect_b32 s27, s56, s60
	s_cselect_b32 s26, s57, s59
	s_add_i32 s64, 0, 0x14000
	v_add_u32_e32 v144, s62, v161
	v_add_u32_e32 v174, s64, v161
	ds_read_b128 v[132:135], v144
	ds_read_b128 v[136:139], v144 offset:1024
	ds_read_b128 v[140:143], v144 offset:2048
	ds_read_b128 v[144:147], v144 offset:3072
	ds_read_b128 v[148:151], v174
	ds_read_b128 v[152:155], v174 offset:1024
	ds_read_b128 v[156:159], v174 offset:2048
	ds_read_b128 v[174:177], v174 offset:3072
	v_lshl_add_u64 v[190:191], s[24:25], 0, v[170:171]
	s_add_i32 m0, s41, 0xc000
	ds_read_b128 v[178:181], v193
	ds_read_b128 v[182:185], v193 offset:1024
	ds_read_b128 v[186:189], v193 offset:2048
	ds_read_b128 v[202:205], v193 offset:3072
	ds_read_b128 v[206:209], v193 offset:4096
	ds_read_b128 v[210:213], v193 offset:5120
	ds_read_b128 v[214:217], v193 offset:6144
	ds_read_b128 v[218:221], v193 offset:7168
	global_load_lds_dwordx4 v[190:191], off
	v_lshl_add_u64 v[190:191], s[24:25], 0, v[172:173]
	s_add_i32 m0, s41, 0xe000
	s_nop 0
	global_load_lds_dwordx4 v[190:191], off
	s_waitcnt vmcnt(8)
	s_waitcnt lgkmcnt(0)
	s_barrier
	s_setprio 1
	s_waitcnt lgkmcnt(0)
	v_mfma_f32_16x16x32_bf16 v[128:131], v[132:135], v[178:181], 0
	v_mfma_f32_16x16x32_bf16 v[124:127], v[140:143], v[178:181], 0
	v_mfma_f32_16x16x32_bf16 v[112:115], v[132:135], v[186:189], 0
	v_mfma_f32_16x16x32_bf16 v[108:111], v[140:143], v[186:189], 0
	v_mfma_f32_16x16x32_bf16 v[96:99], v[132:135], v[206:209], 0
	v_mfma_f32_16x16x32_bf16 v[92:95], v[140:143], v[206:209], 0
	v_mfma_f32_16x16x32_bf16 v[80:83], v[132:135], v[214:217], 0
	v_mfma_f32_16x16x32_bf16 v[76:79], v[140:143], v[214:217], 0
	v_mfma_f32_16x16x32_bf16 v[128:131], v[136:139], v[182:185], v[128:131]
	v_mfma_f32_16x16x32_bf16 v[124:127], v[144:147], v[182:185], v[124:127]
	v_mfma_f32_16x16x32_bf16 v[112:115], v[136:139], v[202:205], v[112:115]
	v_mfma_f32_16x16x32_bf16 v[108:111], v[144:147], v[202:205], v[108:111]
	v_mfma_f32_16x16x32_bf16 v[96:99], v[136:139], v[210:213], v[96:99]
	v_mfma_f32_16x16x32_bf16 v[92:95], v[144:147], v[210:213], v[92:95]
	v_mfma_f32_16x16x32_bf16 v[80:83], v[136:139], v[218:221], v[80:83]
	v_mfma_f32_16x16x32_bf16 v[76:79], v[144:147], v[218:221], v[76:79]
	s_setprio 0
	s_setprio 1
	v_mfma_f32_16x16x32_bf16 v[120:123], v[148:151], v[178:181], 0
	v_mfma_f32_16x16x32_bf16 v[116:119], v[156:159], v[178:181], 0
	v_mfma_f32_16x16x32_bf16 v[104:107], v[148:151], v[186:189], 0
	v_mfma_f32_16x16x32_bf16 v[100:103], v[156:159], v[186:189], 0
	v_mfma_f32_16x16x32_bf16 v[88:91], v[148:151], v[206:209], 0
	v_mfma_f32_16x16x32_bf16 v[84:87], v[156:159], v[206:209], 0
	v_mfma_f32_16x16x32_bf16 v[72:75], v[148:151], v[214:217], 0
	v_mfma_f32_16x16x32_bf16 v[68:71], v[156:159], v[214:217], 0
	v_mfma_f32_16x16x32_bf16 v[120:123], v[152:155], v[182:185], v[120:123]
	v_mfma_f32_16x16x32_bf16 v[116:119], v[174:177], v[182:185], v[116:119]
	v_mfma_f32_16x16x32_bf16 v[104:107], v[152:155], v[202:205], v[104:107]
	v_mfma_f32_16x16x32_bf16 v[100:103], v[174:177], v[202:205], v[100:103]
	v_mfma_f32_16x16x32_bf16 v[88:91], v[152:155], v[210:213], v[88:91]
	v_mfma_f32_16x16x32_bf16 v[84:87], v[174:177], v[210:213], v[84:87]
	v_mfma_f32_16x16x32_bf16 v[72:75], v[152:155], v[218:221], v[72:75]
	v_mfma_f32_16x16x32_bf16 v[68:71], v[174:177], v[218:221], v[68:71]
	s_setprio 0
	s_barrier
	s_add_i32 s62, s62, s40
	v_lshl_add_u64 v[190:191], s[26:27], 0, v[164:165]
	s_mov_b32 m0, s62
	ds_read_b128 v[178:181], v193 offset:16384
	ds_read_b128 v[182:185], v193 offset:17408
	ds_read_b128 v[186:189], v193 offset:18432
	ds_read_b128 v[202:205], v193 offset:19456
	ds_read_b128 v[206:209], v193 offset:20480
	ds_read_b128 v[210:213], v193 offset:21504
	ds_read_b128 v[214:217], v193 offset:22528
	ds_read_b128 v[218:221], v193 offset:23552
	global_load_lds_dwordx4 v[190:191], off
	s_add_i32 m0, s62, 0x2000
	s_add_u32 s62, s26, 0x20000
	v_lshl_add_u64 v[194:195], s[26:27], 0, v[168:169]
	s_addc_u32 s63, s27, 0
	s_add_i32 s64, s64, s40
	global_load_lds_dwordx4 v[194:195], off
	v_lshl_add_u64 v[222:223], s[62:63], 0, v[164:165]
	s_mov_b32 m0, s64
	v_lshl_add_u64 v[224:225], s[28:29], 0, v[166:167]
	global_load_lds_dwordx4 v[222:223], off
	v_lshl_add_u64 v[222:223], s[62:63], 0, v[168:169]
	s_add_i32 m0, s64, 0x2000
	s_nop 0
	global_load_lds_dwordx4 v[222:223], off
	v_lshl_add_u64 v[222:223], s[28:29], 0, v[162:163]
	s_mov_b32 m0, s41
	s_nop 0
	global_load_lds_dwordx4 v[222:223], off
	s_mov_b32 m0, s42
	s_nop 0
	global_load_lds_dwordx4 v[224:225], off
	s_waitcnt vmcnt(8)
	s_waitcnt lgkmcnt(0)
	s_barrier
; #define PG8_STAGE(bufoff, gbase, voff) do { _Pragma("unroll") for (int _i = 0; _i < 2; ++_i) \
;         __builtin_amdgcn_global_load_lds((const unsigned*)((const char*)(gbase) + (voff)[_i]), (LAS unsigned*)(lds + (bufoff) + ldsw + _i * 8192), 16, 0, 0); } while (0)
; #define PG8_LDA(dst, b, h) do { _Pragma("unroll") for (int m = 0; m < 4; ++m) _Pragma("unroll") for (int k = 0; k < 2; ++k) dst[m][k] = *(const LAS bf16x8*)(lds + PG8_SA(b, h) + aoff + m * 2048 + k * 1024); } while (0)
; #define PG8_LDB(dst, b, h) do { _Pragma("unroll") for (int n = 0; n < 2; ++n) _Pragma("unroll") for (int k = 0; k < 2; ++k) dst[n][k] = *(const LAS bf16x8*)(lds + PG8_SB(b, h) + boff + n * 2048 + k * 1024); } while (0)
; #define PG8_MMA(ai, bj, At, Bt) do { __builtin_amdgcn_s_setprio(1); _Pragma("unroll") for (int m = 0; m < 4; ++m) _Pragma("unroll") for (int n = 0; n < 2; ++n) _Pragma("unroll") for (int k = 0; k < 2; ++k) \
;         acc[ai][bj][m][n] = __builtin_amdgcn_mfma_f32_16x16x32_bf16(Bt[n][k], At[m][k], acc[ai][bj][m][n], 0, 0, 0); __builtin_amdgcn_s_setprio(0); } while (0)
; #define PG8_WAIT_V(n) asm volatile("s_waitcnt vmcnt(" #n ")" ::: "memory")
; #define PG8_WAIT_L(n) asm volatile("s_waitcnt lgkmcnt(" #n ")" ::: "memory")
; #define PG8_BAR __builtin_amdgcn_s_barrier()
; #define PG8_SCHED __builtin_amdgcn_sched_barrier(0)
; template <class Epi, bool ALIGN_EPI>
; DI void gemm_phase(LAS unsigned char* lds, const Sched& S, const Epi& E, int tid) {
;     ...
;             PG8_WAIT_V(8); PG8_WAIT_L(0); PG8_BAR; PG8_MMA(1, 0, At, B0); PG8_MMA(1, 1, At, B1); PG8_BAR; PG8_SCHED;
;             PG8_LDB(B0, 1, 0); PG8_LDB(B1, 1, 1); PG8_SCHED; PG8_LDA(At, 1, 0); PG8_STAGE(PG8_SA(0, 1), a2 + hstepA, voffA);
;             PG8_WAIT_V(8); PG8_WAIT_L(0); PG8_BAR; PG8_MMA(0, 0, At, B0); PG8_MMA(0, 1, At, B1); PG8_BAR; PG8_SCHED;
	s_setprio 1
	s_waitcnt lgkmcnt(0)
	v_mfma_f32_16x16x32_bf16 v[64:67], v[132:135], v[178:181], 0
	v_mfma_f32_16x16x32_bf16 v[60:63], v[140:143], v[178:181], 0
	v_mfma_f32_16x16x32_bf16 v[48:51], v[132:135], v[186:189], 0
	v_mfma_f32_16x16x32_bf16 v[44:47], v[140:143], v[186:189], 0
	v_mfma_f32_16x16x32_bf16 v[32:35], v[132:135], v[206:209], 0
	v_mfma_f32_16x16x32_bf16 v[28:31], v[140:143], v[206:209], 0
	v_mfma_f32_16x16x32_bf16 v[16:19], v[132:135], v[214:217], 0
	v_mfma_f32_16x16x32_bf16 v[12:15], v[140:143], v[214:217], 0
	v_mfma_f32_16x16x32_bf16 v[64:67], v[136:139], v[182:185], v[64:67]
	v_mfma_f32_16x16x32_bf16 v[60:63], v[144:147], v[182:185], v[60:63]
	v_mfma_f32_16x16x32_bf16 v[48:51], v[136:139], v[202:205], v[48:51]
	v_mfma_f32_16x16x32_bf16 v[44:47], v[144:147], v[202:205], v[44:47]
	v_mfma_f32_16x16x32_bf16 v[32:35], v[136:139], v[210:213], v[32:35]
	v_mfma_f32_16x16x32_bf16 v[28:31], v[144:147], v[210:213], v[28:31]
	v_mfma_f32_16x16x32_bf16 v[16:19], v[136:139], v[218:221], v[16:19]
	v_mfma_f32_16x16x32_bf16 v[12:15], v[144:147], v[218:221], v[12:15]
	s_setprio 0
	s_setprio 1
	v_mfma_f32_16x16x32_bf16 v[56:59], v[148:151], v[178:181], 0
	v_mfma_f32_16x16x32_bf16 v[52:55], v[156:159], v[178:181], 0
	v_mfma_f32_16x16x32_bf16 v[40:43], v[148:151], v[186:189], 0
	v_mfma_f32_16x16x32_bf16 v[36:39], v[156:159], v[186:189], 0
	v_mfma_f32_16x16x32_bf16 v[24:27], v[148:151], v[206:209], 0
	v_mfma_f32_16x16x32_bf16 v[20:23], v[156:159], v[206:209], 0
	v_mfma_f32_16x16x32_bf16 v[8:11], v[148:151], v[214:217], 0
	v_mfma_f32_16x16x32_bf16 v[4:7], v[156:159], v[214:217], 0
	v_mfma_f32_16x16x32_bf16 v[56:59], v[152:155], v[182:185], v[56:59]
	v_mfma_f32_16x16x32_bf16 v[52:55], v[174:177], v[182:185], v[52:55]
	v_mfma_f32_16x16x32_bf16 v[40:43], v[152:155], v[202:205], v[40:43]
	v_mfma_f32_16x16x32_bf16 v[36:39], v[174:177], v[202:205], v[36:39]
	v_mfma_f32_16x16x32_bf16 v[24:27], v[152:155], v[210:213], v[24:27]
	v_mfma_f32_16x16x32_bf16 v[20:23], v[174:177], v[210:213], v[20:23]
	v_mfma_f32_16x16x32_bf16 v[8:11], v[152:155], v[218:221], v[8:11]
	v_mfma_f32_16x16x32_bf16 v[4:7], v[174:177], v[218:221], v[4:7]
	s_setprio 0
	s_barrier
	s_add_i32 s62, 0, 0x18000
	s_add_i32 s63, 0, 0x1c000
	v_add_u32_e32 v144, s62, v161
	v_add_u32_e32 v174, s63, v161
	ds_read_b128 v[132:135], v144
	ds_read_b128 v[136:139], v144 offset:1024
	ds_read_b128 v[140:143], v144 offset:2048
	ds_read_b128 v[144:147], v144 offset:3072
	ds_read_b128 v[148:151], v174
	ds_read_b128 v[152:155], v174 offset:1024
	ds_read_b128 v[156:159], v174 offset:2048
	ds_read_b128 v[174:177], v174 offset:3072
	s_add_u32 s28, s28, 0x20000
	s_addc_u32 s29, s29, 0
	s_mov_b32 m0, s43
	v_lshl_add_u64 v[226:227], s[28:29], 0, v[162:163]
	ds_read_b128 v[178:181], v193 offset:32768
	ds_read_b128 v[182:185], v193 offset:33792
	ds_read_b128 v[186:189], v193 offset:34816
	ds_read_b128 v[202:205], v193 offset:35840
	ds_read_b128 v[206:209], v193 offset:36864
	ds_read_b128 v[210:213], v193 offset:37888
	ds_read_b128 v[214:217], v193 offset:38912
	ds_read_b128 v[218:221], v193 offset:39936
	global_load_lds_dwordx4 v[226:227], off
	v_lshl_add_u64 v[226:227], s[28:29], 0, v[166:167]
	s_mov_b32 m0, s44
	s_nop 0
	global_load_lds_dwordx4 v[226:227], off
	s_waitcnt vmcnt(8)
	s_waitcnt lgkmcnt(0)
	s_barrier
	s_setprio 1
	s_waitcnt lgkmcnt(0)
	v_mfma_f32_16x16x32_bf16 v[128:131], v[132:135], v[178:181], v[128:131]
	v_mfma_f32_16x16x32_bf16 v[124:127], v[140:143], v[178:181], v[124:127]
	v_mfma_f32_16x16x32_bf16 v[112:115], v[132:135], v[186:189], v[112:115]
	v_mfma_f32_16x16x32_bf16 v[108:111], v[140:143], v[186:189], v[108:111]
	v_mfma_f32_16x16x32_bf16 v[96:99], v[132:135], v[206:209], v[96:99]
	v_mfma_f32_16x16x32_bf16 v[92:95], v[140:143], v[206:209], v[92:95]
	v_mfma_f32_16x16x32_bf16 v[80:83], v[132:135], v[214:217], v[80:83]
	v_mfma_f32_16x16x32_bf16 v[76:79], v[140:143], v[214:217], v[76:79]
	v_mfma_f32_16x16x32_bf16 v[128:131], v[136:139], v[182:185], v[128:131]
	v_mfma_f32_16x16x32_bf16 v[124:127], v[144:147], v[182:185], v[124:127]
	v_mfma_f32_16x16x32_bf16 v[112:115], v[136:139], v[202:205], v[112:115]
	v_mfma_f32_16x16x32_bf16 v[108:111], v[144:147], v[202:205], v[108:111]
	v_mfma_f32_16x16x32_bf16 v[96:99], v[136:139], v[210:213], v[96:99]
	v_mfma_f32_16x16x32_bf16 v[92:95], v[144:147], v[210:213], v[92:95]
	v_mfma_f32_16x16x32_bf16 v[80:83], v[136:139], v[218:221], v[80:83]
	v_mfma_f32_16x16x32_bf16 v[76:79], v[144:147], v[218:221], v[76:79]
	s_setprio 0
	s_setprio 1
	v_mfma_f32_16x16x32_bf16 v[120:123], v[148:151], v[178:181], v[120:123]
	v_mfma_f32_16x16x32_bf16 v[116:119], v[156:159], v[178:181], v[116:119]
	v_mfma_f32_16x16x32_bf16 v[104:107], v[148:151], v[186:189], v[104:107]
	v_mfma_f32_16x16x32_bf16 v[100:103], v[156:159], v[186:189], v[100:103]
	v_mfma_f32_16x16x32_bf16 v[88:91], v[148:151], v[206:209], v[88:91]
	v_mfma_f32_16x16x32_bf16 v[84:87], v[156:159], v[206:209], v[84:87]
	v_mfma_f32_16x16x32_bf16 v[72:75], v[148:151], v[214:217], v[72:75]
	v_mfma_f32_16x16x32_bf16 v[68:71], v[156:159], v[214:217], v[68:71]
	v_mfma_f32_16x16x32_bf16 v[120:123], v[152:155], v[182:185], v[120:123]
	v_mfma_f32_16x16x32_bf16 v[116:119], v[174:177], v[182:185], v[116:119]
	v_mfma_f32_16x16x32_bf16 v[104:107], v[152:155], v[202:205], v[104:107]
	v_mfma_f32_16x16x32_bf16 v[100:103], v[174:177], v[202:205], v[100:103]
	v_mfma_f32_16x16x32_bf16 v[88:91], v[152:155], v[210:213], v[88:91]
	v_mfma_f32_16x16x32_bf16 v[84:87], v[174:177], v[210:213], v[84:87]
	v_mfma_f32_16x16x32_bf16 v[72:75], v[152:155], v[218:221], v[72:75]
	v_mfma_f32_16x16x32_bf16 v[68:71], v[174:177], v[218:221], v[68:71]
	s_setprio 0
	s_barrier
; #define PG8_STAGE(bufoff, gbase, voff) do { _Pragma("unroll") for (int _i = 0; _i < 2; ++_i) \
;         __builtin_amdgcn_global_load_lds((const unsigned*)((const char*)(gbase) + (voff)[_i]), (LAS unsigned*)(lds + (bufoff) + ldsw + _i * 8192), 16, 0, 0); } while (0)
; #define PG8_LDA(dst, b, h) do { _Pragma("unroll") for (int m = 0; m < 4; ++m) _Pragma("unroll") for (int k = 0; k < 2; ++k) dst[m][k] = *(const LAS bf16x8*)(lds + PG8_SA(b, h) + aoff + m * 2048 + k * 1024); } while (0)
; #define PG8_LDB(dst, b, h) do { _Pragma("unroll") for (int n = 0; n < 2; ++n) _Pragma("unroll") for (int k = 0; k < 2; ++k) dst[n][k] = *(const LAS bf16x8*)(lds + PG8_SB(b, h) + boff + n * 2048 + k * 1024); } while (0)
; #define PG8_MMA(ai, bj, At, Bt) do { __builtin_amdgcn_s_setprio(1); _Pragma("unroll") for (int m = 0; m < 4; ++m) _Pragma("unroll") for (int n = 0; n < 2; ++n) _Pragma("unroll") for (int k = 0; k < 2; ++k) \
;         acc[ai][bj][m][n] = __builtin_amdgcn_mfma_f32_16x16x32_bf16(Bt[n][k], At[m][k], acc[ai][bj][m][n], 0, 0, 0); __builtin_amdgcn_s_setprio(0); } while (0)
; #define PG8_WAIT_V(n) asm volatile("s_waitcnt vmcnt(" #n ")" ::: "memory")
; #define PG8_WAIT_L(n) asm volatile("s_waitcnt lgkmcnt(" #n ")" ::: "memory")
; #define PG8_BAR __builtin_amdgcn_s_barrier()
; #define PG8_SCHED __builtin_amdgcn_sched_barrier(0)
; template <class Epi, bool ALIGN_EPI>
; DI void gemm_phase(LAS unsigned char* lds, const Sched& S, const Epi& E, int tid) {
;     ...
;         for (int t = 0; t < nt; t += 2) {
;             const bool last = (t == nt - 2);
;             const char* a1 = cA + (size_t)(t + 1) * kstep;
;             const char* a2 = last ? nA : cA + (size_t)(t + 2) * kstep; const char* b2 = last ? nB : cB + (size_t)(t + 2) * kstep;
;             const char* a3 = a2 + kstep; const char* b3 = b2 + kstep;
;             PG8_LDB(B0, 0, 0); PG8_LDB(B1, 0, 1); PG8_SCHED; PG8_LDA(At, 0, 0); PG8_STAGE(PG8_SA(1, 1), a1 + hstepA, voffA);
;     ...
;             PG8_WAIT_V(8); PG8_WAIT_L(0); PG8_BAR; PG8_MMA(0, 0, At, B0); PG8_MMA(0, 1, At, B1); PG8_BAR; PG8_SCHED;
;             PG8_LDA(At, 1, 1); PG8_STAGE(PG8_SB(1, 0), b3, voffB); PG8_STAGE(PG8_SB(1, 1), b3 + hstepB, voffB); PG8_STAGE(PG8_SA(1, 0), a3, voffA);
;             PG8_WAIT_V(8); PG8_WAIT_L(0); PG8_BAR; PG8_MMA(1, 0, At, B0); PG8_MMA(1, 1, At, B1); PG8_BAR; PG8_SCHED;
	s_add_i32 s28, s62, s40
	v_lshl_add_u64 v[190:191], v[190:191], 0, s[84:85]
	s_mov_b32 m0, s28
	ds_read_b128 v[178:181], v193 offset:49152
	ds_read_b128 v[182:185], v193 offset:50176
	ds_read_b128 v[186:189], v193 offset:51200
	ds_read_b128 v[202:205], v193 offset:52224
	ds_read_b128 v[206:209], v193 offset:53248
	ds_read_b128 v[210:213], v193 offset:54272
	ds_read_b128 v[214:217], v193 offset:55296
	ds_read_b128 v[218:221], v193 offset:56320
	global_load_lds_dwordx4 v[190:191], off
	s_add_i32 m0, s28, 0x2000
	s_add_u32 s26, s26, 0x20080
	v_lshl_add_u64 v[190:191], v[194:195], 0, s[84:85]
	s_addc_u32 s27, s27, 0
	s_add_i32 s28, s63, s40
	global_load_lds_dwordx4 v[190:191], off
	v_lshl_add_u64 v[190:191], s[26:27], 0, v[164:165]
	s_mov_b32 m0, s28
	s_nop 0
	global_load_lds_dwordx4 v[190:191], off
	v_lshl_add_u64 v[190:191], s[26:27], 0, v[168:169]
	s_add_i32 m0, s28, 0x2000
	s_nop 0
	global_load_lds_dwordx4 v[190:191], off
	v_lshl_add_u64 v[190:191], v[222:223], 0, s[84:85]
	s_mov_b32 m0, s46
	s_nop 0
	global_load_lds_dwordx4 v[190:191], off
	v_lshl_add_u64 v[190:191], v[224:225], 0, s[84:85]
	s_mov_b32 m0, s47
	s_nop 0
	global_load_lds_dwordx4 v[190:191], off
	s_waitcnt vmcnt(8)
	s_waitcnt lgkmcnt(0)
	s_barrier
	s_setprio 1
	s_waitcnt lgkmcnt(0)
	v_mfma_f32_16x16x32_bf16 v[64:67], v[132:135], v[178:181], v[64:67]
	v_mfma_f32_16x16x32_bf16 v[60:63], v[140:143], v[178:181], v[60:63]
	v_mfma_f32_16x16x32_bf16 v[48:51], v[132:135], v[186:189], v[48:51]
	v_mfma_f32_16x16x32_bf16 v[44:47], v[140:143], v[186:189], v[44:47]
	v_mfma_f32_16x16x32_bf16 v[32:35], v[132:135], v[206:209], v[32:35]
	v_mfma_f32_16x16x32_bf16 v[28:31], v[140:143], v[206:209], v[28:31]
	v_mfma_f32_16x16x32_bf16 v[16:19], v[132:135], v[214:217], v[16:19]
	v_mfma_f32_16x16x32_bf16 v[12:15], v[140:143], v[214:217], v[12:15]
	v_mfma_f32_16x16x32_bf16 v[64:67], v[136:139], v[182:185], v[64:67]
	v_mfma_f32_16x16x32_bf16 v[60:63], v[144:147], v[182:185], v[60:63]
	v_mfma_f32_16x16x32_bf16 v[48:51], v[136:139], v[202:205], v[48:51]
	v_mfma_f32_16x16x32_bf16 v[44:47], v[144:147], v[202:205], v[44:47]
	v_mfma_f32_16x16x32_bf16 v[32:35], v[136:139], v[210:213], v[32:35]
	v_mfma_f32_16x16x32_bf16 v[28:31], v[144:147], v[210:213], v[28:31]
	v_mfma_f32_16x16x32_bf16 v[16:19], v[136:139], v[218:221], v[16:19]
	v_mfma_f32_16x16x32_bf16 v[12:15], v[144:147], v[218:221], v[12:15]
	s_setprio 0
	s_setprio 1
	v_mfma_f32_16x16x32_bf16 v[56:59], v[148:151], v[178:181], v[56:59]
	v_mfma_f32_16x16x32_bf16 v[52:55], v[156:159], v[178:181], v[52:55]
	v_mfma_f32_16x16x32_bf16 v[40:43], v[148:151], v[186:189], v[40:43]
	v_mfma_f32_16x16x32_bf16 v[36:39], v[156:159], v[186:189], v[36:39]
	v_mfma_f32_16x16x32_bf16 v[24:27], v[148:151], v[206:209], v[24:27]
	v_mfma_f32_16x16x32_bf16 v[20:23], v[156:159], v[206:209], v[20:23]
	v_mfma_f32_16x16x32_bf16 v[8:11], v[148:151], v[214:217], v[8:11]
	v_mfma_f32_16x16x32_bf16 v[4:7], v[156:159], v[214:217], v[4:7]
	v_mfma_f32_16x16x32_bf16 v[56:59], v[152:155], v[182:185], v[56:59]
	v_mfma_f32_16x16x32_bf16 v[52:55], v[174:177], v[182:185], v[52:55]
	v_mfma_f32_16x16x32_bf16 v[40:43], v[152:155], v[202:205], v[40:43]
	v_mfma_f32_16x16x32_bf16 v[36:39], v[174:177], v[202:205], v[36:39]
	v_mfma_f32_16x16x32_bf16 v[24:27], v[152:155], v[210:213], v[24:27]
	v_mfma_f32_16x16x32_bf16 v[20:23], v[174:177], v[210:213], v[20:23]
	v_mfma_f32_16x16x32_bf16 v[8:11], v[152:155], v[218:221], v[8:11]
	v_mfma_f32_16x16x32_bf16 v[4:7], v[174:177], v[218:221], v[4:7]
	s_setprio 0
	s_add_u32 s24, s24, 0x100
	s_addc_u32 s25, s25, 0
	s_add_u32 s59, s59, 0x100
	s_addc_u32 s60, s60, 0
	s_cmp_ge_i32 s61, s23
	s_mov_b32 s26, s61
	s_add_i32 s61, s26, 2
	s_add_u32 s27, s24, 0xfffe0080
	s_addc_u32 s28, s25, -1
	s_add_i32 s62, 0, 0x10000
	s_cmp_eq_u32 s58, s26
	s_cselect_b32 s29, s54, s28
	s_cselect_b32 s28, s55, s27
	s_cselect_b32 s27, s56, s60
	s_cselect_b32 s26, s57, s59
	s_add_i32 s64, 0, 0x14000
	v_add_u32_e32 v144, s62, v161
	v_add_u32_e32 v174, s64, v161
	s_barrier
.LBB0_2125:
	ds_read_b128 v[132:135], v144
	ds_read_b128 v[136:139], v144 offset:1024
	ds_read_b128 v[140:143], v144 offset:2048
	ds_read_b128 v[144:147], v144 offset:3072
	ds_read_b128 v[148:151], v174
	ds_read_b128 v[152:155], v174 offset:1024
	ds_read_b128 v[156:159], v174 offset:2048
	ds_read_b128 v[174:177], v174 offset:3072
	v_lshl_add_u64 v[190:191], s[24:25], 0, v[170:171]
	s_add_i32 m0, s41, 0xc000
	ds_read_b128 v[178:181], v193
	ds_read_b128 v[182:185], v193 offset:1024
	ds_read_b128 v[186:189], v193 offset:2048
	ds_read_b128 v[202:205], v193 offset:3072
	ds_read_b128 v[206:209], v193 offset:4096
	ds_read_b128 v[210:213], v193 offset:5120
	ds_read_b128 v[214:217], v193 offset:6144
	ds_read_b128 v[218:221], v193 offset:7168
	global_load_lds_dwordx4 v[190:191], off
	v_lshl_add_u64 v[190:191], s[24:25], 0, v[172:173]
	s_add_i32 m0, s41, 0xe000
	s_nop 0
	global_load_lds_dwordx4 v[190:191], off
	s_waitcnt vmcnt(8)
	s_waitcnt lgkmcnt(0)
	s_barrier
; #define PG8_STAGE(bufoff, gbase, voff) do { _Pragma("unroll") for (int _i = 0; _i < 2; ++_i) \
;         __builtin_amdgcn_global_load_lds((const unsigned*)((const char*)(gbase) + (voff)[_i]), (LAS unsigned*)(lds + (bufoff) + ldsw + _i * 8192), 16, 0, 0); } while (0)
; #define PG8_LDA(dst, b, h) do { _Pragma("unroll") for (int m = 0; m < 4; ++m) _Pragma("unroll") for (int k = 0; k < 2; ++k) dst[m][k] = *(const LAS bf16x8*)(lds + PG8_SA(b, h) + aoff + m * 2048 + k * 1024); } while (0)
; #define PG8_LDB(dst, b, h) do { _Pragma("unroll") for (int n = 0; n < 2; ++n) _Pragma("unroll") for (int k = 0; k < 2; ++k) dst[n][k] = *(const LAS bf16x8*)(lds + PG8_SB(b, h) + boff + n * 2048 + k * 1024); } while (0)
; #define PG8_MMA(ai, bj, At, Bt) do { __builtin_amdgcn_s_setprio(1); _Pragma("unroll") for (int m = 0; m < 4; ++m) _Pragma("unroll") for (int n = 0; n < 2; ++n) _Pragma("unroll") for (int k = 0; k < 2; ++k) \
;         acc[ai][bj][m][n] = __builtin_amdgcn_mfma_f32_16x16x32_bf16(Bt[n][k], At[m][k], acc[ai][bj][m][n], 0, 0, 0); __builtin_amdgcn_s_setprio(0); } while (0)
; #define PG8_WAIT_V(n) asm volatile("s_waitcnt vmcnt(" #n ")" ::: "memory")
; #define PG8_WAIT_L(n) asm volatile("s_waitcnt lgkmcnt(" #n ")" ::: "memory")
; #define PG8_BAR __builtin_amdgcn_s_barrier()
; #define PG8_SCHED __builtin_amdgcn_sched_barrier(0)
; template <class Epi, bool ALIGN_EPI>
; DI void gemm_phase(LAS unsigned char* lds, const Sched& S, const Epi& E, int tid) {
;     ...
;             PG8_LDB(B0, 0, 0); PG8_LDB(B1, 0, 1); PG8_SCHED; PG8_LDA(At, 0, 0); PG8_STAGE(PG8_SA(1, 1), a1 + hstepA, voffA);
;             PG8_WAIT_V(8); PG8_WAIT_L(0); PG8_BAR; PG8_MMA(0, 0, At, B0); PG8_MMA(0, 1, At, B1); PG8_BAR; PG8_SCHED;
;             PG8_LDA(At, 0, 1); PG8_STAGE(PG8_SB(0, 0), b2, voffB); PG8_STAGE(PG8_SB(0, 1), b2 + hstepB, voffB); PG8_STAGE(PG8_SA(0, 0), a2, voffA);
;             PG8_WAIT_V(8); PG8_WAIT_L(0); PG8_BAR; PG8_MMA(1, 0, At, B0); PG8_MMA(1, 1, At, B1); PG8_BAR; PG8_SCHED;
;             PG8_LDB(B0, 1, 0); PG8_LDB(B1, 1, 1); PG8_SCHED; PG8_LDA(At, 1, 0); PG8_STAGE(PG8_SA(0, 1), a2 + hstepA, voffA);
;             PG8_WAIT_V(8); PG8_WAIT_L(0); PG8_BAR; PG8_MMA(0, 0, At, B0); PG8_MMA(0, 1, At, B1); PG8_BAR; PG8_SCHED;
;             PG8_LDA(At, 1, 1); PG8_STAGE(PG8_SB(1, 0), b3, voffB); PG8_STAGE(PG8_SB(1, 1), b3 + hstepB, voffB); PG8_STAGE(PG8_SA(1, 0), a3, voffA);
	s_setprio 1
	s_waitcnt lgkmcnt(0)
	v_mfma_f32_16x16x32_bf16 v[128:131], v[132:135], v[178:181], v[128:131]
	v_mfma_f32_16x16x32_bf16 v[124:127], v[140:143], v[178:181], v[124:127]
	v_mfma_f32_16x16x32_bf16 v[112:115], v[132:135], v[186:189], v[112:115]
	v_mfma_f32_16x16x32_bf16 v[108:111], v[140:143], v[186:189], v[108:111]
	v_mfma_f32_16x16x32_bf16 v[96:99], v[132:135], v[206:209], v[96:99]
	v_mfma_f32_16x16x32_bf16 v[92:95], v[140:143], v[206:209], v[92:95]
	v_mfma_f32_16x16x32_bf16 v[80:83], v[132:135], v[214:217], v[80:83]
	v_mfma_f32_16x16x32_bf16 v[76:79], v[140:143], v[214:217], v[76:79]
	v_mfma_f32_16x16x32_bf16 v[128:131], v[136:139], v[182:185], v[128:131]
	v_mfma_f32_16x16x32_bf16 v[124:127], v[144:147], v[182:185], v[124:127]
	v_mfma_f32_16x16x32_bf16 v[112:115], v[136:139], v[202:205], v[112:115]
	v_mfma_f32_16x16x32_bf16 v[108:111], v[144:147], v[202:205], v[108:111]
	v_mfma_f32_16x16x32_bf16 v[96:99], v[136:139], v[210:213], v[96:99]
	v_mfma_f32_16x16x32_bf16 v[92:95], v[144:147], v[210:213], v[92:95]
	v_mfma_f32_16x16x32_bf16 v[80:83], v[136:139], v[218:221], v[80:83]
	v_mfma_f32_16x16x32_bf16 v[76:79], v[144:147], v[218:221], v[76:79]
	s_setprio 0
	s_setprio 1
	v_mfma_f32_16x16x32_bf16 v[120:123], v[148:151], v[178:181], v[120:123]
	v_mfma_f32_16x16x32_bf16 v[116:119], v[156:159], v[178:181], v[116:119]
	v_mfma_f32_16x16x32_bf16 v[104:107], v[148:151], v[186:189], v[104:107]
	v_mfma_f32_16x16x32_bf16 v[100:103], v[156:159], v[186:189], v[100:103]
	v_mfma_f32_16x16x32_bf16 v[88:91], v[148:151], v[206:209], v[88:91]
	v_mfma_f32_16x16x32_bf16 v[84:87], v[156:159], v[206:209], v[84:87]
	v_mfma_f32_16x16x32_bf16 v[72:75], v[148:151], v[214:217], v[72:75]
	v_mfma_f32_16x16x32_bf16 v[68:71], v[156:159], v[214:217], v[68:71]
	v_mfma_f32_16x16x32_bf16 v[120:123], v[152:155], v[182:185], v[120:123]
	v_mfma_f32_16x16x32_bf16 v[116:119], v[174:177], v[182:185], v[116:119]
	v_mfma_f32_16x16x32_bf16 v[104:107], v[152:155], v[202:205], v[104:107]
	v_mfma_f32_16x16x32_bf16 v[100:103], v[174:177], v[202:205], v[100:103]
	v_mfma_f32_16x16x32_bf16 v[88:91], v[152:155], v[210:213], v[88:91]
	v_mfma_f32_16x16x32_bf16 v[84:87], v[174:177], v[210:213], v[84:87]
	v_mfma_f32_16x16x32_bf16 v[72:75], v[152:155], v[218:221], v[72:75]
	v_mfma_f32_16x16x32_bf16 v[68:71], v[174:177], v[218:221], v[68:71]
	s_setprio 0
	s_barrier
	s_add_i32 s62, s62, s40
	v_lshl_add_u64 v[190:191], s[26:27], 0, v[164:165]
	s_mov_b32 m0, s62
	ds_read_b128 v[178:181], v193 offset:16384
	ds_read_b128 v[182:185], v193 offset:17408
	ds_read_b128 v[186:189], v193 offset:18432
	ds_read_b128 v[202:205], v193 offset:19456
	ds_read_b128 v[206:209], v193 offset:20480
	ds_read_b128 v[210:213], v193 offset:21504
	ds_read_b128 v[214:217], v193 offset:22528
	ds_read_b128 v[218:221], v193 offset:23552
	global_load_lds_dwordx4 v[190:191], off
	s_add_i32 m0, s62, 0x2000
	s_add_u32 s62, s26, 0x20000
	v_lshl_add_u64 v[194:195], s[26:27], 0, v[168:169]
	s_addc_u32 s63, s27, 0
	s_add_i32 s64, s64, s40
	global_load_lds_dwordx4 v[194:195], off
	v_lshl_add_u64 v[222:223], s[62:63], 0, v[164:165]
	s_mov_b32 m0, s64
	v_lshl_add_u64 v[224:225], s[28:29], 0, v[166:167]
	global_load_lds_dwordx4 v[222:223], off
	v_lshl_add_u64 v[222:223], s[62:63], 0, v[168:169]
	s_add_i32 m0, s64, 0x2000
	s_nop 0
	global_load_lds_dwordx4 v[222:223], off
	v_lshl_add_u64 v[222:223], s[28:29], 0, v[162:163]
	s_mov_b32 m0, s41
	s_nop 0
	global_load_lds_dwordx4 v[222:223], off
	s_mov_b32 m0, s42
	s_nop 0
	global_load_lds_dwordx4 v[224:225], off
	s_waitcnt vmcnt(8)
	s_waitcnt lgkmcnt(0)
	s_barrier
	s_setprio 1
	s_waitcnt lgkmcnt(0)
	v_mfma_f32_16x16x32_bf16 v[64:67], v[132:135], v[178:181], v[64:67]
	v_mfma_f32_16x16x32_bf16 v[60:63], v[140:143], v[178:181], v[60:63]
	v_mfma_f32_16x16x32_bf16 v[48:51], v[132:135], v[186:189], v[48:51]
	v_mfma_f32_16x16x32_bf16 v[44:47], v[140:143], v[186:189], v[44:47]
	v_mfma_f32_16x16x32_bf16 v[32:35], v[132:135], v[206:209], v[32:35]
	v_mfma_f32_16x16x32_bf16 v[28:31], v[140:143], v[206:209], v[28:31]
	v_mfma_f32_16x16x32_bf16 v[16:19], v[132:135], v[214:217], v[16:19]
	v_mfma_f32_16x16x32_bf16 v[12:15], v[140:143], v[214:217], v[12:15]
	v_mfma_f32_16x16x32_bf16 v[64:67], v[136:139], v[182:185], v[64:67]
	v_mfma_f32_16x16x32_bf16 v[60:63], v[144:147], v[182:185], v[60:63]
	v_mfma_f32_16x16x32_bf16 v[48:51], v[136:139], v[202:205], v[48:51]
	v_mfma_f32_16x16x32_bf16 v[44:47], v[144:147], v[202:205], v[44:47]
	v_mfma_f32_16x16x32_bf16 v[32:35], v[136:139], v[210:213], v[32:35]
	v_mfma_f32_16x16x32_bf16 v[28:31], v[144:147], v[210:213], v[28:31]
	v_mfma_f32_16x16x32_bf16 v[16:19], v[136:139], v[218:221], v[16:19]
	v_mfma_f32_16x16x32_bf16 v[12:15], v[144:147], v[218:221], v[12:15]
	s_setprio 0
	s_setprio 1
	v_mfma_f32_16x16x32_bf16 v[56:59], v[148:151], v[178:181], v[56:59]
	v_mfma_f32_16x16x32_bf16 v[52:55], v[156:159], v[178:181], v[52:55]
	v_mfma_f32_16x16x32_bf16 v[40:43], v[148:151], v[186:189], v[40:43]
	v_mfma_f32_16x16x32_bf16 v[36:39], v[156:159], v[186:189], v[36:39]
	v_mfma_f32_16x16x32_bf16 v[24:27], v[148:151], v[206:209], v[24:27]
	v_mfma_f32_16x16x32_bf16 v[20:23], v[156:159], v[206:209], v[20:23]
	v_mfma_f32_16x16x32_bf16 v[8:11], v[148:151], v[214:217], v[8:11]
	v_mfma_f32_16x16x32_bf16 v[4:7], v[156:159], v[214:217], v[4:7]
	v_mfma_f32_16x16x32_bf16 v[56:59], v[152:155], v[182:185], v[56:59]
	v_mfma_f32_16x16x32_bf16 v[52:55], v[174:177], v[182:185], v[52:55]
	v_mfma_f32_16x16x32_bf16 v[40:43], v[152:155], v[202:205], v[40:43]
	v_mfma_f32_16x16x32_bf16 v[36:39], v[174:177], v[202:205], v[36:39]
	v_mfma_f32_16x16x32_bf16 v[24:27], v[152:155], v[210:213], v[24:27]
	v_mfma_f32_16x16x32_bf16 v[20:23], v[174:177], v[210:213], v[20:23]
	v_mfma_f32_16x16x32_bf16 v[8:11], v[152:155], v[218:221], v[8:11]
	v_mfma_f32_16x16x32_bf16 v[4:7], v[174:177], v[218:221], v[4:7]
	s_setprio 0
	s_barrier
; #define PG8_STAGE(bufoff, gbase, voff) do { _Pragma("unroll") for (int _i = 0; _i < 2; ++_i) \
;         __builtin_amdgcn_global_load_lds((const unsigned*)((const char*)(gbase) + (voff)[_i]), (LAS unsigned*)(lds + (bufoff) + ldsw + _i * 8192), 16, 0, 0); } while (0)
; #define PG8_LDA(dst, b, h) do { _Pragma("unroll") for (int m = 0; m < 4; ++m) _Pragma("unroll") for (int k = 0; k < 2; ++k) dst[m][k] = *(const LAS bf16x8*)(lds + PG8_SA(b, h) + aoff + m * 2048 + k * 1024); } while (0)
; #define PG8_LDB(dst, b, h) do { _Pragma("unroll") for (int n = 0; n < 2; ++n) _Pragma("unroll") for (int k = 0; k < 2; ++k) dst[n][k] = *(const LAS bf16x8*)(lds + PG8_SB(b, h) + boff + n * 2048 + k * 1024); } while (0)
; #define PG8_MMA(ai, bj, At, Bt) do { __builtin_amdgcn_s_setprio(1); _Pragma("unroll") for (int m = 0; m < 4; ++m) _Pragma("unroll") for (int n = 0; n < 2; ++n) _Pragma("unroll") for (int k = 0; k < 2; ++k) \
;         acc[ai][bj][m][n] = __builtin_amdgcn_mfma_f32_16x16x32_bf16(Bt[n][k], At[m][k], acc[ai][bj][m][n], 0, 0, 0); __builtin_amdgcn_s_setprio(0); } while (0)
; #define PG8_WAIT_V(n) asm volatile("s_waitcnt vmcnt(" #n ")" ::: "memory")
; #define PG8_WAIT_L(n) asm volatile("s_waitcnt lgkmcnt(" #n ")" ::: "memory")
; #define PG8_BAR __builtin_amdgcn_s_barrier()
; #define PG8_SCHED __builtin_amdgcn_sched_barrier(0)
; template <class Epi, bool ALIGN_EPI>
; DI void gemm_phase(LAS unsigned char* lds, const Sched& S, const Epi& E, int tid) {
;     ...
;             PG8_LDB(B0, 1, 0); PG8_LDB(B1, 1, 1); PG8_SCHED; PG8_LDA(At, 1, 0); PG8_STAGE(PG8_SA(0, 1), a2 + hstepA, voffA);
;             PG8_WAIT_V(8); PG8_WAIT_L(0); PG8_BAR; PG8_MMA(0, 0, At, B0); PG8_MMA(0, 1, At, B1); PG8_BAR; PG8_SCHED;
	s_add_i32 s62, 0, 0x18000
	s_add_i32 s63, 0, 0x1c000
	v_add_u32_e32 v144, s62, v161
	v_add_u32_e32 v174, s63, v161
	ds_read_b128 v[132:135], v144
	ds_read_b128 v[136:139], v144 offset:1024
	ds_read_b128 v[140:143], v144 offset:2048
	ds_read_b128 v[144:147], v144 offset:3072
	ds_read_b128 v[148:151], v174
	ds_read_b128 v[152:155], v174 offset:1024
	ds_read_b128 v[156:159], v174 offset:2048
	ds_read_b128 v[174:177], v174 offset:3072
	s_add_u32 s28, s28, 0x20000
	s_addc_u32 s29, s29, 0
	s_mov_b32 m0, s43
	v_lshl_add_u64 v[226:227], s[28:29], 0, v[162:163]
	ds_read_b128 v[178:181], v193 offset:32768
	ds_read_b128 v[182:185], v193 offset:33792
	ds_read_b128 v[186:189], v193 offset:34816
	ds_read_b128 v[202:205], v193 offset:35840
	ds_read_b128 v[206:209], v193 offset:36864
	ds_read_b128 v[210:213], v193 offset:37888
	ds_read_b128 v[214:217], v193 offset:38912
	ds_read_b128 v[218:221], v193 offset:39936
	global_load_lds_dwordx4 v[226:227], off
	v_lshl_add_u64 v[226:227], s[28:29], 0, v[166:167]
	s_mov_b32 m0, s44
	s_nop 0
	global_load_lds_dwordx4 v[226:227], off
	s_waitcnt vmcnt(8)
	s_waitcnt lgkmcnt(0)
	s_barrier
	s_setprio 1
	s_waitcnt lgkmcnt(0)
	v_mfma_f32_16x16x32_bf16 v[128:131], v[132:135], v[178:181], v[128:131]
	v_mfma_f32_16x16x32_bf16 v[124:127], v[140:143], v[178:181], v[124:127]
	v_mfma_f32_16x16x32_bf16 v[112:115], v[132:135], v[186:189], v[112:115]
	v_mfma_f32_16x16x32_bf16 v[108:111], v[140:143], v[186:189], v[108:111]
	v_mfma_f32_16x16x32_bf16 v[96:99], v[132:135], v[206:209], v[96:99]
	v_mfma_f32_16x16x32_bf16 v[92:95], v[140:143], v[206:209], v[92:95]
	v_mfma_f32_16x16x32_bf16 v[80:83], v[132:135], v[214:217], v[80:83]
	v_mfma_f32_16x16x32_bf16 v[76:79], v[140:143], v[214:217], v[76:79]
	v_mfma_f32_16x16x32_bf16 v[128:131], v[136:139], v[182:185], v[128:131]
	v_mfma_f32_16x16x32_bf16 v[124:127], v[144:147], v[182:185], v[124:127]
	v_mfma_f32_16x16x32_bf16 v[112:115], v[136:139], v[202:205], v[112:115]
	v_mfma_f32_16x16x32_bf16 v[108:111], v[144:147], v[202:205], v[108:111]
	v_mfma_f32_16x16x32_bf16 v[96:99], v[136:139], v[210:213], v[96:99]
	v_mfma_f32_16x16x32_bf16 v[92:95], v[144:147], v[210:213], v[92:95]
	v_mfma_f32_16x16x32_bf16 v[80:83], v[136:139], v[218:221], v[80:83]
	v_mfma_f32_16x16x32_bf16 v[76:79], v[144:147], v[218:221], v[76:79]
	s_setprio 0
	s_setprio 1
	v_mfma_f32_16x16x32_bf16 v[120:123], v[148:151], v[178:181], v[120:123]
	v_mfma_f32_16x16x32_bf16 v[116:119], v[156:159], v[178:181], v[116:119]
	v_mfma_f32_16x16x32_bf16 v[104:107], v[148:151], v[186:189], v[104:107]
	v_mfma_f32_16x16x32_bf16 v[100:103], v[156:159], v[186:189], v[100:103]
	v_mfma_f32_16x16x32_bf16 v[88:91], v[148:151], v[206:209], v[88:91]
	v_mfma_f32_16x16x32_bf16 v[84:87], v[156:159], v[206:209], v[84:87]
	v_mfma_f32_16x16x32_bf16 v[72:75], v[148:151], v[214:217], v[72:75]
	v_mfma_f32_16x16x32_bf16 v[68:71], v[156:159], v[214:217], v[68:71]
	v_mfma_f32_16x16x32_bf16 v[120:123], v[152:155], v[182:185], v[120:123]
	v_mfma_f32_16x16x32_bf16 v[116:119], v[174:177], v[182:185], v[116:119]
	v_mfma_f32_16x16x32_bf16 v[104:107], v[152:155], v[202:205], v[104:107]
	v_mfma_f32_16x16x32_bf16 v[100:103], v[174:177], v[202:205], v[100:103]
	v_mfma_f32_16x16x32_bf16 v[88:91], v[152:155], v[210:213], v[88:91]
	v_mfma_f32_16x16x32_bf16 v[84:87], v[174:177], v[210:213], v[84:87]
	v_mfma_f32_16x16x32_bf16 v[72:75], v[152:155], v[218:221], v[72:75]
	v_mfma_f32_16x16x32_bf16 v[68:71], v[174:177], v[218:221], v[68:71]
	s_setprio 0
	s_barrier
; #define PG8_STAGE(bufoff, gbase, voff) do { _Pragma("unroll") for (int _i = 0; _i < 2; ++_i) \
;         __builtin_amdgcn_global_load_lds((const unsigned*)((const char*)(gbase) + (voff)[_i]), (LAS unsigned*)(lds + (bufoff) + ldsw + _i * 8192), 16, 0, 0); } while (0)
; #define PG8_LDA(dst, b, h) do { _Pragma("unroll") for (int m = 0; m < 4; ++m) _Pragma("unroll") for (int k = 0; k < 2; ++k) dst[m][k] = *(const LAS bf16x8*)(lds + PG8_SA(b, h) + aoff + m * 2048 + k * 1024); } while (0)
; #define PG8_MMA(ai, bj, At, Bt) do { __builtin_amdgcn_s_setprio(1); _Pragma("unroll") for (int m = 0; m < 4; ++m) _Pragma("unroll") for (int n = 0; n < 2; ++n) _Pragma("unroll") for (int k = 0; k < 2; ++k) \
;         acc[ai][bj][m][n] = __builtin_amdgcn_mfma_f32_16x16x32_bf16(Bt[n][k], At[m][k], acc[ai][bj][m][n], 0, 0, 0); __builtin_amdgcn_s_setprio(0); } while (0)
; #define PG8_WAIT_V(n) asm volatile("s_waitcnt vmcnt(" #n ")" ::: "memory")
; #define PG8_WAIT_L(n) asm volatile("s_waitcnt lgkmcnt(" #n ")" ::: "memory")
; #define PG8_BAR __builtin_amdgcn_s_barrier()
; #define PG8_SCHED __builtin_amdgcn_sched_barrier(0)
; template <class Epi, bool ALIGN_EPI>
; DI void gemm_phase(LAS unsigned char* lds, const Sched& S, const Epi& E, int tid) {
;     ...
;             PG8_LDA(At, 1, 1); PG8_STAGE(PG8_SB(1, 0), b3, voffB); PG8_STAGE(PG8_SB(1, 1), b3 + hstepB, voffB); PG8_STAGE(PG8_SA(1, 0), a3, voffA);
;             PG8_WAIT_V(8); PG8_WAIT_L(0); PG8_BAR; PG8_MMA(1, 0, At, B0); PG8_MMA(1, 1, At, B1); PG8_BAR; PG8_SCHED;
;         }
;         if constexpr (ALIGN_EPI) { if (wr == 0) PG8_BAR; }
	s_add_i32 s28, s62, s40
	v_lshl_add_u64 v[190:191], v[190:191], 0, s[84:85]
	s_mov_b32 m0, s28
	ds_read_b128 v[178:181], v193 offset:49152
	ds_read_b128 v[182:185], v193 offset:50176
	ds_read_b128 v[186:189], v193 offset:51200
	ds_read_b128 v[202:205], v193 offset:52224
	ds_read_b128 v[206:209], v193 offset:53248
	ds_read_b128 v[210:213], v193 offset:54272
	ds_read_b128 v[214:217], v193 offset:55296
	ds_read_b128 v[218:221], v193 offset:56320
	global_load_lds_dwordx4 v[190:191], off
	s_add_i32 m0, s28, 0x2000
	s_add_u32 s26, s26, 0x20080
	v_lshl_add_u64 v[190:191], v[194:195], 0, s[84:85]
	s_addc_u32 s27, s27, 0
	s_add_i32 s28, s63, s40
	global_load_lds_dwordx4 v[190:191], off
	v_lshl_add_u64 v[190:191], s[26:27], 0, v[164:165]
	s_mov_b32 m0, s28
	s_nop 0
	global_load_lds_dwordx4 v[190:191], off
	v_lshl_add_u64 v[190:191], s[26:27], 0, v[168:169]
	s_add_i32 m0, s28, 0x2000
	s_nop 0
	global_load_lds_dwordx4 v[190:191], off
	v_lshl_add_u64 v[190:191], v[222:223], 0, s[84:85]
	s_mov_b32 m0, s46
	s_nop 0
	global_load_lds_dwordx4 v[190:191], off
	v_lshl_add_u64 v[190:191], v[224:225], 0, s[84:85]
	s_mov_b32 m0, s47
	s_nop 0
	global_load_lds_dwordx4 v[190:191], off
	s_waitcnt vmcnt(8)
	s_waitcnt lgkmcnt(0)
	s_barrier
	s_setprio 1
	s_waitcnt lgkmcnt(0)
	v_mfma_f32_16x16x32_bf16 v[64:67], v[132:135], v[178:181], v[64:67]
	v_mfma_f32_16x16x32_bf16 v[60:63], v[140:143], v[178:181], v[60:63]
	v_mfma_f32_16x16x32_bf16 v[48:51], v[132:135], v[186:189], v[48:51]
	v_mfma_f32_16x16x32_bf16 v[44:47], v[140:143], v[186:189], v[44:47]
	v_mfma_f32_16x16x32_bf16 v[32:35], v[132:135], v[206:209], v[32:35]
	v_mfma_f32_16x16x32_bf16 v[28:31], v[140:143], v[206:209], v[28:31]
	v_mfma_f32_16x16x32_bf16 v[16:19], v[132:135], v[214:217], v[16:19]
	v_mfma_f32_16x16x32_bf16 v[12:15], v[140:143], v[214:217], v[12:15]
	v_mfma_f32_16x16x32_bf16 v[64:67], v[136:139], v[182:185], v[64:67]
	v_mfma_f32_16x16x32_bf16 v[60:63], v[144:147], v[182:185], v[60:63]
	v_mfma_f32_16x16x32_bf16 v[48:51], v[136:139], v[202:205], v[48:51]
	v_mfma_f32_16x16x32_bf16 v[44:47], v[144:147], v[202:205], v[44:47]
	v_mfma_f32_16x16x32_bf16 v[32:35], v[136:139], v[210:213], v[32:35]
	v_mfma_f32_16x16x32_bf16 v[28:31], v[144:147], v[210:213], v[28:31]
	v_mfma_f32_16x16x32_bf16 v[16:19], v[136:139], v[218:221], v[16:19]
	v_mfma_f32_16x16x32_bf16 v[12:15], v[144:147], v[218:221], v[12:15]
	s_setprio 0
	s_setprio 1
	v_mfma_f32_16x16x32_bf16 v[56:59], v[148:151], v[178:181], v[56:59]
	v_mfma_f32_16x16x32_bf16 v[52:55], v[156:159], v[178:181], v[52:55]
	v_mfma_f32_16x16x32_bf16 v[40:43], v[148:151], v[186:189], v[40:43]
	v_mfma_f32_16x16x32_bf16 v[36:39], v[156:159], v[186:189], v[36:39]
	v_mfma_f32_16x16x32_bf16 v[24:27], v[148:151], v[206:209], v[24:27]
	v_mfma_f32_16x16x32_bf16 v[20:23], v[156:159], v[206:209], v[20:23]
	v_mfma_f32_16x16x32_bf16 v[8:11], v[148:151], v[214:217], v[8:11]
	v_mfma_f32_16x16x32_bf16 v[4:7], v[156:159], v[214:217], v[4:7]
	v_mfma_f32_16x16x32_bf16 v[56:59], v[152:155], v[182:185], v[56:59]
	v_mfma_f32_16x16x32_bf16 v[52:55], v[174:177], v[182:185], v[52:55]
	v_mfma_f32_16x16x32_bf16 v[40:43], v[152:155], v[202:205], v[40:43]
	v_mfma_f32_16x16x32_bf16 v[36:39], v[174:177], v[202:205], v[36:39]
	v_mfma_f32_16x16x32_bf16 v[24:27], v[152:155], v[210:213], v[24:27]
	v_mfma_f32_16x16x32_bf16 v[20:23], v[174:177], v[210:213], v[20:23]
	v_mfma_f32_16x16x32_bf16 v[8:11], v[152:155], v[218:221], v[8:11]
	v_mfma_f32_16x16x32_bf16 v[4:7], v[174:177], v[218:221], v[4:7]
	s_setprio 0
	s_add_u32 s24, s24, 0x100
	s_addc_u32 s25, s25, 0
	s_add_u32 s59, s59, 0x100
	s_addc_u32 s60, s60, 0
	s_cmp_ge_i32 s61, s23
	s_mov_b32 s26, s61
	s_cbranch_scc1 .Lkx_2
	s_add_i32 s61, s26, 2
	s_add_u32 s27, s24, 0xfffe0080
	s_addc_u32 s28, s25, -1
	s_add_i32 s62, 0, 0x10000
	s_cmp_eq_u32 s58, s26
	s_cselect_b32 s29, s54, s28
	s_cselect_b32 s28, s55, s27
	s_cselect_b32 s27, s56, s60
	s_cselect_b32 s26, s57, s59
	s_add_i32 s64, 0, 0x14000
	v_add_u32_e32 v144, s62, v161
	v_add_u32_e32 v174, s64, v161
	s_barrier
	s_branch .LBB0_2125

; #define PG8_STAGE(bufoff, gbase, voff) do { _Pragma("unroll") for (int _i = 0; _i < 2; ++_i) \
;         __builtin_amdgcn_global_load_lds((const unsigned*)((const char*)(gbase) + (voff)[_i]), (LAS unsigned*)(lds + (bufoff) + ldsw + _i * 8192), 16, 0, 0); } while (0)
; #define PG8_LDA(dst, b, h) do { _Pragma("unroll") for (int m = 0; m < 4; ++m) _Pragma("unroll") for (int k = 0; k < 2; ++k) dst[m][k] = *(const LAS bf16x8*)(lds + PG8_SA(b, h) + aoff + m * 2048 + k * 1024); } while (0)
; #define PG8_LDB(dst, b, h) do { _Pragma("unroll") for (int n = 0; n < 2; ++n) _Pragma("unroll") for (int k = 0; k < 2; ++k) dst[n][k] = *(const LAS bf16x8*)(lds + PG8_SB(b, h) + boff + n * 2048 + k * 1024); } while (0)
; #define PG8_MMA(ai, bj, At, Bt) do { __builtin_amdgcn_s_setprio(1); _Pragma("unroll") for (int m = 0; m < 4; ++m) _Pragma("unroll") for (int n = 0; n < 2; ++n) _Pragma("unroll") for (int k = 0; k < 2; ++k) \
;         acc[ai][bj][m][n] = __builtin_amdgcn_mfma_f32_16x16x32_bf16(Bt[n][k], At[m][k], acc[ai][bj][m][n], 0, 0, 0); __builtin_amdgcn_s_setprio(0); } while (0)
; #define PG8_WAIT_V(n) asm volatile("s_waitcnt vmcnt(" #n ")" ::: "memory")
; #define PG8_BAR __builtin_amdgcn_s_barrier()
; template <class Epi, bool ALIGN_EPI>
; DI void gemm_phase(LAS unsigned char* lds, const Sched& S, const Epi& E, int tid) {
;     ...
;         const bool has_next = S.next(ui + 1, nxt);
;         const char* nA = has_next ? nxt.a : cA; const char* nB = has_next ? nxt.b : cB;
;         const int nt = cur.nt;
;         for (int t = 0; t < nt; t += 2) {
;             const bool last = (t == nt - 2);
;             const char* a1 = cA + (size_t)(t + 1) * kstep;
;             const char* a2 = last ? nA : cA + (size_t)(t + 2) * kstep; const char* b2 = last ? nB : cB + (size_t)(t + 2) * kstep;
;             const char* a3 = a2 + kstep; const char* b3 = b2 + kstep;
;             PG8_LDB(B0, 0, 0); PG8_LDB(B1, 0, 1); PG8_SCHED; PG8_LDA(At, 0, 0); PG8_STAGE(PG8_SA(1, 1), a1 + hstepA, voffA);
;             PG8_WAIT_V(8); PG8_WAIT_L(0); PG8_BAR; PG8_MMA(0, 0, At, B0); PG8_MMA(0, 1, At, B1); PG8_BAR; PG8_SCHED;
;             PG8_LDA(At, 0, 1); PG8_STAGE(PG8_SB(0, 0), b2, voffB); PG8_STAGE(PG8_SB(0, 1), b2 + hstepB, voffB); PG8_STAGE(PG8_SA(0, 0), a2, voffA);
;             PG8_WAIT_V(8); PG8_WAIT_L(0); PG8_BAR; PG8_MMA(1, 0, At, B0); PG8_MMA(1, 1, At, B1); PG8_BAR; PG8_SCHED;
.LBB0_2407:
	s_and_b64 s[24:25], s[16:17], exec
	s_cselect_b32 s56, s13, s21
	s_cselect_b32 s57, s12, s20
	s_cselect_b32 s58, s15, s23
	s_cselect_b32 s59, s14, s22
	s_add_i32 s60, s55, -2
	s_add_u32 s61, s22, 0x100
	s_mov_b32 s81, s63
	s_addc_u32 s62, s23, 0
	s_mov_b32 s24, 0
	s_waitcnt lgkmcnt(0)
	s_add_i32 s63, s24, 2
	s_add_u32 s22, s20, 0x100
	s_addc_u32 s23, s21, 0
	s_add_i32 s64, 0, 0x10000
	s_cmp_eq_u32 s60, s24
	s_cselect_b32 s27, s56, s23
	s_cselect_b32 s26, s57, s22
	s_cselect_b32 s25, s58, s62
	s_cselect_b32 s24, s59, s61
	s_add_i32 s65, 0, 0x14000
	v_add_u32_e32 v144, s64, v161
	v_add_u32_e32 v174, s65, v161
	ds_read_b128 v[132:135], v144
	ds_read_b128 v[136:139], v144 offset:1024
	ds_read_b128 v[140:143], v144 offset:2048
	ds_read_b128 v[144:147], v144 offset:3072
	ds_read_b128 v[148:151], v174
	ds_read_b128 v[152:155], v174 offset:1024
	ds_read_b128 v[156:159], v174 offset:2048
	ds_read_b128 v[174:177], v174 offset:3072
	v_lshl_add_u64 v[190:191], s[20:21], 0, v[170:171]
	s_add_i32 m0, s39, 0xc000
	ds_read_b128 v[178:181], v193
	ds_read_b128 v[182:185], v193 offset:1024
	ds_read_b128 v[186:189], v193 offset:2048
	ds_read_b128 v[202:205], v193 offset:3072
	ds_read_b128 v[206:209], v193 offset:4096
	ds_read_b128 v[210:213], v193 offset:5120
	ds_read_b128 v[214:217], v193 offset:6144
	ds_read_b128 v[218:221], v193 offset:7168
	global_load_lds_dwordx4 v[190:191], off
	v_lshl_add_u64 v[190:191], s[20:21], 0, v[172:173]
	s_add_i32 m0, s39, 0xe000
	s_nop 0
	global_load_lds_dwordx4 v[190:191], off
	s_waitcnt vmcnt(8)
	s_waitcnt lgkmcnt(0)
	s_barrier
	s_setprio 1
	s_waitcnt lgkmcnt(0)
	v_mfma_f32_16x16x32_bf16 v[128:131], v[132:135], v[178:181], 0
	v_mfma_f32_16x16x32_bf16 v[124:127], v[140:143], v[178:181], 0
	v_mfma_f32_16x16x32_bf16 v[112:115], v[132:135], v[186:189], 0
	v_mfma_f32_16x16x32_bf16 v[108:111], v[140:143], v[186:189], 0
	v_mfma_f32_16x16x32_bf16 v[96:99], v[132:135], v[206:209], 0
	v_mfma_f32_16x16x32_bf16 v[92:95], v[140:143], v[206:209], 0
	v_mfma_f32_16x16x32_bf16 v[80:83], v[132:135], v[214:217], 0
	v_mfma_f32_16x16x32_bf16 v[76:79], v[140:143], v[214:217], 0
	v_mfma_f32_16x16x32_bf16 v[128:131], v[136:139], v[182:185], v[128:131]
	v_mfma_f32_16x16x32_bf16 v[124:127], v[144:147], v[182:185], v[124:127]
	v_mfma_f32_16x16x32_bf16 v[112:115], v[136:139], v[202:205], v[112:115]
	v_mfma_f32_16x16x32_bf16 v[108:111], v[144:147], v[202:205], v[108:111]
	v_mfma_f32_16x16x32_bf16 v[96:99], v[136:139], v[210:213], v[96:99]
	v_mfma_f32_16x16x32_bf16 v[92:95], v[144:147], v[210:213], v[92:95]
	v_mfma_f32_16x16x32_bf16 v[80:83], v[136:139], v[218:221], v[80:83]
	v_mfma_f32_16x16x32_bf16 v[76:79], v[144:147], v[218:221], v[76:79]
	s_setprio 0
	s_setprio 1
	v_mfma_f32_16x16x32_bf16 v[120:123], v[148:151], v[178:181], 0
	v_mfma_f32_16x16x32_bf16 v[116:119], v[156:159], v[178:181], 0
	v_mfma_f32_16x16x32_bf16 v[104:107], v[148:151], v[186:189], 0
	v_mfma_f32_16x16x32_bf16 v[100:103], v[156:159], v[186:189], 0
	v_mfma_f32_16x16x32_bf16 v[88:91], v[148:151], v[206:209], 0
	v_mfma_f32_16x16x32_bf16 v[84:87], v[156:159], v[206:209], 0
	v_mfma_f32_16x16x32_bf16 v[72:75], v[148:151], v[214:217], 0
	v_mfma_f32_16x16x32_bf16 v[68:71], v[156:159], v[214:217], 0
	v_mfma_f32_16x16x32_bf16 v[120:123], v[152:155], v[182:185], v[120:123]
	v_mfma_f32_16x16x32_bf16 v[116:119], v[174:177], v[182:185], v[116:119]
	v_mfma_f32_16x16x32_bf16 v[104:107], v[152:155], v[202:205], v[104:107]
	v_mfma_f32_16x16x32_bf16 v[100:103], v[174:177], v[202:205], v[100:103]
	v_mfma_f32_16x16x32_bf16 v[88:91], v[152:155], v[210:213], v[88:91]
	v_mfma_f32_16x16x32_bf16 v[84:87], v[174:177], v[210:213], v[84:87]
	v_mfma_f32_16x16x32_bf16 v[72:75], v[152:155], v[218:221], v[72:75]
	v_mfma_f32_16x16x32_bf16 v[68:71], v[174:177], v[218:221], v[68:71]
	s_setprio 0
	s_barrier
	s_add_i32 s20, s64, s38
	v_lshl_add_u64 v[190:191], s[24:25], 0, v[164:165]
	s_mov_b32 m0, s20
	ds_read_b128 v[178:181], v193 offset:16384
	ds_read_b128 v[182:185], v193 offset:17408
	ds_read_b128 v[186:189], v193 offset:18432
	ds_read_b128 v[202:205], v193 offset:19456
	ds_read_b128 v[206:209], v193 offset:20480
	ds_read_b128 v[210:213], v193 offset:21504
	ds_read_b128 v[214:217], v193 offset:22528
	ds_read_b128 v[218:221], v193 offset:23552
	global_load_lds_dwordx4 v[190:191], off
	s_add_i32 m0, s20, 0x2000
	s_add_u32 s20, s24, 0x104000
	v_lshl_add_u64 v[194:195], s[24:25], 0, v[168:169]
	s_addc_u32 s21, s25, 0
	s_add_i32 s64, s65, s38
	global_load_lds_dwordx4 v[194:195], off
	v_lshl_add_u64 v[222:223], s[20:21], 0, v[164:165]
	s_mov_b32 m0, s64
	v_lshl_add_u64 v[224:225], s[26:27], 0, v[166:167]
	global_load_lds_dwordx4 v[222:223], off
	v_lshl_add_u64 v[222:223], s[20:21], 0, v[168:169]
	s_add_i32 m0, s64, 0x2000
	s_nop 0
	global_load_lds_dwordx4 v[222:223], off
	v_lshl_add_u64 v[222:223], s[26:27], 0, v[162:163]
	s_mov_b32 m0, s39
	s_nop 0
	global_load_lds_dwordx4 v[222:223], off
	s_mov_b32 m0, s40
	s_nop 0
	global_load_lds_dwordx4 v[224:225], off
	s_waitcnt vmcnt(8)
	s_waitcnt lgkmcnt(0)
	s_barrier
; #define PG8_STAGE(bufoff, gbase, voff) do { _Pragma("unroll") for (int _i = 0; _i < 2; ++_i) \
;         __builtin_amdgcn_global_load_lds((const unsigned*)((const char*)(gbase) + (voff)[_i]), (LAS unsigned*)(lds + (bufoff) + ldsw + _i * 8192), 16, 0, 0); } while (0)
; #define PG8_LDA(dst, b, h) do { _Pragma("unroll") for (int m = 0; m < 4; ++m) _Pragma("unroll") for (int k = 0; k < 2; ++k) dst[m][k] = *(const LAS bf16x8*)(lds + PG8_SA(b, h) + aoff + m * 2048 + k * 1024); } while (0)
; #define PG8_LDB(dst, b, h) do { _Pragma("unroll") for (int n = 0; n < 2; ++n) _Pragma("unroll") for (int k = 0; k < 2; ++k) dst[n][k] = *(const LAS bf16x8*)(lds + PG8_SB(b, h) + boff + n * 2048 + k * 1024); } while (0)
; #define PG8_MMA(ai, bj, At, Bt) do { __builtin_amdgcn_s_setprio(1); _Pragma("unroll") for (int m = 0; m < 4; ++m) _Pragma("unroll") for (int n = 0; n < 2; ++n) _Pragma("unroll") for (int k = 0; k < 2; ++k) \
;         acc[ai][bj][m][n] = __builtin_amdgcn_mfma_f32_16x16x32_bf16(Bt[n][k], At[m][k], acc[ai][bj][m][n], 0, 0, 0); __builtin_amdgcn_s_setprio(0); } while (0)
; #define PG8_WAIT_V(n) asm volatile("s_waitcnt vmcnt(" #n ")" ::: "memory")
; #define PG8_WAIT_L(n) asm volatile("s_waitcnt lgkmcnt(" #n ")" ::: "memory")
; #define PG8_BAR __builtin_amdgcn_s_barrier()
; #define PG8_SCHED __builtin_amdgcn_sched_barrier(0)
; template <class Epi, bool ALIGN_EPI>
; DI void gemm_phase(LAS unsigned char* lds, const Sched& S, const Epi& E, int tid) {
;     ...
;             PG8_WAIT_V(8); PG8_WAIT_L(0); PG8_BAR; PG8_MMA(1, 0, At, B0); PG8_MMA(1, 1, At, B1); PG8_BAR; PG8_SCHED;
;             PG8_LDB(B0, 1, 0); PG8_LDB(B1, 1, 1); PG8_SCHED; PG8_LDA(At, 1, 0); PG8_STAGE(PG8_SA(0, 1), a2 + hstepA, voffA);
;             PG8_WAIT_V(8); PG8_WAIT_L(0); PG8_BAR; PG8_MMA(0, 0, At, B0); PG8_MMA(0, 1, At, B1); PG8_BAR; PG8_SCHED;
	s_setprio 1
	s_waitcnt lgkmcnt(0)
	v_mfma_f32_16x16x32_bf16 v[64:67], v[132:135], v[178:181], 0
	v_mfma_f32_16x16x32_bf16 v[60:63], v[140:143], v[178:181], 0
	v_mfma_f32_16x16x32_bf16 v[48:51], v[132:135], v[186:189], 0
	v_mfma_f32_16x16x32_bf16 v[44:47], v[140:143], v[186:189], 0
	v_mfma_f32_16x16x32_bf16 v[32:35], v[132:135], v[206:209], 0
	v_mfma_f32_16x16x32_bf16 v[28:31], v[140:143], v[206:209], 0
	v_mfma_f32_16x16x32_bf16 v[16:19], v[132:135], v[214:217], 0
	v_mfma_f32_16x16x32_bf16 v[12:15], v[140:143], v[214:217], 0
	v_mfma_f32_16x16x32_bf16 v[64:67], v[136:139], v[182:185], v[64:67]
	v_mfma_f32_16x16x32_bf16 v[60:63], v[144:147], v[182:185], v[60:63]
	v_mfma_f32_16x16x32_bf16 v[48:51], v[136:139], v[202:205], v[48:51]
	v_mfma_f32_16x16x32_bf16 v[44:47], v[144:147], v[202:205], v[44:47]
	v_mfma_f32_16x16x32_bf16 v[32:35], v[136:139], v[210:213], v[32:35]
	v_mfma_f32_16x16x32_bf16 v[28:31], v[144:147], v[210:213], v[28:31]
	v_mfma_f32_16x16x32_bf16 v[16:19], v[136:139], v[218:221], v[16:19]
	v_mfma_f32_16x16x32_bf16 v[12:15], v[144:147], v[218:221], v[12:15]
	s_setprio 0
	s_setprio 1
	v_mfma_f32_16x16x32_bf16 v[56:59], v[148:151], v[178:181], 0
	v_mfma_f32_16x16x32_bf16 v[52:55], v[156:159], v[178:181], 0
	v_mfma_f32_16x16x32_bf16 v[40:43], v[148:151], v[186:189], 0
	v_mfma_f32_16x16x32_bf16 v[36:39], v[156:159], v[186:189], 0
	v_mfma_f32_16x16x32_bf16 v[24:27], v[148:151], v[206:209], 0
	v_mfma_f32_16x16x32_bf16 v[20:23], v[156:159], v[206:209], 0
	v_mfma_f32_16x16x32_bf16 v[8:11], v[148:151], v[214:217], 0
	v_mfma_f32_16x16x32_bf16 v[4:7], v[156:159], v[214:217], 0
	v_mfma_f32_16x16x32_bf16 v[56:59], v[152:155], v[182:185], v[56:59]
	v_mfma_f32_16x16x32_bf16 v[52:55], v[174:177], v[182:185], v[52:55]
	v_mfma_f32_16x16x32_bf16 v[40:43], v[152:155], v[202:205], v[40:43]
	v_mfma_f32_16x16x32_bf16 v[36:39], v[174:177], v[202:205], v[36:39]
	v_mfma_f32_16x16x32_bf16 v[24:27], v[152:155], v[210:213], v[24:27]
	v_mfma_f32_16x16x32_bf16 v[20:23], v[174:177], v[210:213], v[20:23]
	v_mfma_f32_16x16x32_bf16 v[8:11], v[152:155], v[218:221], v[8:11]
	v_mfma_f32_16x16x32_bf16 v[4:7], v[174:177], v[218:221], v[4:7]
	s_setprio 0
	s_barrier
	s_add_i32 s64, 0, 0x18000
	s_add_i32 s65, 0, 0x1c000
	v_add_u32_e32 v144, s64, v161
	v_add_u32_e32 v174, s65, v161
	ds_read_b128 v[132:135], v144
	ds_read_b128 v[136:139], v144 offset:1024
	ds_read_b128 v[140:143], v144 offset:2048
	ds_read_b128 v[144:147], v144 offset:3072
	ds_read_b128 v[148:151], v174
	ds_read_b128 v[152:155], v174 offset:1024
	ds_read_b128 v[156:159], v174 offset:2048
	ds_read_b128 v[174:177], v174 offset:3072
	s_add_u32 s20, s26, 0x104000
	s_addc_u32 s21, s27, 0
	s_mov_b32 m0, s41
	v_lshl_add_u64 v[226:227], s[20:21], 0, v[162:163]
	ds_read_b128 v[178:181], v193 offset:32768
	ds_read_b128 v[182:185], v193 offset:33792
	ds_read_b128 v[186:189], v193 offset:34816
	ds_read_b128 v[202:205], v193 offset:35840
	ds_read_b128 v[206:209], v193 offset:36864
	ds_read_b128 v[210:213], v193 offset:37888
	ds_read_b128 v[214:217], v193 offset:38912
	ds_read_b128 v[218:221], v193 offset:39936
	global_load_lds_dwordx4 v[226:227], off
	v_lshl_add_u64 v[226:227], s[20:21], 0, v[166:167]
	s_mov_b32 m0, s42
	s_nop 0
	global_load_lds_dwordx4 v[226:227], off
	s_waitcnt vmcnt(8)
	s_waitcnt lgkmcnt(0)
	s_barrier
	s_setprio 1
	s_waitcnt lgkmcnt(0)
	v_mfma_f32_16x16x32_bf16 v[128:131], v[132:135], v[178:181], v[128:131]
	v_mfma_f32_16x16x32_bf16 v[124:127], v[140:143], v[178:181], v[124:127]
	v_mfma_f32_16x16x32_bf16 v[112:115], v[132:135], v[186:189], v[112:115]
	v_mfma_f32_16x16x32_bf16 v[108:111], v[140:143], v[186:189], v[108:111]
	v_mfma_f32_16x16x32_bf16 v[96:99], v[132:135], v[206:209], v[96:99]
	v_mfma_f32_16x16x32_bf16 v[92:95], v[140:143], v[206:209], v[92:95]
	v_mfma_f32_16x16x32_bf16 v[80:83], v[132:135], v[214:217], v[80:83]
	v_mfma_f32_16x16x32_bf16 v[76:79], v[140:143], v[214:217], v[76:79]
	v_mfma_f32_16x16x32_bf16 v[128:131], v[136:139], v[182:185], v[128:131]
	v_mfma_f32_16x16x32_bf16 v[124:127], v[144:147], v[182:185], v[124:127]
	v_mfma_f32_16x16x32_bf16 v[112:115], v[136:139], v[202:205], v[112:115]
	v_mfma_f32_16x16x32_bf16 v[108:111], v[144:147], v[202:205], v[108:111]
	v_mfma_f32_16x16x32_bf16 v[96:99], v[136:139], v[210:213], v[96:99]
	v_mfma_f32_16x16x32_bf16 v[92:95], v[144:147], v[210:213], v[92:95]
	v_mfma_f32_16x16x32_bf16 v[80:83], v[136:139], v[218:221], v[80:83]
	v_mfma_f32_16x16x32_bf16 v[76:79], v[144:147], v[218:221], v[76:79]
	s_setprio 0
	s_setprio 1
	v_mfma_f32_16x16x32_bf16 v[120:123], v[148:151], v[178:181], v[120:123]
	v_mfma_f32_16x16x32_bf16 v[116:119], v[156:159], v[178:181], v[116:119]
	v_mfma_f32_16x16x32_bf16 v[104:107], v[148:151], v[186:189], v[104:107]
	v_mfma_f32_16x16x32_bf16 v[100:103], v[156:159], v[186:189], v[100:103]
	v_mfma_f32_16x16x32_bf16 v[88:91], v[148:151], v[206:209], v[88:91]
	v_mfma_f32_16x16x32_bf16 v[84:87], v[156:159], v[206:209], v[84:87]
	v_mfma_f32_16x16x32_bf16 v[72:75], v[148:151], v[214:217], v[72:75]
	v_mfma_f32_16x16x32_bf16 v[68:71], v[156:159], v[214:217], v[68:71]
	v_mfma_f32_16x16x32_bf16 v[120:123], v[152:155], v[182:185], v[120:123]
	v_mfma_f32_16x16x32_bf16 v[116:119], v[174:177], v[182:185], v[116:119]
	v_mfma_f32_16x16x32_bf16 v[104:107], v[152:155], v[202:205], v[104:107]
	v_mfma_f32_16x16x32_bf16 v[100:103], v[174:177], v[202:205], v[100:103]
	v_mfma_f32_16x16x32_bf16 v[88:91], v[152:155], v[210:213], v[88:91]
	v_mfma_f32_16x16x32_bf16 v[84:87], v[174:177], v[210:213], v[84:87]
	v_mfma_f32_16x16x32_bf16 v[72:75], v[152:155], v[218:221], v[72:75]
	v_mfma_f32_16x16x32_bf16 v[68:71], v[174:177], v[218:221], v[68:71]
	s_setprio 0
	s_barrier
; #define PG8_STAGE(bufoff, gbase, voff) do { _Pragma("unroll") for (int _i = 0; _i < 2; ++_i) \
;         __builtin_amdgcn_global_load_lds((const unsigned*)((const char*)(gbase) + (voff)[_i]), (LAS unsigned*)(lds + (bufoff) + ldsw + _i * 8192), 16, 0, 0); } while (0)
; #define PG8_LDA(dst, b, h) do { _Pragma("unroll") for (int m = 0; m < 4; ++m) _Pragma("unroll") for (int k = 0; k < 2; ++k) dst[m][k] = *(const LAS bf16x8*)(lds + PG8_SA(b, h) + aoff + m * 2048 + k * 1024); } while (0)
; #define PG8_LDB(dst, b, h) do { _Pragma("unroll") for (int n = 0; n < 2; ++n) _Pragma("unroll") for (int k = 0; k < 2; ++k) dst[n][k] = *(const LAS bf16x8*)(lds + PG8_SB(b, h) + boff + n * 2048 + k * 1024); } while (0)
; #define PG8_MMA(ai, bj, At, Bt) do { __builtin_amdgcn_s_setprio(1); _Pragma("unroll") for (int m = 0; m < 4; ++m) _Pragma("unroll") for (int n = 0; n < 2; ++n) _Pragma("unroll") for (int k = 0; k < 2; ++k) \
;         acc[ai][bj][m][n] = __builtin_amdgcn_mfma_f32_16x16x32_bf16(Bt[n][k], At[m][k], acc[ai][bj][m][n], 0, 0, 0); __builtin_amdgcn_s_setprio(0); } while (0)
; #define PG8_WAIT_V(n) asm volatile("s_waitcnt vmcnt(" #n ")" ::: "memory")
; #define PG8_WAIT_L(n) asm volatile("s_waitcnt lgkmcnt(" #n ")" ::: "memory")
; #define PG8_BAR __builtin_amdgcn_s_barrier()
; #define PG8_SCHED __builtin_amdgcn_sched_barrier(0)
; template <class Epi, bool ALIGN_EPI>
; DI void gemm_phase(LAS unsigned char* lds, const Sched& S, const Epi& E, int tid) {
;     ...
;         for (int t = 0; t < nt; t += 2) {
;             const bool last = (t == nt - 2);
;             const char* a1 = cA + (size_t)(t + 1) * kstep;
;             const char* a2 = last ? nA : cA + (size_t)(t + 2) * kstep; const char* b2 = last ? nB : cB + (size_t)(t + 2) * kstep;
;             const char* a3 = a2 + kstep; const char* b3 = b2 + kstep;
;             PG8_LDB(B0, 0, 0); PG8_LDB(B1, 0, 1); PG8_SCHED; PG8_LDA(At, 0, 0); PG8_STAGE(PG8_SA(1, 1), a1 + hstepA, voffA);
;     ...
;             PG8_WAIT_V(8); PG8_WAIT_L(0); PG8_BAR; PG8_MMA(0, 0, At, B0); PG8_MMA(0, 1, At, B1); PG8_BAR; PG8_SCHED;
;             PG8_LDA(At, 1, 1); PG8_STAGE(PG8_SB(1, 0), b3, voffB); PG8_STAGE(PG8_SB(1, 1), b3 + hstepB, voffB); PG8_STAGE(PG8_SA(1, 0), a3, voffA);
;             PG8_WAIT_V(8); PG8_WAIT_L(0); PG8_BAR; PG8_MMA(1, 0, At, B0); PG8_MMA(1, 1, At, B1); PG8_BAR; PG8_SCHED;
	s_add_i32 s20, s64, s38
	v_lshl_add_u64 v[190:191], v[190:191], 0, s[84:85]
	s_mov_b32 m0, s20
	ds_read_b128 v[178:181], v193 offset:49152
	ds_read_b128 v[182:185], v193 offset:50176
	ds_read_b128 v[186:189], v193 offset:51200
	ds_read_b128 v[202:205], v193 offset:52224
	ds_read_b128 v[206:209], v193 offset:53248
	ds_read_b128 v[210:213], v193 offset:54272
	ds_read_b128 v[214:217], v193 offset:55296
	ds_read_b128 v[218:221], v193 offset:56320
	global_load_lds_dwordx4 v[190:191], off
	s_add_i32 m0, s20, 0x2000
	s_add_u32 s20, s24, 0x104080
	v_lshl_add_u64 v[190:191], v[194:195], 0, s[84:85]
	s_addc_u32 s21, s25, 0
	s_add_i32 s24, s65, s38
	global_load_lds_dwordx4 v[190:191], off
	v_lshl_add_u64 v[190:191], s[20:21], 0, v[164:165]
	s_mov_b32 m0, s24
	s_nop 0
	global_load_lds_dwordx4 v[190:191], off
	v_lshl_add_u64 v[190:191], s[20:21], 0, v[168:169]
	s_add_i32 m0, s24, 0x2000
	s_nop 0
	global_load_lds_dwordx4 v[190:191], off
	v_lshl_add_u64 v[190:191], v[222:223], 0, s[84:85]
	s_mov_b32 m0, s44
	s_nop 0
	global_load_lds_dwordx4 v[190:191], off
	v_lshl_add_u64 v[190:191], v[224:225], 0, s[84:85]
	s_mov_b32 m0, s45
	s_nop 0
	global_load_lds_dwordx4 v[190:191], off
	s_waitcnt vmcnt(8)
	s_waitcnt lgkmcnt(0)
	s_barrier
	s_setprio 1
	s_waitcnt lgkmcnt(0)
	v_mfma_f32_16x16x32_bf16 v[64:67], v[132:135], v[178:181], v[64:67]
	v_mfma_f32_16x16x32_bf16 v[60:63], v[140:143], v[178:181], v[60:63]
	v_mfma_f32_16x16x32_bf16 v[48:51], v[132:135], v[186:189], v[48:51]
	v_mfma_f32_16x16x32_bf16 v[44:47], v[140:143], v[186:189], v[44:47]
	v_mfma_f32_16x16x32_bf16 v[32:35], v[132:135], v[206:209], v[32:35]
	v_mfma_f32_16x16x32_bf16 v[28:31], v[140:143], v[206:209], v[28:31]
	v_mfma_f32_16x16x32_bf16 v[16:19], v[132:135], v[214:217], v[16:19]
	v_mfma_f32_16x16x32_bf16 v[12:15], v[140:143], v[214:217], v[12:15]
	v_mfma_f32_16x16x32_bf16 v[64:67], v[136:139], v[182:185], v[64:67]
	v_mfma_f32_16x16x32_bf16 v[60:63], v[144:147], v[182:185], v[60:63]
	v_mfma_f32_16x16x32_bf16 v[48:51], v[136:139], v[202:205], v[48:51]
	v_mfma_f32_16x16x32_bf16 v[44:47], v[144:147], v[202:205], v[44:47]
	v_mfma_f32_16x16x32_bf16 v[32:35], v[136:139], v[210:213], v[32:35]
	v_mfma_f32_16x16x32_bf16 v[28:31], v[144:147], v[210:213], v[28:31]
	v_mfma_f32_16x16x32_bf16 v[16:19], v[136:139], v[218:221], v[16:19]
	v_mfma_f32_16x16x32_bf16 v[12:15], v[144:147], v[218:221], v[12:15]
	s_setprio 0
	s_setprio 1
	v_mfma_f32_16x16x32_bf16 v[56:59], v[148:151], v[178:181], v[56:59]
	v_mfma_f32_16x16x32_bf16 v[52:55], v[156:159], v[178:181], v[52:55]
	v_mfma_f32_16x16x32_bf16 v[40:43], v[148:151], v[186:189], v[40:43]
	v_mfma_f32_16x16x32_bf16 v[36:39], v[156:159], v[186:189], v[36:39]
	v_mfma_f32_16x16x32_bf16 v[24:27], v[148:151], v[206:209], v[24:27]
	v_mfma_f32_16x16x32_bf16 v[20:23], v[156:159], v[206:209], v[20:23]
	v_mfma_f32_16x16x32_bf16 v[8:11], v[148:151], v[214:217], v[8:11]
	v_mfma_f32_16x16x32_bf16 v[4:7], v[156:159], v[214:217], v[4:7]
	v_mfma_f32_16x16x32_bf16 v[56:59], v[152:155], v[182:185], v[56:59]
	v_mfma_f32_16x16x32_bf16 v[52:55], v[174:177], v[182:185], v[52:55]
	v_mfma_f32_16x16x32_bf16 v[40:43], v[152:155], v[202:205], v[40:43]
	v_mfma_f32_16x16x32_bf16 v[36:39], v[174:177], v[202:205], v[36:39]
	v_mfma_f32_16x16x32_bf16 v[24:27], v[152:155], v[210:213], v[24:27]
	v_mfma_f32_16x16x32_bf16 v[20:23], v[174:177], v[210:213], v[20:23]
	v_mfma_f32_16x16x32_bf16 v[8:11], v[152:155], v[218:221], v[8:11]
	v_mfma_f32_16x16x32_bf16 v[4:7], v[174:177], v[218:221], v[4:7]
	s_setprio 0
	s_add_u32 s61, s61, 0x100
	s_addc_u32 s62, s62, 0
	s_cmp_ge_i32 s63, s55
	s_mov_b64 s[20:21], s[22:23]
	s_mov_b32 s24, s63
	s_add_i32 s63, s24, 2
	s_add_u32 s22, s20, 0x100
	s_addc_u32 s23, s21, 0
	s_add_i32 s64, 0, 0x10000
	s_cmp_eq_u32 s60, s24
	s_cselect_b32 s27, s56, s23
	s_cselect_b32 s26, s57, s22
	s_cselect_b32 s25, s58, s62
	s_cselect_b32 s24, s59, s61
	s_add_i32 s65, 0, 0x14000
	v_add_u32_e32 v144, s64, v161
	v_add_u32_e32 v174, s65, v161
	s_barrier
